# all flat_store (global addresses) issued as global_store: stores count on vmcnt only, so lgkmcnt waits for LDS/bpermute results never wait on a store
# baseline (speedup 1.0000x reference)
.LBB0_16:
	s_or_b32 s3, s13, s20
	s_lshl_b32 s15, s13, 2
	v_mad_i64_i32 v[16:17], s[86:87], s3, v29, v[30:31]
	s_or_b32 s3, s13, s28
	s_or_b32 s14, s13, s17
	v_mad_i64_i32 v[14:15], s[86:87], s3, v29, v[30:31]
	s_add_i32 s3, s18, s15
	v_mov_b32_e32 v55, s3
	s_lshl_b32 s3, s14, 2
	s_add_i32 s3, s3, 0
	v_mov_b32_e32 v6, s3
	ds_read_b128 v[56:59], v55 offset:4096
	ds_read_b128 v[2:5], v55 offset:4112
	ds_read_b128 v[60:63], v6
	ds_read_b128 v[64:67], v55 offset:16
	s_or_b32 s2, s13, s19
	s_or_b32 s88, s13, s21
	s_or_b32 s89, s13, s22
	s_or_b32 s90, s13, s23
	s_or_b32 s91, s13, s24
	s_or_b32 s92, s13, s25
	s_or_b32 s93, s13, s26
	v_mad_i64_i32 v[70:71], s[96:97], s14, v29, v[30:31]
	v_mad_i64_i32 v[12:13], s[86:87], s2, v29, v[30:31]
	v_mad_i64_i32 v[20:21], s[86:87], s88, v29, v[30:31]
	v_mad_i64_i32 v[34:35], s[86:87], s89, v29, v[30:31]
	v_mad_i64_i32 v[38:39], s[86:87], s90, v29, v[30:31]
	v_mad_i64_i32 v[44:45], s[86:87], s91, v29, v[30:31]
	v_mad_i64_i32 v[46:47], s[86:87], s92, v29, v[30:31]
	v_mad_i64_i32 v[68:69], s[86:87], s93, v29, v[30:31]
	s_waitcnt lgkmcnt(0)
	v_mov_b32_e32 v72, v60
	v_mov_b32_e32 v74, v62
	global_load_dword v52, v[70:71], off nt
	global_load_dword v54, v[12:13], off nt
	global_load_dword v60, v[16:17], off nt
	global_load_dword v62, v[20:21], off nt
	s_nop 0
	global_load_dword v70, v[34:35], off nt
	global_load_dword v76, v[38:39], off nt
	global_load_dword v78, v[44:45], off nt
	global_load_dword v80, v[46:47], off nt
	global_load_dword v50, v[68:69], off nt
	ds_read_b128 v[44:47], v55 offset:8192
	v_mov_b32_e32 v73, v56
	v_mov_b32_e32 v56, v61
	v_mov_b32_e32 v75, v58
	v_mov_b32_e32 v58, v63
	s_or_b32 s2, s13, s27
	v_mov_b32_e32 v69, v4
	s_waitcnt lgkmcnt(1)
	v_mov_b32_e32 v68, v66
	s_or_b32 s88, s13, s29
	s_or_b32 s89, s13, s30
	s_or_b32 s94, s13, s31
	s_or_b32 s91, s13, s34
	s_or_b32 s95, s13, s35
	s_or_b32 s33, s13, s36
	v_mad_i64_i32 v[10:11], s[86:87], s2, v29, v[30:31]
	v_mov_b32_e32 v4, v67
	v_mad_i64_i32 v[18:19], s[86:87], s88, v29, v[30:31]
	v_mad_i64_i32 v[32:33], s[86:87], s89, v29, v[30:31]
	v_mad_i64_i32 v[36:37], s[86:87], s94, v29, v[30:31]
	v_mad_i64_i32 v[40:41], s[86:87], s91, v29, v[30:31]
	v_mad_i64_i32 v[42:43], s[96:97], s95, v29, v[30:31]
	v_mad_i64_i32 v[48:49], s[14:15], s33, v29, v[30:31]
	s_or_b32 s2, s13, s37
	s_or_b32 s94, s13, s41
	s_or_b32 s90, s13, s38
	s_or_b32 s92, s13, s39
	s_or_b32 s89, s13, s40
	s_or_b32 s87, s13, s42
	s_or_b32 s93, s13, s43
	s_or_b32 s91, s13, s44
	v_mad_i64_i32 v[6:7], s[14:15], s2, v29, v[30:31]
	v_mad_i64_i32 v[34:35], s[96:97], s94, v29, v[30:31]
	v_mad_i64_i32 v[12:13], s[96:97], s90, v29, v[30:31]
	v_mad_i64_i32 v[16:17], s[96:97], s92, v29, v[30:31]
	v_mad_i64_i32 v[20:21], s[96:97], s89, v29, v[30:31]
	v_mad_i64_i32 v[38:39], s[96:97], s87, v29, v[30:31]
	s_or_b32 s86, s13, s45
	s_or_b32 s92, s13, s50
	s_or_b32 s88, s13, s46
	s_or_b32 s15, s13, s47
	s_or_b32 s90, s13, s48
	s_or_b32 s95, s13, s49
	s_or_b32 s89, s13, s51
	s_or_b32 s87, s13, s52
	s_or_b32 s14, s13, s53
	s_or_b32 s94, s13, s58
	s_or_b32 s33, s13, s80
	v_mad_i64_i32 v[82:83], s[2:3], s33, v29, v[30:31]
	s_waitcnt vmcnt(0)
	v_pk_fma_f32 v[8:9], v[52:53], v[72:73], v[8:9] op_sel_hi:[0,1,1]
	s_waitcnt vmcnt(7)
	v_pk_fma_f32 v[8:9], v[54:55], v[56:57], v[8:9] op_sel_hi:[0,1,1]
	s_waitcnt vmcnt(6)
	v_pk_fma_f32 v[8:9], v[60:61], v[74:75], v[8:9] op_sel_hi:[0,1,1]
	s_waitcnt vmcnt(5)
	v_pk_fma_f32 v[8:9], v[62:63], v[58:59], v[8:9] op_sel_hi:[0,1,1]
	ds_read_b128 v[56:59], v55 offset:8208
	s_waitcnt lgkmcnt(1)
	v_fmac_f32_e32 v53, v52, v44
	v_fmac_f32_e32 v53, v54, v45
	v_fmac_f32_e32 v53, v60, v46
	v_fmac_f32_e32 v53, v62, v47
	ds_read_b128 v[60:63], v55 offset:32
	v_mov_b32_e32 v47, v2
	v_mov_b32_e32 v46, v64
	v_mov_b32_e32 v2, v65
	s_waitcnt vmcnt(4)
	v_pk_fma_f32 v[8:9], v[70:71], v[46:47], v[8:9] op_sel_hi:[0,1,1]
	s_waitcnt lgkmcnt(1)
	v_fmac_f32_e32 v53, v70, v56
	s_waitcnt vmcnt(3)
	v_pk_fma_f32 v[2:3], v[76:77], v[2:3], v[8:9] op_sel_hi:[0,1,1]
	v_fmac_f32_e32 v53, v76, v57
	s_waitcnt vmcnt(2)
	v_pk_fma_f32 v[2:3], v[78:79], v[68:69], v[2:3] op_sel_hi:[0,1,1]
	ds_read_b128 v[64:67], v55 offset:48
	s_waitcnt vmcnt(1)
	v_pk_fma_f32 v[56:57], v[80:81], v[4:5], v[2:3] op_sel_hi:[0,1,1]
	ds_read_b128 v[68:71], v55 offset:4128
	ds_read_b128 v[2:5], v55 offset:4144
	v_fmac_f32_e32 v53, v78, v58
	s_waitcnt lgkmcnt(3)
	v_mov_b32_e32 v58, v60
	v_mov_b32_e32 v60, v62
	global_load_dword v10, v[10:11], off nt
	s_nop 0
	global_load_dword v54, v[14:15], off nt
	global_load_dword v62, v[18:19], off nt
	global_load_dword v72, v[32:33], off nt
	global_load_dword v74, v[36:37], off nt
	global_load_dword v76, v[40:41], off nt
	global_load_dword v78, v[42:43], off nt
	global_load_dword v52, v[48:49], off nt
	ds_read_b128 v[40:43], v55 offset:8224
	v_fmac_f32_e32 v53, v80, v59
	s_waitcnt lgkmcnt(2)
	v_mov_b32_e32 v59, v68
	v_mov_b32_e32 v68, v61
	s_waitcnt vmcnt(8)
	v_pk_fma_f32 v[14:15], v[50:51], v[58:59], v[56:57] op_sel_hi:[0,1,1]
	ds_read_b128 v[56:59], v55 offset:8240
	s_waitcnt lgkmcnt(1)
	v_fmac_f32_e32 v53, v50, v40
	v_mov_b32_e32 v61, v70
	v_mov_b32_e32 v70, v63
	v_mad_i64_i32 v[44:45], s[96:97], s93, v29, v[30:31]
	v_mad_i64_i32 v[46:47], s[96:97], s91, v29, v[30:31]
	v_mad_i64_i32 v[8:9], s[96:97], s86, v29, v[30:31]
	v_mad_i64_i32 v[18:19], s[96:97], s15, v29, v[30:31]
	v_mad_i64_i32 v[32:33], s[2:3], s90, v29, v[30:31]
	v_mad_i64_i32 v[36:37], s[2:3], s95, v29, v[30:31]
	s_or_b32 s91, s13, s54
	s_or_b32 s93, s13, s56
	s_or_b32 s86, s13, s55
	s_or_b32 s90, s13, s59
	s_or_b32 s15, s13, s61
	s_or_b32 s95, s13, s65
	s_waitcnt vmcnt(7)
	v_pk_fma_f32 v[14:15], v[10:11], v[68:69], v[14:15] op_sel_hi:[0,1,1]
	v_fmac_f32_e32 v53, v10, v41
	s_waitcnt vmcnt(6)
	v_pk_fma_f32 v[14:15], v[54:55], v[60:61], v[14:15] op_sel_hi:[0,1,1]
	v_fmac_f32_e32 v53, v54, v42
	s_waitcnt vmcnt(5)
	v_pk_fma_f32 v[48:49], v[62:63], v[70:71], v[14:15] op_sel_hi:[0,1,1]
	v_fmac_f32_e32 v53, v62, v43
	ds_read_b128 v[60:63], v55 offset:64
	ds_read_b128 v[68:71], v55 offset:80
	v_mov_b32_e32 v10, v64
	v_mov_b32_e32 v11, v2
	v_mov_b32_e32 v2, v65
	s_waitcnt vmcnt(4)
	v_pk_fma_f32 v[10:11], v[72:73], v[10:11], v[48:49] op_sel_hi:[0,1,1]
	s_waitcnt lgkmcnt(2)
	v_fmac_f32_e32 v53, v72, v56
	v_mov_b32_e32 v64, v66
	v_mov_b32_e32 v65, v4
	s_waitcnt vmcnt(3)
	v_pk_fma_f32 v[2:3], v[74:75], v[2:3], v[10:11] op_sel_hi:[0,1,1]
	v_fmac_f32_e32 v53, v74, v57
	v_mov_b32_e32 v4, v67
	s_waitcnt vmcnt(2)
	v_pk_fma_f32 v[2:3], v[76:77], v[64:65], v[2:3] op_sel_hi:[0,1,1]
	v_fmac_f32_e32 v53, v76, v58
	ds_read_b128 v[64:67], v55 offset:4160
	s_waitcnt vmcnt(1)
	v_pk_fma_f32 v[56:57], v[78:79], v[4:5], v[2:3] op_sel_hi:[0,1,1]
	v_fmac_f32_e32 v53, v78, v59
	ds_read_b128 v[2:5], v55 offset:4176
	s_waitcnt lgkmcnt(3)
	v_mov_b32_e32 v58, v60
	v_mov_b32_e32 v60, v62
	global_load_dword v54, v[6:7], off nt
	global_load_dword v62, v[12:13], off nt
	global_load_dword v72, v[16:17], off nt
	global_load_dword v74, v[20:21], off nt
	s_nop 0
	global_load_dword v34, v[34:35], off nt
	s_nop 0
	global_load_dword v76, v[38:39], off nt
	global_load_dword v78, v[44:45], off nt
	global_load_dword v50, v[46:47], off nt
	ds_read_b128 v[44:47], v55 offset:8256
	s_waitcnt lgkmcnt(2)
	v_mov_b32_e32 v59, v64
	s_waitcnt vmcnt(8)
	v_pk_fma_f32 v[6:7], v[52:53], v[58:59], v[56:57] op_sel_hi:[0,1,1]
	ds_read_b128 v[56:59], v55 offset:8272
	v_mov_b32_e32 v64, v61
	s_waitcnt lgkmcnt(1)
	v_fmac_f32_e32 v53, v52, v44
	v_mov_b32_e32 v61, v66
	v_mov_b32_e32 v66, v63
	v_mad_i64_i32 v[40:41], s[2:3], s92, v29, v[30:31]
	v_mad_i64_i32 v[14:15], s[96:97], s88, v29, v[30:31]
	v_mad_i64_i32 v[42:43], s[2:3], s89, v29, v[30:31]
	v_mad_i64_i32 v[48:49], s[2:3], s87, v29, v[30:31]
	s_or_b32 s96, s13, s57
	s_or_b32 s88, s13, s60
	v_mad_i64_i32 v[10:11], s[2:3], s14, v29, v[30:31]
	v_mad_i64_i32 v[16:17], s[2:3], s93, v29, v[30:31]
	v_mad_i64_i32 v[20:21], s[2:3], s96, v29, v[30:31]
	v_mad_i64_i32 v[12:13], s[2:3], s86, v29, v[30:31]
	v_mad_i64_i32 v[38:39], s[2:3], s94, v29, v[30:31]
	s_or_b32 s87, s13, s63
	s_or_b32 s92, s13, s62
	s_or_b32 s93, s13, s66
	s_or_b32 s89, s13, s67
	s_or_b32 s86, s13, s68
	s_or_b32 s14, s13, s69
	s_waitcnt vmcnt(7)
	v_pk_fma_f32 v[6:7], v[54:55], v[64:65], v[6:7] op_sel_hi:[0,1,1]
	v_fmac_f32_e32 v53, v54, v45
	s_waitcnt vmcnt(6)
	v_pk_fma_f32 v[6:7], v[62:63], v[60:61], v[6:7] op_sel_hi:[0,1,1]
	v_fmac_f32_e32 v53, v62, v46
	s_waitcnt vmcnt(5)
	v_pk_fma_f32 v[60:61], v[72:73], v[66:67], v[6:7] op_sel_hi:[0,1,1]
	v_fmac_f32_e32 v53, v72, v47
	v_mov_b32_e32 v46, v68
	v_mov_b32_e32 v47, v2
	v_mov_b32_e32 v2, v69
	s_waitcnt vmcnt(4)
	v_pk_fma_f32 v[46:47], v[74:75], v[46:47], v[60:61] op_sel_hi:[0,1,1]
	s_waitcnt lgkmcnt(0)
	v_fmac_f32_e32 v53, v74, v56
	v_mov_b32_e32 v64, v70
	v_mov_b32_e32 v65, v4
	s_waitcnt vmcnt(3)
	v_pk_fma_f32 v[2:3], v[34:35], v[2:3], v[46:47] op_sel_hi:[0,1,1]
	v_fmac_f32_e32 v53, v34, v57
	v_mov_b32_e32 v4, v71
	s_waitcnt vmcnt(2)
	v_pk_fma_f32 v[2:3], v[76:77], v[64:65], v[2:3] op_sel_hi:[0,1,1]
	v_fmac_f32_e32 v53, v76, v58
	ds_read_b128 v[60:63], v55 offset:96
	ds_read_b128 v[68:71], v55 offset:112
	ds_read_b128 v[64:67], v55 offset:4192
	s_waitcnt vmcnt(1)
	v_pk_fma_f32 v[56:57], v[78:79], v[4:5], v[2:3] op_sel_hi:[0,1,1]
	v_fmac_f32_e32 v53, v78, v59
	ds_read_b128 v[2:5], v55 offset:4208
	global_load_dword v52, v[8:9], off nt
	global_load_dword v54, v[14:15], off nt
	global_load_dword v72, v[18:19], off nt
	global_load_dword v74, v[32:33], off nt
	global_load_dword v76, v[36:37], off nt
	global_load_dword v78, v[40:41], off nt
	global_load_dword v80, v[42:43], off nt
	s_nop 0
	global_load_dword v40, v[48:49], off nt
	s_waitcnt lgkmcnt(3)
	v_mov_b32_e32 v58, v60
	s_waitcnt lgkmcnt(1)
	v_mov_b32_e32 v59, v64
	s_waitcnt vmcnt(8)
	v_pk_fma_f32 v[8:9], v[50:51], v[58:59], v[56:57] op_sel_hi:[0,1,1]
	ds_read_b128 v[56:59], v55 offset:8288
	v_mov_b32_e32 v64, v61
	v_mov_b32_e32 v60, v62
	v_mov_b32_e32 v61, v66
	v_mov_b32_e32 v66, v63
	v_mad_i64_i32 v[6:7], s[2:3], s91, v29, v[30:31]
	v_mad_i64_i32 v[44:45], s[2:3], s90, v29, v[30:31]
	v_mad_i64_i32 v[46:47], s[2:3], s88, v29, v[30:31]
	s_or_b32 s91, s13, s64
	v_mad_i64_i32 v[34:35], s[2:3], s15, v29, v[30:31]
	v_mad_i64_i32 v[14:15], s[2:3], s87, v29, v[30:31]
	v_mad_i64_i32 v[18:19], s[2:3], s91, v29, v[30:31]
	v_mad_i64_i32 v[32:33], s[2:3], s95, v29, v[30:31]
	v_mad_i64_i32 v[36:37], s[2:3], s93, v29, v[30:31]
	v_mad_i64_i32 v[42:43], s[2:3], s89, v29, v[30:31]
	s_or_b32 s15, s13, s71
	s_or_b32 s90, s13, s72
	s_or_b32 s88, s13, s70
	s_or_b32 s87, s13, s74
	s_or_b32 s91, s13, s75
	s_or_b32 s93, s13, s76
	s_or_b32 s89, s13, s77
	s_waitcnt vmcnt(7)
	v_pk_fma_f32 v[8:9], v[52:53], v[64:65], v[8:9] op_sel_hi:[0,1,1]
	s_waitcnt vmcnt(6)
	v_pk_fma_f32 v[8:9], v[54:55], v[60:61], v[8:9] op_sel_hi:[0,1,1]
	ds_read_b128 v[60:63], v55 offset:8304
	s_waitcnt lgkmcnt(1)
	v_fmac_f32_e32 v53, v50, v56
	s_waitcnt vmcnt(5)
	v_pk_fma_f32 v[48:49], v[72:73], v[66:67], v[8:9] op_sel_hi:[0,1,1]
	v_fmac_f32_e32 v53, v52, v57
	v_mov_b32_e32 v56, v68
	v_mov_b32_e32 v57, v2
	v_fmac_f32_e32 v53, v54, v58
	v_mov_b32_e32 v2, v69
	s_waitcnt vmcnt(4)
	v_pk_fma_f32 v[48:49], v[74:75], v[56:57], v[48:49] op_sel_hi:[0,1,1]
	v_fmac_f32_e32 v53, v72, v59
	v_mov_b32_e32 v64, v70
	v_mov_b32_e32 v65, v4
	s_waitcnt vmcnt(3)
	v_pk_fma_f32 v[2:3], v[76:77], v[2:3], v[48:49] op_sel_hi:[0,1,1]
	v_mov_b32_e32 v4, v71
	s_waitcnt lgkmcnt(0)
	v_fmac_f32_e32 v53, v74, v60
	s_waitcnt vmcnt(2)
	v_pk_fma_f32 v[2:3], v[78:79], v[64:65], v[2:3] op_sel_hi:[0,1,1]
	ds_read_b128 v[56:59], v55 offset:128
	ds_read_b128 v[68:71], v55 offset:144
	v_fmac_f32_e32 v53, v76, v61
	ds_read_b128 v[64:67], v55 offset:4224
	s_waitcnt vmcnt(1)
	v_pk_fma_f32 v[60:61], v[80:81], v[4:5], v[2:3] op_sel_hi:[0,1,1]
	ds_read_b128 v[2:5], v55 offset:4240
	global_load_dword v50, v[10:11], off nt
	s_nop 0
	global_load_dword v6, v[6:7], off nt
	s_nop 0
	global_load_dword v52, v[12:13], off nt
	s_nop 0
	global_load_dword v16, v[16:17], off nt
	s_nop 0
	global_load_dword v20, v[20:21], off nt
	s_nop 0
	global_load_dword v54, v[38:39], off nt
	global_load_dword v72, v[44:45], off nt
	global_load_dword v74, v[46:47], off nt
	v_fmac_f32_e32 v53, v78, v62
	v_fmac_f32_e32 v53, v80, v63
	s_waitcnt lgkmcnt(3)
	v_mov_b32_e32 v62, v56
	s_waitcnt lgkmcnt(1)
	v_mov_b32_e32 v63, v64
	v_mov_b32_e32 v64, v57
	s_waitcnt vmcnt(8)
	v_pk_fma_f32 v[10:11], v[40:41], v[62:63], v[60:61] op_sel_hi:[0,1,1]
	v_mov_b32_e32 v56, v58
	v_mov_b32_e32 v57, v66
	v_mov_b32_e32 v66, v59
	ds_read_b128 v[44:47], v55 offset:8336
	s_waitcnt lgkmcnt(1)
	v_mov_b32_e32 v41, v4
	v_mov_b32_e32 v4, v71
	v_mad_i64_i32 v[8:9], s[2:3], s92, v29, v[30:31]
	v_mad_i64_i32 v[48:49], s[2:3], s86, v29, v[30:31]
	s_or_b32 s92, s13, s73
	v_mad_i64_i32 v[58:59], s[2:3], s14, v29, v[30:31]
	v_mad_i64_i32 v[60:61], s[2:3], s15, v29, v[30:31]
	v_mad_i64_i32 v[62:63], s[2:3], s90, v29, v[30:31]
	s_or_b32 s86, s13, s78
	s_or_b32 s14, s13, s79
	s_or_b32 s15, s13, s81
	s_or_b32 s90, s13, s83
	v_mad_i64_i32 v[80:81], s[2:3], s14, v29, v[30:31]
	v_mad_i64_i32 v[84:85], s[2:3], s15, v29, v[30:31]
	s_waitcnt vmcnt(7)
	v_pk_fma_f32 v[10:11], v[50:51], v[64:65], v[10:11] op_sel_hi:[0,1,1]
	s_waitcnt vmcnt(6)
	v_pk_fma_f32 v[38:39], v[6:7], v[56:57], v[10:11] op_sel_hi:[0,1,1]
	ds_read_b128 v[10:13], v55 offset:8320
	s_waitcnt vmcnt(5)
	v_pk_fma_f32 v[38:39], v[52:53], v[66:67], v[38:39] op_sel_hi:[0,1,1]
	v_mov_b32_e32 v7, v2
	v_mov_b32_e32 v2, v69
	v_mad_i64_i32 v[56:57], s[2:3], s88, v29, v[30:31]
	s_waitcnt lgkmcnt(0)
	v_fmac_f32_e32 v53, v40, v10
	v_fmac_f32_e32 v53, v50, v11
	v_fmac_f32_e32 v53, v6, v12
	v_fmac_f32_e32 v53, v52, v13
	v_mov_b32_e32 v6, v68
	s_waitcnt vmcnt(4)
	v_pk_fma_f32 v[6:7], v[16:17], v[6:7], v[38:39] op_sel_hi:[0,1,1]
	v_fmac_f32_e32 v53, v16, v44
	v_mov_b32_e32 v40, v70
	s_waitcnt vmcnt(3)
	v_pk_fma_f32 v[2:3], v[20:21], v[2:3], v[6:7] op_sel_hi:[0,1,1]
	v_fmac_f32_e32 v53, v20, v45
	s_waitcnt vmcnt(2)
	v_pk_fma_f32 v[2:3], v[54:55], v[40:41], v[2:3] op_sel_hi:[0,1,1]
	v_fmac_f32_e32 v53, v54, v46
	ds_read_b128 v[10:13], v55 offset:160
	ds_read_b128 v[38:41], v55 offset:4256
	s_waitcnt vmcnt(1)
	v_pk_fma_f32 v[6:7], v[72:73], v[4:5], v[2:3] op_sel_hi:[0,1,1]
	ds_read_b128 v[2:5], v55 offset:176
	v_fmac_f32_e32 v53, v72, v47
	ds_read_b128 v[44:47], v55 offset:4272
	global_load_dword v34, v[34:35], off nt
	s_nop 0
	global_load_dword v50, v[8:9], off nt
	s_nop 0
	global_load_dword v14, v[14:15], off nt
	s_nop 0
	global_load_dword v52, v[18:19], off nt
	global_load_dword v54, v[32:33], off nt
	global_load_dword v72, v[36:37], off nt
	global_load_dword v76, v[42:43], off nt
	global_load_dword v78, v[48:49], off nt
	s_waitcnt lgkmcnt(3)
	v_mov_b32_e32 v16, v10
	s_waitcnt lgkmcnt(2)
	v_mov_b32_e32 v17, v38
	v_mov_b32_e32 v38, v11
	s_waitcnt vmcnt(8)
	v_pk_fma_f32 v[6:7], v[74:75], v[16:17], v[6:7] op_sel_hi:[0,1,1]
	v_mov_b32_e32 v10, v12
	v_mov_b32_e32 v11, v40
	v_mov_b32_e32 v40, v13
	v_mad_i64_i32 v[64:65], s[2:3], s92, v29, v[30:31]
	v_mad_i64_i32 v[66:67], s[2:3], s87, v29, v[30:31]
	v_mad_i64_i32 v[68:69], s[2:3], s91, v29, v[30:31]
	v_mad_i64_i32 v[20:21], s[2:3], s93, v29, v[30:31]
	s_or_b32 s88, s13, s82
	v_mad_i64_i32 v[70:71], s[2:3], s89, v29, v[30:31]
	s_add_i32 s13, s13, 64
	s_cmpk_eq_i32 s13, 0x80
	s_waitcnt vmcnt(7)
	v_pk_fma_f32 v[6:7], v[34:35], v[38:39], v[6:7] op_sel_hi:[0,1,1]
	s_waitcnt vmcnt(6)
	v_pk_fma_f32 v[10:11], v[50:51], v[10:11], v[6:7] op_sel_hi:[0,1,1]
	ds_read_b128 v[6:9], v55 offset:8352
	s_waitcnt vmcnt(5)
	v_pk_fma_f32 v[16:17], v[14:15], v[40:41], v[10:11] op_sel_hi:[0,1,1]
	ds_read_b128 v[10:13], v55 offset:8368
	s_waitcnt lgkmcnt(1)
	v_fmac_f32_e32 v53, v74, v6
	v_fmac_f32_e32 v53, v34, v7
	v_fmac_f32_e32 v53, v50, v8
	v_fmac_f32_e32 v53, v14, v9
	global_load_dword v14, v[58:59], off nt
	global_load_dword v50, v[56:57], off nt
	s_nop 0
	global_load_dword v60, v[60:61], off nt
	s_nop 0
	global_load_dword v18, v[62:63], off nt
	s_nop 0
	global_load_dword v62, v[64:65], off nt
	global_load_dword v36, v[66:67], off nt
	global_load_dword v34, v[68:69], off nt
	global_load_dword v32, v[20:21], off nt
	ds_read_b128 v[6:9], v55 offset:192
	ds_read_b128 v[38:41], v55 offset:4288
	v_mov_b32_e32 v20, v2
	v_mov_b32_e32 v21, v44
	v_mov_b32_e32 v44, v3
	v_mov_b32_e32 v2, v4
	v_mov_b32_e32 v3, v46
	v_mov_b32_e32 v46, v5
	s_waitcnt vmcnt(12)
	v_pk_fma_f32 v[4:5], v[52:53], v[20:21], v[16:17] op_sel_hi:[0,1,1]
	s_waitcnt vmcnt(11)
	v_pk_fma_f32 v[4:5], v[54:55], v[44:45], v[4:5] op_sel_hi:[0,1,1]
	ds_read_b128 v[42:45], v55 offset:8384
	s_waitcnt lgkmcnt(3)
	v_fmac_f32_e32 v53, v52, v10
	s_waitcnt vmcnt(10)
	v_pk_fma_f32 v[2:3], v[72:73], v[2:3], v[4:5] op_sel_hi:[0,1,1]
	v_fmac_f32_e32 v53, v54, v11
	s_waitcnt vmcnt(9)
	v_pk_fma_f32 v[16:17], v[76:77], v[46:47], v[2:3] op_sel_hi:[0,1,1]
	ds_read_b128 v[46:49], v55 offset:208
	ds_read_b128 v[2:5], v55 offset:4304
	s_waitcnt lgkmcnt(4)
	v_mov_b32_e32 v20, v6
	s_waitcnt lgkmcnt(3)
	v_mov_b32_e32 v21, v38
	v_fmac_f32_e32 v53, v72, v12
	v_mov_b32_e32 v38, v7
	v_mov_b32_e32 v6, v8
	v_mov_b32_e32 v7, v40
	v_mov_b32_e32 v40, v9
	s_waitcnt vmcnt(8)
	v_pk_fma_f32 v[8:9], v[78:79], v[20:21], v[16:17] op_sel_hi:[0,1,1]
	v_fmac_f32_e32 v53, v76, v13
	ds_read_b128 v[10:13], v55 offset:8400
	s_waitcnt lgkmcnt(3)
	v_fmac_f32_e32 v53, v78, v42
	ds_read_b128 v[56:59], v55 offset:224
	ds_read_b128 v[66:69], v55 offset:240
	s_waitcnt lgkmcnt(4)
	v_mov_b32_e32 v64, v46
	s_waitcnt lgkmcnt(3)
	v_mov_b32_e32 v65, v2
	v_mov_b32_e32 v2, v47
	v_mov_b32_e32 v46, v48
	v_mov_b32_e32 v47, v4
	v_mov_b32_e32 v4, v49
	v_mad_i64_i32 v[48:49], s[2:3], s88, v29, v[30:31]
	v_mad_i64_i32 v[74:75], s[2:3], s86, v29, v[30:31]
	s_waitcnt lgkmcnt(1)
	v_mov_b32_e32 v42, v58
	s_waitcnt vmcnt(7)
	v_pk_fma_f32 v[8:9], v[14:15], v[38:39], v[8:9] op_sel_hi:[0,1,1]
	s_waitcnt vmcnt(6)
	v_pk_fma_f32 v[6:7], v[50:51], v[6:7], v[8:9] op_sel_hi:[0,1,1]
	v_fmac_f32_e32 v53, v14, v43
	ds_read_b128 v[14:17], v55 offset:4320
	s_waitcnt vmcnt(5)
	v_pk_fma_f32 v[20:21], v[60:61], v[40:41], v[6:7] op_sel_hi:[0,1,1]
	ds_read_b128 v[6:9], v55 offset:4336
	v_fmac_f32_e32 v53, v50, v44
	v_fmac_f32_e32 v53, v60, v45
	v_mov_b32_e32 v44, v56
	s_waitcnt lgkmcnt(2)
	v_mov_b32_e32 v40, v66
	s_waitcnt lgkmcnt(0)
	v_mov_b32_e32 v41, v6
	v_mov_b32_e32 v6, v67
	v_mad_i64_i32 v[66:67], s[2:3], s90, v29, v[30:31]
	global_load_dword v60, v[70:71], off nt
	global_load_dword v58, v[74:75], off nt
	global_load_dword v56, v[80:81], off nt
	global_load_dword v54, v[82:83], off nt
	global_load_dword v52, v[84:85], off nt
	global_load_dword v50, v[48:49], off nt
	s_nop 0
	global_load_dword v48, v[66:67], off nt
	s_waitcnt vmcnt(11)
	v_pk_fma_f32 v[64:65], v[18:19], v[64:65], v[20:21] op_sel_hi:[0,1,1]
	v_fmac_f32_e32 v53, v18, v10
	ds_read_b128 v[18:21], v55 offset:8416
	s_waitcnt vmcnt(10)
	v_pk_fma_f32 v[2:3], v[62:63], v[2:3], v[64:65] op_sel_hi:[0,1,1]
	v_fmac_f32_e32 v53, v62, v11
	s_waitcnt vmcnt(9)
	v_pk_fma_f32 v[2:3], v[36:37], v[46:47], v[2:3] op_sel_hi:[0,1,1]
	v_fmac_f32_e32 v53, v36, v12
	v_mov_b32_e32 v45, v14
	ds_read_b128 v[62:65], v55 offset:8432
	s_waitcnt vmcnt(8)
	v_pk_fma_f32 v[2:3], v[34:35], v[4:5], v[2:3] op_sel_hi:[0,1,1]
	v_fmac_f32_e32 v53, v34, v13
	v_mov_b32_e32 v14, v57
	s_waitcnt vmcnt(7)
	v_pk_fma_f32 v[2:3], v[32:33], v[44:45], v[2:3] op_sel_hi:[0,1,1]
	s_waitcnt lgkmcnt(1)
	v_fmac_f32_e32 v53, v32, v18
	v_mov_b32_e32 v43, v16
	v_mov_b32_e32 v16, v59
	v_mov_b32_e32 v38, v68
	v_mov_b32_e32 v39, v8
	v_mov_b32_e32 v8, v69
	s_waitcnt vmcnt(6)
	v_pk_fma_f32 v[2:3], v[60:61], v[14:15], v[2:3] op_sel_hi:[0,1,1]
	v_fmac_f32_e32 v53, v60, v19
	s_waitcnt vmcnt(5)
	v_pk_fma_f32 v[2:3], v[58:59], v[42:43], v[2:3] op_sel_hi:[0,1,1]
	v_fmac_f32_e32 v53, v58, v20
	s_waitcnt vmcnt(4)
	v_pk_fma_f32 v[2:3], v[56:57], v[16:17], v[2:3] op_sel_hi:[0,1,1]
	v_fmac_f32_e32 v53, v56, v21
	s_waitcnt vmcnt(3)
	v_pk_fma_f32 v[2:3], v[54:55], v[40:41], v[2:3] op_sel_hi:[0,1,1]
	s_waitcnt lgkmcnt(0)
	v_fmac_f32_e32 v53, v54, v62
	s_waitcnt vmcnt(2)
	v_pk_fma_f32 v[2:3], v[52:53], v[6:7], v[2:3] op_sel_hi:[0,1,1]
	v_fmac_f32_e32 v53, v52, v63
	s_waitcnt vmcnt(1)
	v_pk_fma_f32 v[2:3], v[50:51], v[38:39], v[2:3] op_sel_hi:[0,1,1]
	v_fmac_f32_e32 v53, v50, v64
	s_waitcnt vmcnt(0)
	v_pk_fma_f32 v[8:9], v[48:49], v[8:9], v[2:3] op_sel_hi:[0,1,1]
	v_fmac_f32_e32 v53, v48, v65
	s_cbranch_scc0 .LBB0_16
	ds_write2st64_b32 v23, v8, v9 offset0:48 offset1:49
	ds_write_b32 v23, v53 offset:12800
	s_waitcnt lgkmcnt(0)
	s_barrier
	s_and_saveexec_b64 s[14:15], vcc
	s_cbranch_execz .LBB0_14
	s_load_dwordx2 s[2:3], s[8:9], 0x38
	s_mul_i32 s13, s85, 0x1800
	s_add_i32 s13, s13, s12
	v_or_b32_e32 v2, s13, v24
	v_ashrrev_i32_e32 v3, 31, v2
	s_waitcnt lgkmcnt(0)
	v_lshl_add_u64 v[2:3], v[2:3], 2, s[2:3]
	global_load_dword v12, v[2:3], off
	ds_read2st64_b32 v[2:3], v51 offset0:48 offset1:51
	ds_read2st64_b32 v[4:5], v51 offset0:54 offset1:57
	ds_read2st64_b32 v[6:7], v51 offset0:60 offset1:63
	ds_read2st64_b32 v[8:9], v51 offset0:66 offset1:69
	v_mad_u64_u32 v[10:11], s[2:3], s85, 3, v[28:29]
	s_waitcnt lgkmcnt(3)
	v_add_f32_e32 v2, 0, v2
	v_add_f32_e32 v2, v2, v3
	s_waitcnt lgkmcnt(2)
	v_add_f32_e32 v2, v2, v4
	s_movk_i32 s2, 0x1800
	v_add_f32_e32 v2, v2, v5
	v_mul_lo_u32 v10, v10, s2
	s_waitcnt lgkmcnt(1)
	v_add_f32_e32 v2, v2, v6
	v_add_u32_e32 v10, s12, v10
	v_add_f32_e32 v2, v2, v7
	v_or_b32_e32 v10, v10, v24
	s_waitcnt lgkmcnt(0)
	v_add_f32_e32 v2, v2, v8
	v_ashrrev_i32_e32 v11, 31, v10
	v_add_f32_e32 v2, v2, v9
	s_waitcnt vmcnt(0)
	v_add_f32_e32 v4, v2, v12
	v_lshl_add_u64 v[2:3], v[10:11], 2, s[0:1]
	global_store_dword v[2:3], v4, off
	s_branch .LBB0_14

.LBB0_53:
	v_lshl_add_u64 v[12:13], v[8:9], 0, s[16:17]
	global_load_dword v22, v[12:13], off
	global_load_dword v24, v[12:13], off offset:256
	global_load_dword v26, v[12:13], off offset:512
	global_load_dword v28, v[12:13], off offset:768
	global_load_dword v30, v[12:13], off offset:1024
	global_load_dword v32, v[12:13], off offset:1280
	global_load_dword v34, v[12:13], off offset:1536
	global_load_dword v36, v[12:13], off offset:1792
	v_and_b32_e32 v12, 56, v4
	v_add_u32_e32 v13, v14, v4
	v_cvt_f32_ubyte0_e32 v12, v12
	v_add_u32_e32 v23, v21, v4
	v_and_b32_e32 v13, 63, v13
	v_mul_f32_e32 v35, 0x3c800000, v12
	v_and_b32_e32 v23, 62, v23
	v_cvt_f32_ubyte0_e32 v37, v13
	v_cos_f32_e32 v12, v35
	v_sin_f32_e32 v13, v35
	v_add_u32_e32 v25, v20, v4
	v_cvt_f32_ubyte0_e32 v23, v23
	v_mul_f32_e32 v35, 0x3c800000, v37
	v_and_b32_e32 v25, 63, v25
	v_mul_f32_e32 v23, 0x3c800000, v23
	v_cos_f32_e32 v38, v35
	v_sin_f32_e32 v39, v35
	v_add_u32_e32 v27, v19, v4
	v_cvt_f32_ubyte0_e32 v25, v25
	v_cos_f32_e32 v40, v23
	v_sin_f32_e32 v41, v23
	v_add_u32_e32 v29, v18, v4
	v_and_b32_e32 v27, 60, v27
	v_mul_f32_e32 v25, 0x3c800000, v25
	v_add_u32_e32 v31, v17, v4
	v_and_b32_e32 v29, 63, v29
	v_cvt_f32_ubyte0_e32 v27, v27
	v_cos_f32_e32 v42, v25
	v_sin_f32_e32 v43, v25
	v_and_b32_e32 v31, 62, v31
	v_cvt_f32_ubyte0_e32 v29, v29
	v_mul_f32_e32 v27, 0x3c800000, v27
	v_add_u32_e32 v33, v16, v4
	v_cvt_f32_ubyte0_e32 v31, v31
	v_mul_f32_e32 v29, 0x3c800000, v29
	v_cos_f32_e32 v44, v27
	v_sin_f32_e32 v45, v27
	v_and_b32_e32 v33, 63, v33
	v_mul_f32_e32 v31, 0x3c800000, v31
	v_cos_f32_e32 v46, v29
	v_sin_f32_e32 v47, v29
	v_cvt_f32_ubyte0_e32 v33, v33
	v_cos_f32_e32 v48, v31
	v_sin_f32_e32 v49, v31
	v_mul_f32_e32 v33, 0x3c800000, v33
	v_cos_f32_e32 v50, v33
	v_sin_f32_e32 v51, v33
	s_add_u32 s16, s16, 0x800
	s_addc_u32 s17, s17, 0
	v_add_u32_e32 v4, v4, v15
	s_cmpk_eq_i32 s16, 0x4000
	s_waitcnt vmcnt(0)
	v_pk_fma_f32 v[52:53], v[22:23], v[12:13], v[10:11] op_sel_hi:[0,1,1]
	v_pk_fma_f32 v[10:11], v[22:23], v[12:13], v[10:11] op_sel_hi:[0,1,1] neg_lo:[1,0,0] neg_hi:[1,0,0]
	v_mov_b32_e32 v53, v11
	v_pk_fma_f32 v[10:11], v[24:25], v[38:39], v[10:11] op_sel_hi:[0,1,1] neg_lo:[1,0,0] neg_hi:[1,0,0]
	v_pk_fma_f32 v[12:13], v[24:25], v[38:39], v[52:53] op_sel_hi:[0,1,1]
	v_pk_fma_f32 v[10:11], v[26:27], v[40:41], v[10:11] op_sel_hi:[0,1,1] neg_lo:[1,0,0] neg_hi:[1,0,0]
	v_pk_fma_f32 v[12:13], v[26:27], v[40:41], v[12:13] op_sel_hi:[0,1,1]
	v_mov_b32_e32 v10, v12
	v_pk_fma_f32 v[12:13], v[28:29], v[42:43], v[12:13] op_sel_hi:[0,1,1]
	v_pk_fma_f32 v[10:11], v[28:29], v[42:43], v[10:11] op_sel_hi:[0,1,1] neg_lo:[1,0,0] neg_hi:[1,0,0]
	v_mov_b32_e32 v13, v11
	v_pk_fma_f32 v[10:11], v[30:31], v[44:45], v[10:11] op_sel_hi:[0,1,1] neg_lo:[1,0,0] neg_hi:[1,0,0]
	v_pk_fma_f32 v[12:13], v[30:31], v[44:45], v[12:13] op_sel_hi:[0,1,1]
	v_pk_fma_f32 v[10:11], v[32:33], v[46:47], v[10:11] op_sel_hi:[0,1,1] neg_lo:[1,0,0] neg_hi:[1,0,0]
	v_pk_fma_f32 v[12:13], v[32:33], v[46:47], v[12:13] op_sel_hi:[0,1,1]
	v_pk_fma_f32 v[10:11], v[34:35], v[48:49], v[10:11] op_sel_hi:[0,1,1] neg_lo:[1,0,0] neg_hi:[1,0,0]
	v_pk_fma_f32 v[12:13], v[34:35], v[48:49], v[12:13] op_sel_hi:[0,1,1]
	v_mov_b32_e32 v13, v11
	v_pk_fma_f32 v[10:11], v[36:37], v[50:51], v[12:13] op_sel_hi:[0,1,1]
	v_pk_fma_f32 v[12:13], v[36:37], v[50:51], v[12:13] op_sel_hi:[0,1,1] neg_lo:[1,0,0] neg_hi:[1,0,0]
	v_mov_b32_e32 v11, v13
	s_cbranch_scc0 .LBB0_53
	v_lshlrev_b32_e32 v4, 1, v3
	v_and_b32_e32 v8, 0xfff, v3
	v_and_or_b32 v4, v4, s18, v8
	v_lshlrev_b32_e32 v4, 2, v4
	v_mul_f32_e32 v10, 0x3e000000, v10
	v_lshl_add_u64 v[8:9], s[12:13], 0, v[4:5]
	global_store_dword v[8:9], v10, off
	v_add_co_u32_e32 v8, vcc, 0x4000, v8
	v_add_u32_e32 v3, s1, v3
	s_nop 0
	v_addc_co_u32_e32 v9, vcc, 0, v9, vcc
	v_cmp_lt_u32_e32 vcc, s19, v3
	v_mul_f32_e32 v4, 0x3e000000, v13
	s_or_b64 s[14:15], vcc, s[14:15]
	global_store_dword v[8:9], v4, off
	s_andn2_b64 exec, exec, s[14:15]
	s_cbranch_execnz .LBB0_52

.LBB0_57:
	s_waitcnt lgkmcnt(0)
	v_lshl_add_u64 v[8:9], s[8:9], 0, v[4:5]
	global_load_dwordx4 v[8:11], v[8:9], off
	v_add_u32_e32 v6, s0, v6
	v_cmp_lt_i32_e32 vcc, s1, v6
	v_lshl_add_u64 v[12:13], s[12:13], 0, v[4:5]
	v_lshl_add_u64 v[4:5], v[4:5], 0, s[14:15]
	s_or_b64 s[16:17], vcc, s[16:17]
	s_waitcnt vmcnt(0)
	global_store_dwordx4 v[12:13], v[8:11], off
	s_andn2_b64 exec, exec, s[16:17]
	s_cbranch_execnz .LBB0_57

.LBB0_61:
	v_cmp_lt_i32_e32 vcc, s1, v2
	s_and_saveexec_b64 s[2:3], vcc
	s_xor_b64 s[16:17], exec, s[2:3]
	s_cbranch_execz .LBB0_67
	v_cmp_lt_u32_e32 vcc, s20, v2
	s_and_saveexec_b64 s[2:3], vcc
	s_xor_b64 s[18:19], exec, s[2:3]
	s_cbranch_execz .LBB0_64
	v_add_u32_e32 v6, 0xffff4000, v2
	v_lshrrev_b32_e32 v3, 9, v6
	v_mul_lo_u32 v3, v3, v2
	v_cvt_f32_ubyte0_e32 v3, v3
	v_mul_f32_e32 v3, 0x3b800000, v3
	v_cos_f32_e32 v8, v3
	v_sin_f32_e32 v3, v3
	v_and_b32_e32 v9, 0x100, v2
	v_cmp_eq_u32_e32 vcc, 0, v9
	s_nop 1
	v_cndmask_b32_e32 v3, v3, v8, vcc
	v_mul_f32_e32 v3, 0x3d800000, v3
	v_bfe_u32 v8, v3, 16, 1
	v_add3_u32 v3, v3, v8, s21
	v_lshl_add_u64 v[8:9], v[6:7], 1, s[12:13]
	global_store_short_d16_hi v[8:9], v3, off
.LBB0_64:
	s_andn2_saveexec_b64 s[18:19], s[18:19]
	s_cbranch_execz .LBB0_66
	v_add_u32_e32 v6, 0xffffc000, v2
	v_lshrrev_b32_e32 v3, 8, v6
	v_mul_lo_u32 v3, v3, v2
	v_and_b32_e32 v3, 0x7f, v3
	v_cvt_f32_ubyte0_e32 v3, v3
	v_mul_f32_e32 v3, 0x3c000000, v3
	v_cos_f32_e32 v8, v3
	v_sin_f32_e32 v3, v3
	v_and_b32_e32 v9, 0x80, v2
	v_cmp_eq_u32_e32 vcc, 0, v9
	s_nop 1
	v_cndmask_b32_e32 v3, v3, v8, vcc
	v_mul_f32_e32 v3, 0x3c3504f3, v3
	v_bfe_u32 v8, v3, 16, 1
	v_add3_u32 v3, v3, v8, s21
	v_lshl_add_u64 v[8:9], v[6:7], 1, s[10:11]
	global_store_short_d16_hi v[8:9], v3, off

.LBB0_67:
	s_andn2_saveexec_b64 s[16:17], s[16:17]
	s_cbranch_execz .LBB0_60
	v_ashrrev_i32_e32 v3, 7, v2
	v_mul_lo_u32 v6, v3, v2
	v_and_b32_e32 v6, 63, v6
	v_cvt_f32_ubyte0_e32 v6, v6
	v_mul_f32_e32 v6, 0x3c800000, v6
	v_cos_f32_e32 v8, v6
	v_sin_f32_e32 v6, v6
	v_and_b32_e32 v9, 64, v2
	v_cmp_eq_u32_e32 vcc, 0, v9
	s_nop 1
	v_cndmask_b32_e32 v9, v6, v8, vcc
	v_cndmask_b32_e64 v6, v8, -v6, vcc
	v_cmp_gt_i32_e32 vcc, 64, v3
	s_nop 1
	v_cndmask_b32_e32 v3, v6, v9, vcc
	v_bfe_u32 v6, v3, 16, 1
	v_add3_u32 v3, v3, v6, s21
	global_store_short_d16_hi v[4:5], v3, off
	s_branch .LBB0_60

.LBB0_133:
	s_add_i32 s36, s70, s5
	s_cmpk_lt_i32 s36, 0x4000
	s_cselect_b32 s0, s36, 0x3fff
	s_ashr_i32 s1, s0, 31
	s_lshl_b64 s[24:25], s[0:1], 11
	s_add_i32 s18, s67, s5
	s_cmpk_lt_i32 s18, 0x4000
	s_cselect_b64 s[26:27], -1, 0
	v_lshl_add_u64 v[0:1], s[16:17], 0, v[168:169]
	s_and_b64 s[0:1], s[26:27], exec
	global_load_dwordx2 v[42:43], v[0:1], off offset:512
	global_load_dwordx2 v[44:45], v[0:1], off offset:1024
	s_cselect_b32 s0, s18, 0x3fff
	s_ashr_i32 s1, s0, 31
	v_lshl_add_u64 v[2:3], v[30:31], 0, s[24:25]
	s_add_i32 s18, s72, s5
	s_lshl_b64 s[22:23], s[0:1], 11
	global_load_dwordx2 v[50:51], v[2:3], off
	global_load_dwordx2 v[68:69], v[2:3], off offset:512
	global_load_dwordx2 v[70:71], v[2:3], off offset:1024
	global_load_dwordx4 v[46:49], v[28:29], off
	global_load_dwordx4 v[52:55], v[28:29], off offset:1024
	global_load_dwordx4 v[20:23], v[28:29], off offset:2048
	global_load_dwordx4 v[16:19], v[28:29], off offset:3072
	global_load_dwordx2 v[110:111], v[0:1], off offset:1536
	global_load_dwordx2 v[112:113], v[0:1], off
	global_load_dwordx2 v[72:73], v[2:3], off offset:1536
	s_cmpk_lt_i32 s18, 0x4000
	s_cselect_b64 s[20:21], -1, 0
	s_and_b64 s[0:1], s[20:21], exec
	s_cselect_b32 s0, s18, 0x3fff
	s_ashr_i32 s18, s5, 13
	v_lshl_add_u64 v[0:1], v[30:31], 0, s[22:23]
	s_mul_i32 s30, s18, 0x1800
	global_load_dwordx2 v[74:75], v[0:1], off
	global_load_dwordx2 v[76:77], v[0:1], off offset:512
	global_load_dwordx2 v[126:127], v[0:1], off offset:1024
	global_load_dwordx2 v[128:129], v[0:1], off offset:1536
	s_ashr_i32 s1, s0, 31
	s_ashr_i32 s31, s30, 31
	s_lshl_b64 s[18:19], s[0:1], 11
	s_lshl_b64 s[0:1], s[30:31], 2
	s_add_u32 s0, s28, s0
	s_addc_u32 s1, s29, s1
	s_add_u32 s30, s0, 0x1000
	s_addc_u32 s31, s1, 0
	v_lshl_add_u64 v[0:1], v[30:31], 0, s[18:19]
	v_lshl_add_u64 v[4:5], s[0:1], 0, v[34:35]
	v_lshl_add_u64 v[6:7], s[30:31], 0, v[34:35]
	v_lshl_add_u64 v[60:61], s[30:31], 0, v[36:37]
	s_waitcnt lgkmcnt(0)
	v_lshl_add_u64 v[24:25], s[30:31], 0, v[38:39]
	v_lshl_add_u64 v[26:27], s[30:31], 0, v[40:41]
	global_load_dwordx2 v[130:131], v[0:1], off
	global_load_dwordx2 v[132:133], v[0:1], off offset:512
	global_load_dwordx2 v[134:135], v[0:1], off offset:1024
	global_load_dwordx2 v[136:137], v[0:1], off offset:1536
	flat_load_dwordx4 v[8:11], v[4:5] offset:1024
	s_nop 0
	flat_load_dwordx4 v[0:3], v[4:5] offset:2048
	flat_load_dwordx4 v[56:59], v[6:7]
	flat_load_dwordx4 v[12:15], v[4:5]
	flat_load_dwordx4 v[64:67], v[24:25]
	s_nop 0
	flat_load_dwordx4 v[24:27], v[26:27]
	s_nop 0
	flat_load_dwordx4 v[60:63], v[60:61]
	s_nop 0
	flat_load_dwordx4 v[4:7], v[4:5] offset:3072
	s_cmpk_gt_i32 s36, 0x3fff
	s_waitcnt vmcnt(0)
	v_and_b32_e32 v99, 0xffff0000, v51
	v_and_b32_e32 v98, 0xffff0000, v50
	v_and_b32_e32 v105, 0xffff0000, v43
	v_and_b32_e32 v104, 0xffff0000, v42
	v_lshlrev_b32_e32 v107, 16, v43
	v_lshlrev_b32_e32 v106, 16, v42
	v_and_b32_e32 v109, 0xffff0000, v44
	v_pk_mul_f32 v[42:43], v[104:105], v[104:105]
	v_lshlrev_b32_e32 v108, 16, v44
	v_mul_f32_e32 v44, v109, v109
	v_pk_fma_f32 v[42:43], v[106:107], v[106:107], v[42:43]
	v_and_b32_e32 v95, 0xffff0000, v69
	v_and_b32_e32 v94, 0xffff0000, v68
	v_lshlrev_b32_e32 v102, 16, v45
	v_and_b32_e32 v103, 0xffff0000, v45
	v_pk_fma_f32 v[116:117], v[108:109], v[108:109], v[44:45] op_sel_hi:[1,1,0]
	v_pk_add_f32 v[114:115], v[42:43], v[42:43] op_sel:[0,1] op_sel_hi:[1,0]
	v_lshlrev_b32_e32 v101, 16, v51
	v_lshlrev_b32_e32 v100, 16, v50
	v_lshlrev_b32_e32 v97, 16, v69
	v_lshlrev_b32_e32 v96, 16, v68
	v_pk_mul_f32 v[42:43], v[98:99], v[98:99]
	v_pk_mul_f32 v[44:45], v[94:95], v[94:95]
	v_and_b32_e32 v91, 0xffff0000, v71
	v_and_b32_e32 v90, 0xffff0000, v70
	v_pk_fma_f32 v[42:43], v[100:101], v[100:101], v[42:43]
	v_pk_fma_f32 v[44:45], v[96:97], v[96:97], v[44:45]
	v_lshlrev_b32_e32 v93, 16, v71
	v_lshlrev_b32_e32 v92, 16, v70
	v_pk_mul_f32 v[50:51], v[90:91], v[90:91]
	v_and_b32_e32 v85, 0xffff0000, v73
	v_and_b32_e32 v84, 0xffff0000, v72
	v_pk_fma_f32 v[50:51], v[92:93], v[92:93], v[50:51]
	v_lshlrev_b32_e32 v87, 16, v73
	v_lshlrev_b32_e32 v86, 16, v72
	v_pk_mul_f32 v[68:69], v[84:85], v[84:85]
	v_add_f32_e32 v44, v44, v45
	v_add_f32_e32 v42, v42, v43
	v_mul_f32_e32 v78, v103, v103
	v_pk_fma_f32 v[68:69], v[86:87], v[86:87], v[68:69]
	v_add_f32_e32 v42, v42, v44
	v_add_f32_e32 v43, v50, v51
	v_pk_fma_f32 v[118:119], v[102:103], v[102:103], v[78:79] op_sel_hi:[1,1,0]
	v_add_f32_e32 v42, v42, v43
	v_add_f32_e32 v43, v68, v69
	v_and_b32_e32 v81, 0xffff0000, v75
	v_and_b32_e32 v80, 0xffff0000, v74
	v_lshlrev_b32_e32 v79, 16, v77
	v_lshlrev_b32_e32 v78, 16, v76
	v_and_b32_e32 v77, 0xffff0000, v77
	v_and_b32_e32 v76, 0xffff0000, v76
	v_add_f32_e32 v115, v42, v43
	v_lshlrev_b32_e32 v83, 16, v75
	v_lshlrev_b32_e32 v82, 16, v74
	v_pk_mul_f32 v[42:43], v[80:81], v[80:81]
	v_pk_mul_f32 v[44:45], v[76:77], v[76:77]
	v_and_b32_e32 v73, 0xffff0000, v127
	v_and_b32_e32 v72, 0xffff0000, v126
	v_pk_fma_f32 v[42:43], v[82:83], v[82:83], v[42:43]
	v_pk_fma_f32 v[44:45], v[78:79], v[78:79], v[44:45]
	v_lshlrev_b32_e32 v75, 16, v127
	v_lshlrev_b32_e32 v74, 16, v126
	v_pk_mul_f32 v[50:51], v[72:73], v[72:73]
	v_and_b32_e32 v69, 0xffff0000, v129
	v_and_b32_e32 v68, 0xffff0000, v128
	v_pk_fma_f32 v[50:51], v[74:75], v[74:75], v[50:51]
	v_lshlrev_b32_e32 v71, 16, v129
	v_lshlrev_b32_e32 v70, 16, v128
	v_pk_mul_f32 v[126:127], v[68:69], v[68:69]
	v_add_f32_e32 v44, v44, v45
	v_add_f32_e32 v42, v42, v43
	v_pk_fma_f32 v[126:127], v[70:71], v[70:71], v[126:127]
	v_add_f32_e32 v42, v42, v44
	v_add_f32_e32 v43, v50, v51
	v_add_f32_e32 v42, v42, v43
	v_add_f32_e32 v43, v126, v127
	v_add_f32_e32 v117, v42, v43
	v_and_b32_e32 v43, 0xffff0000, v131
	v_and_b32_e32 v42, 0xffff0000, v130
	s_waitcnt lgkmcnt(0)
	v_mov_b32_e32 v50, v56
	v_mov_b32_e32 v51, v58
	v_lshlrev_b32_e32 v45, 16, v131
	v_lshlrev_b32_e32 v44, 16, v130
	v_pk_add_f32 v[50:51], v[50:51], 1.0 op_sel_hi:[1,0]
	v_mov_b32_e32 v126, v46
	v_mov_b32_e32 v127, v48
	v_mov_b32_e32 v58, v57
	v_mov_b32_e32 v48, v47
	v_pk_mul_f32 v[46:47], v[42:43], v[42:43]
	v_pk_mul_f32 v[50:51], v[126:127], v[50:51]
	v_pk_add_f32 v[56:57], v[58:59], 1.0 op_sel_hi:[1,0]
	v_pk_fma_f32 v[126:127], v[44:45], v[44:45], v[46:47]
	v_and_b32_e32 v47, 0xffff0000, v133
	v_and_b32_e32 v46, 0xffff0000, v132
	v_mov_b32_e32 v58, v60
	v_mov_b32_e32 v59, v62
	v_pk_mul_f32 v[56:57], v[48:49], v[56:57]
	v_lshlrev_b32_e32 v49, 16, v133
	v_lshlrev_b32_e32 v48, 16, v132
	v_pk_add_f32 v[58:59], v[58:59], 1.0 op_sel_hi:[1,0]
	v_mov_b32_e32 v128, v52
	v_mov_b32_e32 v129, v54
	v_mov_b32_e32 v54, v53
	v_pk_mul_f32 v[52:53], v[46:47], v[46:47]
	v_pk_mul_f32 v[58:59], v[128:129], v[58:59]
	v_pk_fma_f32 v[128:129], v[48:49], v[48:49], v[52:53]
	v_mov_b32_e32 v62, v61
	v_mov_b32_e32 v132, v16
	v_mov_b32_e32 v133, v18
	v_add_f32_e32 v16, v128, v129
	v_add_f32_e32 v18, v126, v127
	v_pk_add_f32 v[60:61], v[62:63], 1.0 op_sel_hi:[1,0]
	v_and_b32_e32 v53, 0xffff0000, v135
	v_and_b32_e32 v52, 0xffff0000, v134
	v_mov_b32_e32 v62, v64
	v_mov_b32_e32 v63, v66
	v_mov_b32_e32 v66, v65
	v_add_f32_e32 v16, v18, v16
	ds_bpermute_b32 v18, v89, v115
	v_pk_mul_f32 v[60:61], v[54:55], v[60:61]
	v_lshlrev_b32_e32 v55, 16, v135
	v_lshlrev_b32_e32 v54, 16, v134
	v_pk_add_f32 v[62:63], v[62:63], 1.0 op_sel_hi:[1,0]
	v_mov_b32_e32 v130, v20
	v_mov_b32_e32 v131, v22
	v_pk_add_f32 v[64:65], v[66:67], 1.0 op_sel_hi:[1,0]
	v_mov_b32_e32 v22, v21
	v_pk_mul_f32 v[20:21], v[52:53], v[52:53]
	v_mov_b32_e32 v66, v24
	v_mov_b32_e32 v67, v26
	v_pk_mul_f32 v[62:63], v[130:131], v[62:63]
	v_pk_fma_f32 v[130:131], v[54:55], v[54:55], v[20:21]
	v_and_b32_e32 v21, 0xffff0000, v137
	v_and_b32_e32 v20, 0xffff0000, v136
	v_pk_add_f32 v[66:67], v[66:67], 1.0 op_sel_hi:[1,0]
	v_pk_mul_f32 v[64:65], v[22:23], v[64:65]
	v_lshlrev_b32_e32 v23, 16, v137
	v_lshlrev_b32_e32 v22, 16, v136
	v_pk_mul_f32 v[66:67], v[132:133], v[66:67]
	v_pk_mul_f32 v[132:133], v[20:21], v[20:21]
	v_add_f32_e32 v24, v130, v131
	v_pk_fma_f32 v[132:133], v[22:23], v[22:23], v[132:133]
	v_add_f32_e32 v16, v16, v24
	v_add_f32_e32 v24, v132, v133
	s_waitcnt lgkmcnt(0)
	v_add_f32_e32 v18, v115, v18
	ds_bpermute_b32 v115, v89, v117
	v_add_f32_e32 v16, v16, v24
	ds_bpermute_b32 v119, v89, v16
	ds_bpermute_b32 v125, v120, v18
	v_mov_b32_e32 v26, v25
	v_pk_add_f32 v[24:25], v[26:27], 1.0 op_sel_hi:[1,0]
	s_waitcnt lgkmcnt(2)
	v_add_f32_e32 v26, v117, v115
	ds_bpermute_b32 v117, v120, v26
	s_waitcnt lgkmcnt(2)
	v_add_f32_e32 v27, v16, v119
	s_waitcnt lgkmcnt(1)
	v_add_f32_e32 v115, v18, v125
	ds_bpermute_b32 v119, v120, v27
	ds_bpermute_b32 v125, v121, v115
	v_mov_b32_e32 v18, v17
	v_lshlrev_b32_e32 v126, 16, v112
	v_and_b32_e32 v112, 0xffff0000, v112
	v_pk_mul_f32 v[16:17], v[18:19], v[24:25]
	v_lshlrev_b32_e32 v127, 16, v113
	v_and_b32_e32 v113, 0xffff0000, v113
	v_mov_b32_e32 v18, v126
	v_mov_b32_e32 v19, v112
	v_mul_f32_e32 v24, v112, v112
	s_waitcnt lgkmcnt(2)
	v_add_f32_e32 v132, v26, v117
	v_pk_fma_f32 v[18:19], v[18:19], v[18:19], v[24:25] op_sel_hi:[1,1,0]
	v_mov_b32_e32 v24, v127
	v_mov_b32_e32 v25, v113
	v_mul_f32_e32 v26, v113, v113
	v_pk_fma_f32 v[24:25], v[24:25], v[24:25], v[26:27] op_sel_hi:[1,1,0]
	v_lshlrev_b32_e32 v129, 16, v111
	v_lshlrev_b32_e32 v128, 16, v110
	v_and_b32_e32 v131, 0xffff0000, v111
	v_and_b32_e32 v130, 0xffff0000, v110
	s_waitcnt lgkmcnt(1)
	v_add_f32_e32 v133, v27, v119
	v_pk_mul_f32 v[26:27], v[130:131], v[130:131]
	v_pk_mul_f32 v[110:111], v[128:129], v[128:129]
	v_pk_add_f32 v[18:19], v[18:19], v[24:25]
	s_waitcnt lgkmcnt(0)
	v_add_f32_e32 v125, v115, v125
	v_mov_b32_e32 v117, v111
	v_mov_b32_e32 v119, v27
	v_mov_b32_e32 v19, v110
	v_mov_b32_e32 v115, v26
	v_pk_add_f32 v[116:117], v[116:117], v[118:119]
	v_pk_add_f32 v[18:19], v[18:19], v[114:115]
	ds_bpermute_b32 v134, v121, v132
	v_pk_add_f32 v[18:19], v[18:19], v[116:117]
	ds_bpermute_b32 v135, v121, v133
	v_add_f32_e32 v18, v18, v19
	ds_bpermute_b32 v19, v89, v18
	s_waitcnt lgkmcnt(2)
	v_add_f32_e32 v24, v132, v134
	ds_bpermute_b32 v27, v122, v24
	s_waitcnt lgkmcnt(2)
	v_add_f32_e32 v26, v133, v135
	ds_bpermute_b32 v110, v122, v26
	s_waitcnt lgkmcnt(2)
	v_add_f32_e32 v18, v18, v19
	ds_bpermute_b32 v19, v120, v18
	s_waitcnt lgkmcnt(2)
	v_add_f32_e32 v24, v24, v27
	ds_bpermute_b32 v25, v122, v125
	s_waitcnt lgkmcnt(2)
	v_add_f32_e32 v111, v26, v110
	ds_bpermute_b32 v26, v123, v24
	s_waitcnt lgkmcnt(2)
	v_add_f32_e32 v18, v18, v19
	ds_bpermute_b32 v19, v121, v18
	ds_bpermute_b32 v114, v123, v111
	s_waitcnt lgkmcnt(3)
	v_add_f32_e32 v25, v125, v25
	s_waitcnt lgkmcnt(2)
	v_add_f32_e32 v26, v24, v26
	ds_bpermute_b32 v27, v123, v25
	s_waitcnt lgkmcnt(2)
	v_add_f32_e32 v18, v18, v19
	ds_bpermute_b32 v19, v122, v18
	s_waitcnt lgkmcnt(2)
	v_add_f32_e32 v24, v111, v114
	s_waitcnt lgkmcnt(1)
	v_add_f32_e32 v110, v25, v27
	ds_bpermute_b32 v111, v124, v110
	s_waitcnt lgkmcnt(1)
	v_add_f32_e32 v114, v18, v19
	ds_bpermute_b32 v115, v123, v114
	v_mov_b32_e32 v18, v12
	v_mov_b32_e32 v12, v8
	v_mov_b32_e32 v19, v14
	v_mov_b32_e32 v14, v13
	s_waitcnt lgkmcnt(0)
	v_add_f32_e32 v116, v114, v115
	ds_bpermute_b32 v117, v124, v116
	v_mov_b32_e32 v13, v10
	v_mov_b32_e32 v10, v9
	v_lshl_add_u64 v[114:115], s[14:15], 0, v[168:169]
	ds_bpermute_b32 v27, v124, v26
	s_waitcnt lgkmcnt(1)
	v_add_f32_e32 v8, v116, v117
	v_fmamk_f32 v8, v8, 0x3a800000, v206
	v_mul_f32_e32 v9, 0x4f800000, v8
	v_cmp_gt_f32_e32 vcc, s57, v8
	v_mov_b32_e32 v117, v102
	v_mov_b32_e32 v116, v108
	v_cndmask_b32_e32 v9, v8, v9, vcc
	v_sqrt_f32_e32 v118, v9
	v_mov_b32_e32 v8, v0
	ds_bpermute_b32 v25, v124, v24
	v_add_u32_e32 v0, -1, v118
	v_fma_f32 v102, -v0, v118, v9
	v_cmp_ge_f32_e64 s[0:1], 0, v102
	v_add_u32_e32 v102, 1, v118
	v_fma_f32 v108, -v102, v118, v9
	v_cndmask_b32_e64 v0, v118, v0, s[0:1]
	v_cmp_lt_f32_e64 s[0:1], 0, v108
	s_nop 1
	v_cndmask_b32_e64 v0, v0, v102, s[0:1]
	v_mul_f32_e32 v102, 0x37800000, v0
	v_cndmask_b32_e32 v0, v0, v102, vcc
	v_cmp_class_f32_e32 vcc, v9, v207
	v_mov_b32_e32 v102, v109
	s_nop 0
	v_cndmask_b32_e32 v0, v0, v9, vcc
	v_div_scale_f32 v108, s[0:1], v0, v0, 1.0
	v_rcp_f32_e32 v118, v108
	v_mov_b32_e32 v9, v2
	v_mov_b32_e32 v2, v1
	s_mov_b32 s0, 0x3200000
	v_fma_f32 v1, -v108, v118, 1.0
	v_fmac_f32_e32 v118, v1, v118
	v_div_scale_f32 v1, vcc, 1.0, v0, 1.0
	v_mul_f32_e32 v109, v1, v118
	v_fma_f32 v119, -v108, v109, v1
	v_fmac_f32_e32 v109, v119, v118
	v_fma_f32 v1, -v108, v109, v1
	v_div_fmas_f32 v1, v1, v118, v109
	v_div_fixup_f32 v108, v1, v0, 1.0
	v_pk_mul_f32 v[0:1], v[108:109], v[126:127] op_sel_hi:[0,1]
	v_pk_fma_f32 v[0:1], v[50:51], v[0:1], v[18:19]
	v_pk_mul_f32 v[112:113], v[108:109], v[112:113] op_sel_hi:[0,1]
	v_pk_fma_f32 v[112:113], v[56:57], v[112:113], v[14:15]
	v_and_b32_sdwa v118, v0, v209 dst_sel:DWORD dst_unused:UNUSED_PAD src0_sel:WORD_1 src1_sel:DWORD
	v_and_b32_sdwa v109, v1, v209 dst_sel:DWORD dst_unused:UNUSED_PAD src0_sel:WORD_1 src1_sel:DWORD
	v_add3_u32 v0, v0, v118, s77
	v_and_b32_sdwa v118, v112, v209 dst_sel:DWORD dst_unused:UNUSED_PAD src0_sel:WORD_1 src1_sel:DWORD
	v_add3_u32 v1, v1, v109, s77
	v_and_b32_sdwa v109, v113, v209 dst_sel:DWORD dst_unused:UNUSED_PAD src0_sel:WORD_1 src1_sel:DWORD
	v_add3_u32 v112, v112, v118, s77
	v_add3_u32 v109, v113, v109, s77
	v_and_b32_e32 v112, 0xffff0000, v112
	v_and_b32_e32 v109, 0xffff0000, v109
	v_or_b32_sdwa v0, v112, v0 dst_sel:DWORD dst_unused:UNUSED_PAD src0_sel:DWORD src1_sel:WORD_1
	v_add_co_u32_e32 v112, vcc, s0, v114
	v_or_b32_sdwa v1, v109, v1 dst_sel:DWORD dst_unused:UNUSED_PAD src0_sel:DWORD src1_sel:WORD_1
	s_nop 0
	v_addc_co_u32_e32 v113, vcc, 0, v115, vcc
	global_store_dwordx2 v[112:113], v[0:1], off
	v_pk_mul_f32 v[0:1], v[108:109], v[106:107] op_sel_hi:[0,1]
	v_pk_fma_f32 v[0:1], v[58:59], v[0:1], v[12:13]
	v_pk_mul_f32 v[104:105], v[108:109], v[104:105] op_sel_hi:[0,1]
	v_pk_fma_f32 v[104:105], v[60:61], v[104:105], v[10:11]
	v_and_b32_sdwa v106, v1, v209 dst_sel:DWORD dst_unused:UNUSED_PAD src0_sel:WORD_1 src1_sel:DWORD
	v_and_b32_sdwa v107, v0, v209 dst_sel:DWORD dst_unused:UNUSED_PAD src0_sel:WORD_1 src1_sel:DWORD
	v_add3_u32 v0, v0, v107, s77
	v_add3_u32 v1, v1, v106, s77
	v_and_b32_sdwa v106, v105, v209 dst_sel:DWORD dst_unused:UNUSED_PAD src0_sel:WORD_1 src1_sel:DWORD
	v_and_b32_sdwa v107, v104, v209 dst_sel:DWORD dst_unused:UNUSED_PAD src0_sel:WORD_1 src1_sel:DWORD
	v_add3_u32 v105, v105, v106, s77
	v_add3_u32 v104, v104, v107, s77
	v_and_b32_e32 v105, 0xffff0000, v105
	v_and_b32_e32 v104, 0xffff0000, v104
	v_or_b32_sdwa v1, v105, v1 dst_sel:DWORD dst_unused:UNUSED_PAD src0_sel:DWORD src1_sel:WORD_1
	v_or_b32_sdwa v0, v104, v0 dst_sel:DWORD dst_unused:UNUSED_PAD src0_sel:DWORD src1_sel:WORD_1
	global_store_dwordx2 v[112:113], v[0:1], off offset:512
	v_pk_mul_f32 v[0:1], v[108:109], v[116:117] op_sel_hi:[0,1]
	v_pk_fma_f32 v[0:1], v[62:63], v[0:1], v[8:9]
	v_pk_mul_f32 v[102:103], v[108:109], v[102:103] op_sel_hi:[0,1]
	v_pk_fma_f32 v[102:103], v[64:65], v[102:103], v[2:3]
	v_and_b32_sdwa v104, v1, v209 dst_sel:DWORD dst_unused:UNUSED_PAD src0_sel:WORD_1 src1_sel:DWORD
	v_and_b32_sdwa v105, v0, v209 dst_sel:DWORD dst_unused:UNUSED_PAD src0_sel:WORD_1 src1_sel:DWORD
	v_add3_u32 v0, v0, v105, s77
	v_add3_u32 v1, v1, v104, s77
	v_and_b32_sdwa v104, v103, v209 dst_sel:DWORD dst_unused:UNUSED_PAD src0_sel:WORD_1 src1_sel:DWORD
	v_and_b32_sdwa v105, v102, v209 dst_sel:DWORD dst_unused:UNUSED_PAD src0_sel:WORD_1 src1_sel:DWORD
	v_add3_u32 v103, v103, v104, s77
	v_add3_u32 v102, v102, v105, s77
	v_and_b32_e32 v103, 0xffff0000, v103
	v_and_b32_e32 v102, 0xffff0000, v102
	v_or_b32_sdwa v1, v103, v1 dst_sel:DWORD dst_unused:UNUSED_PAD src0_sel:DWORD src1_sel:WORD_1
	v_or_b32_sdwa v0, v102, v0 dst_sel:DWORD dst_unused:UNUSED_PAD src0_sel:DWORD src1_sel:WORD_1
	global_store_dwordx2 v[112:113], v[0:1], off offset:1024
	v_pk_mul_f32 v[102:103], v[108:109], v[128:129] op_sel_hi:[0,1]
	v_mov_b32_e32 v0, v4
	v_mov_b32_e32 v1, v6
	v_pk_fma_f32 v[102:103], v[66:67], v[102:103], v[0:1]
	v_pk_mul_f32 v[104:105], v[108:109], v[130:131] op_sel_hi:[0,1]
	v_mov_b32_e32 v6, v5
	v_pk_fma_f32 v[4:5], v[16:17], v[104:105], v[6:7]
	v_and_b32_sdwa v104, v103, v209 dst_sel:DWORD dst_unused:UNUSED_PAD src0_sel:WORD_1 src1_sel:DWORD
	v_and_b32_sdwa v105, v102, v209 dst_sel:DWORD dst_unused:UNUSED_PAD src0_sel:WORD_1 src1_sel:DWORD
	v_add3_u32 v102, v102, v105, s77
	v_add3_u32 v103, v103, v104, s77
	v_and_b32_sdwa v104, v5, v209 dst_sel:DWORD dst_unused:UNUSED_PAD src0_sel:WORD_1 src1_sel:DWORD
	v_and_b32_sdwa v105, v4, v209 dst_sel:DWORD dst_unused:UNUSED_PAD src0_sel:WORD_1 src1_sel:DWORD
	v_add3_u32 v5, v5, v104, s77
	v_add3_u32 v4, v4, v105, s77
	v_and_b32_e32 v5, 0xffff0000, v5
	v_and_b32_e32 v4, 0xffff0000, v4
	v_or_b32_sdwa v5, v5, v103 dst_sel:DWORD dst_unused:UNUSED_PAD src0_sel:DWORD src1_sel:WORD_1
	v_or_b32_sdwa v4, v4, v102 dst_sel:DWORD dst_unused:UNUSED_PAD src0_sel:DWORD src1_sel:WORD_1
	global_store_dwordx2 v[112:113], v[4:5], off offset:1536
	s_cbranch_scc0 .LBB0_136
	s_andn2_b64 vcc, exec, s[26:27]
	s_cbranch_vccz .LBB0_137

.LBB0_136:
	v_add_f32_e32 v4, v110, v111
	v_fmamk_f32 v4, v4, 0x3a800000, v206
	v_mul_f32_e32 v5, 0x4f800000, v4
	v_cmp_gt_f32_e32 vcc, s57, v4
	s_nop 1
	v_cndmask_b32_e32 v4, v4, v5, vcc
	v_sqrt_f32_e32 v5, v4
	s_nop 0
	v_add_u32_e32 v102, -1, v5
	v_fma_f32 v104, -v102, v5, v4
	v_add_u32_e32 v103, 1, v5
	v_cmp_ge_f32_e64 s[0:1], 0, v104
	s_nop 1
	v_cndmask_b32_e64 v102, v5, v102, s[0:1]
	v_fma_f32 v5, -v103, v5, v4
	v_cmp_lt_f32_e64 s[0:1], 0, v5
	s_nop 1
	v_cndmask_b32_e64 v5, v102, v103, s[0:1]
	v_mul_f32_e32 v102, 0x37800000, v5
	v_cndmask_b32_e32 v5, v5, v102, vcc
	v_cmp_class_f32_e32 vcc, v4, v207
	s_nop 1
	v_cndmask_b32_e32 v4, v5, v4, vcc
	v_div_scale_f32 v5, s[0:1], v4, v4, 1.0
	v_rcp_f32_e32 v102, v5
	s_nop 0
	v_fma_f32 v103, -v5, v102, 1.0
	v_fmac_f32_e32 v102, v103, v102
	v_div_scale_f32 v103, vcc, 1.0, v4, 1.0
	v_mul_f32_e32 v104, v103, v102
	v_fma_f32 v105, -v5, v104, v103
	v_fmac_f32_e32 v104, v105, v102
	v_fma_f32 v5, -v5, v104, v103
	v_div_fmas_f32 v5, v5, v102, v104
	v_div_fixup_f32 v4, v5, v4, 1.0
	v_pk_mul_f32 v[100:101], v[4:5], v[100:101] op_sel_hi:[0,1]
	v_pk_fma_f32 v[100:101], v[50:51], v[100:101], v[18:19]
	v_pk_mul_f32 v[98:99], v[4:5], v[98:99] op_sel_hi:[0,1]
	v_pk_fma_f32 v[98:99], v[56:57], v[98:99], v[14:15]
	v_and_b32_sdwa v5, v101, v209 dst_sel:DWORD dst_unused:UNUSED_PAD src0_sel:WORD_1 src1_sel:DWORD
	v_add3_u32 v5, v101, v5, s77
	v_and_b32_sdwa v101, v99, v209 dst_sel:DWORD dst_unused:UNUSED_PAD src0_sel:WORD_1 src1_sel:DWORD
	v_add3_u32 v99, v99, v101, s77
	v_pk_mul_f32 v[96:97], v[4:5], v[96:97] op_sel_hi:[0,1]
	v_and_b32_sdwa v102, v100, v209 dst_sel:DWORD dst_unused:UNUSED_PAD src0_sel:WORD_1 src1_sel:DWORD
	v_and_b32_e32 v99, 0xffff0000, v99
	v_pk_fma_f32 v[96:97], v[58:59], v[96:97], v[12:13]
	v_pk_mul_f32 v[94:95], v[4:5], v[94:95] op_sel_hi:[0,1]
	v_add3_u32 v100, v100, v102, s77
	v_and_b32_sdwa v102, v98, v209 dst_sel:DWORD dst_unused:UNUSED_PAD src0_sel:WORD_1 src1_sel:DWORD
	v_or_b32_sdwa v99, v99, v5 dst_sel:DWORD dst_unused:UNUSED_PAD src0_sel:DWORD src1_sel:WORD_1
	v_pk_fma_f32 v[94:95], v[60:61], v[94:95], v[10:11]
	v_and_b32_sdwa v5, v97, v209 dst_sel:DWORD dst_unused:UNUSED_PAD src0_sel:WORD_1 src1_sel:DWORD
	v_add3_u32 v98, v98, v102, s77
	v_add3_u32 v5, v97, v5, s77
	v_and_b32_sdwa v97, v95, v209 dst_sel:DWORD dst_unused:UNUSED_PAD src0_sel:WORD_1 src1_sel:DWORD
	v_and_b32_e32 v98, 0xffff0000, v98
	v_add3_u32 v95, v95, v97, s77
	v_pk_mul_f32 v[92:93], v[4:5], v[92:93] op_sel_hi:[0,1]
	v_or_b32_sdwa v98, v98, v100 dst_sel:DWORD dst_unused:UNUSED_PAD src0_sel:DWORD src1_sel:WORD_1
	v_lshl_add_u64 v[100:101], v[32:33], 0, s[24:25]
	v_and_b32_e32 v95, 0xffff0000, v95
	v_pk_fma_f32 v[92:93], v[62:63], v[92:93], v[8:9]
	v_pk_mul_f32 v[90:91], v[4:5], v[90:91] op_sel_hi:[0,1]
	global_store_dwordx2 v[100:101], v[98:99], off
	v_and_b32_sdwa v98, v96, v209 dst_sel:DWORD dst_unused:UNUSED_PAD src0_sel:WORD_1 src1_sel:DWORD
	v_or_b32_sdwa v95, v95, v5 dst_sel:DWORD dst_unused:UNUSED_PAD src0_sel:DWORD src1_sel:WORD_1
	v_pk_fma_f32 v[90:91], v[64:65], v[90:91], v[2:3]
	v_and_b32_sdwa v5, v93, v209 dst_sel:DWORD dst_unused:UNUSED_PAD src0_sel:WORD_1 src1_sel:DWORD
	v_add3_u32 v96, v96, v98, s77
	v_and_b32_sdwa v98, v94, v209 dst_sel:DWORD dst_unused:UNUSED_PAD src0_sel:WORD_1 src1_sel:DWORD
	v_add3_u32 v5, v93, v5, s77
	v_and_b32_sdwa v93, v91, v209 dst_sel:DWORD dst_unused:UNUSED_PAD src0_sel:WORD_1 src1_sel:DWORD
	v_add3_u32 v94, v94, v98, s77
	v_add3_u32 v91, v91, v93, s77
	v_and_b32_e32 v94, 0xffff0000, v94
	v_and_b32_e32 v91, 0xffff0000, v91
	v_pk_mul_f32 v[86:87], v[4:5], v[86:87] op_sel_hi:[0,1]
	v_or_b32_sdwa v94, v94, v96 dst_sel:DWORD dst_unused:UNUSED_PAD src0_sel:DWORD src1_sel:WORD_1
	v_or_b32_sdwa v91, v91, v5 dst_sel:DWORD dst_unused:UNUSED_PAD src0_sel:DWORD src1_sel:WORD_1
	v_pk_fma_f32 v[86:87], v[66:67], v[86:87], v[0:1]
	v_pk_mul_f32 v[4:5], v[4:5], v[84:85] op_sel_hi:[0,1]
	global_store_dwordx2 v[100:101], v[94:95], off offset:512
	v_and_b32_sdwa v94, v92, v209 dst_sel:DWORD dst_unused:UNUSED_PAD src0_sel:WORD_1 src1_sel:DWORD
	v_pk_fma_f32 v[4:5], v[16:17], v[4:5], v[6:7]
	v_and_b32_sdwa v84, v87, v209 dst_sel:DWORD dst_unused:UNUSED_PAD src0_sel:WORD_1 src1_sel:DWORD
	v_and_b32_sdwa v85, v86, v209 dst_sel:DWORD dst_unused:UNUSED_PAD src0_sel:WORD_1 src1_sel:DWORD
	v_add3_u32 v92, v92, v94, s77
	v_and_b32_sdwa v94, v90, v209 dst_sel:DWORD dst_unused:UNUSED_PAD src0_sel:WORD_1 src1_sel:DWORD
	v_add3_u32 v85, v86, v85, s77
	v_add3_u32 v84, v87, v84, s77
	v_and_b32_sdwa v86, v5, v209 dst_sel:DWORD dst_unused:UNUSED_PAD src0_sel:WORD_1 src1_sel:DWORD
	v_and_b32_sdwa v87, v4, v209 dst_sel:DWORD dst_unused:UNUSED_PAD src0_sel:WORD_1 src1_sel:DWORD
	v_add3_u32 v90, v90, v94, s77
	v_add3_u32 v5, v5, v86, s77
	v_add3_u32 v4, v4, v87, s77
	v_and_b32_e32 v90, 0xffff0000, v90
	v_and_b32_e32 v5, 0xffff0000, v5
	v_and_b32_e32 v4, 0xffff0000, v4
	v_or_b32_sdwa v90, v90, v92 dst_sel:DWORD dst_unused:UNUSED_PAD src0_sel:DWORD src1_sel:WORD_1
	v_or_b32_sdwa v5, v5, v84 dst_sel:DWORD dst_unused:UNUSED_PAD src0_sel:DWORD src1_sel:WORD_1
	v_or_b32_sdwa v4, v4, v85 dst_sel:DWORD dst_unused:UNUSED_PAD src0_sel:DWORD src1_sel:WORD_1
	global_store_dwordx2 v[100:101], v[90:91], off offset:1024
	global_store_dwordx2 v[100:101], v[4:5], off offset:1536
	s_andn2_b64 vcc, exec, s[26:27]
	s_cbranch_vccnz .LBB0_135
.LBB0_137:
	s_waitcnt lgkmcnt(0)
	v_add_f32_e32 v4, v26, v27
	v_fmamk_f32 v4, v4, 0x3a800000, v206
	v_mul_f32_e32 v5, 0x4f800000, v4
	v_cmp_gt_f32_e32 vcc, s57, v4
	s_nop 1
	v_cndmask_b32_e32 v4, v4, v5, vcc
	v_sqrt_f32_e32 v5, v4
	s_nop 0
	v_add_u32_e32 v26, -1, v5
	v_fma_f32 v84, -v26, v5, v4
	v_add_u32_e32 v27, 1, v5
	v_cmp_ge_f32_e64 s[0:1], 0, v84
	s_nop 1
	v_cndmask_b32_e64 v26, v5, v26, s[0:1]
	v_fma_f32 v5, -v27, v5, v4
	v_cmp_lt_f32_e64 s[0:1], 0, v5
	s_nop 1
	v_cndmask_b32_e64 v5, v26, v27, s[0:1]
	v_mul_f32_e32 v26, 0x37800000, v5
	v_cndmask_b32_e32 v5, v5, v26, vcc
	v_cmp_class_f32_e32 vcc, v4, v207
	s_nop 1
	v_cndmask_b32_e32 v4, v5, v4, vcc
	v_div_scale_f32 v5, s[0:1], v4, v4, 1.0
	v_rcp_f32_e32 v26, v5
	s_nop 0
	v_fma_f32 v27, -v5, v26, 1.0
	v_fmac_f32_e32 v26, v27, v26
	v_div_scale_f32 v27, vcc, 1.0, v4, 1.0
	v_mul_f32_e32 v84, v27, v26
	v_fma_f32 v85, -v5, v84, v27
	v_fmac_f32_e32 v84, v85, v26
	v_fma_f32 v5, -v5, v84, v27
	v_div_fmas_f32 v5, v5, v26, v84
	v_div_fixup_f32 v4, v5, v4, 1.0
	v_pk_mul_f32 v[26:27], v[4:5], v[82:83] op_sel_hi:[0,1]
	v_pk_fma_f32 v[26:27], v[50:51], v[26:27], v[18:19]
	v_pk_mul_f32 v[80:81], v[4:5], v[80:81] op_sel_hi:[0,1]
	v_pk_fma_f32 v[80:81], v[56:57], v[80:81], v[14:15]
	v_and_b32_sdwa v5, v27, v209 dst_sel:DWORD dst_unused:UNUSED_PAD src0_sel:WORD_1 src1_sel:DWORD
	v_and_b32_sdwa v82, v26, v209 dst_sel:DWORD dst_unused:UNUSED_PAD src0_sel:WORD_1 src1_sel:DWORD
	v_add3_u32 v26, v26, v82, s77
	v_add3_u32 v5, v27, v5, s77
	v_and_b32_sdwa v27, v81, v209 dst_sel:DWORD dst_unused:UNUSED_PAD src0_sel:WORD_1 src1_sel:DWORD
	v_and_b32_sdwa v82, v80, v209 dst_sel:DWORD dst_unused:UNUSED_PAD src0_sel:WORD_1 src1_sel:DWORD
	v_add3_u32 v27, v81, v27, s77
	v_add3_u32 v80, v80, v82, s77
	v_and_b32_e32 v27, 0xffff0000, v27
	v_and_b32_e32 v80, 0xffff0000, v80
	v_or_b32_sdwa v27, v27, v5 dst_sel:DWORD dst_unused:UNUSED_PAD src0_sel:DWORD src1_sel:WORD_1
	v_or_b32_sdwa v26, v80, v26 dst_sel:DWORD dst_unused:UNUSED_PAD src0_sel:DWORD src1_sel:WORD_1
	v_lshl_add_u64 v[80:81], v[32:33], 0, s[22:23]
	global_store_dwordx2 v[80:81], v[26:27], off
	v_pk_mul_f32 v[26:27], v[4:5], v[78:79] op_sel_hi:[0,1]
	v_pk_fma_f32 v[26:27], v[58:59], v[26:27], v[12:13]
	v_pk_mul_f32 v[76:77], v[4:5], v[76:77] op_sel_hi:[0,1]
	v_pk_fma_f32 v[76:77], v[60:61], v[76:77], v[10:11]
	v_and_b32_sdwa v5, v27, v209 dst_sel:DWORD dst_unused:UNUSED_PAD src0_sel:WORD_1 src1_sel:DWORD
	v_and_b32_sdwa v78, v26, v209 dst_sel:DWORD dst_unused:UNUSED_PAD src0_sel:WORD_1 src1_sel:DWORD
	v_add3_u32 v26, v26, v78, s77
	v_add3_u32 v5, v27, v5, s77
	v_and_b32_sdwa v27, v77, v209 dst_sel:DWORD dst_unused:UNUSED_PAD src0_sel:WORD_1 src1_sel:DWORD
	v_and_b32_sdwa v78, v76, v209 dst_sel:DWORD dst_unused:UNUSED_PAD src0_sel:WORD_1 src1_sel:DWORD
	v_add3_u32 v27, v77, v27, s77
	v_add3_u32 v76, v76, v78, s77
	v_and_b32_e32 v27, 0xffff0000, v27
	v_and_b32_e32 v76, 0xffff0000, v76
	v_or_b32_sdwa v27, v27, v5 dst_sel:DWORD dst_unused:UNUSED_PAD src0_sel:DWORD src1_sel:WORD_1
	v_or_b32_sdwa v26, v76, v26 dst_sel:DWORD dst_unused:UNUSED_PAD src0_sel:DWORD src1_sel:WORD_1
	global_store_dwordx2 v[80:81], v[26:27], off offset:512
	v_pk_mul_f32 v[26:27], v[4:5], v[74:75] op_sel_hi:[0,1]
	v_pk_fma_f32 v[26:27], v[62:63], v[26:27], v[8:9]
	v_pk_mul_f32 v[72:73], v[4:5], v[72:73] op_sel_hi:[0,1]
	v_pk_fma_f32 v[72:73], v[64:65], v[72:73], v[2:3]
	v_and_b32_sdwa v5, v27, v209 dst_sel:DWORD dst_unused:UNUSED_PAD src0_sel:WORD_1 src1_sel:DWORD
	v_and_b32_sdwa v74, v26, v209 dst_sel:DWORD dst_unused:UNUSED_PAD src0_sel:WORD_1 src1_sel:DWORD
	v_add3_u32 v26, v26, v74, s77
	v_add3_u32 v5, v27, v5, s77
	v_and_b32_sdwa v27, v73, v209 dst_sel:DWORD dst_unused:UNUSED_PAD src0_sel:WORD_1 src1_sel:DWORD
	v_and_b32_sdwa v74, v72, v209 dst_sel:DWORD dst_unused:UNUSED_PAD src0_sel:WORD_1 src1_sel:DWORD
	v_add3_u32 v27, v73, v27, s77
	v_add3_u32 v72, v72, v74, s77
	v_and_b32_e32 v27, 0xffff0000, v27
	v_and_b32_e32 v72, 0xffff0000, v72
	v_or_b32_sdwa v27, v27, v5 dst_sel:DWORD dst_unused:UNUSED_PAD src0_sel:DWORD src1_sel:WORD_1
	v_or_b32_sdwa v26, v72, v26 dst_sel:DWORD dst_unused:UNUSED_PAD src0_sel:DWORD src1_sel:WORD_1
	global_store_dwordx2 v[80:81], v[26:27], off offset:1024
	v_pk_mul_f32 v[26:27], v[4:5], v[70:71] op_sel_hi:[0,1]
	v_pk_fma_f32 v[26:27], v[66:67], v[26:27], v[0:1]
	v_pk_mul_f32 v[4:5], v[4:5], v[68:69] op_sel_hi:[0,1]
	v_pk_fma_f32 v[4:5], v[16:17], v[4:5], v[6:7]
	v_and_b32_sdwa v68, v27, v209 dst_sel:DWORD dst_unused:UNUSED_PAD src0_sel:WORD_1 src1_sel:DWORD
	v_and_b32_sdwa v69, v26, v209 dst_sel:DWORD dst_unused:UNUSED_PAD src0_sel:WORD_1 src1_sel:DWORD
	v_add3_u32 v26, v26, v69, s77
	v_add3_u32 v27, v27, v68, s77
	v_and_b32_sdwa v68, v5, v209 dst_sel:DWORD dst_unused:UNUSED_PAD src0_sel:WORD_1 src1_sel:DWORD
	v_and_b32_sdwa v69, v4, v209 dst_sel:DWORD dst_unused:UNUSED_PAD src0_sel:WORD_1 src1_sel:DWORD
	v_add3_u32 v5, v5, v68, s77
	v_add3_u32 v4, v4, v69, s77
	v_and_b32_e32 v5, 0xffff0000, v5
	v_and_b32_e32 v4, 0xffff0000, v4
	v_or_b32_sdwa v5, v5, v27 dst_sel:DWORD dst_unused:UNUSED_PAD src0_sel:DWORD src1_sel:WORD_1
	v_or_b32_sdwa v4, v4, v26 dst_sel:DWORD dst_unused:UNUSED_PAD src0_sel:DWORD src1_sel:WORD_1
	global_store_dwordx2 v[80:81], v[4:5], off offset:1536
	s_andn2_b64 vcc, exec, s[20:21]
	s_cbranch_vccnz .LBB0_132
.LBB0_138:
	s_waitcnt lgkmcnt(0)
	v_add_f32_e32 v4, v24, v25
	v_fmamk_f32 v4, v4, 0x3a800000, v206
	v_mul_f32_e32 v5, 0x4f800000, v4
	v_cmp_gt_f32_e32 vcc, s57, v4
	s_nop 1
	v_cndmask_b32_e32 v4, v4, v5, vcc
	v_sqrt_f32_e32 v5, v4
	s_nop 0
	v_add_u32_e32 v24, -1, v5
	v_fma_f32 v26, -v24, v5, v4
	v_add_u32_e32 v25, 1, v5
	v_cmp_ge_f32_e64 s[0:1], 0, v26
	s_nop 1
	v_cndmask_b32_e64 v24, v5, v24, s[0:1]
	v_fma_f32 v5, -v25, v5, v4
	v_cmp_lt_f32_e64 s[0:1], 0, v5
	s_nop 1
	v_cndmask_b32_e64 v5, v24, v25, s[0:1]
	v_mul_f32_e32 v24, 0x37800000, v5
	v_cndmask_b32_e32 v5, v5, v24, vcc
	v_cmp_class_f32_e32 vcc, v4, v207
	s_nop 1
	v_cndmask_b32_e32 v4, v5, v4, vcc
	v_div_scale_f32 v5, s[0:1], v4, v4, 1.0
	v_rcp_f32_e32 v24, v5
	s_nop 0
	v_fma_f32 v25, -v5, v24, 1.0
	v_fmac_f32_e32 v24, v25, v24
	v_div_scale_f32 v25, vcc, 1.0, v4, 1.0
	v_mul_f32_e32 v26, v25, v24
	v_fma_f32 v27, -v5, v26, v25
	v_fmac_f32_e32 v26, v27, v24
	v_fma_f32 v5, -v5, v26, v25
	v_div_fmas_f32 v5, v5, v24, v26
	v_div_fixup_f32 v4, v5, v4, 1.0
	v_pk_mul_f32 v[24:25], v[4:5], v[44:45] op_sel_hi:[0,1]
	v_pk_fma_f32 v[18:19], v[50:51], v[24:25], v[18:19]
	v_pk_mul_f32 v[24:25], v[4:5], v[42:43] op_sel_hi:[0,1]
	v_pk_fma_f32 v[14:15], v[56:57], v[24:25], v[14:15]
	v_and_b32_sdwa v5, v19, v209 dst_sel:DWORD dst_unused:UNUSED_PAD src0_sel:WORD_1 src1_sel:DWORD
	v_and_b32_sdwa v24, v18, v209 dst_sel:DWORD dst_unused:UNUSED_PAD src0_sel:WORD_1 src1_sel:DWORD
	v_add3_u32 v18, v18, v24, s77
	v_add3_u32 v5, v19, v5, s77
	v_and_b32_sdwa v19, v15, v209 dst_sel:DWORD dst_unused:UNUSED_PAD src0_sel:WORD_1 src1_sel:DWORD
	v_and_b32_sdwa v24, v14, v209 dst_sel:DWORD dst_unused:UNUSED_PAD src0_sel:WORD_1 src1_sel:DWORD
	v_add3_u32 v15, v15, v19, s77
	v_add3_u32 v14, v14, v24, s77
	v_and_b32_e32 v15, 0xffff0000, v15
	v_and_b32_e32 v14, 0xffff0000, v14
	v_or_b32_sdwa v15, v15, v5 dst_sel:DWORD dst_unused:UNUSED_PAD src0_sel:DWORD src1_sel:WORD_1
	v_or_b32_sdwa v14, v14, v18 dst_sel:DWORD dst_unused:UNUSED_PAD src0_sel:DWORD src1_sel:WORD_1
	v_lshl_add_u64 v[18:19], v[32:33], 0, s[18:19]
	global_store_dwordx2 v[18:19], v[14:15], off
	v_pk_mul_f32 v[14:15], v[4:5], v[48:49] op_sel_hi:[0,1]
	v_pk_fma_f32 v[12:13], v[58:59], v[14:15], v[12:13]
	v_pk_mul_f32 v[14:15], v[4:5], v[46:47] op_sel_hi:[0,1]
	v_pk_fma_f32 v[10:11], v[60:61], v[14:15], v[10:11]
	v_and_b32_sdwa v5, v13, v209 dst_sel:DWORD dst_unused:UNUSED_PAD src0_sel:WORD_1 src1_sel:DWORD
	v_and_b32_sdwa v14, v12, v209 dst_sel:DWORD dst_unused:UNUSED_PAD src0_sel:WORD_1 src1_sel:DWORD
	v_add3_u32 v12, v12, v14, s77
	v_add3_u32 v5, v13, v5, s77
	v_and_b32_sdwa v13, v11, v209 dst_sel:DWORD dst_unused:UNUSED_PAD src0_sel:WORD_1 src1_sel:DWORD
	v_and_b32_sdwa v14, v10, v209 dst_sel:DWORD dst_unused:UNUSED_PAD src0_sel:WORD_1 src1_sel:DWORD
	v_add3_u32 v11, v11, v13, s77
	v_add3_u32 v10, v10, v14, s77
	v_and_b32_e32 v11, 0xffff0000, v11
	v_and_b32_e32 v10, 0xffff0000, v10
	v_or_b32_sdwa v11, v11, v5 dst_sel:DWORD dst_unused:UNUSED_PAD src0_sel:DWORD src1_sel:WORD_1
	v_or_b32_sdwa v10, v10, v12 dst_sel:DWORD dst_unused:UNUSED_PAD src0_sel:DWORD src1_sel:WORD_1
	global_store_dwordx2 v[18:19], v[10:11], off offset:512
	v_pk_mul_f32 v[10:11], v[4:5], v[54:55] op_sel_hi:[0,1]
	v_pk_fma_f32 v[8:9], v[62:63], v[10:11], v[8:9]
	v_pk_mul_f32 v[10:11], v[4:5], v[52:53] op_sel_hi:[0,1]
	v_pk_fma_f32 v[2:3], v[64:65], v[10:11], v[2:3]
	v_and_b32_sdwa v5, v9, v209 dst_sel:DWORD dst_unused:UNUSED_PAD src0_sel:WORD_1 src1_sel:DWORD
	v_and_b32_sdwa v10, v8, v209 dst_sel:DWORD dst_unused:UNUSED_PAD src0_sel:WORD_1 src1_sel:DWORD
	v_add3_u32 v8, v8, v10, s77
	v_add3_u32 v5, v9, v5, s77
	v_and_b32_sdwa v9, v3, v209 dst_sel:DWORD dst_unused:UNUSED_PAD src0_sel:WORD_1 src1_sel:DWORD
	v_and_b32_sdwa v10, v2, v209 dst_sel:DWORD dst_unused:UNUSED_PAD src0_sel:WORD_1 src1_sel:DWORD
	v_add3_u32 v3, v3, v9, s77
	v_add3_u32 v2, v2, v10, s77
	v_and_b32_e32 v3, 0xffff0000, v3
	v_and_b32_e32 v2, 0xffff0000, v2
	v_or_b32_sdwa v3, v3, v5 dst_sel:DWORD dst_unused:UNUSED_PAD src0_sel:DWORD src1_sel:WORD_1
	v_or_b32_sdwa v2, v2, v8 dst_sel:DWORD dst_unused:UNUSED_PAD src0_sel:DWORD src1_sel:WORD_1
	global_store_dwordx2 v[18:19], v[2:3], off offset:1024
	v_pk_mul_f32 v[2:3], v[4:5], v[22:23] op_sel_hi:[0,1]
	v_pk_fma_f32 v[0:1], v[66:67], v[2:3], v[0:1]
	v_pk_mul_f32 v[2:3], v[4:5], v[20:21] op_sel_hi:[0,1]
	v_pk_fma_f32 v[2:3], v[16:17], v[2:3], v[6:7]
	v_and_b32_sdwa v4, v1, v209 dst_sel:DWORD dst_unused:UNUSED_PAD src0_sel:WORD_1 src1_sel:DWORD
	v_and_b32_sdwa v5, v0, v209 dst_sel:DWORD dst_unused:UNUSED_PAD src0_sel:WORD_1 src1_sel:DWORD
	v_add3_u32 v0, v0, v5, s77
	v_add3_u32 v1, v1, v4, s77
	v_and_b32_sdwa v4, v3, v209 dst_sel:DWORD dst_unused:UNUSED_PAD src0_sel:WORD_1 src1_sel:DWORD
	v_and_b32_sdwa v5, v2, v209 dst_sel:DWORD dst_unused:UNUSED_PAD src0_sel:WORD_1 src1_sel:DWORD
	v_add3_u32 v3, v3, v4, s77
	v_add3_u32 v2, v2, v5, s77
	v_and_b32_e32 v3, 0xffff0000, v3
	v_and_b32_e32 v2, 0xffff0000, v2
	v_or_b32_sdwa v1, v3, v1 dst_sel:DWORD dst_unused:UNUSED_PAD src0_sel:DWORD src1_sel:WORD_1
	v_or_b32_sdwa v0, v2, v0 dst_sel:DWORD dst_unused:UNUSED_PAD src0_sel:DWORD src1_sel:WORD_1
	global_store_dwordx2 v[18:19], v[0:1], off offset:1536
	s_branch .LBB0_132

.LBB0_144:
	global_load_dwordx4 v[56:59], v[98:99], off offset:-2048 nt
	s_waitcnt lgkmcnt(0)
	global_load_dwordx4 v[52:55], v[98:99], off offset:-1024 nt
	global_load_dwordx4 v[44:47], v[98:99], off nt
	global_load_dwordx4 v[4:7], v[98:99], off offset:1024 nt
	s_add_i32 s36, s70, s5
	s_cmpk_lt_i32 s36, 0x4000
	s_cselect_b32 s22, s36, 0x3fff
	s_ashr_i32 s23, s22, 31
	s_add_i32 s14, s67, s5
	s_lshl_b64 s[24:25], s[22:23], 12
	s_cmpk_lt_i32 s14, 0x4000
	s_cselect_b64 s[20:21], -1, 0
	s_and_b64 s[0:1], s[20:21], exec
	s_cselect_b32 s18, s14, 0x3fff
	s_ashr_i32 s19, s18, 31
	s_add_i32 s14, s72, s5
	s_lshl_b64 s[28:29], s[18:19], 12
	s_cmpk_lt_i32 s14, 0x4000
	s_cselect_b64 s[16:17], -1, 0
	s_and_b64 s[0:1], s[16:17], exec
	s_cselect_b32 s14, s14, 0x3fff
	s_ashr_i32 s0, s5, 13
	s_mul_i32 s26, s0, 0x1800
	global_load_dwordx4 v[32:35], v[90:91], off
	s_ashr_i32 s15, s14, 31
	s_ashr_i32 s27, s26, 31
	s_lshl_b64 s[0:1], s[14:15], 12
	s_lshl_b64 s[26:27], s[26:27], 2
	s_add_u32 s26, s34, s26
	s_addc_u32 s27, s35, s27
	s_add_u32 s30, s26, 0x1000
	s_addc_u32 s31, s27, 0
	v_lshl_add_u64 v[0:1], s[30:31], 0, v[168:169]
	flat_load_dwordx4 v[84:87], v[0:1]
	global_load_dwordx4 v[60:63], v[90:91], off offset:1024
	v_mov_b32_e32 v101, v169
	v_lshl_add_u64 v[0:1], s[30:31], 0, v[100:101]
	v_mov_b32_e32 v103, v169
	flat_load_dwordx4 v[80:83], v[0:1]
	v_lshl_add_u64 v[0:1], s[30:31], 0, v[102:103]
	flat_load_dwordx4 v[68:71], v[0:1]
	global_load_dwordx4 v[64:67], v[90:91], off offset:2048
	global_load_dwordx4 v[72:75], v[90:91], off offset:3072
	v_mov_b32_e32 v105, v169
	v_lshl_add_u64 v[0:1], v[92:93], 0, s[24:25]
	v_lshl_add_u64 v[2:3], s[30:31], 0, v[104:105]
	global_load_dwordx4 v[48:51], v[0:1], off nt
	global_load_dwordx4 v[40:43], v[0:1], off offset:1024 nt
	global_load_dwordx4 v[36:39], v[0:1], off offset:2048 nt
	global_load_dwordx4 v[28:31], v[0:1], off offset:3072 nt
	v_lshl_add_u64 v[0:1], v[92:93], 0, s[28:29]
	flat_load_dwordx4 v[76:79], v[2:3]
	global_load_dwordx4 v[24:27], v[0:1], off nt
	global_load_dwordx4 v[16:19], v[0:1], off offset:1024 nt
	global_load_dwordx4 v[12:15], v[0:1], off offset:2048 nt
	global_load_dwordx4 v[8:11], v[0:1], off offset:3072 nt
	v_lshl_add_u64 v[114:115], s[26:27], 0, v[168:169]
	flat_load_dwordx4 v[0:3], v[114:115] offset:1024
	v_lshl_add_u64 v[112:113], v[92:93], 0, s[0:1]
	s_cmpk_gt_i32 s36, 0x3fff
	s_waitcnt vmcnt(0)
	v_pk_mul_f32 v[20:21], v[58:59], v[58:59]
	v_pk_mul_f32 v[22:23], v[56:57], v[56:57]
	v_pk_mul_f32 v[106:107], v[54:55], v[54:55]
	v_pk_mul_f32 v[108:109], v[52:53], v[52:53]
	v_pk_mov_b32 v[110:111], v[22:23], v[20:21] op_sel:[1,0]
	v_mov_b32_e32 v23, v21
	v_pk_mov_b32 v[20:21], v[108:109], v[106:107] op_sel:[1,0]
	v_mov_b32_e32 v109, v107
	v_pk_add_f32 v[106:107], v[110:111], v[22:23]
	v_mul_f32_e32 v22, v45, v45
	v_pk_add_f32 v[108:109], v[20:21], v[108:109]
	v_mul_f32_e32 v20, v47, v47
	v_mul_f32_e32 v101, v6, v6
	v_mul_f32_e32 v103, v7, v7
	v_pk_fma_f32 v[22:23], v[44:45], v[44:45], v[22:23] op_sel_hi:[1,1,0]
	v_pk_fma_f32 v[20:21], v[46:47], v[46:47], v[20:21] op_sel_hi:[1,1,0]
	v_mov_b32_e32 v23, v101
	v_mov_b32_e32 v21, v103
	v_pk_add_f32 v[110:111], v[22:23], v[20:21]
	flat_load_dwordx4 v[20:23], v[114:115]
	v_mul_f32_e32 v101, v4, v4
	v_pk_add_f32 v[106:107], v[106:107], v[106:107] op_sel:[0,1] op_sel_hi:[1,0]
	v_pk_add_f32 v[108:109], v[108:109], v[108:109] op_sel:[0,1] op_sel_hi:[1,0]
	v_mov_b32_e32 v107, v101
	v_mul_f32_e32 v101, v5, v5
	v_mov_b32_e32 v109, v101
	v_pk_add_f32 v[108:109], v[106:107], v[108:109]
	v_mov_b32_e32 v106, v32
	v_mov_b32_e32 v107, v34
	v_mov_b32_e32 v34, v33
	v_pk_add_f32 v[32:33], v[108:109], v[110:111]
	s_waitcnt lgkmcnt(0)
	v_mov_b32_e32 v109, v86
	v_add_f32_e32 v101, v32, v33
	ds_bpermute_b32 v103, v89, v101
	v_mov_b32_e32 v86, v85
	v_pk_add_f32 v[32:33], v[86:87], 1.0 op_sel_hi:[1,0]
	v_mov_b32_e32 v86, v60
	v_mov_b32_e32 v111, v82
	s_waitcnt lgkmcnt(0)
	v_add_f32_e32 v60, v101, v103
	ds_bpermute_b32 v101, v116, v60
	v_mov_b32_e32 v82, v81
	v_mov_b32_e32 v87, v62
	v_mov_b32_e32 v110, v80
	v_pk_add_f32 v[80:81], v[82:83], 1.0 op_sel_hi:[1,0]
	s_waitcnt lgkmcnt(0)
	v_add_f32_e32 v101, v60, v101
	ds_bpermute_b32 v103, v117, v101
	v_mov_b32_e32 v60, v68
	v_mov_b32_e32 v62, v61
	v_pk_mul_f32 v[82:83], v[62:63], v[80:81]
	v_mov_b32_e32 v62, v64
	s_waitcnt lgkmcnt(0)
	v_add_f32_e32 v68, v101, v103
	ds_bpermute_b32 v101, v118, v68
	v_mov_b32_e32 v108, v84
	v_pk_add_f32 v[108:109], v[108:109], 1.0 op_sel_hi:[1,0]
	v_mov_b32_e32 v61, v70
	v_mov_b32_e32 v70, v69
	s_waitcnt lgkmcnt(0)
	v_add_f32_e32 v64, v68, v101
	ds_bpermute_b32 v101, v119, v64
	v_pk_add_f32 v[110:111], v[110:111], 1.0 op_sel_hi:[1,0]
	v_pk_mul_f32 v[108:109], v[106:107], v[108:109]
	v_mov_b32_e32 v63, v66
	v_pk_add_f32 v[106:107], v[70:71], 1.0 op_sel_hi:[1,0]
	s_waitcnt lgkmcnt(0)
	v_add_f32_e32 v101, v64, v101
	ds_bpermute_b32 v103, v120, v101
	v_mov_b32_e32 v66, v65
	v_pk_mul_f32 v[86:87], v[86:87], v[110:111]
	v_pk_mul_f32 v[110:111], v[66:67], v[106:107]
	v_mov_b32_e32 v64, v76
	s_waitcnt lgkmcnt(0)
	v_add_f32_e32 v66, v101, v103
	v_fmamk_f32 v66, v66, 0x3a800000, v206
	v_mul_f32_e32 v67, 0x4f800000, v66
	v_cmp_gt_f32_e32 vcc, s57, v66
	v_mov_b32_e32 v65, v78
	v_pk_add_f32 v[64:65], v[64:65], 1.0 op_sel_hi:[1,0]
	v_cndmask_b32_e32 v76, v66, v67, vcc
	v_sqrt_f32_e32 v78, v76
	v_mov_b32_e32 v66, v72
	v_mov_b32_e32 v67, v74
	v_pk_mul_f32 v[106:107], v[66:67], v[64:65]
	v_add_u32_e32 v64, -1, v78
	v_fma_f32 v65, -v64, v78, v76
	v_cmp_ge_f32_e64 s[0:1], 0, v65
	v_add_u32_e32 v74, 1, v78
	v_pk_add_f32 v[60:61], v[60:61], 1.0 op_sel_hi:[1,0]
	v_cndmask_b32_e64 v72, v78, v64, s[0:1]
	v_fma_f32 v64, -v74, v78, v76
	v_cmp_lt_f32_e64 s[0:1], 0, v64
	v_pk_mul_f32 v[84:85], v[34:35], v[32:33]
	flat_load_dwordx4 v[32:35], v[114:115] offset:3072
	v_cndmask_b32_e64 v72, v72, v74, s[0:1]
	v_pk_mul_f32 v[80:81], v[62:63], v[60:61]
	global_load_dwordx4 v[68:71], v[112:113], off nt
	global_load_dwordx4 v[60:63], v[112:113], off offset:1024 nt
	flat_load_dwordx4 v[64:67], v[114:115] offset:2048
	v_mul_f32_e32 v74, 0x37800000, v72
	v_cndmask_b32_e32 v72, v72, v74, vcc
	v_cmp_class_f32_e32 vcc, v76, v207
	v_mov_b32_e32 v78, v77
	v_mov_b32_e32 v74, v73
	v_cndmask_b32_e32 v72, v72, v76, vcc
	v_div_scale_f32 v101, s[0:1], v72, v72, 1.0
	v_rcp_f32_e32 v103, v101
	v_pk_add_f32 v[76:77], v[78:79], 1.0 op_sel_hi:[1,0]
	s_waitcnt vmcnt(0)
	v_mov_b32_e32 v79, v22
	v_pk_mul_f32 v[76:77], v[74:75], v[76:77]
	v_fma_f32 v73, -v101, v103, 1.0
	v_fmac_f32_e32 v103, v73, v103
	v_div_scale_f32 v73, vcc, 1.0, v72, 1.0
	v_mul_f32_e32 v74, v73, v103
	v_fma_f32 v75, -v101, v74, v73
	v_fmac_f32_e32 v74, v75, v103
	v_fma_f32 v73, -v101, v74, v73
	v_div_fmas_f32 v73, v73, v103, v74
	v_div_fixup_f32 v114, v73, v72, 1.0
	v_mov_b32_e32 v73, v58
	v_mov_b32_e32 v58, v57
	v_mov_b32_e32 v72, v56
	v_pk_mul_f32 v[56:57], v[58:59], v[114:115] op_sel_hi:[1,0]
	v_mov_b32_e32 v22, v21
	v_pk_mul_f32 v[72:73], v[72:73], v[114:115] op_sel_hi:[1,0]
	v_mov_b32_e32 v78, v20
	v_pk_fma_f32 v[20:21], v[84:85], v[56:57], v[22:23]
	v_pk_fma_f32 v[72:73], v[108:109], v[72:73], v[78:79]
	v_and_b32_sdwa v58, v21, v209 dst_sel:DWORD dst_unused:UNUSED_PAD src0_sel:WORD_1 src1_sel:DWORD
	v_and_b32_sdwa v59, v20, v209 dst_sel:DWORD dst_unused:UNUSED_PAD src0_sel:WORD_1 src1_sel:DWORD
	v_and_b32_sdwa v56, v73, v209 dst_sel:DWORD dst_unused:UNUSED_PAD src0_sel:WORD_1 src1_sel:DWORD
	v_and_b32_sdwa v57, v72, v209 dst_sel:DWORD dst_unused:UNUSED_PAD src0_sel:WORD_1 src1_sel:DWORD
	v_add3_u32 v21, v21, v58, s77
	v_add3_u32 v20, v20, v59, s77
	v_add3_u32 v57, v72, v57, s77
	v_add3_u32 v56, v73, v56, s77
	v_and_b32_e32 v21, 0xffff0000, v21
	v_and_b32_e32 v20, 0xffff0000, v20
	v_or_b32_sdwa v21, v21, v56 dst_sel:DWORD dst_unused:UNUSED_PAD src0_sel:DWORD src1_sel:WORD_1
	v_or_b32_sdwa v20, v20, v57 dst_sel:DWORD dst_unused:UNUSED_PAD src0_sel:DWORD src1_sel:WORD_1
	global_load_dwordx4 v[72:75], v[112:113], off offset:2048 nt
	global_load_dwordx4 v[56:59], v[112:113], off offset:3072 nt
	v_mul_f32_e32 v101, v43, v43
	global_store_dwordx2 v[96:97], v[20:21], off
	v_mov_b32_e32 v20, v52
	v_mov_b32_e32 v21, v54
	v_pk_mul_f32 v[112:113], v[20:21], v[114:115] op_sel_hi:[1,0]
	v_mov_b32_e32 v54, v53
	v_mov_b32_e32 v20, v0
	v_mov_b32_e32 v21, v2
	v_pk_mul_f32 v[52:53], v[54:55], v[114:115] op_sel_hi:[1,0]
	v_pk_fma_f32 v[54:55], v[86:87], v[112:113], v[20:21]
	v_mov_b32_e32 v2, v1
	v_and_b32_sdwa v0, v54, v209 dst_sel:DWORD dst_unused:UNUSED_PAD src0_sel:WORD_1 src1_sel:DWORD
	v_add3_u32 v54, v54, v0, s77
	v_and_b32_sdwa v0, v55, v209 dst_sel:DWORD dst_unused:UNUSED_PAD src0_sel:WORD_1 src1_sel:DWORD
	v_add3_u32 v55, v55, v0, s77
	v_pk_fma_f32 v[0:1], v[82:83], v[52:53], v[2:3]
	v_mul_f32_e32 v53, v51, v51
	v_and_b32_sdwa v52, v1, v209 dst_sel:DWORD dst_unused:UNUSED_PAD src0_sel:WORD_1 src1_sel:DWORD
	v_add3_u32 v1, v1, v52, s77
	v_and_b32_sdwa v52, v0, v209 dst_sel:DWORD dst_unused:UNUSED_PAD src0_sel:WORD_1 src1_sel:DWORD
	v_add3_u32 v0, v0, v52, s77
	v_mul_f32_e32 v52, v49, v49
	v_fmac_f32_e32 v52, v48, v48
	v_fmac_f32_e32 v53, v50, v50
	v_add_f32_e32 v52, v52, v53
	v_mul_f32_e32 v53, v41, v41
	v_fmac_f32_e32 v53, v40, v40
	v_fmac_f32_e32 v101, v42, v42
	v_add_f32_e32 v53, v53, v101
	v_add_f32_e32 v52, v52, v53
	v_mul_f32_e32 v53, v37, v37
	v_mul_f32_e32 v101, v39, v39
	v_fmac_f32_e32 v53, v36, v36
	v_fmac_f32_e32 v101, v38, v38
	v_add_f32_e32 v53, v53, v101
	v_add_f32_e32 v52, v52, v53
	v_mul_f32_e32 v53, v29, v29
	v_mul_f32_e32 v101, v31, v31
	v_and_b32_e32 v1, 0xffff0000, v1
	v_and_b32_e32 v0, 0xffff0000, v0
	v_fmac_f32_e32 v53, v28, v28
	v_fmac_f32_e32 v101, v30, v30
	v_or_b32_sdwa v1, v1, v55 dst_sel:DWORD dst_unused:UNUSED_PAD src0_sel:DWORD src1_sel:WORD_1
	v_or_b32_sdwa v0, v0, v54 dst_sel:DWORD dst_unused:UNUSED_PAD src0_sel:DWORD src1_sel:WORD_1
	v_add_f32_e32 v53, v53, v101
	global_store_dwordx2 v[96:97], v[0:1], off offset:512
	v_mov_b32_e32 v0, v44
	v_mov_b32_e32 v1, v46
	v_add_f32_e32 v101, v52, v53
	v_pk_mul_f32 v[52:53], v[0:1], v[114:115] op_sel_hi:[1,0]
	s_waitcnt lgkmcnt(0)
	v_mov_b32_e32 v0, v64
	v_mov_b32_e32 v1, v66
	v_mov_b32_e32 v46, v45
	v_pk_fma_f32 v[52:53], v[80:81], v[52:53], v[0:1]
	v_pk_mul_f32 v[44:45], v[46:47], v[114:115] op_sel_hi:[1,0]
	v_mov_b32_e32 v66, v65
	v_pk_fma_f32 v[44:45], v[110:111], v[44:45], v[66:67]
	v_and_b32_sdwa v46, v53, v209 dst_sel:DWORD dst_unused:UNUSED_PAD src0_sel:WORD_1 src1_sel:DWORD
	v_and_b32_sdwa v47, v52, v209 dst_sel:DWORD dst_unused:UNUSED_PAD src0_sel:WORD_1 src1_sel:DWORD
	v_add3_u32 v52, v52, v47, s77
	v_add3_u32 v46, v53, v46, s77
	v_and_b32_sdwa v47, v45, v209 dst_sel:DWORD dst_unused:UNUSED_PAD src0_sel:WORD_1 src1_sel:DWORD
	v_and_b32_sdwa v53, v44, v209 dst_sel:DWORD dst_unused:UNUSED_PAD src0_sel:WORD_1 src1_sel:DWORD
	v_add3_u32 v54, v45, v47, s77
	v_add3_u32 v53, v44, v53, s77
	v_mul_f32_e32 v44, v25, v25
	v_mul_f32_e32 v45, v27, v27
	v_fmac_f32_e32 v44, v24, v24
	v_fmac_f32_e32 v45, v26, v26
	v_add_f32_e32 v44, v44, v45
	v_mul_f32_e32 v45, v17, v17
	v_mul_f32_e32 v47, v19, v19
	v_fmac_f32_e32 v45, v16, v16
	v_fmac_f32_e32 v47, v18, v18
	v_add_f32_e32 v45, v45, v47
	v_add_f32_e32 v44, v44, v45
	v_mul_f32_e32 v45, v13, v13
	v_mul_f32_e32 v47, v15, v15
	v_fmac_f32_e32 v45, v12, v12
	v_fmac_f32_e32 v47, v14, v14
	v_add_f32_e32 v45, v45, v47
	v_add_f32_e32 v44, v44, v45
	v_mul_f32_e32 v45, v9, v9
	v_mul_f32_e32 v47, v11, v11
	v_fmac_f32_e32 v45, v8, v8
	v_fmac_f32_e32 v47, v10, v10
	v_add_f32_e32 v45, v45, v47
	v_add_f32_e32 v44, v44, v45
	v_mul_f32_e32 v45, v69, v69
	v_mul_f32_e32 v47, v71, v71
	v_fmac_f32_e32 v45, v68, v68
	v_fmac_f32_e32 v47, v70, v70
	v_add_f32_e32 v45, v45, v47
	v_mul_f32_e32 v47, v61, v61
	v_mul_f32_e32 v55, v63, v63
	v_fmac_f32_e32 v47, v60, v60
	v_fmac_f32_e32 v55, v62, v62
	v_add_f32_e32 v47, v47, v55
	v_add_f32_e32 v45, v45, v47
	s_waitcnt vmcnt(0)
	v_mul_f32_e32 v47, v73, v73
	v_mul_f32_e32 v55, v75, v75
	v_fmac_f32_e32 v47, v72, v72
	v_fmac_f32_e32 v55, v74, v74
	v_add_f32_e32 v47, v47, v55
	v_add_f32_e32 v45, v45, v47
	v_mul_f32_e32 v47, v57, v57
	v_mul_f32_e32 v55, v59, v59
	v_fmac_f32_e32 v47, v56, v56
	v_fmac_f32_e32 v55, v58, v58
	v_add_f32_e32 v47, v47, v55
	ds_bpermute_b32 v55, v89, v44
	v_add_f32_e32 v45, v45, v47
	ds_bpermute_b32 v47, v89, v101
	v_and_b32_e32 v54, 0xffff0000, v54
	v_and_b32_e32 v53, 0xffff0000, v53
	s_waitcnt lgkmcnt(1)
	v_add_f32_e32 v44, v44, v55
	ds_bpermute_b32 v55, v89, v45
	s_waitcnt lgkmcnt(1)
	v_add_f32_e32 v47, v101, v47
	s_waitcnt lgkmcnt(0)
	v_add_f32_e32 v45, v45, v55
	ds_bpermute_b32 v55, v116, v47
	s_waitcnt lgkmcnt(0)
	v_add_f32_e32 v47, v47, v55
	ds_bpermute_b32 v55, v116, v44
	s_waitcnt lgkmcnt(0)
	v_add_f32_e32 v44, v44, v55
	ds_bpermute_b32 v55, v116, v45
	s_waitcnt lgkmcnt(0)
	v_add_f32_e32 v45, v45, v55
	ds_bpermute_b32 v55, v117, v47
	s_waitcnt lgkmcnt(0)
	v_add_f32_e32 v47, v47, v55
	ds_bpermute_b32 v55, v117, v44
	s_waitcnt lgkmcnt(0)
	v_add_f32_e32 v44, v44, v55
	ds_bpermute_b32 v55, v117, v45
	s_waitcnt lgkmcnt(0)
	v_add_f32_e32 v45, v45, v55
	ds_bpermute_b32 v55, v118, v47
	s_waitcnt lgkmcnt(0)
	v_add_f32_e32 v47, v47, v55
	ds_bpermute_b32 v55, v118, v44
	s_waitcnt lgkmcnt(0)
	v_add_f32_e32 v44, v44, v55
	ds_bpermute_b32 v55, v118, v45
	s_waitcnt lgkmcnt(0)
	v_add_f32_e32 v55, v45, v55
	ds_bpermute_b32 v45, v119, v47
	s_waitcnt lgkmcnt(0)
	v_add_f32_e32 v47, v47, v45
	ds_bpermute_b32 v45, v119, v44
	s_waitcnt lgkmcnt(0)
	v_add_f32_e32 v45, v44, v45
	ds_bpermute_b32 v44, v119, v55
	s_waitcnt lgkmcnt(0)
	v_add_f32_e32 v44, v55, v44
	v_or_b32_sdwa v55, v54, v46 dst_sel:DWORD dst_unused:UNUSED_PAD src0_sel:DWORD src1_sel:WORD_1
	v_or_b32_sdwa v54, v53, v52 dst_sel:DWORD dst_unused:UNUSED_PAD src0_sel:DWORD src1_sel:WORD_1
	global_store_dwordx2 v[96:97], v[54:55], off offset:1024
	v_mov_b32_e32 v54, v4
	v_mov_b32_e32 v55, v6
	v_pk_mul_f32 v[54:55], v[54:55], v[114:115] op_sel_hi:[1,0]
	v_mov_b32_e32 v6, v5
	v_mov_b32_e32 v4, v32
	v_mov_b32_e32 v5, v34
	v_pk_mul_f32 v[6:7], v[6:7], v[114:115] op_sel_hi:[1,0]
	v_pk_fma_f32 v[54:55], v[106:107], v[54:55], v[4:5]
	v_mov_b32_e32 v34, v33
	v_pk_fma_f32 v[6:7], v[76:77], v[6:7], v[34:35]
	v_and_b32_sdwa v33, v54, v209 dst_sel:DWORD dst_unused:UNUSED_PAD src0_sel:WORD_1 src1_sel:DWORD
	v_add3_u32 v53, v54, v33, s77
	v_and_b32_sdwa v33, v7, v209 dst_sel:DWORD dst_unused:UNUSED_PAD src0_sel:WORD_1 src1_sel:DWORD
	v_and_b32_sdwa v54, v6, v209 dst_sel:DWORD dst_unused:UNUSED_PAD src0_sel:WORD_1 src1_sel:DWORD
	ds_bpermute_b32 v52, v120, v47
	ds_bpermute_b32 v46, v120, v45
	v_add3_u32 v7, v7, v33, s77
	v_add3_u32 v33, v6, v54, s77
	ds_bpermute_b32 v6, v120, v44
	v_and_b32_sdwa v32, v55, v209 dst_sel:DWORD dst_unused:UNUSED_PAD src0_sel:WORD_1 src1_sel:DWORD
	v_add3_u32 v32, v55, v32, s77
	v_and_b32_e32 v7, 0xffff0000, v7
	v_and_b32_e32 v54, 0xffff0000, v33
	v_or_b32_sdwa v33, v7, v32 dst_sel:DWORD dst_unused:UNUSED_PAD src0_sel:DWORD src1_sel:WORD_1
	v_or_b32_sdwa v32, v54, v53 dst_sel:DWORD dst_unused:UNUSED_PAD src0_sel:DWORD src1_sel:WORD_1
	global_store_dwordx2 v[96:97], v[32:33], off offset:1536
	s_cbranch_scc0 .LBB0_147
	s_andn2_b64 vcc, exec, s[20:21]
	s_cbranch_vccz .LBB0_148

.LBB0_147:
	s_waitcnt lgkmcnt(0)
	v_add_f32_e32 v7, v47, v52
	v_fmamk_f32 v7, v7, 0x3a800000, v206
	v_mul_f32_e32 v32, 0x4f800000, v7
	v_cmp_gt_f32_e32 vcc, s57, v7
	s_nop 1
	v_cndmask_b32_e32 v7, v7, v32, vcc
	v_sqrt_f32_e32 v32, v7
	s_nop 0
	v_add_u32_e32 v33, -1, v32
	v_fma_f32 v52, -v33, v32, v7
	v_add_u32_e32 v47, 1, v32
	v_cmp_ge_f32_e64 s[0:1], 0, v52
	s_nop 1
	v_cndmask_b32_e64 v33, v32, v33, s[0:1]
	v_fma_f32 v32, -v47, v32, v7
	v_cmp_lt_f32_e64 s[0:1], 0, v32
	s_nop 1
	v_cndmask_b32_e64 v32, v33, v47, s[0:1]
	v_mul_f32_e32 v33, 0x37800000, v32
	v_cndmask_b32_e32 v32, v32, v33, vcc
	v_cmp_class_f32_e32 vcc, v7, v207
	s_nop 1
	v_cndmask_b32_e32 v7, v32, v7, vcc
	v_div_scale_f32 v32, s[0:1], v7, v7, 1.0
	v_rcp_f32_e32 v33, v32
	s_lshl_b64 s[0:1], s[22:23], 11
	v_fma_f32 v47, -v32, v33, 1.0
	v_fmac_f32_e32 v33, v47, v33
	v_div_scale_f32 v47, vcc, 1.0, v7, 1.0
	v_mul_f32_e32 v52, v47, v33
	v_fma_f32 v53, -v32, v52, v47
	v_fmac_f32_e32 v52, v53, v33
	v_fma_f32 v32, -v32, v52, v47
	v_div_fmas_f32 v32, v32, v33, v52
	v_div_fixup_f32 v32, v32, v7, 1.0
	v_mov_b32_e32 v53, v50
	v_mov_b32_e32 v50, v49
	v_mov_b32_e32 v52, v48
	v_pk_mul_f32 v[48:49], v[50:51], v[32:33] op_sel_hi:[1,0]
	v_pk_mul_f32 v[52:53], v[52:53], v[32:33] op_sel_hi:[1,0]
	v_pk_fma_f32 v[48:49], v[84:85], v[48:49], v[22:23]
	v_pk_fma_f32 v[52:53], v[108:109], v[52:53], v[78:79]
	v_and_b32_sdwa v47, v49, v209 dst_sel:DWORD dst_unused:UNUSED_PAD src0_sel:WORD_1 src1_sel:DWORD
	v_and_b32_sdwa v50, v48, v209 dst_sel:DWORD dst_unused:UNUSED_PAD src0_sel:WORD_1 src1_sel:DWORD
	v_and_b32_sdwa v7, v53, v209 dst_sel:DWORD dst_unused:UNUSED_PAD src0_sel:WORD_1 src1_sel:DWORD
	v_and_b32_sdwa v33, v52, v209 dst_sel:DWORD dst_unused:UNUSED_PAD src0_sel:WORD_1 src1_sel:DWORD
	v_add3_u32 v47, v49, v47, s77
	v_add3_u32 v48, v48, v50, s77
	v_add3_u32 v33, v52, v33, s77
	v_add3_u32 v7, v53, v7, s77
	v_and_b32_e32 v47, 0xffff0000, v47
	v_and_b32_e32 v48, 0xffff0000, v48
	v_or_b32_sdwa v49, v47, v7 dst_sel:DWORD dst_unused:UNUSED_PAD src0_sel:DWORD src1_sel:WORD_1
	v_or_b32_sdwa v48, v48, v33 dst_sel:DWORD dst_unused:UNUSED_PAD src0_sel:DWORD src1_sel:WORD_1
	v_lshl_add_u64 v[50:51], v[94:95], 0, s[0:1]
	global_store_dwordx2 v[50:51], v[48:49], off
	v_mov_b32_e32 v49, v42
	v_mov_b32_e32 v42, v41
	v_mov_b32_e32 v48, v40
	v_pk_mul_f32 v[40:41], v[42:43], v[32:33] op_sel_hi:[1,0]
	v_pk_mul_f32 v[48:49], v[48:49], v[32:33] op_sel_hi:[1,0]
	v_pk_fma_f32 v[40:41], v[82:83], v[40:41], v[2:3]
	v_pk_fma_f32 v[48:49], v[86:87], v[48:49], v[20:21]
	v_and_b32_sdwa v42, v41, v209 dst_sel:DWORD dst_unused:UNUSED_PAD src0_sel:WORD_1 src1_sel:DWORD
	v_and_b32_sdwa v43, v40, v209 dst_sel:DWORD dst_unused:UNUSED_PAD src0_sel:WORD_1 src1_sel:DWORD
	v_and_b32_sdwa v7, v49, v209 dst_sel:DWORD dst_unused:UNUSED_PAD src0_sel:WORD_1 src1_sel:DWORD
	v_and_b32_sdwa v33, v48, v209 dst_sel:DWORD dst_unused:UNUSED_PAD src0_sel:WORD_1 src1_sel:DWORD
	v_add3_u32 v41, v41, v42, s77
	v_add3_u32 v40, v40, v43, s77
	v_add3_u32 v33, v48, v33, s77
	v_add3_u32 v7, v49, v7, s77
	v_and_b32_e32 v41, 0xffff0000, v41
	v_and_b32_e32 v40, 0xffff0000, v40
	v_or_b32_sdwa v41, v41, v7 dst_sel:DWORD dst_unused:UNUSED_PAD src0_sel:DWORD src1_sel:WORD_1
	v_or_b32_sdwa v40, v40, v33 dst_sel:DWORD dst_unused:UNUSED_PAD src0_sel:DWORD src1_sel:WORD_1
	global_store_dwordx2 v[50:51], v[40:41], off offset:512
	v_mov_b32_e32 v41, v38
	v_mov_b32_e32 v38, v37
	v_mov_b32_e32 v40, v36
	v_pk_mul_f32 v[36:37], v[38:39], v[32:33] op_sel_hi:[1,0]
	v_pk_mul_f32 v[40:41], v[40:41], v[32:33] op_sel_hi:[1,0]
	v_pk_fma_f32 v[36:37], v[110:111], v[36:37], v[66:67]
	v_pk_fma_f32 v[40:41], v[80:81], v[40:41], v[0:1]
	v_and_b32_sdwa v38, v37, v209 dst_sel:DWORD dst_unused:UNUSED_PAD src0_sel:WORD_1 src1_sel:DWORD
	v_and_b32_sdwa v39, v36, v209 dst_sel:DWORD dst_unused:UNUSED_PAD src0_sel:WORD_1 src1_sel:DWORD
	v_and_b32_sdwa v7, v41, v209 dst_sel:DWORD dst_unused:UNUSED_PAD src0_sel:WORD_1 src1_sel:DWORD
	v_and_b32_sdwa v33, v40, v209 dst_sel:DWORD dst_unused:UNUSED_PAD src0_sel:WORD_1 src1_sel:DWORD
	v_add3_u32 v37, v37, v38, s77
	v_add3_u32 v36, v36, v39, s77
	v_add3_u32 v33, v40, v33, s77
	v_add3_u32 v7, v41, v7, s77
	v_and_b32_e32 v37, 0xffff0000, v37
	v_and_b32_e32 v36, 0xffff0000, v36
	v_or_b32_sdwa v37, v37, v7 dst_sel:DWORD dst_unused:UNUSED_PAD src0_sel:DWORD src1_sel:WORD_1
	v_or_b32_sdwa v36, v36, v33 dst_sel:DWORD dst_unused:UNUSED_PAD src0_sel:DWORD src1_sel:WORD_1
	global_store_dwordx2 v[50:51], v[36:37], off offset:1024
	v_mov_b32_e32 v37, v30
	v_mov_b32_e32 v30, v29
	v_mov_b32_e32 v36, v28
	v_pk_mul_f32 v[28:29], v[30:31], v[32:33] op_sel_hi:[1,0]
	v_pk_mul_f32 v[36:37], v[36:37], v[32:33] op_sel_hi:[1,0]
	v_pk_fma_f32 v[28:29], v[76:77], v[28:29], v[34:35]
	v_pk_fma_f32 v[36:37], v[106:107], v[36:37], v[4:5]
	v_and_b32_sdwa v31, v29, v209 dst_sel:DWORD dst_unused:UNUSED_PAD src0_sel:WORD_1 src1_sel:DWORD
	v_and_b32_sdwa v32, v28, v209 dst_sel:DWORD dst_unused:UNUSED_PAD src0_sel:WORD_1 src1_sel:DWORD
	v_and_b32_sdwa v7, v37, v209 dst_sel:DWORD dst_unused:UNUSED_PAD src0_sel:WORD_1 src1_sel:DWORD
	v_and_b32_sdwa v30, v36, v209 dst_sel:DWORD dst_unused:UNUSED_PAD src0_sel:WORD_1 src1_sel:DWORD
	v_add3_u32 v29, v29, v31, s77
	v_add3_u32 v28, v28, v32, s77
	v_add3_u32 v30, v36, v30, s77
	v_add3_u32 v7, v37, v7, s77
	v_and_b32_e32 v29, 0xffff0000, v29
	v_and_b32_e32 v28, 0xffff0000, v28
	v_or_b32_sdwa v29, v29, v7 dst_sel:DWORD dst_unused:UNUSED_PAD src0_sel:DWORD src1_sel:WORD_1
	v_or_b32_sdwa v28, v28, v30 dst_sel:DWORD dst_unused:UNUSED_PAD src0_sel:DWORD src1_sel:WORD_1
	global_store_dwordx2 v[50:51], v[28:29], off offset:1536
	s_andn2_b64 vcc, exec, s[20:21]
	s_cbranch_vccnz .LBB0_146
.LBB0_148:
	s_waitcnt lgkmcnt(0)
	v_add_f32_e32 v7, v45, v46
	v_fmamk_f32 v7, v7, 0x3a800000, v206
	v_mul_f32_e32 v28, 0x4f800000, v7
	v_cmp_gt_f32_e32 vcc, s57, v7
	s_nop 1
	v_cndmask_b32_e32 v7, v7, v28, vcc
	v_sqrt_f32_e32 v28, v7
	s_nop 0
	v_add_u32_e32 v29, -1, v28
	v_fma_f32 v31, -v29, v28, v7
	v_add_u32_e32 v30, 1, v28
	v_cmp_ge_f32_e64 s[0:1], 0, v31
	s_nop 1
	v_cndmask_b32_e64 v29, v28, v29, s[0:1]
	v_fma_f32 v28, -v30, v28, v7
	v_cmp_lt_f32_e64 s[0:1], 0, v28
	s_nop 1
	v_cndmask_b32_e64 v28, v29, v30, s[0:1]
	v_mul_f32_e32 v29, 0x37800000, v28
	v_cndmask_b32_e32 v28, v28, v29, vcc
	v_cmp_class_f32_e32 vcc, v7, v207
	s_nop 1
	v_cndmask_b32_e32 v7, v28, v7, vcc
	v_div_scale_f32 v28, s[0:1], v7, v7, 1.0
	v_rcp_f32_e32 v29, v28
	s_lshl_b64 s[0:1], s[18:19], 11
	v_fma_f32 v30, -v28, v29, 1.0
	v_fmac_f32_e32 v29, v30, v29
	v_div_scale_f32 v30, vcc, 1.0, v7, 1.0
	v_mul_f32_e32 v31, v30, v29
	v_fma_f32 v32, -v28, v31, v30
	v_fmac_f32_e32 v31, v32, v29
	v_fma_f32 v28, -v28, v31, v30
	v_div_fmas_f32 v28, v28, v29, v31
	v_div_fixup_f32 v28, v28, v7, 1.0
	v_mov_b32_e32 v31, v26
	v_mov_b32_e32 v26, v25
	v_mov_b32_e32 v30, v24
	v_pk_mul_f32 v[24:25], v[26:27], v[28:29] op_sel_hi:[1,0]
	v_pk_mul_f32 v[30:31], v[30:31], v[28:29] op_sel_hi:[1,0]
	v_pk_fma_f32 v[24:25], v[84:85], v[24:25], v[22:23]
	v_pk_fma_f32 v[30:31], v[108:109], v[30:31], v[78:79]
	v_and_b32_sdwa v27, v25, v209 dst_sel:DWORD dst_unused:UNUSED_PAD src0_sel:WORD_1 src1_sel:DWORD
	v_and_b32_sdwa v29, v24, v209 dst_sel:DWORD dst_unused:UNUSED_PAD src0_sel:WORD_1 src1_sel:DWORD
	v_and_b32_sdwa v7, v31, v209 dst_sel:DWORD dst_unused:UNUSED_PAD src0_sel:WORD_1 src1_sel:DWORD
	v_and_b32_sdwa v26, v30, v209 dst_sel:DWORD dst_unused:UNUSED_PAD src0_sel:WORD_1 src1_sel:DWORD
	v_add3_u32 v25, v25, v27, s77
	v_add3_u32 v24, v24, v29, s77
	v_add3_u32 v26, v30, v26, s77
	v_add3_u32 v7, v31, v7, s77
	v_and_b32_e32 v25, 0xffff0000, v25
	v_and_b32_e32 v24, 0xffff0000, v24
	v_or_b32_sdwa v25, v25, v7 dst_sel:DWORD dst_unused:UNUSED_PAD src0_sel:DWORD src1_sel:WORD_1
	v_or_b32_sdwa v24, v24, v26 dst_sel:DWORD dst_unused:UNUSED_PAD src0_sel:DWORD src1_sel:WORD_1
	v_lshl_add_u64 v[26:27], v[94:95], 0, s[0:1]
	global_store_dwordx2 v[26:27], v[24:25], off
	v_mov_b32_e32 v24, v16
	v_mov_b32_e32 v25, v18
	v_pk_mul_f32 v[24:25], v[24:25], v[28:29] op_sel_hi:[1,0]
	v_mov_b32_e32 v18, v17
	v_pk_fma_f32 v[24:25], v[86:87], v[24:25], v[20:21]
	v_pk_mul_f32 v[16:17], v[18:19], v[28:29] op_sel_hi:[1,0]
	v_and_b32_sdwa v18, v24, v209 dst_sel:DWORD dst_unused:UNUSED_PAD src0_sel:WORD_1 src1_sel:DWORD
	v_pk_fma_f32 v[16:17], v[82:83], v[16:17], v[2:3]
	v_add3_u32 v18, v24, v18, s77
	v_and_b32_sdwa v19, v17, v209 dst_sel:DWORD dst_unused:UNUSED_PAD src0_sel:WORD_1 src1_sel:DWORD
	v_and_b32_sdwa v24, v16, v209 dst_sel:DWORD dst_unused:UNUSED_PAD src0_sel:WORD_1 src1_sel:DWORD
	v_and_b32_sdwa v7, v25, v209 dst_sel:DWORD dst_unused:UNUSED_PAD src0_sel:WORD_1 src1_sel:DWORD
	v_add3_u32 v17, v17, v19, s77
	v_add3_u32 v16, v16, v24, s77
	v_add3_u32 v7, v25, v7, s77
	v_and_b32_e32 v17, 0xffff0000, v17
	v_and_b32_e32 v16, 0xffff0000, v16
	v_or_b32_sdwa v17, v17, v7 dst_sel:DWORD dst_unused:UNUSED_PAD src0_sel:DWORD src1_sel:WORD_1
	v_or_b32_sdwa v16, v16, v18 dst_sel:DWORD dst_unused:UNUSED_PAD src0_sel:DWORD src1_sel:WORD_1
	global_store_dwordx2 v[26:27], v[16:17], off offset:512
	v_mov_b32_e32 v16, v12
	v_mov_b32_e32 v17, v14
	v_pk_mul_f32 v[16:17], v[16:17], v[28:29] op_sel_hi:[1,0]
	v_mov_b32_e32 v14, v13
	v_pk_fma_f32 v[16:17], v[80:81], v[16:17], v[0:1]
	v_pk_mul_f32 v[12:13], v[14:15], v[28:29] op_sel_hi:[1,0]
	v_and_b32_sdwa v14, v16, v209 dst_sel:DWORD dst_unused:UNUSED_PAD src0_sel:WORD_1 src1_sel:DWORD
	v_pk_fma_f32 v[12:13], v[110:111], v[12:13], v[66:67]
	v_add3_u32 v14, v16, v14, s77
	v_and_b32_sdwa v15, v13, v209 dst_sel:DWORD dst_unused:UNUSED_PAD src0_sel:WORD_1 src1_sel:DWORD
	v_and_b32_sdwa v16, v12, v209 dst_sel:DWORD dst_unused:UNUSED_PAD src0_sel:WORD_1 src1_sel:DWORD
	v_and_b32_sdwa v7, v17, v209 dst_sel:DWORD dst_unused:UNUSED_PAD src0_sel:WORD_1 src1_sel:DWORD
	v_add3_u32 v13, v13, v15, s77
	v_add3_u32 v12, v12, v16, s77
	v_add3_u32 v7, v17, v7, s77
	v_and_b32_e32 v13, 0xffff0000, v13
	v_and_b32_e32 v12, 0xffff0000, v12
	v_or_b32_sdwa v13, v13, v7 dst_sel:DWORD dst_unused:UNUSED_PAD src0_sel:DWORD src1_sel:WORD_1
	v_or_b32_sdwa v12, v12, v14 dst_sel:DWORD dst_unused:UNUSED_PAD src0_sel:DWORD src1_sel:WORD_1
	global_store_dwordx2 v[26:27], v[12:13], off offset:1024
	v_mov_b32_e32 v12, v8
	v_mov_b32_e32 v13, v10
	v_pk_mul_f32 v[12:13], v[12:13], v[28:29] op_sel_hi:[1,0]
	v_mov_b32_e32 v10, v9
	v_pk_fma_f32 v[12:13], v[106:107], v[12:13], v[4:5]
	v_pk_mul_f32 v[8:9], v[10:11], v[28:29] op_sel_hi:[1,0]
	v_and_b32_sdwa v10, v12, v209 dst_sel:DWORD dst_unused:UNUSED_PAD src0_sel:WORD_1 src1_sel:DWORD
	v_pk_fma_f32 v[8:9], v[76:77], v[8:9], v[34:35]
	v_add3_u32 v10, v12, v10, s77
	v_and_b32_sdwa v11, v9, v209 dst_sel:DWORD dst_unused:UNUSED_PAD src0_sel:WORD_1 src1_sel:DWORD
	v_and_b32_sdwa v12, v8, v209 dst_sel:DWORD dst_unused:UNUSED_PAD src0_sel:WORD_1 src1_sel:DWORD
	v_and_b32_sdwa v7, v13, v209 dst_sel:DWORD dst_unused:UNUSED_PAD src0_sel:WORD_1 src1_sel:DWORD
	v_add3_u32 v9, v9, v11, s77
	v_add3_u32 v8, v8, v12, s77
	v_add3_u32 v7, v13, v7, s77
	v_and_b32_e32 v9, 0xffff0000, v9
	v_and_b32_e32 v8, 0xffff0000, v8
	v_or_b32_sdwa v9, v9, v7 dst_sel:DWORD dst_unused:UNUSED_PAD src0_sel:DWORD src1_sel:WORD_1
	v_or_b32_sdwa v8, v8, v10 dst_sel:DWORD dst_unused:UNUSED_PAD src0_sel:DWORD src1_sel:WORD_1
	global_store_dwordx2 v[26:27], v[8:9], off offset:1536
	s_andn2_b64 vcc, exec, s[16:17]
	s_cbranch_vccnz .LBB0_143
.LBB0_149:
	s_waitcnt lgkmcnt(0)
	v_add_f32_e32 v6, v44, v6
	v_fmamk_f32 v6, v6, 0x3a800000, v206
	v_mul_f32_e32 v7, 0x4f800000, v6
	v_cmp_gt_f32_e32 vcc, s57, v6
	s_nop 1
	v_cndmask_b32_e32 v6, v6, v7, vcc
	v_sqrt_f32_e32 v7, v6
	s_nop 0
	v_add_u32_e32 v8, -1, v7
	v_fma_f32 v10, -v8, v7, v6
	v_add_u32_e32 v9, 1, v7
	v_cmp_ge_f32_e64 s[0:1], 0, v10
	s_nop 1
	v_cndmask_b32_e64 v8, v7, v8, s[0:1]
	v_fma_f32 v7, -v9, v7, v6
	v_cmp_lt_f32_e64 s[0:1], 0, v7
	s_nop 1
	v_cndmask_b32_e64 v7, v8, v9, s[0:1]
	v_mul_f32_e32 v8, 0x37800000, v7
	v_cndmask_b32_e32 v7, v7, v8, vcc
	v_cmp_class_f32_e32 vcc, v6, v207
	s_nop 1
	v_cndmask_b32_e32 v6, v7, v6, vcc
	v_div_scale_f32 v7, s[0:1], v6, v6, 1.0
	v_rcp_f32_e32 v8, v7
	s_lshl_b64 s[0:1], s[14:15], 11
	v_fma_f32 v9, -v7, v8, 1.0
	v_fmac_f32_e32 v8, v9, v8
	v_div_scale_f32 v9, vcc, 1.0, v6, 1.0
	v_mul_f32_e32 v10, v9, v8
	v_fma_f32 v11, -v7, v10, v9
	v_fmac_f32_e32 v10, v11, v8
	v_fma_f32 v7, -v7, v10, v9
	v_div_fmas_f32 v7, v7, v8, v10
	v_div_fixup_f32 v6, v7, v6, 1.0
	v_mov_b32_e32 v8, v68
	v_mov_b32_e32 v9, v70
	v_pk_mul_f32 v[8:9], v[8:9], v[6:7] op_sel_hi:[1,0]
	v_mov_b32_e32 v70, v69
	v_pk_fma_f32 v[8:9], v[108:109], v[8:9], v[78:79]
	v_pk_mul_f32 v[10:11], v[70:71], v[6:7] op_sel_hi:[1,0]
	v_and_b32_sdwa v7, v9, v209 dst_sel:DWORD dst_unused:UNUSED_PAD src0_sel:WORD_1 src1_sel:DWORD
	v_pk_fma_f32 v[10:11], v[84:85], v[10:11], v[22:23]
	v_and_b32_sdwa v12, v8, v209 dst_sel:DWORD dst_unused:UNUSED_PAD src0_sel:WORD_1 src1_sel:DWORD
	v_add3_u32 v8, v8, v12, s77
	v_add3_u32 v7, v9, v7, s77
	v_and_b32_sdwa v9, v11, v209 dst_sel:DWORD dst_unused:UNUSED_PAD src0_sel:WORD_1 src1_sel:DWORD
	v_and_b32_sdwa v12, v10, v209 dst_sel:DWORD dst_unused:UNUSED_PAD src0_sel:WORD_1 src1_sel:DWORD
	v_add3_u32 v9, v11, v9, s77
	v_add3_u32 v10, v10, v12, s77
	v_and_b32_e32 v9, 0xffff0000, v9
	v_and_b32_e32 v10, 0xffff0000, v10
	v_or_b32_sdwa v9, v9, v7 dst_sel:DWORD dst_unused:UNUSED_PAD src0_sel:DWORD src1_sel:WORD_1
	v_or_b32_sdwa v8, v10, v8 dst_sel:DWORD dst_unused:UNUSED_PAD src0_sel:DWORD src1_sel:WORD_1
	v_lshl_add_u64 v[10:11], v[94:95], 0, s[0:1]
	global_store_dwordx2 v[10:11], v[8:9], off
	v_mov_b32_e32 v8, v60
	v_mov_b32_e32 v9, v62
	v_pk_mul_f32 v[8:9], v[8:9], v[6:7] op_sel_hi:[1,0]
	v_mov_b32_e32 v62, v61
	v_pk_fma_f32 v[8:9], v[86:87], v[8:9], v[20:21]
	v_pk_mul_f32 v[12:13], v[62:63], v[6:7] op_sel_hi:[1,0]
	v_and_b32_sdwa v7, v9, v209 dst_sel:DWORD dst_unused:UNUSED_PAD src0_sel:WORD_1 src1_sel:DWORD
	v_pk_fma_f32 v[2:3], v[82:83], v[12:13], v[2:3]
	v_and_b32_sdwa v12, v8, v209 dst_sel:DWORD dst_unused:UNUSED_PAD src0_sel:WORD_1 src1_sel:DWORD
	v_add3_u32 v8, v8, v12, s77
	v_add3_u32 v7, v9, v7, s77
	v_and_b32_sdwa v9, v3, v209 dst_sel:DWORD dst_unused:UNUSED_PAD src0_sel:WORD_1 src1_sel:DWORD
	v_and_b32_sdwa v12, v2, v209 dst_sel:DWORD dst_unused:UNUSED_PAD src0_sel:WORD_1 src1_sel:DWORD
	v_add3_u32 v3, v3, v9, s77
	v_add3_u32 v2, v2, v12, s77
	v_and_b32_e32 v3, 0xffff0000, v3
	v_and_b32_e32 v2, 0xffff0000, v2
	v_or_b32_sdwa v3, v3, v7 dst_sel:DWORD dst_unused:UNUSED_PAD src0_sel:DWORD src1_sel:WORD_1
	v_or_b32_sdwa v2, v2, v8 dst_sel:DWORD dst_unused:UNUSED_PAD src0_sel:DWORD src1_sel:WORD_1
	global_store_dwordx2 v[10:11], v[2:3], off offset:512
	v_mov_b32_e32 v2, v72
	v_mov_b32_e32 v3, v74
	v_pk_mul_f32 v[2:3], v[2:3], v[6:7] op_sel_hi:[1,0]
	v_mov_b32_e32 v74, v73
	v_pk_fma_f32 v[0:1], v[80:81], v[2:3], v[0:1]
	v_pk_mul_f32 v[2:3], v[74:75], v[6:7] op_sel_hi:[1,0]
	v_and_b32_sdwa v7, v1, v209 dst_sel:DWORD dst_unused:UNUSED_PAD src0_sel:WORD_1 src1_sel:DWORD
	v_pk_fma_f32 v[2:3], v[110:111], v[2:3], v[66:67]
	v_and_b32_sdwa v8, v0, v209 dst_sel:DWORD dst_unused:UNUSED_PAD src0_sel:WORD_1 src1_sel:DWORD
	v_add3_u32 v0, v0, v8, s77
	v_add3_u32 v1, v1, v7, s77
	v_and_b32_sdwa v7, v3, v209 dst_sel:DWORD dst_unused:UNUSED_PAD src0_sel:WORD_1 src1_sel:DWORD
	v_and_b32_sdwa v8, v2, v209 dst_sel:DWORD dst_unused:UNUSED_PAD src0_sel:WORD_1 src1_sel:DWORD
	v_add3_u32 v3, v3, v7, s77
	v_add3_u32 v2, v2, v8, s77
	v_and_b32_e32 v3, 0xffff0000, v3
	v_and_b32_e32 v2, 0xffff0000, v2
	v_or_b32_sdwa v1, v3, v1 dst_sel:DWORD dst_unused:UNUSED_PAD src0_sel:DWORD src1_sel:WORD_1
	v_or_b32_sdwa v0, v2, v0 dst_sel:DWORD dst_unused:UNUSED_PAD src0_sel:DWORD src1_sel:WORD_1
	global_store_dwordx2 v[10:11], v[0:1], off offset:1024
	v_mov_b32_e32 v0, v56
	v_mov_b32_e32 v1, v58
	v_pk_mul_f32 v[0:1], v[0:1], v[6:7] op_sel_hi:[1,0]
	v_mov_b32_e32 v58, v57
	v_pk_fma_f32 v[0:1], v[106:107], v[0:1], v[4:5]
	v_pk_mul_f32 v[2:3], v[58:59], v[6:7] op_sel_hi:[1,0]
	v_and_b32_sdwa v4, v1, v209 dst_sel:DWORD dst_unused:UNUSED_PAD src0_sel:WORD_1 src1_sel:DWORD
	v_pk_fma_f32 v[2:3], v[76:77], v[2:3], v[34:35]
	v_and_b32_sdwa v5, v0, v209 dst_sel:DWORD dst_unused:UNUSED_PAD src0_sel:WORD_1 src1_sel:DWORD
	v_add3_u32 v0, v0, v5, s77
	v_add3_u32 v1, v1, v4, s77
	v_and_b32_sdwa v4, v3, v209 dst_sel:DWORD dst_unused:UNUSED_PAD src0_sel:WORD_1 src1_sel:DWORD
	v_and_b32_sdwa v5, v2, v209 dst_sel:DWORD dst_unused:UNUSED_PAD src0_sel:WORD_1 src1_sel:DWORD
	v_add3_u32 v3, v3, v4, s77
	v_add3_u32 v2, v2, v5, s77
	v_and_b32_e32 v3, 0xffff0000, v3
	v_and_b32_e32 v2, 0xffff0000, v2
	v_or_b32_sdwa v1, v3, v1 dst_sel:DWORD dst_unused:UNUSED_PAD src0_sel:DWORD src1_sel:WORD_1
	v_or_b32_sdwa v0, v2, v0 dst_sel:DWORD dst_unused:UNUSED_PAD src0_sel:DWORD src1_sel:WORD_1
	global_store_dwordx2 v[10:11], v[0:1], off offset:1536
	s_branch .LBB0_143

.LBB0_152:
	s_waitcnt vmcnt(0) lgkmcnt(0)
	v_pk_mul_f32 v[50:51], v[14:15], v[14:15]
	v_pk_mul_f32 v[52:53], v[12:13], v[12:13]
	v_mov_b32_e32 v16, v1
	v_pk_mov_b32 v[54:55], v[52:53], v[50:51] op_sel:[1,0]
	v_mov_b32_e32 v53, v51
	v_mov_b32_e32 v1, v2
	v_mov_b32_e32 v17, v3
	v_pk_mul_f32 v[2:3], v[10:11], v[10:11]
	v_pk_mul_f32 v[18:19], v[8:9], v[8:9]
	v_pk_add_f32 v[50:51], v[54:55], v[52:53]
	flat_load_dwordx4 v[54:57], v[22:23]
	v_pk_add_f32 v[72:73], v[50:51], v[50:51] op_sel_hi:[0,1]
	v_pk_mov_b32 v[50:51], v[18:19], v[2:3] op_sel:[1,0]
	v_mov_b32_e32 v19, v3
	v_pk_add_f32 v[2:3], v[50:51], v[18:19]
	global_load_dwordx4 v[50:53], v[20:21], off
	v_pk_add_f32 v[2:3], v[2:3], v[2:3] op_sel_hi:[0,1]
	v_mul_f32_e32 v2, v4, v4
	v_pk_fma_f32 v[18:19], v[4:5], v[4:5], v[2:3] op_sel_hi:[1,1,0]
	v_mul_f32_e32 v2, v6, v6
	v_pk_fma_f32 v[58:59], v[6:7], v[6:7], v[2:3] op_sel_hi:[1,1,0]
	v_mul_f32_e32 v18, v0, v0
	v_mul_f32_e32 v58, v16, v16
	v_pk_add_f32 v[18:19], v[18:19], v[58:59]
	flat_load_dwordx4 v[58:61], v[24:25]
	global_load_dwordx4 v[104:107], v[20:21], off offset:1024
	flat_load_dwordx4 v[108:111], v[26:27]
	flat_load_dwordx4 v[112:115], v[28:29]
	global_load_dwordx4 v[116:119], v[20:21], off offset:2048
	flat_load_dwordx4 v[120:123], v[30:31]
	flat_load_dwordx4 v[124:127], v[32:33]
	global_load_dwordx4 v[128:131], v[20:21], off offset:3072
	flat_load_dwordx4 v[132:135], v[34:35]
	flat_load_dwordx4 v[136:139], v[36:37]
	v_mul_f32_e32 v72, v1, v1
	v_mul_f32_e32 v2, v17, v17
	v_pk_add_f32 v[2:3], v[72:73], v[2:3]
	s_add_i32 s4, s4, s70
	v_pk_add_f32 v[2:3], v[18:19], v[2:3]
	s_waitcnt vmcnt(0) lgkmcnt(0)
	v_mov_b32_e32 v73, v56
	v_add_f32_e32 v2, v2, v3
	ds_bpermute_b32 v3, v62, v2
	v_mov_b32_e32 v56, v55
	s_waitcnt lgkmcnt(0)
	v_add_f32_e32 v2, v2, v3
	ds_bpermute_b32 v3, v63, v2
	s_waitcnt lgkmcnt(0)
	v_add_f32_e32 v2, v2, v3
	ds_bpermute_b32 v3, v64, v2
	v_mov_b32_e32 v74, v58
	v_mov_b32_e32 v75, v60
	v_mov_b32_e32 v60, v59
	s_waitcnt lgkmcnt(0)
	v_add_f32_e32 v2, v2, v3
	ds_bpermute_b32 v3, v65, v2
	s_waitcnt lgkmcnt(0)
	v_add_f32_e32 v2, v2, v3
	ds_bpermute_b32 v3, v66, v2
	s_waitcnt lgkmcnt(0)
	v_add_f32_e32 v2, v2, v3
	ds_bpermute_b32 v3, v67, v2
	s_waitcnt lgkmcnt(0)
	v_add_f32_e32 v2, v2, v3
	v_fmamk_f32 v2, v2, 0x3a800000, v206
	v_mul_f32_e32 v3, 0x4f800000, v2
	v_cmp_gt_f32_e32 vcc, s57, v2
	s_nop 1
	v_cndmask_b32_e32 v18, v2, v3, vcc
	v_sqrt_f32_e32 v19, v18
	v_mov_b32_e32 v2, v12
	v_mov_b32_e32 v3, v14
	v_add_u32_e32 v12, -1, v19
	v_add_u32_e32 v14, 1, v19
	v_fma_f32 v71, -v12, v19, v18
	v_fma_f32 v72, -v14, v19, v18
	v_cmp_ge_f32_e64 s[0:1], 0, v71
	s_nop 1
	v_cndmask_b32_e64 v12, v19, v12, s[0:1]
	v_cmp_lt_f32_e64 s[0:1], 0, v72
	s_nop 1
	v_cndmask_b32_e64 v12, v12, v14, s[0:1]
	v_mul_f32_e32 v14, 0x37800000, v12
	v_cndmask_b32_e32 v12, v12, v14, vcc
	v_cmp_class_f32_e32 vcc, v18, v207
	v_mov_b32_e32 v14, v13
	s_nop 0
	v_cndmask_b32_e32 v12, v12, v18, vcc
	v_div_scale_f32 v18, s[0:1], v12, v12, 1.0
	v_rcp_f32_e32 v19, v18
	v_div_scale_f32 v13, vcc, 1.0, v12, 1.0
	s_add_i32 s0, s4, 0x4000
	v_fma_f32 v71, -v18, v19, 1.0
	v_fmac_f32_e32 v19, v71, v19
	v_mul_f32_e32 v71, v13, v19
	v_fma_f32 v72, -v18, v71, v13
	v_fmac_f32_e32 v71, v72, v19
	v_fma_f32 v13, -v18, v71, v13
	v_div_fmas_f32 v13, v13, v19, v71
	v_div_fixup_f32 v18, v13, v12, 1.0
	v_pk_mul_f32 v[2:3], v[2:3], v[18:19] op_sel_hi:[1,0]
	v_mov_b32_e32 v12, v50
	v_mov_b32_e32 v13, v52
	v_mov_b32_e32 v72, v54
	v_pk_mul_f32 v[2:3], v[12:13], v[2:3]
	v_pk_add_f32 v[12:13], v[72:73], 1.0 op_sel_hi:[1,0]
	v_mov_b32_e32 v52, v51
	v_pk_fma_f32 v[2:3], v[12:13], v[2:3], v[74:75]
	v_pk_mul_f32 v[12:13], v[14:15], v[18:19] op_sel_hi:[1,0]
	v_pk_add_f32 v[14:15], v[56:57], 1.0 op_sel_hi:[1,0]
	v_pk_mul_f32 v[12:13], v[52:53], v[12:13]
	v_pk_mul_f32 v[0:1], v[0:1], v[18:19] op_sel_hi:[1,0]
	v_pk_fma_f32 v[12:13], v[14:15], v[12:13], v[60:61]
	v_and_b32_sdwa v14, v3, v209 dst_sel:DWORD dst_unused:UNUSED_PAD src0_sel:WORD_1 src1_sel:DWORD
	v_and_b32_sdwa v15, v2, v209 dst_sel:DWORD dst_unused:UNUSED_PAD src0_sel:WORD_1 src1_sel:DWORD
	v_add3_u32 v2, v2, v15, s77
	v_add3_u32 v3, v3, v14, s77
	v_and_b32_sdwa v14, v13, v209 dst_sel:DWORD dst_unused:UNUSED_PAD src0_sel:WORD_1 src1_sel:DWORD
	v_and_b32_sdwa v15, v12, v209 dst_sel:DWORD dst_unused:UNUSED_PAD src0_sel:WORD_1 src1_sel:DWORD
	v_add3_u32 v13, v13, v14, s77
	v_add3_u32 v12, v12, v15, s77
	v_and_b32_e32 v13, 0xffff0000, v13
	v_and_b32_e32 v12, 0xffff0000, v12
	v_or_b32_sdwa v3, v13, v3 dst_sel:DWORD dst_unused:UNUSED_PAD src0_sel:DWORD src1_sel:WORD_1
	v_or_b32_sdwa v2, v12, v2 dst_sel:DWORD dst_unused:UNUSED_PAD src0_sel:DWORD src1_sel:WORD_1
	global_store_dwordx2 v[48:49], v[2:3], off
	v_mov_b32_e32 v3, v10
	v_mov_b32_e32 v10, v9
	v_mov_b32_e32 v2, v8
	v_pk_mul_f32 v[8:9], v[10:11], v[18:19] op_sel_hi:[1,0]
	v_pk_mul_f32 v[2:3], v[2:3], v[18:19] op_sel_hi:[1,0]
	s_cmpk_lt_i32 s0, 0x4200
	v_mov_b32_e32 v12, v104
	v_mov_b32_e32 v13, v105
	v_mov_b32_e32 v14, v106
	v_mov_b32_e32 v15, v107
	v_mov_b32_e32 v50, v108
	v_mov_b32_e32 v51, v109
	v_mov_b32_e32 v52, v110
	v_mov_b32_e32 v53, v111
	v_mov_b32_e32 v54, v112
	v_mov_b32_e32 v55, v113
	v_mov_b32_e32 v56, v114
	v_mov_b32_e32 v57, v115
	v_mov_b32_e32 v11, v14
	s_waitcnt lgkmcnt(0)
	v_mov_b32_e32 v59, v52
	v_mov_b32_e32 v14, v13
	v_mov_b32_e32 v52, v51
	v_mov_b32_e32 v10, v12
	v_mov_b32_e32 v58, v50
	v_mov_b32_e32 v61, v56
	v_mov_b32_e32 v56, v55
	v_pk_mul_f32 v[8:9], v[14:15], v[8:9]
	v_pk_add_f32 v[12:13], v[52:53], 1.0 op_sel_hi:[1,0]
	v_mov_b32_e32 v60, v54
	v_pk_mul_f32 v[2:3], v[10:11], v[2:3]
	v_pk_add_f32 v[10:11], v[58:59], 1.0 op_sel_hi:[1,0]
	v_pk_fma_f32 v[8:9], v[12:13], v[8:9], v[56:57]
	v_pk_fma_f32 v[2:3], v[10:11], v[2:3], v[60:61]
	v_and_b32_sdwa v12, v9, v209 dst_sel:DWORD dst_unused:UNUSED_PAD src0_sel:WORD_1 src1_sel:DWORD
	v_and_b32_sdwa v13, v8, v209 dst_sel:DWORD dst_unused:UNUSED_PAD src0_sel:WORD_1 src1_sel:DWORD
	v_and_b32_sdwa v10, v3, v209 dst_sel:DWORD dst_unused:UNUSED_PAD src0_sel:WORD_1 src1_sel:DWORD
	v_and_b32_sdwa v11, v2, v209 dst_sel:DWORD dst_unused:UNUSED_PAD src0_sel:WORD_1 src1_sel:DWORD
	v_add3_u32 v9, v9, v12, s77
	v_add3_u32 v8, v8, v13, s77
	v_add3_u32 v2, v2, v11, s77
	v_add3_u32 v3, v3, v10, s77
	v_and_b32_e32 v9, 0xffff0000, v9
	v_and_b32_e32 v8, 0xffff0000, v8
	v_or_b32_sdwa v3, v9, v3 dst_sel:DWORD dst_unused:UNUSED_PAD src0_sel:DWORD src1_sel:WORD_1
	v_or_b32_sdwa v2, v8, v2 dst_sel:DWORD dst_unused:UNUSED_PAD src0_sel:DWORD src1_sel:WORD_1
	global_store_dwordx2 v[48:49], v[2:3], off offset:512
	v_mov_b32_e32 v3, v6
	v_mov_b32_e32 v6, v5
	v_mov_b32_e32 v2, v4
	v_pk_mul_f32 v[4:5], v[6:7], v[18:19] op_sel_hi:[1,0]
	v_pk_mul_f32 v[2:3], v[2:3], v[18:19] op_sel_hi:[1,0]
	v_mov_b32_e32 v8, v116
	v_mov_b32_e32 v9, v117
	v_mov_b32_e32 v10, v118
	v_mov_b32_e32 v11, v119
	v_mov_b32_e32 v12, v120
	v_mov_b32_e32 v13, v121
	v_mov_b32_e32 v14, v122
	v_mov_b32_e32 v15, v123
	v_mov_b32_e32 v50, v124
	v_mov_b32_e32 v51, v125
	v_mov_b32_e32 v52, v126
	v_mov_b32_e32 v53, v127
	v_mov_b32_e32 v7, v10
	s_waitcnt lgkmcnt(0)
	v_mov_b32_e32 v55, v14
	v_mov_b32_e32 v10, v9
	v_mov_b32_e32 v14, v13
	v_mov_b32_e32 v6, v8
	v_mov_b32_e32 v54, v12
	v_mov_b32_e32 v57, v52
	v_mov_b32_e32 v52, v51
	v_pk_mul_f32 v[4:5], v[10:11], v[4:5]
	v_pk_add_f32 v[8:9], v[14:15], 1.0 op_sel_hi:[1,0]
	v_mov_b32_e32 v56, v50
	v_pk_mul_f32 v[2:3], v[6:7], v[2:3]
	v_pk_add_f32 v[6:7], v[54:55], 1.0 op_sel_hi:[1,0]
	v_pk_fma_f32 v[4:5], v[8:9], v[4:5], v[52:53]
	v_pk_fma_f32 v[2:3], v[6:7], v[2:3], v[56:57]
	v_and_b32_sdwa v8, v5, v209 dst_sel:DWORD dst_unused:UNUSED_PAD src0_sel:WORD_1 src1_sel:DWORD
	v_and_b32_sdwa v9, v4, v209 dst_sel:DWORD dst_unused:UNUSED_PAD src0_sel:WORD_1 src1_sel:DWORD
	v_and_b32_sdwa v6, v3, v209 dst_sel:DWORD dst_unused:UNUSED_PAD src0_sel:WORD_1 src1_sel:DWORD
	v_and_b32_sdwa v7, v2, v209 dst_sel:DWORD dst_unused:UNUSED_PAD src0_sel:WORD_1 src1_sel:DWORD
	v_add3_u32 v5, v5, v8, s77
	v_add3_u32 v4, v4, v9, s77
	v_add3_u32 v2, v2, v7, s77
	v_add3_u32 v3, v3, v6, s77
	v_and_b32_e32 v5, 0xffff0000, v5
	v_and_b32_e32 v4, 0xffff0000, v4
	v_or_b32_sdwa v3, v5, v3 dst_sel:DWORD dst_unused:UNUSED_PAD src0_sel:DWORD src1_sel:WORD_1
	v_or_b32_sdwa v2, v4, v2 dst_sel:DWORD dst_unused:UNUSED_PAD src0_sel:DWORD src1_sel:WORD_1
	global_store_dwordx2 v[48:49], v[2:3], off offset:1024
	s_nop 0
	v_pk_mul_f32 v[14:15], v[16:17], v[18:19] op_sel_hi:[1,0]
	v_mov_b32_e32 v2, v128
	v_mov_b32_e32 v3, v129
	v_mov_b32_e32 v4, v130
	v_mov_b32_e32 v5, v131
	v_mov_b32_e32 v6, v132
	v_mov_b32_e32 v7, v133
	v_mov_b32_e32 v8, v134
	v_mov_b32_e32 v9, v135
	v_mov_b32_e32 v10, v136
	v_mov_b32_e32 v11, v137
	v_mov_b32_e32 v12, v138
	v_mov_b32_e32 v13, v139
	v_mov_b32_e32 v16, v2
	v_mov_b32_e32 v17, v4
	s_waitcnt lgkmcnt(0)
	v_mov_b32_e32 v18, v6
	v_mov_b32_e32 v19, v8
	v_mov_b32_e32 v4, v3
	v_mov_b32_e32 v8, v7
	v_mov_b32_e32 v50, v10
	v_mov_b32_e32 v51, v12
	v_mov_b32_e32 v12, v11
	v_pk_mul_f32 v[0:1], v[0:1], v[16:17]
	v_pk_add_f32 v[2:3], v[18:19], 1.0 op_sel_hi:[1,0]
	v_pk_mul_f32 v[4:5], v[14:15], v[4:5]
	v_pk_add_f32 v[6:7], v[8:9], 1.0 op_sel_hi:[1,0]
	v_pk_fma_f32 v[0:1], v[0:1], v[2:3], v[50:51]
	v_pk_fma_f32 v[2:3], v[4:5], v[6:7], v[12:13]
	v_and_b32_sdwa v4, v1, v209 dst_sel:DWORD dst_unused:UNUSED_PAD src0_sel:WORD_1 src1_sel:DWORD
	v_and_b32_sdwa v6, v3, v209 dst_sel:DWORD dst_unused:UNUSED_PAD src0_sel:WORD_1 src1_sel:DWORD
	v_and_b32_sdwa v7, v2, v209 dst_sel:DWORD dst_unused:UNUSED_PAD src0_sel:WORD_1 src1_sel:DWORD
	v_and_b32_sdwa v5, v0, v209 dst_sel:DWORD dst_unused:UNUSED_PAD src0_sel:WORD_1 src1_sel:DWORD
	v_add3_u32 v3, v3, v6, s77
	v_add3_u32 v2, v2, v7, s77
	v_add3_u32 v0, v0, v5, s77
	v_add3_u32 v1, v1, v4, s77
	v_and_b32_e32 v3, 0xffff0000, v3
	v_and_b32_e32 v2, 0xffff0000, v2
	v_or_b32_sdwa v1, v3, v1 dst_sel:DWORD dst_unused:UNUSED_PAD src0_sel:DWORD src1_sel:WORD_1
	v_or_b32_sdwa v0, v2, v0 dst_sel:DWORD dst_unused:UNUSED_PAD src0_sel:DWORD src1_sel:WORD_1
	global_store_dwordx2 v[48:49], v[0:1], off offset:1536
	v_lshl_add_u64 v[48:49], v[48:49], 0, s[58:59]
	s_cbranch_scc0 .LBB0_157

.LBB0_237:
	v_lshl_add_u32 v130, s6, 8, v150
	v_mov_b64_e32 v[128:129], s[8:9]
	v_mad_i64_i32 v[128:129], s[0:1], v130, s88, v[128:129]
	v_cvt_pk_bf16_f32 v120, v120, v121
	v_cvt_pk_bf16_f32 v121, v122, v123
	v_cvt_pk_bf16_f32 v122, v124, v125
	v_cndmask_b32_e64 v124, 0, 1, s[24:25]
	v_lshl_add_u64 v[128:129], v[148:149], 1, v[128:129]
	v_cmp_ne_u32_e64 s[6:7], 1, v124
	s_andn2_b64 vcc, exec, s[24:25]
	v_cvt_pk_bf16_f32 v123, v126, v127
	global_store_dwordx4 v[128:129], v[120:123], off
	s_cbranch_vccnz .LBB0_239
	global_load_dwordx4 v[120:123], v[146:147], off offset:-1520
	global_load_dwordx4 v[124:127], v[146:147], off offset:-1536
	s_waitcnt vmcnt(0)
	v_add_f32_e32 v120, v116, v120
	v_add_f32_e32 v124, v112, v124
	v_mul_f32_e64 v116, |v124|, s84
	v_exp_f32_e32 v116, v116
	v_min_f32_e32 v112, 0, v124
	v_add_f32_e32 v125, v113, v125
	v_add_f32_e32 v121, v117, v121
	v_add_f32_e32 v116, 1.0, v116
	v_mul_f32_e64 v117, |v125|, s84
	v_exp_f32_e32 v117, v117
	v_log_f32_e32 v116, v116
	v_add_f32_e32 v117, 1.0, v117
	v_min_f32_e32 v113, 0, v125
	v_add_f32_e32 v126, v114, v126
	v_mul_f32_e32 v124, 0x3f317217, v116
	v_fma_f32 v124, v116, s86, -v124
	v_fmac_f32_e32 v124, 0x3377d1cf, v116
	v_fmac_f32_e32 v124, 0x3f317217, v116
	v_min_f32_e32 v114, 0, v126
	v_add_f32_e32 v127, v115, v127
	v_mov_b32_e32 v116, v124
	v_min_f32_e32 v116, 0, v120
	v_mul_f32_e64 v120, |v120|, s84
	v_exp_f32_e32 v120, v120
	v_min_f32_e32 v115, 0, v127
	v_add_f32_e32 v120, 1.0, v120
	v_log_f32_e32 v120, v120
	s_nop 0
	v_mul_f32_e32 v131, 0x3f317217, v120
	v_fma_f32 v131, v120, s86, -v131
	v_fmac_f32_e32 v131, 0x3377d1cf, v120
	v_fmac_f32_e32 v131, 0x3f317217, v120
	v_mov_b32_e32 v120, v131
	v_log_f32_e32 v117, v117
	s_nop 0
	v_mul_f32_e32 v125, 0x3f317217, v117
	v_fma_f32 v125, v117, s86, -v125
	v_fmac_f32_e32 v125, 0x3377d1cf, v117
	v_fmac_f32_e32 v125, 0x3f317217, v117
	v_mov_b32_e32 v117, v125
	v_min_f32_e32 v117, 0, v121
	v_mul_f32_e64 v121, |v121|, s84
	v_exp_f32_e32 v121, v121
	v_pk_add_f32 v[112:113], v[112:113], v[124:125] neg_lo:[0,1] neg_hi:[0,1]
	v_add_f32_e32 v121, 1.0, v121
	v_pk_mul_f32 v[112:113], v[112:113], s[76:77] op_sel_hi:[1,0]
	v_log_f32_e32 v121, v121
	s_nop 0
	v_mul_f32_e32 v131, 0x3f317217, v121
	v_fma_f32 v131, v121, s86, -v131
	v_fmac_f32_e32 v131, 0x3377d1cf, v121
	v_fmac_f32_e32 v131, 0x3f317217, v121
	v_mov_b32_e32 v121, v131
	v_add_f32_e32 v131, v118, v122
	v_mul_f32_e64 v118, |v126|, s84
	v_exp_f32_e32 v118, v118
	v_mul_f32_e64 v126, |v131|, s84
	v_exp_f32_e32 v126, v126
	v_pk_add_f32 v[116:117], v[116:117], v[120:121] neg_lo:[0,1] neg_hi:[0,1]
	v_add_f32_e32 v118, 1.0, v118
	v_add_f32_e32 v126, 1.0, v126
	v_pk_mul_f32 v[116:117], v[116:117], s[76:77] op_sel_hi:[1,0]
	v_log_f32_e32 v118, v118
	s_nop 0
	v_mul_f32_e32 v122, 0x3f317217, v118
	v_fma_f32 v122, v118, s86, -v122
	v_fmac_f32_e32 v122, 0x3377d1cf, v118
	v_fmac_f32_e32 v122, 0x3f317217, v118
	v_mov_b32_e32 v118, v122
	v_min_f32_e32 v118, 0, v131
	v_log_f32_e32 v126, v126
	s_nop 0
	v_mul_f32_e32 v131, 0x3f317217, v126
	v_fma_f32 v131, v126, s86, -v131
	v_fmac_f32_e32 v131, 0x3377d1cf, v126
	v_fmac_f32_e32 v131, 0x3f317217, v126
	v_mov_b32_e32 v126, v131
	v_add_f32_e32 v131, v119, v123
	v_mul_f32_e64 v119, |v127|, s84
	v_exp_f32_e32 v119, v119
	s_nop 0
	v_add_f32_e32 v119, 1.0, v119
	v_log_f32_e32 v119, v119
	s_nop 0
	v_mul_f32_e32 v123, 0x3f317217, v119
	v_fma_f32 v123, v119, s86, -v123
	v_fmac_f32_e32 v123, 0x3377d1cf, v119
	v_fmac_f32_e32 v123, 0x3f317217, v119
	v_mov_b32_e32 v119, v123
	v_pk_add_f32 v[114:115], v[114:115], v[122:123] neg_lo:[0,1] neg_hi:[0,1]
	v_mul_f32_e64 v122, |v131|, s84
	v_exp_f32_e32 v122, v122
	v_min_f32_e32 v119, 0, v131
	v_pk_mul_f32 v[114:115], v[114:115], s[76:77] op_sel_hi:[1,0]
	v_add_f32_e32 v122, 1.0, v122
	v_log_f32_e32 v122, v122
	s_nop 0
	v_mul_f32_e32 v123, 0x3f317217, v122
	v_fma_f32 v123, v122, s86, -v123
	v_fmac_f32_e32 v123, 0x3377d1cf, v122
	v_fmac_f32_e32 v123, 0x3f317217, v122
	v_mov_b32_e32 v122, v123
	v_mov_b32_e32 v127, v122
	v_pk_add_f32 v[118:119], v[118:119], v[126:127] neg_lo:[0,1] neg_hi:[0,1]
	v_pk_mul_f32 v[118:119], v[118:119], s[76:77] op_sel_hi:[1,0]
.LBB0_239:
	s_and_b64 vcc, exec, s[6:7]
	v_cvt_pk_bf16_f32 v112, v112, v113
	v_cvt_pk_bf16_f32 v113, v114, v115
	v_cvt_pk_bf16_f32 v114, v116, v117
	v_cvt_pk_bf16_f32 v115, v118, v119
	global_store_dwordx4 v[128:129], v[112:115], off offset:256
	s_cbranch_vccnz .LBB0_241
	global_load_dwordx4 v[112:115], v[146:147], off offset:-2032
	global_load_dwordx4 v[116:119], v[146:147], off offset:-2048
	s_waitcnt vmcnt(0)
	v_add_f32_e32 v112, v108, v112
	v_add_f32_e32 v116, v104, v116
	v_mul_f32_e64 v108, |v116|, s84
	v_exp_f32_e32 v108, v108
	v_min_f32_e32 v104, 0, v116
	v_add_f32_e32 v117, v105, v117
	v_add_f32_e32 v113, v109, v113
	v_add_f32_e32 v108, 1.0, v108
	v_mul_f32_e64 v109, |v117|, s84
	v_exp_f32_e32 v109, v109
	v_log_f32_e32 v108, v108
	v_add_f32_e32 v109, 1.0, v109
	v_min_f32_e32 v105, 0, v117
	v_add_f32_e32 v118, v106, v118
	v_mul_f32_e32 v116, 0x3f317217, v108
	v_fma_f32 v116, v108, s86, -v116
	v_fmac_f32_e32 v116, 0x3377d1cf, v108
	v_fmac_f32_e32 v116, 0x3f317217, v108
	v_min_f32_e32 v106, 0, v118
	v_add_f32_e32 v119, v107, v119
	v_mov_b32_e32 v108, v116
	v_min_f32_e32 v108, 0, v112
	v_mul_f32_e64 v112, |v112|, s84
	v_exp_f32_e32 v112, v112
	v_min_f32_e32 v107, 0, v119
	v_add_f32_e32 v112, 1.0, v112
	v_log_f32_e32 v112, v112
	s_nop 0
	v_mul_f32_e32 v120, 0x3f317217, v112
	v_fma_f32 v120, v112, s86, -v120
	v_fmac_f32_e32 v120, 0x3377d1cf, v112
	v_fmac_f32_e32 v120, 0x3f317217, v112
	v_mov_b32_e32 v112, v120
	v_log_f32_e32 v109, v109
	s_nop 0
	v_mul_f32_e32 v117, 0x3f317217, v109
	v_fma_f32 v117, v109, s86, -v117
	v_fmac_f32_e32 v117, 0x3377d1cf, v109
	v_fmac_f32_e32 v117, 0x3f317217, v109
	v_mov_b32_e32 v109, v117
	v_min_f32_e32 v109, 0, v113
	v_mul_f32_e64 v113, |v113|, s84
	v_exp_f32_e32 v113, v113
	v_pk_add_f32 v[104:105], v[104:105], v[116:117] neg_lo:[0,1] neg_hi:[0,1]
	v_add_f32_e32 v113, 1.0, v113
	v_pk_mul_f32 v[104:105], v[104:105], s[76:77] op_sel_hi:[1,0]
	v_log_f32_e32 v113, v113
	s_nop 0
	v_mul_f32_e32 v120, 0x3f317217, v113
	v_fma_f32 v120, v113, s86, -v120
	v_fmac_f32_e32 v120, 0x3377d1cf, v113
	v_fmac_f32_e32 v120, 0x3f317217, v113
	v_mov_b32_e32 v113, v120
	v_add_f32_e32 v120, v110, v114
	v_mul_f32_e64 v110, |v118|, s84
	v_exp_f32_e32 v110, v110
	v_mul_f32_e64 v118, |v120|, s84
	v_exp_f32_e32 v118, v118
	v_pk_add_f32 v[108:109], v[108:109], v[112:113] neg_lo:[0,1] neg_hi:[0,1]
	v_add_f32_e32 v110, 1.0, v110
	v_add_f32_e32 v118, 1.0, v118
	v_pk_mul_f32 v[108:109], v[108:109], s[76:77] op_sel_hi:[1,0]
	v_log_f32_e32 v110, v110
	s_nop 0
	v_mul_f32_e32 v114, 0x3f317217, v110
	v_fma_f32 v114, v110, s86, -v114
	v_fmac_f32_e32 v114, 0x3377d1cf, v110
	v_fmac_f32_e32 v114, 0x3f317217, v110
	v_mov_b32_e32 v110, v114
	v_min_f32_e32 v110, 0, v120
	v_log_f32_e32 v118, v118
	s_nop 0
	v_mul_f32_e32 v120, 0x3f317217, v118
	v_fma_f32 v120, v118, s86, -v120
	v_fmac_f32_e32 v120, 0x3377d1cf, v118
	v_fmac_f32_e32 v120, 0x3f317217, v118
	v_mov_b32_e32 v118, v120
	v_add_f32_e32 v120, v111, v115
	v_mul_f32_e64 v111, |v119|, s84
	v_exp_f32_e32 v111, v111
	s_nop 0
	v_add_f32_e32 v111, 1.0, v111
	v_log_f32_e32 v111, v111
	s_nop 0
	v_mul_f32_e32 v115, 0x3f317217, v111
	v_fma_f32 v115, v111, s86, -v115
	v_fmac_f32_e32 v115, 0x3377d1cf, v111
	v_fmac_f32_e32 v115, 0x3f317217, v111
	v_mov_b32_e32 v111, v115
	v_pk_add_f32 v[106:107], v[106:107], v[114:115] neg_lo:[0,1] neg_hi:[0,1]
	v_mul_f32_e64 v114, |v120|, s84
	v_exp_f32_e32 v114, v114
	v_min_f32_e32 v111, 0, v120
	v_pk_mul_f32 v[106:107], v[106:107], s[76:77] op_sel_hi:[1,0]
	v_add_f32_e32 v114, 1.0, v114
	v_log_f32_e32 v114, v114
	s_nop 0
	v_mul_f32_e32 v115, 0x3f317217, v114
	v_fma_f32 v115, v114, s86, -v115
	v_fmac_f32_e32 v115, 0x3377d1cf, v114
	v_fmac_f32_e32 v115, 0x3f317217, v114
	v_mov_b32_e32 v114, v115
	v_mov_b32_e32 v119, v114
	v_pk_add_f32 v[110:111], v[110:111], v[118:119] neg_lo:[0,1] neg_hi:[0,1]
	v_pk_mul_f32 v[110:111], v[110:111], s[76:77] op_sel_hi:[1,0]
.LBB0_241:
	s_nop 0
	v_or_b32_e32 v114, 16, v130
	v_mov_b64_e32 v[112:113], s[8:9]
	v_mad_i64_i32 v[112:113], s[0:1], v114, s88, v[112:113]
	v_lshl_add_u64 v[112:113], v[148:149], 1, v[112:113]
	s_and_b64 vcc, exec, s[6:7]
	v_cvt_pk_bf16_f32 v104, v104, v105
	v_cvt_pk_bf16_f32 v105, v106, v107
	v_cvt_pk_bf16_f32 v106, v108, v109
	v_cvt_pk_bf16_f32 v107, v110, v111
	global_store_dwordx4 v[112:113], v[104:107], off
	s_cbranch_vccnz .LBB0_243
	global_load_dwordx4 v[104:107], v[146:147], off offset:-1520
	global_load_dwordx4 v[108:111], v[146:147], off offset:-1536
	s_waitcnt vmcnt(0)
	v_add_f32_e32 v104, v100, v104
	v_add_f32_e32 v108, v96, v108
	v_mul_f32_e64 v100, |v108|, s84
	v_exp_f32_e32 v100, v100
	v_min_f32_e32 v96, 0, v108
	v_add_f32_e32 v109, v97, v109
	v_add_f32_e32 v105, v101, v105
	v_add_f32_e32 v100, 1.0, v100
	v_mul_f32_e64 v101, |v109|, s84
	v_exp_f32_e32 v101, v101
	v_log_f32_e32 v100, v100
	v_add_f32_e32 v101, 1.0, v101
	v_min_f32_e32 v97, 0, v109
	v_add_f32_e32 v110, v98, v110
	v_mul_f32_e32 v108, 0x3f317217, v100
	v_fma_f32 v108, v100, s86, -v108
	v_fmac_f32_e32 v108, 0x3377d1cf, v100
	v_fmac_f32_e32 v108, 0x3f317217, v100
	v_min_f32_e32 v98, 0, v110
	v_add_f32_e32 v111, v99, v111
	v_mov_b32_e32 v100, v108
	v_min_f32_e32 v100, 0, v104
	v_mul_f32_e64 v104, |v104|, s84
	v_exp_f32_e32 v104, v104
	v_min_f32_e32 v99, 0, v111
	v_add_f32_e32 v104, 1.0, v104
	v_log_f32_e32 v104, v104
	s_nop 0
	v_mul_f32_e32 v114, 0x3f317217, v104
	v_fma_f32 v114, v104, s86, -v114
	v_fmac_f32_e32 v114, 0x3377d1cf, v104
	v_fmac_f32_e32 v114, 0x3f317217, v104
	v_mov_b32_e32 v104, v114
	v_log_f32_e32 v101, v101
	s_nop 0
	v_mul_f32_e32 v109, 0x3f317217, v101
	v_fma_f32 v109, v101, s86, -v109
	v_fmac_f32_e32 v109, 0x3377d1cf, v101
	v_fmac_f32_e32 v109, 0x3f317217, v101
	v_mov_b32_e32 v101, v109
	v_min_f32_e32 v101, 0, v105
	v_mul_f32_e64 v105, |v105|, s84
	v_exp_f32_e32 v105, v105
	v_pk_add_f32 v[96:97], v[96:97], v[108:109] neg_lo:[0,1] neg_hi:[0,1]
	v_add_f32_e32 v105, 1.0, v105
	v_pk_mul_f32 v[96:97], v[96:97], s[76:77] op_sel_hi:[1,0]
	v_log_f32_e32 v105, v105
	s_nop 0
	v_mul_f32_e32 v114, 0x3f317217, v105
	v_fma_f32 v114, v105, s86, -v114
	v_fmac_f32_e32 v114, 0x3377d1cf, v105
	v_fmac_f32_e32 v114, 0x3f317217, v105
	v_mov_b32_e32 v105, v114
	v_add_f32_e32 v114, v102, v106
	v_mul_f32_e64 v102, |v110|, s84
	v_exp_f32_e32 v102, v102
	v_mul_f32_e64 v110, |v114|, s84
	v_exp_f32_e32 v110, v110
	v_pk_add_f32 v[100:101], v[100:101], v[104:105] neg_lo:[0,1] neg_hi:[0,1]
	v_add_f32_e32 v102, 1.0, v102
	v_add_f32_e32 v110, 1.0, v110
	v_pk_mul_f32 v[100:101], v[100:101], s[76:77] op_sel_hi:[1,0]
	v_log_f32_e32 v102, v102
	s_nop 0
	v_mul_f32_e32 v106, 0x3f317217, v102
	v_fma_f32 v106, v102, s86, -v106
	v_fmac_f32_e32 v106, 0x3377d1cf, v102
	v_fmac_f32_e32 v106, 0x3f317217, v102
	v_mov_b32_e32 v102, v106
	v_min_f32_e32 v102, 0, v114
	v_log_f32_e32 v110, v110
	s_nop 0
	v_mul_f32_e32 v114, 0x3f317217, v110
	v_fma_f32 v114, v110, s86, -v114
	v_fmac_f32_e32 v114, 0x3377d1cf, v110
	v_fmac_f32_e32 v114, 0x3f317217, v110
	v_mov_b32_e32 v110, v114
	v_add_f32_e32 v114, v103, v107
	v_mul_f32_e64 v103, |v111|, s84
	v_exp_f32_e32 v103, v103
	s_nop 0
	v_add_f32_e32 v103, 1.0, v103
	v_log_f32_e32 v103, v103
	s_nop 0
	v_mul_f32_e32 v107, 0x3f317217, v103
	v_fma_f32 v107, v103, s86, -v107
	v_fmac_f32_e32 v107, 0x3377d1cf, v103
	v_fmac_f32_e32 v107, 0x3f317217, v103
	v_mov_b32_e32 v103, v107
	v_pk_add_f32 v[98:99], v[98:99], v[106:107] neg_lo:[0,1] neg_hi:[0,1]
	v_mul_f32_e64 v106, |v114|, s84
	v_exp_f32_e32 v106, v106
	v_min_f32_e32 v103, 0, v114
	v_pk_mul_f32 v[98:99], v[98:99], s[76:77] op_sel_hi:[1,0]
	v_add_f32_e32 v106, 1.0, v106
	v_log_f32_e32 v106, v106
	s_nop 0
	v_mul_f32_e32 v107, 0x3f317217, v106
	v_fma_f32 v107, v106, s86, -v107
	v_fmac_f32_e32 v107, 0x3377d1cf, v106
	v_fmac_f32_e32 v107, 0x3f317217, v106
	v_mov_b32_e32 v106, v107
	v_mov_b32_e32 v111, v106
	v_pk_add_f32 v[102:103], v[102:103], v[110:111] neg_lo:[0,1] neg_hi:[0,1]
	v_pk_mul_f32 v[102:103], v[102:103], s[76:77] op_sel_hi:[1,0]
.LBB0_243:
	s_and_b64 vcc, exec, s[6:7]
	v_cvt_pk_bf16_f32 v96, v96, v97
	v_cvt_pk_bf16_f32 v97, v98, v99
	v_cvt_pk_bf16_f32 v98, v100, v101
	v_cvt_pk_bf16_f32 v99, v102, v103
	global_store_dwordx4 v[112:113], v[96:99], off offset:256
	s_cbranch_vccnz .LBB0_245
	global_load_dwordx4 v[96:99], v[146:147], off offset:-2032
	global_load_dwordx4 v[100:103], v[146:147], off offset:-2048
	s_waitcnt vmcnt(0)
	v_add_f32_e32 v96, v92, v96
	v_add_f32_e32 v100, v88, v100
	v_mul_f32_e64 v92, |v100|, s84
	v_exp_f32_e32 v92, v92
	v_min_f32_e32 v88, 0, v100
	v_add_f32_e32 v101, v89, v101
	v_add_f32_e32 v97, v93, v97
	v_add_f32_e32 v92, 1.0, v92
	v_mul_f32_e64 v93, |v101|, s84
	v_exp_f32_e32 v93, v93
	v_log_f32_e32 v92, v92
	v_add_f32_e32 v93, 1.0, v93
	v_min_f32_e32 v89, 0, v101
	v_add_f32_e32 v102, v90, v102
	v_mul_f32_e32 v100, 0x3f317217, v92
	v_fma_f32 v100, v92, s86, -v100
	v_fmac_f32_e32 v100, 0x3377d1cf, v92
	v_fmac_f32_e32 v100, 0x3f317217, v92
	v_min_f32_e32 v90, 0, v102
	v_add_f32_e32 v103, v91, v103
	v_mov_b32_e32 v92, v100
	v_min_f32_e32 v92, 0, v96
	v_mul_f32_e64 v96, |v96|, s84
	v_exp_f32_e32 v96, v96
	v_min_f32_e32 v91, 0, v103
	v_add_f32_e32 v96, 1.0, v96
	v_log_f32_e32 v96, v96
	s_nop 0
	v_mul_f32_e32 v104, 0x3f317217, v96
	v_fma_f32 v104, v96, s86, -v104
	v_fmac_f32_e32 v104, 0x3377d1cf, v96
	v_fmac_f32_e32 v104, 0x3f317217, v96
	v_mov_b32_e32 v96, v104
	v_log_f32_e32 v93, v93
	s_nop 0
	v_mul_f32_e32 v101, 0x3f317217, v93
	v_fma_f32 v101, v93, s86, -v101
	v_fmac_f32_e32 v101, 0x3377d1cf, v93
	v_fmac_f32_e32 v101, 0x3f317217, v93
	v_mov_b32_e32 v93, v101
	v_min_f32_e32 v93, 0, v97
	v_mul_f32_e64 v97, |v97|, s84
	v_exp_f32_e32 v97, v97
	v_pk_add_f32 v[88:89], v[88:89], v[100:101] neg_lo:[0,1] neg_hi:[0,1]
	v_add_f32_e32 v97, 1.0, v97
	v_pk_mul_f32 v[88:89], v[88:89], s[76:77] op_sel_hi:[1,0]
	v_log_f32_e32 v97, v97
	s_nop 0
	v_mul_f32_e32 v104, 0x3f317217, v97
	v_fma_f32 v104, v97, s86, -v104
	v_fmac_f32_e32 v104, 0x3377d1cf, v97
	v_fmac_f32_e32 v104, 0x3f317217, v97
	v_mov_b32_e32 v97, v104
	v_add_f32_e32 v104, v94, v98
	v_mul_f32_e64 v94, |v102|, s84
	v_exp_f32_e32 v94, v94
	v_mul_f32_e64 v102, |v104|, s84
	v_exp_f32_e32 v102, v102
	v_pk_add_f32 v[92:93], v[92:93], v[96:97] neg_lo:[0,1] neg_hi:[0,1]
	v_add_f32_e32 v94, 1.0, v94
	v_add_f32_e32 v102, 1.0, v102
	v_pk_mul_f32 v[92:93], v[92:93], s[76:77] op_sel_hi:[1,0]
	v_log_f32_e32 v94, v94
	s_nop 0
	v_mul_f32_e32 v98, 0x3f317217, v94
	v_fma_f32 v98, v94, s86, -v98
	v_fmac_f32_e32 v98, 0x3377d1cf, v94
	v_fmac_f32_e32 v98, 0x3f317217, v94
	v_mov_b32_e32 v94, v98
	v_min_f32_e32 v94, 0, v104
	v_log_f32_e32 v102, v102
	s_nop 0
	v_mul_f32_e32 v104, 0x3f317217, v102
	v_fma_f32 v104, v102, s86, -v104
	v_fmac_f32_e32 v104, 0x3377d1cf, v102
	v_fmac_f32_e32 v104, 0x3f317217, v102
	v_mov_b32_e32 v102, v104
	v_add_f32_e32 v104, v95, v99
	v_mul_f32_e64 v95, |v103|, s84
	v_exp_f32_e32 v95, v95
	s_nop 0
	v_add_f32_e32 v95, 1.0, v95
	v_log_f32_e32 v95, v95
	s_nop 0
	v_mul_f32_e32 v99, 0x3f317217, v95
	v_fma_f32 v99, v95, s86, -v99
	v_fmac_f32_e32 v99, 0x3377d1cf, v95
	v_fmac_f32_e32 v99, 0x3f317217, v95
	v_mov_b32_e32 v95, v99
	v_pk_add_f32 v[90:91], v[90:91], v[98:99] neg_lo:[0,1] neg_hi:[0,1]
	v_mul_f32_e64 v98, |v104|, s84
	v_exp_f32_e32 v98, v98
	v_min_f32_e32 v95, 0, v104
	v_pk_mul_f32 v[90:91], v[90:91], s[76:77] op_sel_hi:[1,0]
	v_add_f32_e32 v98, 1.0, v98
	v_log_f32_e32 v98, v98
	s_nop 0
	v_mul_f32_e32 v99, 0x3f317217, v98
	v_fma_f32 v99, v98, s86, -v99
	v_fmac_f32_e32 v99, 0x3377d1cf, v98
	v_fmac_f32_e32 v99, 0x3f317217, v98
	v_mov_b32_e32 v98, v99
	v_mov_b32_e32 v103, v98
	v_pk_add_f32 v[94:95], v[94:95], v[102:103] neg_lo:[0,1] neg_hi:[0,1]
	v_pk_mul_f32 v[94:95], v[94:95], s[76:77] op_sel_hi:[1,0]
.LBB0_245:
	s_nop 0
	v_or_b32_e32 v98, 32, v130
	v_mov_b64_e32 v[96:97], s[8:9]
	v_mad_i64_i32 v[96:97], s[0:1], v98, s88, v[96:97]
	v_lshl_add_u64 v[96:97], v[148:149], 1, v[96:97]
	s_and_b64 vcc, exec, s[6:7]
	v_cvt_pk_bf16_f32 v88, v88, v89
	v_cvt_pk_bf16_f32 v89, v90, v91
	v_cvt_pk_bf16_f32 v90, v92, v93
	v_cvt_pk_bf16_f32 v91, v94, v95
	global_store_dwordx4 v[96:97], v[88:91], off
	s_cbranch_vccnz .LBB0_247
	global_load_dwordx4 v[88:91], v[146:147], off offset:-1520
	global_load_dwordx4 v[92:95], v[146:147], off offset:-1536
	s_waitcnt vmcnt(0)
	v_add_f32_e32 v88, v84, v88
	v_add_f32_e32 v92, v80, v92
	v_mul_f32_e64 v84, |v92|, s84
	v_exp_f32_e32 v84, v84
	v_min_f32_e32 v80, 0, v92
	v_add_f32_e32 v93, v81, v93
	v_add_f32_e32 v89, v85, v89
	v_add_f32_e32 v84, 1.0, v84
	v_mul_f32_e64 v85, |v93|, s84
	v_exp_f32_e32 v85, v85
	v_log_f32_e32 v84, v84
	v_add_f32_e32 v85, 1.0, v85
	v_min_f32_e32 v81, 0, v93
	v_add_f32_e32 v94, v82, v94
	v_mul_f32_e32 v92, 0x3f317217, v84
	v_fma_f32 v92, v84, s86, -v92
	v_fmac_f32_e32 v92, 0x3377d1cf, v84
	v_fmac_f32_e32 v92, 0x3f317217, v84
	v_min_f32_e32 v82, 0, v94
	v_add_f32_e32 v95, v83, v95
	v_mov_b32_e32 v84, v92
	v_min_f32_e32 v84, 0, v88
	v_mul_f32_e64 v88, |v88|, s84
	v_exp_f32_e32 v88, v88
	v_min_f32_e32 v83, 0, v95
	v_add_f32_e32 v88, 1.0, v88
	v_log_f32_e32 v88, v88
	s_nop 0
	v_mul_f32_e32 v98, 0x3f317217, v88
	v_fma_f32 v98, v88, s86, -v98
	v_fmac_f32_e32 v98, 0x3377d1cf, v88
	v_fmac_f32_e32 v98, 0x3f317217, v88
	v_mov_b32_e32 v88, v98
	v_log_f32_e32 v85, v85
	s_nop 0
	v_mul_f32_e32 v93, 0x3f317217, v85
	v_fma_f32 v93, v85, s86, -v93
	v_fmac_f32_e32 v93, 0x3377d1cf, v85
	v_fmac_f32_e32 v93, 0x3f317217, v85
	v_mov_b32_e32 v85, v93
	v_min_f32_e32 v85, 0, v89
	v_mul_f32_e64 v89, |v89|, s84
	v_exp_f32_e32 v89, v89
	v_pk_add_f32 v[80:81], v[80:81], v[92:93] neg_lo:[0,1] neg_hi:[0,1]
	v_add_f32_e32 v89, 1.0, v89
	v_pk_mul_f32 v[80:81], v[80:81], s[76:77] op_sel_hi:[1,0]
	v_log_f32_e32 v89, v89
	s_nop 0
	v_mul_f32_e32 v98, 0x3f317217, v89
	v_fma_f32 v98, v89, s86, -v98
	v_fmac_f32_e32 v98, 0x3377d1cf, v89
	v_fmac_f32_e32 v98, 0x3f317217, v89
	v_mov_b32_e32 v89, v98
	v_add_f32_e32 v98, v86, v90
	v_mul_f32_e64 v86, |v94|, s84
	v_exp_f32_e32 v86, v86
	v_mul_f32_e64 v94, |v98|, s84
	v_exp_f32_e32 v94, v94
	v_pk_add_f32 v[84:85], v[84:85], v[88:89] neg_lo:[0,1] neg_hi:[0,1]
	v_add_f32_e32 v86, 1.0, v86
	v_add_f32_e32 v94, 1.0, v94
	v_pk_mul_f32 v[84:85], v[84:85], s[76:77] op_sel_hi:[1,0]
	v_log_f32_e32 v86, v86
	s_nop 0
	v_mul_f32_e32 v90, 0x3f317217, v86
	v_fma_f32 v90, v86, s86, -v90
	v_fmac_f32_e32 v90, 0x3377d1cf, v86
	v_fmac_f32_e32 v90, 0x3f317217, v86
	v_mov_b32_e32 v86, v90
	v_min_f32_e32 v86, 0, v98
	v_log_f32_e32 v94, v94
	s_nop 0
	v_mul_f32_e32 v98, 0x3f317217, v94
	v_fma_f32 v98, v94, s86, -v98
	v_fmac_f32_e32 v98, 0x3377d1cf, v94
	v_fmac_f32_e32 v98, 0x3f317217, v94
	v_mov_b32_e32 v94, v98
	v_add_f32_e32 v98, v87, v91
	v_mul_f32_e64 v87, |v95|, s84
	v_exp_f32_e32 v87, v87
	s_nop 0
	v_add_f32_e32 v87, 1.0, v87
	v_log_f32_e32 v87, v87
	s_nop 0
	v_mul_f32_e32 v91, 0x3f317217, v87
	v_fma_f32 v91, v87, s86, -v91
	v_fmac_f32_e32 v91, 0x3377d1cf, v87
	v_fmac_f32_e32 v91, 0x3f317217, v87
	v_mov_b32_e32 v87, v91
	v_pk_add_f32 v[82:83], v[82:83], v[90:91] neg_lo:[0,1] neg_hi:[0,1]
	v_mul_f32_e64 v90, |v98|, s84
	v_exp_f32_e32 v90, v90
	v_min_f32_e32 v87, 0, v98
	v_pk_mul_f32 v[82:83], v[82:83], s[76:77] op_sel_hi:[1,0]
	v_add_f32_e32 v90, 1.0, v90
	v_log_f32_e32 v90, v90
	s_nop 0
	v_mul_f32_e32 v91, 0x3f317217, v90
	v_fma_f32 v91, v90, s86, -v91
	v_fmac_f32_e32 v91, 0x3377d1cf, v90
	v_fmac_f32_e32 v91, 0x3f317217, v90
	v_mov_b32_e32 v90, v91
	v_mov_b32_e32 v95, v90
	v_pk_add_f32 v[86:87], v[86:87], v[94:95] neg_lo:[0,1] neg_hi:[0,1]
	v_pk_mul_f32 v[86:87], v[86:87], s[76:77] op_sel_hi:[1,0]
.LBB0_247:
	s_and_b64 vcc, exec, s[6:7]
	v_cvt_pk_bf16_f32 v80, v80, v81
	v_cvt_pk_bf16_f32 v81, v82, v83
	v_cvt_pk_bf16_f32 v82, v84, v85
	v_cvt_pk_bf16_f32 v83, v86, v87
	global_store_dwordx4 v[96:97], v[80:83], off offset:256
	s_cbranch_vccnz .LBB0_249
	global_load_dwordx4 v[80:83], v[146:147], off offset:-2032
	global_load_dwordx4 v[84:87], v[146:147], off offset:-2048
	s_waitcnt vmcnt(0)
	v_add_f32_e32 v80, v76, v80
	v_add_f32_e32 v84, v72, v84
	v_mul_f32_e64 v76, |v84|, s84
	v_exp_f32_e32 v76, v76
	v_min_f32_e32 v72, 0, v84
	v_add_f32_e32 v85, v73, v85
	v_add_f32_e32 v81, v77, v81
	v_add_f32_e32 v76, 1.0, v76
	v_mul_f32_e64 v77, |v85|, s84
	v_exp_f32_e32 v77, v77
	v_log_f32_e32 v76, v76
	v_add_f32_e32 v77, 1.0, v77
	v_min_f32_e32 v73, 0, v85
	v_add_f32_e32 v86, v74, v86
	v_mul_f32_e32 v84, 0x3f317217, v76
	v_fma_f32 v84, v76, s86, -v84
	v_fmac_f32_e32 v84, 0x3377d1cf, v76
	v_fmac_f32_e32 v84, 0x3f317217, v76
	v_min_f32_e32 v74, 0, v86
	v_add_f32_e32 v87, v75, v87
	v_mov_b32_e32 v76, v84
	v_min_f32_e32 v76, 0, v80
	v_mul_f32_e64 v80, |v80|, s84
	v_exp_f32_e32 v80, v80
	v_min_f32_e32 v75, 0, v87
	v_add_f32_e32 v80, 1.0, v80
	v_log_f32_e32 v80, v80
	s_nop 0
	v_mul_f32_e32 v88, 0x3f317217, v80
	v_fma_f32 v88, v80, s86, -v88
	v_fmac_f32_e32 v88, 0x3377d1cf, v80
	v_fmac_f32_e32 v88, 0x3f317217, v80
	v_mov_b32_e32 v80, v88
	v_log_f32_e32 v77, v77
	s_nop 0
	v_mul_f32_e32 v85, 0x3f317217, v77
	v_fma_f32 v85, v77, s86, -v85
	v_fmac_f32_e32 v85, 0x3377d1cf, v77
	v_fmac_f32_e32 v85, 0x3f317217, v77
	v_mov_b32_e32 v77, v85
	v_min_f32_e32 v77, 0, v81
	v_mul_f32_e64 v81, |v81|, s84
	v_exp_f32_e32 v81, v81
	v_pk_add_f32 v[72:73], v[72:73], v[84:85] neg_lo:[0,1] neg_hi:[0,1]
	v_add_f32_e32 v81, 1.0, v81
	v_pk_mul_f32 v[72:73], v[72:73], s[76:77] op_sel_hi:[1,0]
	v_log_f32_e32 v81, v81
	s_nop 0
	v_mul_f32_e32 v88, 0x3f317217, v81
	v_fma_f32 v88, v81, s86, -v88
	v_fmac_f32_e32 v88, 0x3377d1cf, v81
	v_fmac_f32_e32 v88, 0x3f317217, v81
	v_mov_b32_e32 v81, v88
	v_add_f32_e32 v88, v78, v82
	v_mul_f32_e64 v78, |v86|, s84
	v_exp_f32_e32 v78, v78
	v_mul_f32_e64 v86, |v88|, s84
	v_exp_f32_e32 v86, v86
	v_pk_add_f32 v[76:77], v[76:77], v[80:81] neg_lo:[0,1] neg_hi:[0,1]
	v_add_f32_e32 v78, 1.0, v78
	v_add_f32_e32 v86, 1.0, v86
	v_pk_mul_f32 v[76:77], v[76:77], s[76:77] op_sel_hi:[1,0]
	v_log_f32_e32 v78, v78
	s_nop 0
	v_mul_f32_e32 v82, 0x3f317217, v78
	v_fma_f32 v82, v78, s86, -v82
	v_fmac_f32_e32 v82, 0x3377d1cf, v78
	v_fmac_f32_e32 v82, 0x3f317217, v78
	v_mov_b32_e32 v78, v82
	v_min_f32_e32 v78, 0, v88
	v_log_f32_e32 v86, v86
	s_nop 0
	v_mul_f32_e32 v88, 0x3f317217, v86
	v_fma_f32 v88, v86, s86, -v88
	v_fmac_f32_e32 v88, 0x3377d1cf, v86
	v_fmac_f32_e32 v88, 0x3f317217, v86
	v_mov_b32_e32 v86, v88
	v_add_f32_e32 v88, v79, v83
	v_mul_f32_e64 v79, |v87|, s84
	v_exp_f32_e32 v79, v79
	s_nop 0
	v_add_f32_e32 v79, 1.0, v79
	v_log_f32_e32 v79, v79
	s_nop 0
	v_mul_f32_e32 v83, 0x3f317217, v79
	v_fma_f32 v83, v79, s86, -v83
	v_fmac_f32_e32 v83, 0x3377d1cf, v79
	v_fmac_f32_e32 v83, 0x3f317217, v79
	v_mov_b32_e32 v79, v83
	v_pk_add_f32 v[74:75], v[74:75], v[82:83] neg_lo:[0,1] neg_hi:[0,1]
	v_mul_f32_e64 v82, |v88|, s84
	v_exp_f32_e32 v82, v82
	v_min_f32_e32 v79, 0, v88
	v_pk_mul_f32 v[74:75], v[74:75], s[76:77] op_sel_hi:[1,0]
	v_add_f32_e32 v82, 1.0, v82
	v_log_f32_e32 v82, v82
	s_nop 0
	v_mul_f32_e32 v83, 0x3f317217, v82
	v_fma_f32 v83, v82, s86, -v83
	v_fmac_f32_e32 v83, 0x3377d1cf, v82
	v_fmac_f32_e32 v83, 0x3f317217, v82
	v_mov_b32_e32 v82, v83
	v_mov_b32_e32 v87, v82
	v_pk_add_f32 v[78:79], v[78:79], v[86:87] neg_lo:[0,1] neg_hi:[0,1]
	v_pk_mul_f32 v[78:79], v[78:79], s[76:77] op_sel_hi:[1,0]
.LBB0_249:
	s_nop 0
	v_or_b32_e32 v82, 48, v130
	v_mov_b64_e32 v[80:81], s[8:9]
	v_mad_i64_i32 v[80:81], s[0:1], v82, s88, v[80:81]
	v_lshl_add_u64 v[80:81], v[148:149], 1, v[80:81]
	s_and_b64 vcc, exec, s[6:7]
	v_cvt_pk_bf16_f32 v72, v72, v73
	v_cvt_pk_bf16_f32 v73, v74, v75
	v_cvt_pk_bf16_f32 v74, v76, v77
	v_cvt_pk_bf16_f32 v75, v78, v79
	global_store_dwordx4 v[80:81], v[72:75], off
	s_cbranch_vccnz .LBB0_251
	global_load_dwordx4 v[72:75], v[146:147], off offset:-1520
	global_load_dwordx4 v[76:79], v[146:147], off offset:-1536
	s_waitcnt vmcnt(0)
	v_add_f32_e32 v72, v68, v72
	v_add_f32_e32 v76, v64, v76
	v_mul_f32_e64 v68, |v76|, s84
	v_exp_f32_e32 v68, v68
	v_min_f32_e32 v64, 0, v76
	v_add_f32_e32 v77, v65, v77
	v_add_f32_e32 v73, v69, v73
	v_add_f32_e32 v68, 1.0, v68
	v_mul_f32_e64 v69, |v77|, s84
	v_exp_f32_e32 v69, v69
	v_log_f32_e32 v68, v68
	v_add_f32_e32 v69, 1.0, v69
	v_min_f32_e32 v65, 0, v77
	v_add_f32_e32 v78, v66, v78
	v_mul_f32_e32 v76, 0x3f317217, v68
	v_fma_f32 v76, v68, s86, -v76
	v_fmac_f32_e32 v76, 0x3377d1cf, v68
	v_fmac_f32_e32 v76, 0x3f317217, v68
	v_min_f32_e32 v66, 0, v78
	v_add_f32_e32 v79, v67, v79
	v_mov_b32_e32 v68, v76
	v_min_f32_e32 v68, 0, v72
	v_mul_f32_e64 v72, |v72|, s84
	v_exp_f32_e32 v72, v72
	v_min_f32_e32 v67, 0, v79
	v_add_f32_e32 v72, 1.0, v72
	v_log_f32_e32 v72, v72
	s_nop 0
	v_mul_f32_e32 v82, 0x3f317217, v72
	v_fma_f32 v82, v72, s86, -v82
	v_fmac_f32_e32 v82, 0x3377d1cf, v72
	v_fmac_f32_e32 v82, 0x3f317217, v72
	v_mov_b32_e32 v72, v82
	v_log_f32_e32 v69, v69
	s_nop 0
	v_mul_f32_e32 v77, 0x3f317217, v69
	v_fma_f32 v77, v69, s86, -v77
	v_fmac_f32_e32 v77, 0x3377d1cf, v69
	v_fmac_f32_e32 v77, 0x3f317217, v69
	v_mov_b32_e32 v69, v77
	v_min_f32_e32 v69, 0, v73
	v_mul_f32_e64 v73, |v73|, s84
	v_exp_f32_e32 v73, v73
	v_pk_add_f32 v[64:65], v[64:65], v[76:77] neg_lo:[0,1] neg_hi:[0,1]
	v_add_f32_e32 v73, 1.0, v73
	v_pk_mul_f32 v[64:65], v[64:65], s[76:77] op_sel_hi:[1,0]
	v_log_f32_e32 v73, v73
	s_nop 0
	v_mul_f32_e32 v82, 0x3f317217, v73
	v_fma_f32 v82, v73, s86, -v82
	v_fmac_f32_e32 v82, 0x3377d1cf, v73
	v_fmac_f32_e32 v82, 0x3f317217, v73
	v_mov_b32_e32 v73, v82
	v_add_f32_e32 v82, v70, v74
	v_mul_f32_e64 v70, |v78|, s84
	v_exp_f32_e32 v70, v70
	v_mul_f32_e64 v78, |v82|, s84
	v_exp_f32_e32 v78, v78
	v_pk_add_f32 v[68:69], v[68:69], v[72:73] neg_lo:[0,1] neg_hi:[0,1]
	v_add_f32_e32 v70, 1.0, v70
	v_add_f32_e32 v78, 1.0, v78
	v_pk_mul_f32 v[68:69], v[68:69], s[76:77] op_sel_hi:[1,0]
	v_log_f32_e32 v70, v70
	s_nop 0
	v_mul_f32_e32 v74, 0x3f317217, v70
	v_fma_f32 v74, v70, s86, -v74
	v_fmac_f32_e32 v74, 0x3377d1cf, v70
	v_fmac_f32_e32 v74, 0x3f317217, v70
	v_mov_b32_e32 v70, v74
	v_min_f32_e32 v70, 0, v82
	v_log_f32_e32 v78, v78
	s_nop 0
	v_mul_f32_e32 v82, 0x3f317217, v78
	v_fma_f32 v82, v78, s86, -v82
	v_fmac_f32_e32 v82, 0x3377d1cf, v78
	v_fmac_f32_e32 v82, 0x3f317217, v78
	v_mov_b32_e32 v78, v82
	v_add_f32_e32 v82, v71, v75
	v_mul_f32_e64 v71, |v79|, s84
	v_exp_f32_e32 v71, v71
	s_nop 0
	v_add_f32_e32 v71, 1.0, v71
	v_log_f32_e32 v71, v71
	s_nop 0
	v_mul_f32_e32 v75, 0x3f317217, v71
	v_fma_f32 v75, v71, s86, -v75
	v_fmac_f32_e32 v75, 0x3377d1cf, v71
	v_fmac_f32_e32 v75, 0x3f317217, v71
	v_mov_b32_e32 v71, v75
	v_pk_add_f32 v[66:67], v[66:67], v[74:75] neg_lo:[0,1] neg_hi:[0,1]
	v_mul_f32_e64 v74, |v82|, s84
	v_exp_f32_e32 v74, v74
	v_min_f32_e32 v71, 0, v82
	v_pk_mul_f32 v[66:67], v[66:67], s[76:77] op_sel_hi:[1,0]
	v_add_f32_e32 v74, 1.0, v74
	v_log_f32_e32 v74, v74
	s_nop 0
	v_mul_f32_e32 v75, 0x3f317217, v74
	v_fma_f32 v75, v74, s86, -v75
	v_fmac_f32_e32 v75, 0x3377d1cf, v74
	v_fmac_f32_e32 v75, 0x3f317217, v74
	v_mov_b32_e32 v74, v75
	v_mov_b32_e32 v79, v74
	v_pk_add_f32 v[70:71], v[70:71], v[78:79] neg_lo:[0,1] neg_hi:[0,1]
	v_pk_mul_f32 v[70:71], v[70:71], s[76:77] op_sel_hi:[1,0]
.LBB0_251:
	s_and_b64 vcc, exec, s[6:7]
	v_cvt_pk_bf16_f32 v64, v64, v65
	v_cvt_pk_bf16_f32 v65, v66, v67
	v_cvt_pk_bf16_f32 v66, v68, v69
	v_cvt_pk_bf16_f32 v67, v70, v71
	global_store_dwordx4 v[80:81], v[64:67], off offset:256
	s_cbranch_vccnz .LBB0_253
	global_load_dwordx4 v[64:67], v[146:147], off offset:-2032
	global_load_dwordx4 v[68:71], v[146:147], off offset:-2048
	s_waitcnt vmcnt(0)
	v_add_f32_e32 v64, v60, v64
	v_add_f32_e32 v68, v56, v68
	v_mul_f32_e64 v60, |v68|, s84
	v_exp_f32_e32 v60, v60
	v_min_f32_e32 v56, 0, v68
	v_add_f32_e32 v69, v57, v69
	v_add_f32_e32 v65, v61, v65
	v_add_f32_e32 v60, 1.0, v60
	v_mul_f32_e64 v61, |v69|, s84
	v_exp_f32_e32 v61, v61
	v_log_f32_e32 v60, v60
	v_add_f32_e32 v61, 1.0, v61
	v_min_f32_e32 v57, 0, v69
	v_add_f32_e32 v70, v58, v70
	v_mul_f32_e32 v68, 0x3f317217, v60
	v_fma_f32 v68, v60, s86, -v68
	v_fmac_f32_e32 v68, 0x3377d1cf, v60
	v_fmac_f32_e32 v68, 0x3f317217, v60
	v_min_f32_e32 v58, 0, v70
	v_add_f32_e32 v71, v59, v71
	v_mov_b32_e32 v60, v68
	v_min_f32_e32 v60, 0, v64
	v_mul_f32_e64 v64, |v64|, s84
	v_exp_f32_e32 v64, v64
	v_min_f32_e32 v59, 0, v71
	v_add_f32_e32 v64, 1.0, v64
	v_log_f32_e32 v64, v64
	s_nop 0
	v_mul_f32_e32 v72, 0x3f317217, v64
	v_fma_f32 v72, v64, s86, -v72
	v_fmac_f32_e32 v72, 0x3377d1cf, v64
	v_fmac_f32_e32 v72, 0x3f317217, v64
	v_mov_b32_e32 v64, v72
	v_log_f32_e32 v61, v61
	s_nop 0
	v_mul_f32_e32 v69, 0x3f317217, v61
	v_fma_f32 v69, v61, s86, -v69
	v_fmac_f32_e32 v69, 0x3377d1cf, v61
	v_fmac_f32_e32 v69, 0x3f317217, v61
	v_mov_b32_e32 v61, v69
	v_min_f32_e32 v61, 0, v65
	v_mul_f32_e64 v65, |v65|, s84
	v_exp_f32_e32 v65, v65
	v_pk_add_f32 v[56:57], v[56:57], v[68:69] neg_lo:[0,1] neg_hi:[0,1]
	v_add_f32_e32 v65, 1.0, v65
	v_pk_mul_f32 v[56:57], v[56:57], s[76:77] op_sel_hi:[1,0]
	v_log_f32_e32 v65, v65
	s_nop 0
	v_mul_f32_e32 v72, 0x3f317217, v65
	v_fma_f32 v72, v65, s86, -v72
	v_fmac_f32_e32 v72, 0x3377d1cf, v65
	v_fmac_f32_e32 v72, 0x3f317217, v65
	v_mov_b32_e32 v65, v72
	v_add_f32_e32 v72, v62, v66
	v_mul_f32_e64 v62, |v70|, s84
	v_exp_f32_e32 v62, v62
	v_mul_f32_e64 v70, |v72|, s84
	v_exp_f32_e32 v70, v70
	v_pk_add_f32 v[60:61], v[60:61], v[64:65] neg_lo:[0,1] neg_hi:[0,1]
	v_add_f32_e32 v62, 1.0, v62
	v_add_f32_e32 v70, 1.0, v70
	v_pk_mul_f32 v[60:61], v[60:61], s[76:77] op_sel_hi:[1,0]
	v_log_f32_e32 v62, v62
	s_nop 0
	v_mul_f32_e32 v66, 0x3f317217, v62
	v_fma_f32 v66, v62, s86, -v66
	v_fmac_f32_e32 v66, 0x3377d1cf, v62
	v_fmac_f32_e32 v66, 0x3f317217, v62
	v_mov_b32_e32 v62, v66
	v_min_f32_e32 v62, 0, v72
	v_log_f32_e32 v70, v70
	s_nop 0
	v_mul_f32_e32 v72, 0x3f317217, v70
	v_fma_f32 v72, v70, s86, -v72
	v_fmac_f32_e32 v72, 0x3377d1cf, v70
	v_fmac_f32_e32 v72, 0x3f317217, v70
	v_mov_b32_e32 v70, v72
	v_add_f32_e32 v72, v63, v67
	v_mul_f32_e64 v63, |v71|, s84
	v_exp_f32_e32 v63, v63
	s_nop 0
	v_add_f32_e32 v63, 1.0, v63
	v_log_f32_e32 v63, v63
	s_nop 0
	v_mul_f32_e32 v67, 0x3f317217, v63
	v_fma_f32 v67, v63, s86, -v67
	v_fmac_f32_e32 v67, 0x3377d1cf, v63
	v_fmac_f32_e32 v67, 0x3f317217, v63
	v_mov_b32_e32 v63, v67
	v_pk_add_f32 v[58:59], v[58:59], v[66:67] neg_lo:[0,1] neg_hi:[0,1]
	v_mul_f32_e64 v66, |v72|, s84
	v_exp_f32_e32 v66, v66
	v_min_f32_e32 v63, 0, v72
	v_pk_mul_f32 v[58:59], v[58:59], s[76:77] op_sel_hi:[1,0]
	v_add_f32_e32 v66, 1.0, v66
	v_log_f32_e32 v66, v66
	s_nop 0
	v_mul_f32_e32 v67, 0x3f317217, v66
	v_fma_f32 v67, v66, s86, -v67
	v_fmac_f32_e32 v67, 0x3377d1cf, v66
	v_fmac_f32_e32 v67, 0x3f317217, v66
	v_mov_b32_e32 v66, v67
	v_mov_b32_e32 v71, v66
	v_pk_add_f32 v[62:63], v[62:63], v[70:71] neg_lo:[0,1] neg_hi:[0,1]
	v_pk_mul_f32 v[62:63], v[62:63], s[76:77] op_sel_hi:[1,0]
.LBB0_253:
	s_nop 0
	v_add_u32_e32 v66, 0x80, v130
	v_mov_b64_e32 v[64:65], s[8:9]
	v_mad_i64_i32 v[64:65], s[0:1], v66, s88, v[64:65]
	v_lshl_add_u64 v[64:65], v[148:149], 1, v[64:65]
	s_and_b64 vcc, exec, s[6:7]
	v_cvt_pk_bf16_f32 v56, v56, v57
	v_cvt_pk_bf16_f32 v57, v58, v59
	v_cvt_pk_bf16_f32 v58, v60, v61
	v_cvt_pk_bf16_f32 v59, v62, v63
	global_store_dwordx4 v[64:65], v[56:59], off
	s_cbranch_vccnz .LBB0_255
	global_load_dwordx4 v[56:59], v[146:147], off offset:-1520
	global_load_dwordx4 v[60:63], v[146:147], off offset:-1536
	s_waitcnt vmcnt(0)
	v_add_f32_e32 v56, v52, v56
	v_add_f32_e32 v60, v48, v60
	v_mul_f32_e64 v52, |v60|, s84
	v_exp_f32_e32 v52, v52
	v_min_f32_e32 v48, 0, v60
	v_add_f32_e32 v61, v49, v61
	v_add_f32_e32 v57, v53, v57
	v_add_f32_e32 v52, 1.0, v52
	v_mul_f32_e64 v53, |v61|, s84
	v_exp_f32_e32 v53, v53
	v_log_f32_e32 v52, v52
	v_add_f32_e32 v53, 1.0, v53
	v_min_f32_e32 v49, 0, v61
	v_add_f32_e32 v62, v50, v62
	v_mul_f32_e32 v60, 0x3f317217, v52
	v_fma_f32 v60, v52, s86, -v60
	v_fmac_f32_e32 v60, 0x3377d1cf, v52
	v_fmac_f32_e32 v60, 0x3f317217, v52
	v_min_f32_e32 v50, 0, v62
	v_add_f32_e32 v63, v51, v63
	v_mov_b32_e32 v52, v60
	v_min_f32_e32 v52, 0, v56
	v_mul_f32_e64 v56, |v56|, s84
	v_exp_f32_e32 v56, v56
	v_min_f32_e32 v51, 0, v63
	v_add_f32_e32 v56, 1.0, v56
	v_log_f32_e32 v56, v56
	s_nop 0
	v_mul_f32_e32 v66, 0x3f317217, v56
	v_fma_f32 v66, v56, s86, -v66
	v_fmac_f32_e32 v66, 0x3377d1cf, v56
	v_fmac_f32_e32 v66, 0x3f317217, v56
	v_mov_b32_e32 v56, v66
	v_log_f32_e32 v53, v53
	s_nop 0
	v_mul_f32_e32 v61, 0x3f317217, v53
	v_fma_f32 v61, v53, s86, -v61
	v_fmac_f32_e32 v61, 0x3377d1cf, v53
	v_fmac_f32_e32 v61, 0x3f317217, v53
	v_mov_b32_e32 v53, v61
	v_min_f32_e32 v53, 0, v57
	v_mul_f32_e64 v57, |v57|, s84
	v_exp_f32_e32 v57, v57
	v_pk_add_f32 v[48:49], v[48:49], v[60:61] neg_lo:[0,1] neg_hi:[0,1]
	v_add_f32_e32 v57, 1.0, v57
	v_pk_mul_f32 v[48:49], v[48:49], s[76:77] op_sel_hi:[1,0]
	v_log_f32_e32 v57, v57
	s_nop 0
	v_mul_f32_e32 v66, 0x3f317217, v57
	v_fma_f32 v66, v57, s86, -v66
	v_fmac_f32_e32 v66, 0x3377d1cf, v57
	v_fmac_f32_e32 v66, 0x3f317217, v57
	v_mov_b32_e32 v57, v66
	v_add_f32_e32 v66, v54, v58
	v_mul_f32_e64 v54, |v62|, s84
	v_exp_f32_e32 v54, v54
	v_mul_f32_e64 v62, |v66|, s84
	v_exp_f32_e32 v62, v62
	v_pk_add_f32 v[52:53], v[52:53], v[56:57] neg_lo:[0,1] neg_hi:[0,1]
	v_add_f32_e32 v54, 1.0, v54
	v_add_f32_e32 v62, 1.0, v62
	v_pk_mul_f32 v[52:53], v[52:53], s[76:77] op_sel_hi:[1,0]
	v_log_f32_e32 v54, v54
	s_nop 0
	v_mul_f32_e32 v58, 0x3f317217, v54
	v_fma_f32 v58, v54, s86, -v58
	v_fmac_f32_e32 v58, 0x3377d1cf, v54
	v_fmac_f32_e32 v58, 0x3f317217, v54
	v_mov_b32_e32 v54, v58
	v_min_f32_e32 v54, 0, v66
	v_log_f32_e32 v62, v62
	s_nop 0
	v_mul_f32_e32 v66, 0x3f317217, v62
	v_fma_f32 v66, v62, s86, -v66
	v_fmac_f32_e32 v66, 0x3377d1cf, v62
	v_fmac_f32_e32 v66, 0x3f317217, v62
	v_mov_b32_e32 v62, v66
	v_add_f32_e32 v66, v55, v59
	v_mul_f32_e64 v55, |v63|, s84
	v_exp_f32_e32 v55, v55
	s_nop 0
	v_add_f32_e32 v55, 1.0, v55
	v_log_f32_e32 v55, v55
	s_nop 0
	v_mul_f32_e32 v59, 0x3f317217, v55
	v_fma_f32 v59, v55, s86, -v59
	v_fmac_f32_e32 v59, 0x3377d1cf, v55
	v_fmac_f32_e32 v59, 0x3f317217, v55
	v_mov_b32_e32 v55, v59
	v_pk_add_f32 v[50:51], v[50:51], v[58:59] neg_lo:[0,1] neg_hi:[0,1]
	v_mul_f32_e64 v58, |v66|, s84
	v_exp_f32_e32 v58, v58
	v_min_f32_e32 v55, 0, v66
	v_pk_mul_f32 v[50:51], v[50:51], s[76:77] op_sel_hi:[1,0]
	v_add_f32_e32 v58, 1.0, v58
	v_log_f32_e32 v58, v58
	s_nop 0
	v_mul_f32_e32 v59, 0x3f317217, v58
	v_fma_f32 v59, v58, s86, -v59
	v_fmac_f32_e32 v59, 0x3377d1cf, v58
	v_fmac_f32_e32 v59, 0x3f317217, v58
	v_mov_b32_e32 v58, v59
	v_mov_b32_e32 v63, v58
	v_pk_add_f32 v[54:55], v[54:55], v[62:63] neg_lo:[0,1] neg_hi:[0,1]
	v_pk_mul_f32 v[54:55], v[54:55], s[76:77] op_sel_hi:[1,0]
.LBB0_255:
	s_and_b64 vcc, exec, s[6:7]
	v_cvt_pk_bf16_f32 v48, v48, v49
	v_cvt_pk_bf16_f32 v49, v50, v51
	v_cvt_pk_bf16_f32 v50, v52, v53
	v_cvt_pk_bf16_f32 v51, v54, v55
	global_store_dwordx4 v[64:65], v[48:51], off offset:256
	s_cbranch_vccnz .LBB0_257
	global_load_dwordx4 v[48:51], v[146:147], off offset:-2032
	global_load_dwordx4 v[52:55], v[146:147], off offset:-2048
	s_waitcnt vmcnt(0)
	v_add_f32_e32 v48, v44, v48
	v_add_f32_e32 v52, v40, v52
	v_mul_f32_e64 v44, |v52|, s84
	v_exp_f32_e32 v44, v44
	v_min_f32_e32 v40, 0, v52
	v_add_f32_e32 v53, v41, v53
	v_add_f32_e32 v49, v45, v49
	v_add_f32_e32 v44, 1.0, v44
	v_mul_f32_e64 v45, |v53|, s84
	v_exp_f32_e32 v45, v45
	v_log_f32_e32 v44, v44
	v_add_f32_e32 v45, 1.0, v45
	v_min_f32_e32 v41, 0, v53
	v_add_f32_e32 v54, v42, v54
	v_mul_f32_e32 v52, 0x3f317217, v44
	v_fma_f32 v52, v44, s86, -v52
	v_fmac_f32_e32 v52, 0x3377d1cf, v44
	v_fmac_f32_e32 v52, 0x3f317217, v44
	v_min_f32_e32 v42, 0, v54
	v_add_f32_e32 v55, v43, v55
	v_mov_b32_e32 v44, v52
	v_min_f32_e32 v44, 0, v48
	v_mul_f32_e64 v48, |v48|, s84
	v_exp_f32_e32 v48, v48
	v_min_f32_e32 v43, 0, v55
	v_add_f32_e32 v48, 1.0, v48
	v_log_f32_e32 v48, v48
	s_nop 0
	v_mul_f32_e32 v56, 0x3f317217, v48
	v_fma_f32 v56, v48, s86, -v56
	v_fmac_f32_e32 v56, 0x3377d1cf, v48
	v_fmac_f32_e32 v56, 0x3f317217, v48
	v_mov_b32_e32 v48, v56
	v_log_f32_e32 v45, v45
	s_nop 0
	v_mul_f32_e32 v53, 0x3f317217, v45
	v_fma_f32 v53, v45, s86, -v53
	v_fmac_f32_e32 v53, 0x3377d1cf, v45
	v_fmac_f32_e32 v53, 0x3f317217, v45
	v_mov_b32_e32 v45, v53
	v_min_f32_e32 v45, 0, v49
	v_mul_f32_e64 v49, |v49|, s84
	v_exp_f32_e32 v49, v49
	v_pk_add_f32 v[40:41], v[40:41], v[52:53] neg_lo:[0,1] neg_hi:[0,1]
	v_add_f32_e32 v49, 1.0, v49
	v_pk_mul_f32 v[40:41], v[40:41], s[76:77] op_sel_hi:[1,0]
	v_log_f32_e32 v49, v49
	s_nop 0
	v_mul_f32_e32 v56, 0x3f317217, v49
	v_fma_f32 v56, v49, s86, -v56
	v_fmac_f32_e32 v56, 0x3377d1cf, v49
	v_fmac_f32_e32 v56, 0x3f317217, v49
	v_mov_b32_e32 v49, v56
	v_add_f32_e32 v56, v46, v50
	v_mul_f32_e64 v46, |v54|, s84
	v_exp_f32_e32 v46, v46
	v_mul_f32_e64 v54, |v56|, s84
	v_exp_f32_e32 v54, v54
	v_pk_add_f32 v[44:45], v[44:45], v[48:49] neg_lo:[0,1] neg_hi:[0,1]
	v_add_f32_e32 v46, 1.0, v46
	v_add_f32_e32 v54, 1.0, v54
	v_pk_mul_f32 v[44:45], v[44:45], s[76:77] op_sel_hi:[1,0]
	v_log_f32_e32 v46, v46
	s_nop 0
	v_mul_f32_e32 v50, 0x3f317217, v46
	v_fma_f32 v50, v46, s86, -v50
	v_fmac_f32_e32 v50, 0x3377d1cf, v46
	v_fmac_f32_e32 v50, 0x3f317217, v46
	v_mov_b32_e32 v46, v50
	v_min_f32_e32 v46, 0, v56
	v_log_f32_e32 v54, v54
	s_nop 0
	v_mul_f32_e32 v56, 0x3f317217, v54
	v_fma_f32 v56, v54, s86, -v56
	v_fmac_f32_e32 v56, 0x3377d1cf, v54
	v_fmac_f32_e32 v56, 0x3f317217, v54
	v_mov_b32_e32 v54, v56
	v_add_f32_e32 v56, v47, v51
	v_mul_f32_e64 v47, |v55|, s84
	v_exp_f32_e32 v47, v47
	s_nop 0
	v_add_f32_e32 v47, 1.0, v47
	v_log_f32_e32 v47, v47
	s_nop 0
	v_mul_f32_e32 v51, 0x3f317217, v47
	v_fma_f32 v51, v47, s86, -v51
	v_fmac_f32_e32 v51, 0x3377d1cf, v47
	v_fmac_f32_e32 v51, 0x3f317217, v47
	v_mov_b32_e32 v47, v51
	v_pk_add_f32 v[42:43], v[42:43], v[50:51] neg_lo:[0,1] neg_hi:[0,1]
	v_mul_f32_e64 v50, |v56|, s84
	v_exp_f32_e32 v50, v50
	v_min_f32_e32 v47, 0, v56
	v_pk_mul_f32 v[42:43], v[42:43], s[76:77] op_sel_hi:[1,0]
	v_add_f32_e32 v50, 1.0, v50
	v_log_f32_e32 v50, v50
	s_nop 0
	v_mul_f32_e32 v51, 0x3f317217, v50
	v_fma_f32 v51, v50, s86, -v51
	v_fmac_f32_e32 v51, 0x3377d1cf, v50
	v_fmac_f32_e32 v51, 0x3f317217, v50
	v_mov_b32_e32 v50, v51
	v_mov_b32_e32 v55, v50
	v_pk_add_f32 v[46:47], v[46:47], v[54:55] neg_lo:[0,1] neg_hi:[0,1]
	v_pk_mul_f32 v[46:47], v[46:47], s[76:77] op_sel_hi:[1,0]
.LBB0_257:
	s_nop 0
	v_add_u32_e32 v50, 0x90, v130
	v_mov_b64_e32 v[48:49], s[8:9]
	v_mad_i64_i32 v[48:49], s[0:1], v50, s88, v[48:49]
	v_lshl_add_u64 v[48:49], v[148:149], 1, v[48:49]
	s_and_b64 vcc, exec, s[6:7]
	v_cvt_pk_bf16_f32 v40, v40, v41
	v_cvt_pk_bf16_f32 v41, v42, v43
	v_cvt_pk_bf16_f32 v42, v44, v45
	v_cvt_pk_bf16_f32 v43, v46, v47
	global_store_dwordx4 v[48:49], v[40:43], off
	s_cbranch_vccnz .LBB0_259
	global_load_dwordx4 v[40:43], v[146:147], off offset:-1520
	global_load_dwordx4 v[44:47], v[146:147], off offset:-1536
	s_waitcnt vmcnt(0)
	v_add_f32_e32 v40, v36, v40
	v_add_f32_e32 v44, v32, v44
	v_mul_f32_e64 v36, |v44|, s84
	v_exp_f32_e32 v36, v36
	v_min_f32_e32 v32, 0, v44
	v_add_f32_e32 v45, v33, v45
	v_add_f32_e32 v41, v37, v41
	v_add_f32_e32 v36, 1.0, v36
	v_mul_f32_e64 v37, |v45|, s84
	v_exp_f32_e32 v37, v37
	v_log_f32_e32 v36, v36
	v_add_f32_e32 v37, 1.0, v37
	v_min_f32_e32 v33, 0, v45
	v_add_f32_e32 v46, v34, v46
	v_mul_f32_e32 v44, 0x3f317217, v36
	v_fma_f32 v44, v36, s86, -v44
	v_fmac_f32_e32 v44, 0x3377d1cf, v36
	v_fmac_f32_e32 v44, 0x3f317217, v36
	v_min_f32_e32 v34, 0, v46
	v_add_f32_e32 v47, v35, v47
	v_mov_b32_e32 v36, v44
	v_min_f32_e32 v36, 0, v40
	v_mul_f32_e64 v40, |v40|, s84
	v_exp_f32_e32 v40, v40
	v_min_f32_e32 v35, 0, v47
	v_add_f32_e32 v40, 1.0, v40
	v_log_f32_e32 v40, v40
	s_nop 0
	v_mul_f32_e32 v50, 0x3f317217, v40
	v_fma_f32 v50, v40, s86, -v50
	v_fmac_f32_e32 v50, 0x3377d1cf, v40
	v_fmac_f32_e32 v50, 0x3f317217, v40
	v_mov_b32_e32 v40, v50
	v_log_f32_e32 v37, v37
	s_nop 0
	v_mul_f32_e32 v45, 0x3f317217, v37
	v_fma_f32 v45, v37, s86, -v45
	v_fmac_f32_e32 v45, 0x3377d1cf, v37
	v_fmac_f32_e32 v45, 0x3f317217, v37
	v_mov_b32_e32 v37, v45
	v_min_f32_e32 v37, 0, v41
	v_mul_f32_e64 v41, |v41|, s84
	v_exp_f32_e32 v41, v41
	v_pk_add_f32 v[32:33], v[32:33], v[44:45] neg_lo:[0,1] neg_hi:[0,1]
	v_add_f32_e32 v41, 1.0, v41
	v_pk_mul_f32 v[32:33], v[32:33], s[76:77] op_sel_hi:[1,0]
	v_log_f32_e32 v41, v41
	s_nop 0
	v_mul_f32_e32 v50, 0x3f317217, v41
	v_fma_f32 v50, v41, s86, -v50
	v_fmac_f32_e32 v50, 0x3377d1cf, v41
	v_fmac_f32_e32 v50, 0x3f317217, v41
	v_mov_b32_e32 v41, v50
	v_add_f32_e32 v50, v38, v42
	v_mul_f32_e64 v38, |v46|, s84
	v_exp_f32_e32 v38, v38
	v_mul_f32_e64 v46, |v50|, s84
	v_exp_f32_e32 v46, v46
	v_pk_add_f32 v[36:37], v[36:37], v[40:41] neg_lo:[0,1] neg_hi:[0,1]
	v_add_f32_e32 v38, 1.0, v38
	v_add_f32_e32 v46, 1.0, v46
	v_pk_mul_f32 v[36:37], v[36:37], s[76:77] op_sel_hi:[1,0]
	v_log_f32_e32 v38, v38
	s_nop 0
	v_mul_f32_e32 v42, 0x3f317217, v38
	v_fma_f32 v42, v38, s86, -v42
	v_fmac_f32_e32 v42, 0x3377d1cf, v38
	v_fmac_f32_e32 v42, 0x3f317217, v38
	v_mov_b32_e32 v38, v42
	v_min_f32_e32 v38, 0, v50
	v_log_f32_e32 v46, v46
	s_nop 0
	v_mul_f32_e32 v50, 0x3f317217, v46
	v_fma_f32 v50, v46, s86, -v50
	v_fmac_f32_e32 v50, 0x3377d1cf, v46
	v_fmac_f32_e32 v50, 0x3f317217, v46
	v_mov_b32_e32 v46, v50
	v_add_f32_e32 v50, v39, v43
	v_mul_f32_e64 v39, |v47|, s84
	v_exp_f32_e32 v39, v39
	s_nop 0
	v_add_f32_e32 v39, 1.0, v39
	v_log_f32_e32 v39, v39
	s_nop 0
	v_mul_f32_e32 v43, 0x3f317217, v39
	v_fma_f32 v43, v39, s86, -v43
	v_fmac_f32_e32 v43, 0x3377d1cf, v39
	v_fmac_f32_e32 v43, 0x3f317217, v39
	v_mov_b32_e32 v39, v43
	v_pk_add_f32 v[34:35], v[34:35], v[42:43] neg_lo:[0,1] neg_hi:[0,1]
	v_mul_f32_e64 v42, |v50|, s84
	v_exp_f32_e32 v42, v42
	v_min_f32_e32 v39, 0, v50
	v_pk_mul_f32 v[34:35], v[34:35], s[76:77] op_sel_hi:[1,0]
	v_add_f32_e32 v42, 1.0, v42
	v_log_f32_e32 v42, v42
	s_nop 0
	v_mul_f32_e32 v43, 0x3f317217, v42
	v_fma_f32 v43, v42, s86, -v43
	v_fmac_f32_e32 v43, 0x3377d1cf, v42
	v_fmac_f32_e32 v43, 0x3f317217, v42
	v_mov_b32_e32 v42, v43
	v_mov_b32_e32 v47, v42
	v_pk_add_f32 v[38:39], v[38:39], v[46:47] neg_lo:[0,1] neg_hi:[0,1]
	v_pk_mul_f32 v[38:39], v[38:39], s[76:77] op_sel_hi:[1,0]
.LBB0_259:
	s_and_b64 vcc, exec, s[6:7]
	v_cvt_pk_bf16_f32 v32, v32, v33
	v_cvt_pk_bf16_f32 v33, v34, v35
	v_cvt_pk_bf16_f32 v34, v36, v37
	v_cvt_pk_bf16_f32 v35, v38, v39
	global_store_dwordx4 v[48:49], v[32:35], off offset:256
	s_cbranch_vccnz .LBB0_261
	global_load_dwordx4 v[32:35], v[146:147], off offset:-2032
	global_load_dwordx4 v[36:39], v[146:147], off offset:-2048
	s_waitcnt vmcnt(0)
	v_add_f32_e32 v32, v28, v32
	v_add_f32_e32 v36, v24, v36
	v_mul_f32_e64 v28, |v36|, s84
	v_exp_f32_e32 v28, v28
	v_min_f32_e32 v24, 0, v36
	v_add_f32_e32 v37, v25, v37
	v_add_f32_e32 v33, v29, v33
	v_add_f32_e32 v28, 1.0, v28
	v_mul_f32_e64 v29, |v37|, s84
	v_exp_f32_e32 v29, v29
	v_log_f32_e32 v28, v28
	v_add_f32_e32 v29, 1.0, v29
	v_min_f32_e32 v25, 0, v37
	v_add_f32_e32 v38, v26, v38
	v_mul_f32_e32 v36, 0x3f317217, v28
	v_fma_f32 v36, v28, s86, -v36
	v_fmac_f32_e32 v36, 0x3377d1cf, v28
	v_fmac_f32_e32 v36, 0x3f317217, v28
	v_min_f32_e32 v26, 0, v38
	v_add_f32_e32 v39, v27, v39
	v_mov_b32_e32 v28, v36
	v_min_f32_e32 v28, 0, v32
	v_mul_f32_e64 v32, |v32|, s84
	v_exp_f32_e32 v32, v32
	v_min_f32_e32 v27, 0, v39
	v_add_f32_e32 v32, 1.0, v32
	v_log_f32_e32 v32, v32
	s_nop 0
	v_mul_f32_e32 v40, 0x3f317217, v32
	v_fma_f32 v40, v32, s86, -v40
	v_fmac_f32_e32 v40, 0x3377d1cf, v32
	v_fmac_f32_e32 v40, 0x3f317217, v32
	v_mov_b32_e32 v32, v40
	v_log_f32_e32 v29, v29
	s_nop 0
	v_mul_f32_e32 v37, 0x3f317217, v29
	v_fma_f32 v37, v29, s86, -v37
	v_fmac_f32_e32 v37, 0x3377d1cf, v29
	v_fmac_f32_e32 v37, 0x3f317217, v29
	v_mov_b32_e32 v29, v37
	v_min_f32_e32 v29, 0, v33
	v_mul_f32_e64 v33, |v33|, s84
	v_exp_f32_e32 v33, v33
	v_pk_add_f32 v[24:25], v[24:25], v[36:37] neg_lo:[0,1] neg_hi:[0,1]
	v_add_f32_e32 v33, 1.0, v33
	v_pk_mul_f32 v[24:25], v[24:25], s[76:77] op_sel_hi:[1,0]
	v_log_f32_e32 v33, v33
	s_nop 0
	v_mul_f32_e32 v40, 0x3f317217, v33
	v_fma_f32 v40, v33, s86, -v40
	v_fmac_f32_e32 v40, 0x3377d1cf, v33
	v_fmac_f32_e32 v40, 0x3f317217, v33
	v_mov_b32_e32 v33, v40
	v_add_f32_e32 v40, v30, v34
	v_mul_f32_e64 v30, |v38|, s84
	v_exp_f32_e32 v30, v30
	v_mul_f32_e64 v38, |v40|, s84
	v_exp_f32_e32 v38, v38
	v_pk_add_f32 v[28:29], v[28:29], v[32:33] neg_lo:[0,1] neg_hi:[0,1]
	v_add_f32_e32 v30, 1.0, v30
	v_add_f32_e32 v38, 1.0, v38
	v_pk_mul_f32 v[28:29], v[28:29], s[76:77] op_sel_hi:[1,0]
	v_log_f32_e32 v30, v30
	s_nop 0
	v_mul_f32_e32 v34, 0x3f317217, v30
	v_fma_f32 v34, v30, s86, -v34
	v_fmac_f32_e32 v34, 0x3377d1cf, v30
	v_fmac_f32_e32 v34, 0x3f317217, v30
	v_mov_b32_e32 v30, v34
	v_min_f32_e32 v30, 0, v40
	v_log_f32_e32 v38, v38
	s_nop 0
	v_mul_f32_e32 v40, 0x3f317217, v38
	v_fma_f32 v40, v38, s86, -v40
	v_fmac_f32_e32 v40, 0x3377d1cf, v38
	v_fmac_f32_e32 v40, 0x3f317217, v38
	v_mov_b32_e32 v38, v40
	v_add_f32_e32 v40, v31, v35
	v_mul_f32_e64 v31, |v39|, s84
	v_exp_f32_e32 v31, v31
	s_nop 0
	v_add_f32_e32 v31, 1.0, v31
	v_log_f32_e32 v31, v31
	s_nop 0
	v_mul_f32_e32 v35, 0x3f317217, v31
	v_fma_f32 v35, v31, s86, -v35
	v_fmac_f32_e32 v35, 0x3377d1cf, v31
	v_fmac_f32_e32 v35, 0x3f317217, v31
	v_mov_b32_e32 v31, v35
	v_pk_add_f32 v[26:27], v[26:27], v[34:35] neg_lo:[0,1] neg_hi:[0,1]
	v_mul_f32_e64 v34, |v40|, s84
	v_exp_f32_e32 v34, v34
	v_min_f32_e32 v31, 0, v40
	v_pk_mul_f32 v[26:27], v[26:27], s[76:77] op_sel_hi:[1,0]
	v_add_f32_e32 v34, 1.0, v34
	v_log_f32_e32 v34, v34
	s_nop 0
	v_mul_f32_e32 v35, 0x3f317217, v34
	v_fma_f32 v35, v34, s86, -v35
	v_fmac_f32_e32 v35, 0x3377d1cf, v34
	v_fmac_f32_e32 v35, 0x3f317217, v34
	v_mov_b32_e32 v34, v35
	v_mov_b32_e32 v39, v34
	v_pk_add_f32 v[30:31], v[30:31], v[38:39] neg_lo:[0,1] neg_hi:[0,1]
	v_pk_mul_f32 v[30:31], v[30:31], s[76:77] op_sel_hi:[1,0]
.LBB0_261:
	s_nop 0
	v_add_u32_e32 v34, 0xa0, v130
	v_mov_b64_e32 v[32:33], s[8:9]
	v_mad_i64_i32 v[32:33], s[0:1], v34, s88, v[32:33]
	v_lshl_add_u64 v[32:33], v[148:149], 1, v[32:33]
	s_and_b64 vcc, exec, s[6:7]
	v_cvt_pk_bf16_f32 v24, v24, v25
	v_cvt_pk_bf16_f32 v25, v26, v27
	v_cvt_pk_bf16_f32 v26, v28, v29
	v_cvt_pk_bf16_f32 v27, v30, v31
	global_store_dwordx4 v[32:33], v[24:27], off
	s_cbranch_vccnz .LBB0_263
	global_load_dwordx4 v[24:27], v[146:147], off offset:-1520
	global_load_dwordx4 v[28:31], v[146:147], off offset:-1536
	s_waitcnt vmcnt(0)
	v_add_f32_e32 v24, v20, v24
	v_add_f32_e32 v28, v16, v28
	v_mul_f32_e64 v20, |v28|, s84
	v_exp_f32_e32 v20, v20
	v_min_f32_e32 v16, 0, v28
	v_add_f32_e32 v29, v17, v29
	v_add_f32_e32 v25, v21, v25
	v_add_f32_e32 v20, 1.0, v20
	v_mul_f32_e64 v21, |v29|, s84
	v_exp_f32_e32 v21, v21
	v_log_f32_e32 v20, v20
	v_add_f32_e32 v21, 1.0, v21
	v_min_f32_e32 v17, 0, v29
	v_add_f32_e32 v30, v18, v30
	v_mul_f32_e32 v28, 0x3f317217, v20
	v_fma_f32 v28, v20, s86, -v28
	v_fmac_f32_e32 v28, 0x3377d1cf, v20
	v_fmac_f32_e32 v28, 0x3f317217, v20
	v_min_f32_e32 v18, 0, v30
	v_add_f32_e32 v31, v19, v31
	v_mov_b32_e32 v20, v28
	v_min_f32_e32 v20, 0, v24
	v_mul_f32_e64 v24, |v24|, s84
	v_exp_f32_e32 v24, v24
	v_min_f32_e32 v19, 0, v31
	v_add_f32_e32 v24, 1.0, v24
	v_log_f32_e32 v24, v24
	s_nop 0
	v_mul_f32_e32 v34, 0x3f317217, v24
	v_fma_f32 v34, v24, s86, -v34
	v_fmac_f32_e32 v34, 0x3377d1cf, v24
	v_fmac_f32_e32 v34, 0x3f317217, v24
	v_mov_b32_e32 v24, v34
	v_log_f32_e32 v21, v21
	s_nop 0
	v_mul_f32_e32 v29, 0x3f317217, v21
	v_fma_f32 v29, v21, s86, -v29
	v_fmac_f32_e32 v29, 0x3377d1cf, v21
	v_fmac_f32_e32 v29, 0x3f317217, v21
	v_mov_b32_e32 v21, v29
	v_min_f32_e32 v21, 0, v25
	v_mul_f32_e64 v25, |v25|, s84
	v_exp_f32_e32 v25, v25
	v_pk_add_f32 v[16:17], v[16:17], v[28:29] neg_lo:[0,1] neg_hi:[0,1]
	v_add_f32_e32 v25, 1.0, v25
	v_pk_mul_f32 v[16:17], v[16:17], s[76:77] op_sel_hi:[1,0]
	v_log_f32_e32 v25, v25
	s_nop 0
	v_mul_f32_e32 v34, 0x3f317217, v25
	v_fma_f32 v34, v25, s86, -v34
	v_fmac_f32_e32 v34, 0x3377d1cf, v25
	v_fmac_f32_e32 v34, 0x3f317217, v25
	v_mov_b32_e32 v25, v34
	v_add_f32_e32 v34, v22, v26
	v_mul_f32_e64 v22, |v30|, s84
	v_exp_f32_e32 v22, v22
	v_mul_f32_e64 v30, |v34|, s84
	v_exp_f32_e32 v30, v30
	v_pk_add_f32 v[20:21], v[20:21], v[24:25] neg_lo:[0,1] neg_hi:[0,1]
	v_add_f32_e32 v22, 1.0, v22
	v_add_f32_e32 v30, 1.0, v30
	v_pk_mul_f32 v[20:21], v[20:21], s[76:77] op_sel_hi:[1,0]
	v_log_f32_e32 v22, v22
	s_nop 0
	v_mul_f32_e32 v26, 0x3f317217, v22
	v_fma_f32 v26, v22, s86, -v26
	v_fmac_f32_e32 v26, 0x3377d1cf, v22
	v_fmac_f32_e32 v26, 0x3f317217, v22
	v_mov_b32_e32 v22, v26
	v_min_f32_e32 v22, 0, v34
	v_log_f32_e32 v30, v30
	s_nop 0
	v_mul_f32_e32 v34, 0x3f317217, v30
	v_fma_f32 v34, v30, s86, -v34
	v_fmac_f32_e32 v34, 0x3377d1cf, v30
	v_fmac_f32_e32 v34, 0x3f317217, v30
	v_mov_b32_e32 v30, v34
	v_add_f32_e32 v34, v23, v27
	v_mul_f32_e64 v23, |v31|, s84
	v_exp_f32_e32 v23, v23
	s_nop 0
	v_add_f32_e32 v23, 1.0, v23
	v_log_f32_e32 v23, v23
	s_nop 0
	v_mul_f32_e32 v27, 0x3f317217, v23
	v_fma_f32 v27, v23, s86, -v27
	v_fmac_f32_e32 v27, 0x3377d1cf, v23
	v_fmac_f32_e32 v27, 0x3f317217, v23
	v_mov_b32_e32 v23, v27
	v_pk_add_f32 v[18:19], v[18:19], v[26:27] neg_lo:[0,1] neg_hi:[0,1]
	v_mul_f32_e64 v26, |v34|, s84
	v_exp_f32_e32 v26, v26
	v_min_f32_e32 v23, 0, v34
	v_pk_mul_f32 v[18:19], v[18:19], s[76:77] op_sel_hi:[1,0]
	v_add_f32_e32 v26, 1.0, v26
	v_log_f32_e32 v26, v26
	s_nop 0
	v_mul_f32_e32 v27, 0x3f317217, v26
	v_fma_f32 v27, v26, s86, -v27
	v_fmac_f32_e32 v27, 0x3377d1cf, v26
	v_fmac_f32_e32 v27, 0x3f317217, v26
	v_mov_b32_e32 v26, v27
	v_mov_b32_e32 v31, v26
	v_pk_add_f32 v[22:23], v[22:23], v[30:31] neg_lo:[0,1] neg_hi:[0,1]
	v_pk_mul_f32 v[22:23], v[22:23], s[76:77] op_sel_hi:[1,0]
.LBB0_263:
	s_and_b64 vcc, exec, s[6:7]
	v_cvt_pk_bf16_f32 v16, v16, v17
	v_cvt_pk_bf16_f32 v17, v18, v19
	v_cvt_pk_bf16_f32 v18, v20, v21
	v_cvt_pk_bf16_f32 v19, v22, v23
	global_store_dwordx4 v[32:33], v[16:19], off offset:256
	s_cbranch_vccnz .LBB0_265
	global_load_dwordx4 v[16:19], v[146:147], off offset:-2032
	global_load_dwordx4 v[20:23], v[146:147], off offset:-2048
	s_waitcnt vmcnt(0)
	v_add_f32_e32 v16, v12, v16
	v_add_f32_e32 v20, v8, v20
	v_mul_f32_e64 v12, |v20|, s84
	v_exp_f32_e32 v12, v12
	v_min_f32_e32 v8, 0, v20
	v_add_f32_e32 v21, v9, v21
	v_add_f32_e32 v17, v13, v17
	v_add_f32_e32 v12, 1.0, v12
	v_mul_f32_e64 v13, |v21|, s84
	v_exp_f32_e32 v13, v13
	v_log_f32_e32 v12, v12
	v_add_f32_e32 v13, 1.0, v13
	v_min_f32_e32 v9, 0, v21
	v_add_f32_e32 v22, v10, v22
	v_mul_f32_e32 v20, 0x3f317217, v12
	v_fma_f32 v20, v12, s86, -v20
	v_fmac_f32_e32 v20, 0x3377d1cf, v12
	v_fmac_f32_e32 v20, 0x3f317217, v12
	v_min_f32_e32 v10, 0, v22
	v_add_f32_e32 v23, v11, v23
	v_mov_b32_e32 v12, v20
	v_min_f32_e32 v12, 0, v16
	v_mul_f32_e64 v16, |v16|, s84
	v_exp_f32_e32 v16, v16
	v_min_f32_e32 v11, 0, v23
	v_add_f32_e32 v16, 1.0, v16
	v_log_f32_e32 v16, v16
	s_nop 0
	v_mul_f32_e32 v24, 0x3f317217, v16
	v_fma_f32 v24, v16, s86, -v24
	v_fmac_f32_e32 v24, 0x3377d1cf, v16
	v_fmac_f32_e32 v24, 0x3f317217, v16
	v_mov_b32_e32 v16, v24
	v_log_f32_e32 v13, v13
	s_nop 0
	v_mul_f32_e32 v21, 0x3f317217, v13
	v_fma_f32 v21, v13, s86, -v21
	v_fmac_f32_e32 v21, 0x3377d1cf, v13
	v_fmac_f32_e32 v21, 0x3f317217, v13
	v_mov_b32_e32 v13, v21
	v_min_f32_e32 v13, 0, v17
	v_mul_f32_e64 v17, |v17|, s84
	v_exp_f32_e32 v17, v17
	v_pk_add_f32 v[8:9], v[8:9], v[20:21] neg_lo:[0,1] neg_hi:[0,1]
	v_add_f32_e32 v17, 1.0, v17
	v_pk_mul_f32 v[8:9], v[8:9], s[76:77] op_sel_hi:[1,0]
	v_log_f32_e32 v17, v17
	s_nop 0
	v_mul_f32_e32 v24, 0x3f317217, v17
	v_fma_f32 v24, v17, s86, -v24
	v_fmac_f32_e32 v24, 0x3377d1cf, v17
	v_fmac_f32_e32 v24, 0x3f317217, v17
	v_mov_b32_e32 v17, v24
	v_add_f32_e32 v24, v14, v18
	v_mul_f32_e64 v14, |v22|, s84
	v_exp_f32_e32 v14, v14
	v_mul_f32_e64 v22, |v24|, s84
	v_exp_f32_e32 v22, v22
	v_pk_add_f32 v[12:13], v[12:13], v[16:17] neg_lo:[0,1] neg_hi:[0,1]
	v_add_f32_e32 v14, 1.0, v14
	v_add_f32_e32 v22, 1.0, v22
	v_pk_mul_f32 v[12:13], v[12:13], s[76:77] op_sel_hi:[1,0]
	v_log_f32_e32 v14, v14
	s_nop 0
	v_mul_f32_e32 v18, 0x3f317217, v14
	v_fma_f32 v18, v14, s86, -v18
	v_fmac_f32_e32 v18, 0x3377d1cf, v14
	v_fmac_f32_e32 v18, 0x3f317217, v14
	v_mov_b32_e32 v14, v18
	v_min_f32_e32 v14, 0, v24
	v_log_f32_e32 v22, v22
	s_nop 0
	v_mul_f32_e32 v24, 0x3f317217, v22
	v_fma_f32 v24, v22, s86, -v24
	v_fmac_f32_e32 v24, 0x3377d1cf, v22
	v_fmac_f32_e32 v24, 0x3f317217, v22
	v_mov_b32_e32 v22, v24
	v_add_f32_e32 v24, v15, v19
	v_mul_f32_e64 v15, |v23|, s84
	v_exp_f32_e32 v15, v15
	s_nop 0
	v_add_f32_e32 v15, 1.0, v15
	v_log_f32_e32 v15, v15
	s_nop 0
	v_mul_f32_e32 v19, 0x3f317217, v15
	v_fma_f32 v19, v15, s86, -v19
	v_fmac_f32_e32 v19, 0x3377d1cf, v15
	v_fmac_f32_e32 v19, 0x3f317217, v15
	v_mov_b32_e32 v15, v19
	v_pk_add_f32 v[10:11], v[10:11], v[18:19] neg_lo:[0,1] neg_hi:[0,1]
	v_mul_f32_e64 v18, |v24|, s84
	v_exp_f32_e32 v18, v18
	v_min_f32_e32 v15, 0, v24
	v_pk_mul_f32 v[10:11], v[10:11], s[76:77] op_sel_hi:[1,0]
	v_add_f32_e32 v18, 1.0, v18
	v_log_f32_e32 v18, v18
	s_nop 0
	v_mul_f32_e32 v19, 0x3f317217, v18
	v_fma_f32 v19, v18, s86, -v19
	v_fmac_f32_e32 v19, 0x3377d1cf, v18
	v_fmac_f32_e32 v19, 0x3f317217, v18
	v_mov_b32_e32 v18, v19
	v_mov_b32_e32 v23, v18
	v_pk_add_f32 v[14:15], v[14:15], v[22:23] neg_lo:[0,1] neg_hi:[0,1]
	v_pk_mul_f32 v[14:15], v[14:15], s[76:77] op_sel_hi:[1,0]
.LBB0_265:
	s_nop 0
	v_add_u32_e32 v18, 0xb0, v130
	v_mov_b64_e32 v[16:17], s[8:9]
	v_mad_i64_i32 v[16:17], s[0:1], v18, s88, v[16:17]
	v_lshl_add_u64 v[16:17], v[148:149], 1, v[16:17]
	s_and_b64 vcc, exec, s[6:7]
	v_cvt_pk_bf16_f32 v8, v8, v9
	v_cvt_pk_bf16_f32 v9, v10, v11
	v_cvt_pk_bf16_f32 v10, v12, v13
	v_cvt_pk_bf16_f32 v11, v14, v15
	global_store_dwordx4 v[16:17], v[8:11], off
	s_cbranch_vccnz .LBB0_267
	global_load_dwordx4 v[8:11], v[146:147], off offset:-1520
	global_load_dwordx4 v[12:15], v[146:147], off offset:-1536
	s_waitcnt vmcnt(0)
	v_add_f32_e32 v8, v4, v8
	v_add_f32_e32 v12, v0, v12
	v_mul_f32_e64 v4, |v12|, s84
	v_exp_f32_e32 v4, v4
	v_min_f32_e32 v0, 0, v12
	v_add_f32_e32 v13, v1, v13
	v_add_f32_e32 v9, v5, v9
	v_add_f32_e32 v4, 1.0, v4
	v_mul_f32_e64 v5, |v13|, s84
	v_exp_f32_e32 v5, v5
	v_log_f32_e32 v4, v4
	v_add_f32_e32 v5, 1.0, v5
	v_min_f32_e32 v1, 0, v13
	v_add_f32_e32 v14, v2, v14
	v_mul_f32_e32 v12, 0x3f317217, v4
	v_fma_f32 v12, v4, s86, -v12
	v_fmac_f32_e32 v12, 0x3377d1cf, v4
	v_fmac_f32_e32 v12, 0x3f317217, v4
	v_min_f32_e32 v2, 0, v14
	v_add_f32_e32 v15, v3, v15
	v_mov_b32_e32 v4, v12
	v_min_f32_e32 v4, 0, v8
	v_mul_f32_e64 v8, |v8|, s84
	v_exp_f32_e32 v8, v8
	v_min_f32_e32 v3, 0, v15
	v_add_f32_e32 v8, 1.0, v8
	v_log_f32_e32 v8, v8
	s_nop 0
	v_mul_f32_e32 v18, 0x3f317217, v8
	v_fma_f32 v18, v8, s86, -v18
	v_fmac_f32_e32 v18, 0x3377d1cf, v8
	v_fmac_f32_e32 v18, 0x3f317217, v8
	v_mov_b32_e32 v8, v18
	v_log_f32_e32 v5, v5
	s_nop 0
	v_mul_f32_e32 v13, 0x3f317217, v5
	v_fma_f32 v13, v5, s86, -v13
	v_fmac_f32_e32 v13, 0x3377d1cf, v5
	v_fmac_f32_e32 v13, 0x3f317217, v5
	v_mov_b32_e32 v5, v13
	v_min_f32_e32 v5, 0, v9
	v_mul_f32_e64 v9, |v9|, s84
	v_exp_f32_e32 v9, v9
	v_pk_add_f32 v[0:1], v[0:1], v[12:13] neg_lo:[0,1] neg_hi:[0,1]
	v_add_f32_e32 v9, 1.0, v9
	v_pk_mul_f32 v[0:1], v[0:1], s[76:77] op_sel_hi:[1,0]
	v_log_f32_e32 v9, v9
	s_nop 0
	v_mul_f32_e32 v18, 0x3f317217, v9
	v_fma_f32 v18, v9, s86, -v18
	v_fmac_f32_e32 v18, 0x3377d1cf, v9
	v_fmac_f32_e32 v18, 0x3f317217, v9
	v_mov_b32_e32 v9, v18
	v_add_f32_e32 v18, v6, v10
	v_mul_f32_e64 v6, |v14|, s84
	v_exp_f32_e32 v6, v6
	v_mul_f32_e64 v14, |v18|, s84
	v_exp_f32_e32 v14, v14
	v_pk_add_f32 v[4:5], v[4:5], v[8:9] neg_lo:[0,1] neg_hi:[0,1]
	v_add_f32_e32 v6, 1.0, v6
	v_add_f32_e32 v14, 1.0, v14
	v_pk_mul_f32 v[4:5], v[4:5], s[76:77] op_sel_hi:[1,0]
	v_log_f32_e32 v6, v6
	s_nop 0
	v_mul_f32_e32 v10, 0x3f317217, v6
	v_fma_f32 v10, v6, s86, -v10
	v_fmac_f32_e32 v10, 0x3377d1cf, v6
	v_fmac_f32_e32 v10, 0x3f317217, v6
	v_mov_b32_e32 v6, v10
	v_min_f32_e32 v6, 0, v18
	v_log_f32_e32 v14, v14
	s_nop 0
	v_mul_f32_e32 v18, 0x3f317217, v14
	v_fma_f32 v18, v14, s86, -v18
	v_fmac_f32_e32 v18, 0x3377d1cf, v14
	v_fmac_f32_e32 v18, 0x3f317217, v14
	v_mov_b32_e32 v14, v18
	v_add_f32_e32 v18, v7, v11
	v_mul_f32_e64 v7, |v15|, s84
	v_exp_f32_e32 v7, v7
	s_nop 0
	v_add_f32_e32 v7, 1.0, v7
	v_log_f32_e32 v7, v7
	s_nop 0
	v_mul_f32_e32 v11, 0x3f317217, v7
	v_fma_f32 v11, v7, s86, -v11
	v_fmac_f32_e32 v11, 0x3377d1cf, v7
	v_fmac_f32_e32 v11, 0x3f317217, v7
	v_mov_b32_e32 v7, v11
	v_pk_add_f32 v[2:3], v[2:3], v[10:11] neg_lo:[0,1] neg_hi:[0,1]
	v_mul_f32_e64 v10, |v18|, s84
	v_exp_f32_e32 v10, v10
	v_min_f32_e32 v7, 0, v18
	v_pk_mul_f32 v[2:3], v[2:3], s[76:77] op_sel_hi:[1,0]
	v_add_f32_e32 v10, 1.0, v10
	v_log_f32_e32 v10, v10
	s_nop 0
	v_mul_f32_e32 v11, 0x3f317217, v10
	v_fma_f32 v11, v10, s86, -v11
	v_fmac_f32_e32 v11, 0x3377d1cf, v10
	v_fmac_f32_e32 v11, 0x3f317217, v10
	v_mov_b32_e32 v10, v11
	v_mov_b32_e32 v15, v10
	v_pk_add_f32 v[6:7], v[6:7], v[14:15] neg_lo:[0,1] neg_hi:[0,1]
	v_pk_mul_f32 v[6:7], v[6:7], s[76:77] op_sel_hi:[1,0]
.LBB0_267:
	s_andn2_b64 vcc, exec, s[4:5]
	s_mov_b64 s[0:1], -1
	v_cvt_pk_bf16_f32 v0, v0, v1
	v_cvt_pk_bf16_f32 v1, v2, v3
	v_cvt_pk_bf16_f32 v2, v4, v5
	v_cvt_pk_bf16_f32 v3, v6, v7
	global_store_dwordx4 v[16:17], v[0:3], off offset:256

.LBB0_327:
	s_or_b64 exec, exec, s[6:7]
	v_lshlrev_b32_e32 v0, 16, v13
	v_or_b32_sdwa v12, v0, v12 dst_sel:DWORD dst_unused:UNUSED_PAD src0_sel:DWORD src1_sel:WORD_0
	v_lshlrev_b32_e32 v0, 16, v15
	v_or_b32_sdwa v13, v0, v14 dst_sel:DWORD dst_unused:UNUSED_PAD src0_sel:DWORD src1_sel:WORD_0
	v_lshlrev_b32_e32 v0, 16, v103
	v_or_b32_sdwa v14, v0, v101 dst_sel:DWORD dst_unused:UNUSED_PAD src0_sel:DWORD src1_sel:WORD_0
	v_lshlrev_b32_e32 v0, 16, v106
	v_or_b32_sdwa v15, v0, v105 dst_sel:DWORD dst_unused:UNUSED_PAD src0_sel:DWORD src1_sel:WORD_0
	v_lshlrev_b32_e32 v0, 16, v17
	v_or_b32_sdwa v16, v0, v16 dst_sel:DWORD dst_unused:UNUSED_PAD src0_sel:DWORD src1_sel:WORD_0
	v_lshlrev_b32_e32 v0, 16, v19
	v_or_b32_sdwa v17, v0, v18 dst_sel:DWORD dst_unused:UNUSED_PAD src0_sel:DWORD src1_sel:WORD_0
	v_lshlrev_b32_e32 v0, 16, v99
	v_or_b32_sdwa v18, v0, v97 dst_sel:DWORD dst_unused:UNUSED_PAD src0_sel:DWORD src1_sel:WORD_0
	v_lshlrev_b32_e32 v0, 16, v104
	v_or_b32_sdwa v19, v0, v102 dst_sel:DWORD dst_unused:UNUSED_PAD src0_sel:DWORD src1_sel:WORD_0
	v_lshlrev_b32_e32 v0, 16, v35
	v_or_b32_sdwa v102, v0, v34 dst_sel:DWORD dst_unused:UNUSED_PAD src0_sel:DWORD src1_sel:WORD_0
	v_lshlrev_b32_e32 v0, 16, v90
	v_or_b32_sdwa v103, v0, v89 dst_sel:DWORD dst_unused:UNUSED_PAD src0_sel:DWORD src1_sel:WORD_0
	v_lshlrev_b32_e32 v0, 16, v94
	v_or_b32_sdwa v104, v0, v93 dst_sel:DWORD dst_unused:UNUSED_PAD src0_sel:DWORD src1_sel:WORD_0
	v_lshlrev_b32_e32 v0, 16, v100
	v_or_b32_sdwa v105, v0, v98 dst_sel:DWORD dst_unused:UNUSED_PAD src0_sel:DWORD src1_sel:WORD_0
	v_lshlrev_b32_e32 v0, 16, v86
	v_or_b32_sdwa v86, v0, v85 dst_sel:DWORD dst_unused:UNUSED_PAD src0_sel:DWORD src1_sel:WORD_0
	v_lshlrev_b32_e32 v0, 16, v88
	v_or_b32_sdwa v87, v0, v87 dst_sel:DWORD dst_unused:UNUSED_PAD src0_sel:DWORD src1_sel:WORD_0
	v_lshlrev_b32_e32 v0, 16, v92
	v_or_b32_sdwa v88, v0, v91 dst_sel:DWORD dst_unused:UNUSED_PAD src0_sel:DWORD src1_sel:WORD_0
	s_waitcnt lgkmcnt(0)
	s_barrier
	ds_read2_b32 v[34:35], v40 offset1:16
	ds_read2_b32 v[90:91], v43 offset1:16
	v_add_u32_e32 v11, 0x400, v43
	ds_read2_b32 v[92:93], v11 offset0:4 offset1:20
	v_lshlrev_b32_e32 v0, 16, v96
	v_or_b32_sdwa v89, v0, v95 dst_sel:DWORD dst_unused:UNUSED_PAD src0_sel:DWORD src1_sel:WORD_0
	s_waitcnt lgkmcnt(1)
	v_sub_f32_e32 v11, v34, v90
	v_mul_f32_e32 v11, 0x3fb8aa3b, v11
	v_exp_f32_e32 v94, v11
	s_waitcnt lgkmcnt(0)
	v_sub_f32_e32 v11, v34, v92
	v_mul_f32_e32 v11, 0x3fb8aa3b, v11
	v_exp_f32_e32 v95, v11
	v_add_u32_e32 v11, 0x800, v43
	ds_read2_b32 v[98:99], v11 offset0:8 offset1:24
	v_add_u32_e32 v11, 0xc00, v43
	ds_read2_b32 v[100:101], v11 offset0:12 offset1:28
	v_lshlrev_b32_e32 v97, 16, v78
	v_lshlrev_b32_e32 v96, 16, v73
	s_waitcnt lgkmcnt(1)
	v_sub_f32_e32 v11, v34, v98
	v_mul_f32_e32 v11, 0x3fb8aa3b, v11
	v_pk_mul_f32 v[94:95], v[94:95], v[96:97]
	v_exp_f32_e32 v96, v11
	s_waitcnt lgkmcnt(0)
	v_sub_f32_e32 v11, v34, v100
	v_mul_f32_e32 v11, 0x3fb8aa3b, v11
	v_lshlrev_b32_e32 v10, 16, v113
	v_exp_f32_e32 v97, v11
	v_add_u32_e32 v11, 0x1000, v43
	v_or_b32_sdwa v10, v10, v107 dst_sel:DWORD dst_unused:UNUSED_PAD src0_sel:DWORD src1_sel:WORD_0
	ds_read2_b32 v[106:107], v11 offset0:16 offset1:32
	v_lshlrev_b32_e32 v4, 16, v110
	v_lshlrev_b32_e32 v8, 16, v111
	v_add_u32_e32 v11, 0x1400, v43
	v_or_b32_sdwa v4, v4, v108 dst_sel:DWORD dst_unused:UNUSED_PAD src0_sel:DWORD src1_sel:WORD_0
	v_or_b32_sdwa v8, v8, v109 dst_sel:DWORD dst_unused:UNUSED_PAD src0_sel:DWORD src1_sel:WORD_0
	ds_read2_b32 v[108:109], v11 offset0:20 offset1:36
	s_waitcnt lgkmcnt(1)
	v_sub_f32_e32 v11, v34, v106
	v_lshlrev_b32_e32 v73, 16, v72
	v_lshlrev_b32_e32 v72, 16, v71
	v_mul_f32_e32 v11, 0x3fb8aa3b, v11
	v_pk_mul_f32 v[72:73], v[96:97], v[72:73]
	v_exp_f32_e32 v96, v11
	s_waitcnt lgkmcnt(0)
	v_sub_f32_e32 v11, v34, v108
	v_mul_f32_e32 v11, 0x3fb8aa3b, v11
	v_exp_f32_e32 v97, v11
	v_add_u32_e32 v11, 0x1800, v43
	ds_read2_b32 v[110:111], v11 offset0:24 offset1:40
	v_lshlrev_b32_e32 v0, 16, v114
	v_add_u32_e32 v11, 0x1c00, v43
	v_or_b32_sdwa v0, v0, v112 dst_sel:DWORD dst_unused:UNUSED_PAD src0_sel:DWORD src1_sel:WORD_0
	ds_read2_b32 v[112:113], v11 offset0:28 offset1:44
	s_waitcnt lgkmcnt(1)
	v_sub_f32_e32 v11, v34, v110
	v_mul_f32_e32 v11, 0x3fb8aa3b, v11
	v_exp_f32_e32 v114, v11
	v_lshlrev_b32_e32 v9, 16, v116
	s_waitcnt lgkmcnt(0)
	v_sub_f32_e32 v11, v34, v112
	v_mul_f32_e32 v11, 0x3fb8aa3b, v11
	v_or_b32_sdwa v9, v9, v115 dst_sel:DWORD dst_unused:UNUSED_PAD src0_sel:DWORD src1_sel:WORD_0
	v_exp_f32_e32 v115, v11
	v_sub_f32_e32 v11, v35, v91
	v_lshlrev_b32_e32 v71, 16, v70
	v_lshlrev_b32_e32 v70, 16, v69
	v_lshlrev_b32_e32 v69, 16, v68
	v_lshlrev_b32_e32 v68, 16, v67
	v_mul_f32_e32 v11, 0x3fb8aa3b, v11
	v_pk_mul_f32 v[70:71], v[96:97], v[70:71]
	v_pk_mul_f32 v[96:97], v[114:115], v[68:69]
	v_cvt_pk_bf16_f32 v69, v72, v73
	v_exp_f32_e32 v72, v11
	v_sub_f32_e32 v11, v35, v93
	v_mul_f32_e32 v11, 0x3fb8aa3b, v11
	v_exp_f32_e32 v73, v11
	v_sub_f32_e32 v11, v35, v99
	v_lshlrev_b32_e32 v67, 16, v66
	v_lshlrev_b32_e32 v66, 16, v65
	v_mul_f32_e32 v11, 0x3fb8aa3b, v11
	v_pk_mul_f32 v[66:67], v[72:73], v[66:67]
	v_exp_f32_e32 v72, v11
	v_sub_f32_e32 v11, v35, v101
	v_mul_f32_e32 v11, 0x3fb8aa3b, v11
	v_exp_f32_e32 v73, v11
	v_sub_f32_e32 v11, v35, v107
	v_mul_f32_e32 v11, 0x3fb8aa3b, v11
	v_exp_f32_e32 v90, v11
	v_sub_f32_e32 v11, v35, v109
	v_mul_f32_e32 v11, 0x3fb8aa3b, v11
	v_exp_f32_e32 v91, v11
	v_sub_f32_e32 v11, v35, v111
	v_mul_f32_e32 v11, 0x3fb8aa3b, v11
	v_cvt_pk_bf16_f32 v68, v94, v95
	v_exp_f32_e32 v94, v11
	v_sub_f32_e32 v11, v35, v113
	v_cvt_pk_bf16_f32 v70, v70, v71
	v_cvt_pk_bf16_f32 v71, v96, v97
	v_mul_f32_e32 v11, 0x3fb8aa3b, v11
	v_exp_f32_e32 v95, v11
	v_lshlrev_b32_e32 v63, 16, v63
	v_lshlrev_b32_e32 v62, 16, v62
	v_lshlrev_b32_e32 v61, 16, v61
	v_lshlrev_b32_e32 v60, 16, v60
	v_lshlrev_b32_e32 v99, 16, v52
	v_lshlrev_b32_e32 v98, 16, v51
	v_lshlrev_b32_e32 v51, 16, v75
	v_pk_mul_f32 v[72:73], v[72:73], v[62:63]
	v_pk_mul_f32 v[96:97], v[90:91], v[60:61]
	v_mfma_f32_16x16x32_bf16 v[60:63], v[68:71], v[12:15], 0
	v_mul_f32_e64 v106, v94, v98
	v_mul_f32_e64 v107, v95, v99
	v_cvt_pk_bf16_f32 v94, v66, v67
	v_lshlrev_b32_e32 v11, 16, v84
	v_mfma_f32_16x16x32_bf16 v[90:93], v[68:71], v[16:19], 0
	v_cvt_pk_bf16_f32 v95, v72, v73
	v_or_b32_sdwa v11, v11, v83 dst_sel:DWORD dst_unused:UNUSED_PAD src0_sel:DWORD src1_sel:WORD_0
	v_cvt_pk_bf16_f32 v96, v96, v97
	v_mfma_f32_16x16x32_bf16 v[98:101], v[68:71], v[102:105], 0
	v_cvt_pk_bf16_f32 v97, v106, v107
	v_lshlrev_b32_e32 v65, 16, v64
	v_lshlrev_b32_e32 v64, 16, v59
	v_mfma_f32_16x16x32_bf16 v[66:69], v[68:71], v[86:89], 0
	v_or_b32_sdwa v70, v51, v74 dst_sel:DWORD dst_unused:UNUSED_PAD src0_sel:DWORD src1_sel:WORD_0
	v_lshlrev_b32_e32 v51, 16, v77
	v_or_b32_sdwa v71, v51, v76 dst_sel:DWORD dst_unused:UNUSED_PAD src0_sel:DWORD src1_sel:WORD_0
	v_lshlrev_b32_e32 v51, 16, v80
	v_or_b32_sdwa v72, v51, v79 dst_sel:DWORD dst_unused:UNUSED_PAD src0_sel:DWORD src1_sel:WORD_0
	v_lshlrev_b32_e32 v51, 16, v82
	ds_read2_b32 v[82:83], v44 offset1:16
	v_or_b32_sdwa v73, v51, v81 dst_sel:DWORD dst_unused:UNUSED_PAD src0_sel:DWORD src1_sel:WORD_0
	v_add_u32_e32 v51, 0x8400, v43
	ds_read2_b32 v[84:85], v51 offset0:132 offset1:148
	v_mfma_f32_16x16x32_bf16 v[78:81], v[94:97], v[86:89], 0
	s_waitcnt lgkmcnt(1)
	v_sub_f32_e32 v51, v34, v82
	v_mul_f32_e32 v51, 0x3fb8aa3b, v51
	v_exp_f32_e32 v86, v51
	s_waitcnt lgkmcnt(0)
	v_sub_f32_e32 v51, v34, v84
	v_mul_f32_e32 v51, 0x3fb8aa3b, v51
	v_exp_f32_e32 v87, v51
	v_add_u32_e32 v51, 0x8800, v43
	ds_read2_b32 v[88:89], v51 offset0:136 offset1:152
	v_add_u32_e32 v51, 0x8c00, v43
	v_mfma_f32_16x16x32_bf16 v[12:15], v[94:97], v[12:15], 0
	v_mul_f32_e64 v64, v86, v64
	v_mul_f32_e64 v65, v87, v65
	v_lshlrev_b32_e32 v59, 16, v58
	v_lshlrev_b32_e32 v58, 16, v57
	v_mfma_f32_16x16x32_bf16 v[16:19], v[94:97], v[16:19], 0
	v_lshlrev_b32_e32 v57, 16, v56
	v_lshlrev_b32_e32 v56, 16, v55
	v_lshlrev_b32_e32 v55, 16, v54
	v_mfma_f32_16x16x32_bf16 v[74:77], v[94:97], v[102:105], 0
	ds_read2_b32 v[94:95], v51 offset0:140 offset1:156
	s_waitcnt lgkmcnt(1)
	v_sub_f32_e32 v51, v34, v88
	v_mul_f32_e32 v51, 0x3fb8aa3b, v51
	v_exp_f32_e32 v86, v51
	v_lshlrev_b32_e32 v54, 16, v53
	s_waitcnt lgkmcnt(0)
	v_sub_f32_e32 v51, v34, v94
	v_mul_f32_e32 v51, 0x3fb8aa3b, v51
	v_exp_f32_e32 v87, v51
	v_add_u32_e32 v51, 0x9000, v43
	ds_read2_b32 v[96:97], v51 offset0:144 offset1:160
	v_add_u32_e32 v51, 0x9400, v43
	ds_read2_b32 v[102:103], v51 offset0:148 offset1:164
	v_pk_mul_f32 v[58:59], v[86:87], v[58:59]
	v_cvt_pk_bf16_f32 v52, v64, v65
	s_waitcnt lgkmcnt(1)
	v_sub_f32_e32 v51, v34, v96
	v_mul_f32_e32 v51, 0x3fb8aa3b, v51
	v_exp_f32_e32 v86, v51
	s_waitcnt lgkmcnt(0)
	v_sub_f32_e32 v51, v34, v102
	v_mul_f32_e32 v51, 0x3fb8aa3b, v51
	v_exp_f32_e32 v87, v51
	v_add_u32_e32 v51, 0x9800, v43
	ds_read2_b32 v[104:105], v51 offset0:152 offset1:168
	v_add_u32_e32 v51, 0x9c00, v43
	ds_read2_b32 v[106:107], v51 offset0:156 offset1:172
	v_pk_mul_f32 v[56:57], v[86:87], v[56:57]
	v_cvt_pk_bf16_f32 v53, v58, v59
	s_waitcnt lgkmcnt(1)
	v_sub_f32_e32 v51, v34, v104
	v_mul_f32_e32 v51, 0x3fb8aa3b, v51
	s_waitcnt lgkmcnt(0)
	v_sub_f32_e32 v34, v34, v106
	v_mul_f32_e32 v34, 0x3fb8aa3b, v34
	v_exp_f32_e32 v108, v51
	v_exp_f32_e32 v109, v34
	v_sub_f32_e32 v34, v35, v83
	v_mul_f32_e32 v34, 0x3fb8aa3b, v34
	v_lshlrev_b32_e32 v51, 16, v50
	v_pk_mul_f32 v[86:87], v[108:109], v[54:55]
	v_cvt_pk_bf16_f32 v54, v56, v57
	v_exp_f32_e32 v56, v34
	v_sub_f32_e32 v34, v35, v85
	v_mul_f32_e32 v34, 0x3fb8aa3b, v34
	v_exp_f32_e32 v57, v34
	v_sub_f32_e32 v34, v35, v89
	v_lshlrev_b32_e32 v50, 16, v49
	v_mul_f32_e32 v34, 0x3fb8aa3b, v34
	v_pk_mul_f32 v[50:51], v[56:57], v[50:51]
	v_exp_f32_e32 v56, v34
	v_sub_f32_e32 v34, v35, v95
	v_mul_f32_e32 v34, 0x3fb8aa3b, v34
	v_exp_f32_e32 v57, v34
	v_sub_f32_e32 v34, v35, v97
	v_mul_f32_e32 v34, 0x3fb8aa3b, v34
	v_exp_f32_e32 v58, v34
	v_sub_f32_e32 v34, v35, v103
	v_mul_f32_e32 v34, 0x3fb8aa3b, v34
	v_cvt_pk_bf16_f32 v55, v86, v87
	v_exp_f32_e32 v59, v34
	v_sub_f32_e32 v34, v35, v105
	v_sub_f32_e32 v35, v35, v107
	v_mul_f32_e32 v34, 0x3fb8aa3b, v34
	v_mul_f32_e32 v35, 0x3fb8aa3b, v35
	v_exp_f32_e32 v34, v34
	v_exp_f32_e32 v35, v35
	v_lshlrev_b32_e32 v1, 16, v121
	v_lshlrev_b32_e32 v2, 16, v125
	v_lshlrev_b32_e32 v3, 16, v128
	v_or_b32_sdwa v1, v1, v119 dst_sel:DWORD dst_unused:UNUSED_PAD src0_sel:DWORD src1_sel:WORD_0
	v_or_b32_sdwa v2, v2, v123 dst_sel:DWORD dst_unused:UNUSED_PAD src0_sel:DWORD src1_sel:WORD_0
	v_or_b32_sdwa v3, v3, v127 dst_sel:DWORD dst_unused:UNUSED_PAD src0_sel:DWORD src1_sel:WORD_0
	v_lshlrev_b32_e32 v49, 16, v48
	v_lshlrev_b32_e32 v48, 16, v47
	v_lshlrev_b32_e32 v47, 16, v46
	v_lshlrev_b32_e32 v46, 16, v45
	v_pk_mul_f32 v[64:65], v[56:57], v[48:49]
	v_pk_mul_f32 v[84:85], v[58:59], v[46:47]
	v_mfma_f32_16x16x32_bf16 v[46:49], v[52:55], v[0:3], v[60:63]
	v_cvt_pk_bf16_f32 v82, v50, v51
	v_cvt_pk_bf16_f32 v83, v64, v65
	v_cvt_pk_bf16_f32 v84, v84, v85
	v_lshlrev_b32_e32 v61, 16, v33
	v_lshlrev_b32_e32 v60, 16, v31
	v_pk_mul_f32 v[34:35], v[34:35], v[60:61]
	s_mulk_i32 s14, 0x39c
	v_cvt_pk_bf16_f32 v85, v34, v35
	s_add_i32 s6, s10, s13
	v_lshlrev_b32_e32 v5, 16, v118
	v_lshlrev_b32_e32 v6, 16, v122
	v_lshlrev_b32_e32 v7, 16, v126
	s_add_i32 s6, s6, s14
	v_or_b32_sdwa v5, v5, v117 dst_sel:DWORD dst_unused:UNUSED_PAD src0_sel:DWORD src1_sel:WORD_0
	v_or_b32_sdwa v6, v6, v120 dst_sel:DWORD dst_unused:UNUSED_PAD src0_sel:DWORD src1_sel:WORD_0
	v_or_b32_sdwa v7, v7, v124 dst_sel:DWORD dst_unused:UNUSED_PAD src0_sel:DWORD src1_sel:WORD_0
	v_mfma_f32_16x16x32_bf16 v[60:63], v[52:55], v[8:11], v[98:101]
	s_ashr_i32 s7, s6, 31
	s_lshl_b64 s[8:9], s[6:7], 13
	v_mov_b32_e32 v31, v169
	v_mfma_f32_16x16x32_bf16 v[56:59], v[52:55], v[4:7], v[90:93]
	v_mov_b32_e32 v33, v169
	v_mfma_f32_16x16x32_bf16 v[50:53], v[52:55], v[70:73], v[66:69]
	v_mfma_f32_16x16x32_bf16 v[0:3], v[82:85], v[0:3], v[12:15]
	v_mfma_f32_16x16x32_bf16 v[4:7], v[82:85], v[4:7], v[16:19]
	v_mfma_f32_16x16x32_bf16 v[8:11], v[82:85], v[8:11], v[74:77]
	s_nop 1
	v_lshl_add_u64 v[16:17], v[24:25], 0, s[8:9]
	v_lshl_add_u64 v[18:19], v[16:17], 0, v[168:169]
	v_lshl_add_u64 v[34:35], v[16:17], 0, v[30:31]
	v_mfma_f32_16x16x32_bf16 v[12:15], v[82:85], v[70:73], v[78:81]
	global_store_dwordx4 v[18:19], v[46:49], off
	global_store_dwordx4 v[18:19], v[56:59], off offset:2048
	global_store_dwordx4 v[34:35], v[60:63], off
	v_lshl_add_u64 v[34:35], v[16:17], 0, v[32:33]
	v_lshl_add_u64 v[16:17], v[16:17], 0, 64
	global_store_dwordx4 v[34:35], v[50:53], off
	global_store_dwordx4 v[18:19], v[0:3], off offset:64
	global_store_dwordx4 v[18:19], v[4:7], off offset:2112
	s_nop 0
	v_lshl_add_u64 v[0:1], v[16:17], 0, v[30:31]
	global_store_dwordx4 v[0:1], v[8:11], off
	v_lshl_add_u64 v[0:1], v[16:17], 0, v[32:33]
	global_store_dwordx4 v[0:1], v[12:15], off
	s_and_saveexec_b64 s[8:9], s[4:5]
	s_cbranch_execz .LBB0_317
	ds_read_b32 v2, v41
	s_lshl_b64 s[6:7], s[6:7], 7
	v_lshl_add_u64 v[0:1], v[26:27], 0, s[6:7]
	s_waitcnt lgkmcnt(0)
	v_mul_f32_e32 v2, 0x3fb8aa3b, v2
	v_exp_f32_e32 v2, v2
	global_store_dword v[0:1], v2, off
	s_branch .LBB0_317

.Lf1_b:
	s_add_i32 s5, s5, s81
	s_cmpk_lt_i32 s2, 0x1000
	s_waitcnt vmcnt(0) lgkmcnt(0)
	v_perm_b32 v0, v53, v52, s89
	ds_read_b128 v[50:53], v49 offset:17408
	v_perm_b32 v1, v55, v54, s89
	v_perm_b32 v2, v57, v56, s89
	ds_read_b128 v[54:57], v49 offset:21760
	v_perm_b32 v3, v59, v58, s89
	ds_read_b128 v[58:61], v49 offset:26112
	s_nop 0
	v_mfma_f32_16x16x32_bf16 v[12:15], v[12:15], v[0:3], 0
	v_mfma_f32_16x16x32_bf16 v[16:19], v[16:19], v[0:3], 0
	v_mfma_f32_16x16x32_bf16 v[20:23], v[20:23], v[0:3], 0
	v_mfma_f32_16x16x32_bf16 v[24:27], v[24:27], v[0:3], 0
	s_waitcnt lgkmcnt(2)
	v_mfma_f32_16x16x32_bf16 v[50:53], v[50:53], v[0:3], 0
	s_waitcnt lgkmcnt(1)
	v_mfma_f32_16x16x32_bf16 v[54:57], v[54:57], v[0:3], 0
	s_waitcnt lgkmcnt(0)
	v_mfma_f32_16x16x32_bf16 v[58:61], v[58:61], v[0:3], 0
	v_mfma_f32_16x16x32_bf16 v[0:3], v[62:65], v[0:3], 0
	v_perm_b32 v63, v69, v68, s89
	v_perm_b32 v62, v67, v66, s89
	ds_read_b128 v[66:69], v49 offset:64
	v_perm_b32 v64, v71, v70, s89
	v_perm_b32 v65, v73, v72, s89
	v_perm_b32 v70, v5, v4, s89
	v_perm_b32 v71, v7, v6, s89
	ds_read_b128 v[4:7], v49 offset:17600
	s_waitcnt lgkmcnt(1)
	v_mfma_f32_16x16x32_bf16 v[12:15], v[66:69], v[62:65], v[12:15]
	ds_read_b128 v[66:69], v49 offset:4416
	v_perm_b32 v73, v11, v10, s89
	v_perm_b32 v72, v9, v8, s89
	s_waitcnt lgkmcnt(0)
	v_mfma_f32_16x16x32_bf16 v[16:19], v[66:69], v[62:65], v[16:19]
	ds_read_b128 v[66:69], v49 offset:8768
	s_waitcnt lgkmcnt(0)
	v_mfma_f32_16x16x32_bf16 v[20:23], v[66:69], v[62:65], v[20:23]
	ds_read_b128 v[66:69], v49 offset:13120
	s_waitcnt lgkmcnt(0)
	v_mfma_f32_16x16x32_bf16 v[24:27], v[66:69], v[62:65], v[24:27]
	ds_read_b128 v[66:69], v49 offset:17472
	s_waitcnt lgkmcnt(0)
	v_mfma_f32_16x16x32_bf16 v[50:53], v[66:69], v[62:65], v[50:53]
	ds_read_b128 v[66:69], v49 offset:21824
	s_waitcnt lgkmcnt(0)
	v_mfma_f32_16x16x32_bf16 v[54:57], v[66:69], v[62:65], v[54:57]
	ds_read_b128 v[66:69], v49 offset:26176
	s_waitcnt lgkmcnt(0)
	v_mfma_f32_16x16x32_bf16 v[58:61], v[66:69], v[62:65], v[58:61]
	ds_read_b128 v[66:69], v49 offset:30528
	s_waitcnt lgkmcnt(0)
	v_mfma_f32_16x16x32_bf16 v[0:3], v[66:69], v[62:65], v[0:3]
	ds_read_b128 v[66:69], v49 offset:128
	v_perm_b32 v65, v81, v80, s89
	v_perm_b32 v64, v79, v78, s89
	v_perm_b32 v63, v77, v76, s89
	v_perm_b32 v62, v75, v74, s89
	s_waitcnt lgkmcnt(0)
	s_nop 0
	v_mfma_f32_16x16x32_bf16 v[12:15], v[66:69], v[62:65], v[12:15]
	ds_read_b128 v[66:69], v49 offset:4480
	s_waitcnt lgkmcnt(0)
	v_mfma_f32_16x16x32_bf16 v[16:19], v[66:69], v[62:65], v[16:19]
	ds_read_b128 v[66:69], v49 offset:8832
	s_waitcnt lgkmcnt(0)
	v_mfma_f32_16x16x32_bf16 v[20:23], v[66:69], v[62:65], v[20:23]
	ds_read_b128 v[66:69], v49 offset:13184
	s_waitcnt lgkmcnt(0)
	v_mfma_f32_16x16x32_bf16 v[66:69], v[66:69], v[62:65], v[24:27]
	s_nop 2
	ds_read_b128 v[24:27], v49 offset:17536
	s_waitcnt lgkmcnt(0)
	v_mfma_f32_16x16x32_bf16 v[50:53], v[24:27], v[62:65], v[50:53]
	ds_read_b128 v[24:27], v49 offset:21888
	s_waitcnt lgkmcnt(0)
	v_mfma_f32_16x16x32_bf16 v[54:57], v[24:27], v[62:65], v[54:57]
	ds_read_b128 v[24:27], v49 offset:26240
	s_waitcnt lgkmcnt(0)
	v_mfma_f32_16x16x32_bf16 v[58:61], v[24:27], v[62:65], v[58:61]
	ds_read_b128 v[24:27], v49 offset:30592
	s_waitcnt lgkmcnt(0)
	v_mfma_f32_16x16x32_bf16 v[62:65], v[24:27], v[62:65], v[0:3]
	s_nop 2
	ds_read_b128 v[0:3], v49 offset:192
	v_mfma_f32_16x16x32_bf16 v[50:53], v[4:7], v[70:73], v[50:53]
	ds_read_b128 v[4:7], v49 offset:21952
	s_waitcnt lgkmcnt(1)
	v_mfma_f32_16x16x32_bf16 v[24:27], v[0:3], v[70:73], v[12:15]
	ds_read_b128 v[0:3], v49 offset:4544
	s_waitcnt lgkmcnt(0)
	v_mfma_f32_16x16x32_bf16 v[16:19], v[0:3], v[70:73], v[16:19]
	ds_read_b128 v[0:3], v49 offset:8896
	s_waitcnt lgkmcnt(0)
	v_mfma_f32_16x16x32_bf16 v[8:11], v[0:3], v[70:73], v[20:23]
	ds_read_b128 v[0:3], v49 offset:13248
	v_mfma_f32_16x16x32_bf16 v[20:23], v[4:7], v[70:73], v[54:57]
	ds_read_b128 v[4:7], v49 offset:26304
	s_nop 1
	v_mul_u32_u24_e32 v54, s6, v32
	v_cvt_f32_u32_e32 v54, v54
	s_waitcnt lgkmcnt(0)
	v_mfma_f32_16x16x32_bf16 v[12:15], v[4:7], v[70:73], v[58:61]
	v_mul_f32_e32 v54, 0x39000000, v54
	v_cos_f32_e32 v55, v54
	v_sin_f32_e32 v54, v54
	ds_read_b128 v[4:7], v49 offset:30656
	s_waitcnt lgkmcnt(0)
	v_mfma_f32_16x16x32_bf16 v[4:7], v[4:7], v[70:73], v[62:65]
	v_mul_f32_e32 v56, v54, v50
	v_fmac_f32_e32 v56, v55, v24
	v_mul_f32_e32 v24, v54, v24
	v_or_b32_e32 v54, s7, v33
	v_fma_f32 v24, v55, v50, -v24
	v_ashrrev_i32_e32 v55, 31, v54
	v_lshlrev_b64 v[54:55], 16, v[54:55]
	v_bfe_u32 v50, v56, 16, 1
	v_lshl_add_u64 v[54:55], v[30:31], 0, v[54:55]
	v_add3_u32 v50, v56, v50, s77
	global_store_short_d16_hi v[54:55], v50, off
	v_bfe_u32 v50, v24, 16, 1
	v_add_co_u32_e32 v54, vcc, s49, v54
	v_add3_u32 v24, v24, v50, s77
	s_nop 0
	v_addc_co_u32_e32 v55, vcc, 0, v55, vcc
	v_mad_u32_u24 v50, s6, v32, s6
	global_store_short_d16_hi v[54:55], v24, off
	v_cvt_f32_u32_e32 v24, v50
	v_add_u32_e32 v50, s6, v50
	v_mfma_f32_16x16x32_bf16 v[0:3], v[0:3], v[70:73], v[66:69]
	v_mul_f32_e32 v24, 0x39000000, v24
	v_cos_f32_e32 v54, v24
	v_sin_f32_e32 v24, v24
	s_nop 0
	v_mul_f32_e32 v55, v24, v51
	v_mul_f32_e32 v24, v24, v25
	v_fma_f32 v51, v54, v51, -v24
	v_or_b32_e32 v24, s7, v34
	v_fmac_f32_e32 v55, v54, v25
	v_ashrrev_i32_e32 v25, 31, v24
	v_lshlrev_b64 v[24:25], 16, v[24:25]
	v_bfe_u32 v54, v55, 16, 1
	v_lshl_add_u64 v[24:25], v[30:31], 0, v[24:25]
	v_add3_u32 v54, v55, v54, s77
	global_store_short_d16_hi v[24:25], v54, off
	v_bfe_u32 v54, v51, 16, 1
	v_add_co_u32_e32 v24, vcc, s49, v24
	v_add3_u32 v51, v51, v54, s77
	s_nop 0
	v_addc_co_u32_e32 v25, vcc, 0, v25, vcc
	global_store_short_d16_hi v[24:25], v51, off
	v_cvt_f32_u32_e32 v24, v50
	v_mul_f32_e32 v24, 0x39000000, v24
	v_cos_f32_e32 v25, v24
	v_sin_f32_e32 v24, v24
	s_nop 0
	v_mul_f32_e32 v51, v24, v52
	v_mul_f32_e32 v24, v24, v26
	v_fmac_f32_e32 v51, v25, v26
	v_fma_f32 v26, v25, v52, -v24
	v_or_b32_e32 v24, s7, v35
	v_ashrrev_i32_e32 v25, 31, v24
	v_lshlrev_b64 v[24:25], 16, v[24:25]
	v_bfe_u32 v52, v51, 16, 1
	v_lshl_add_u64 v[24:25], v[30:31], 0, v[24:25]
	v_add3_u32 v51, v51, v52, s77
	global_store_short_d16_hi v[24:25], v51, off
	v_bfe_u32 v51, v26, 16, 1
	v_add_co_u32_e32 v24, vcc, s49, v24
	v_add3_u32 v26, v26, v51, s77
	s_nop 0
	v_addc_co_u32_e32 v25, vcc, 0, v25, vcc
	global_store_short_d16_hi v[24:25], v26, off
	v_add_u32_e32 v26, s6, v50
	v_cvt_f32_u32_e32 v24, v26
	v_add_u32_e32 v26, s8, v26
	v_mul_f32_e32 v24, 0x39000000, v24
	v_cos_f32_e32 v25, v24
	v_sin_f32_e32 v24, v24
	s_nop 0
	v_mul_f32_e32 v50, v24, v53
	v_mul_f32_e32 v24, v24, v27
	v_fmac_f32_e32 v50, v25, v27
	v_fma_f32 v27, v25, v53, -v24
	v_or_b32_e32 v24, s7, v36
	v_ashrrev_i32_e32 v25, 31, v24
	v_lshlrev_b64 v[24:25], 16, v[24:25]
	v_bfe_u32 v51, v50, 16, 1
	v_lshl_add_u64 v[24:25], v[30:31], 0, v[24:25]
	v_add3_u32 v50, v50, v51, s77
	global_store_short_d16_hi v[24:25], v50, off
	v_bfe_u32 v50, v27, 16, 1
	v_add_co_u32_e32 v24, vcc, s49, v24
	v_add3_u32 v27, v27, v50, s77
	s_nop 0
	v_addc_co_u32_e32 v25, vcc, 0, v25, vcc
	global_store_short_d16_hi v[24:25], v27, off
	v_cvt_f32_u32_e32 v24, v26
	v_mul_f32_e32 v24, 0x39000000, v24
	v_cos_f32_e32 v25, v24
	v_sin_f32_e32 v24, v24
	s_nop 0
	v_mul_f32_e32 v27, v24, v20
	v_fmac_f32_e32 v27, v25, v16
	v_mul_f32_e32 v16, v24, v16
	v_or_b32_e32 v24, s7, v37
	v_fma_f32 v16, v25, v20, -v16
	v_ashrrev_i32_e32 v25, 31, v24
	v_lshlrev_b64 v[24:25], 16, v[24:25]
	v_bfe_u32 v20, v27, 16, 1
	v_lshl_add_u64 v[24:25], v[30:31], 0, v[24:25]
	v_add3_u32 v20, v27, v20, s77
	global_store_short_d16_hi v[24:25], v20, off
	v_bfe_u32 v20, v16, 16, 1
	v_add_co_u32_e32 v24, vcc, s49, v24
	v_add3_u32 v16, v16, v20, s77
	s_nop 0
	v_addc_co_u32_e32 v25, vcc, 0, v25, vcc
	v_add_u32_e32 v20, s6, v26
	global_store_short_d16_hi v[24:25], v16, off
	v_cvt_f32_u32_e32 v16, v20
	v_add_u32_e32 v20, s6, v20
	v_mul_f32_e32 v16, 0x39000000, v16
	v_cos_f32_e32 v24, v16
	v_sin_f32_e32 v16, v16
	s_nop 0
	v_mul_f32_e32 v25, v16, v21
	v_mul_f32_e32 v16, v16, v17
	v_fma_f32 v21, v24, v21, -v16
	v_or_b32_e32 v16, s7, v38
	v_fmac_f32_e32 v25, v24, v17
	v_ashrrev_i32_e32 v17, 31, v16
	v_lshlrev_b64 v[16:17], 16, v[16:17]
	v_bfe_u32 v24, v25, 16, 1
	v_lshl_add_u64 v[16:17], v[30:31], 0, v[16:17]
	v_add3_u32 v24, v25, v24, s77
	global_store_short_d16_hi v[16:17], v24, off
	v_bfe_u32 v24, v21, 16, 1
	v_add_co_u32_e32 v16, vcc, s49, v16
	v_add3_u32 v21, v21, v24, s77
	s_nop 0
	v_addc_co_u32_e32 v17, vcc, 0, v17, vcc
	global_store_short_d16_hi v[16:17], v21, off
	v_cvt_f32_u32_e32 v16, v20
	v_mul_f32_e32 v16, 0x39000000, v16
	v_cos_f32_e32 v17, v16
	v_sin_f32_e32 v16, v16
	s_nop 0
	v_mul_f32_e32 v21, v16, v22
	v_mul_f32_e32 v16, v16, v18
	v_fmac_f32_e32 v21, v17, v18
	v_fma_f32 v18, v17, v22, -v16
	v_or_b32_e32 v16, s7, v39
	v_ashrrev_i32_e32 v17, 31, v16
	v_lshlrev_b64 v[16:17], 16, v[16:17]
	v_bfe_u32 v22, v21, 16, 1
	v_lshl_add_u64 v[16:17], v[30:31], 0, v[16:17]
	v_add3_u32 v21, v21, v22, s77
	global_store_short_d16_hi v[16:17], v21, off
	v_bfe_u32 v21, v18, 16, 1
	v_add_co_u32_e32 v16, vcc, s49, v16
	v_add3_u32 v18, v18, v21, s77
	s_nop 0
	v_addc_co_u32_e32 v17, vcc, 0, v17, vcc
	global_store_short_d16_hi v[16:17], v18, off
	v_add_u32_e32 v18, s6, v20
	v_cvt_f32_u32_e32 v16, v18
	v_add_u32_e32 v18, s8, v18
	v_mul_f32_e32 v16, 0x39000000, v16
	v_cos_f32_e32 v17, v16
	v_sin_f32_e32 v16, v16
	s_nop 0
	v_mul_f32_e32 v20, v16, v23
	v_mul_f32_e32 v16, v16, v19
	v_fmac_f32_e32 v20, v17, v19
	v_fma_f32 v19, v17, v23, -v16
	v_or_b32_e32 v16, s7, v40
	v_ashrrev_i32_e32 v17, 31, v16
	v_lshlrev_b64 v[16:17], 16, v[16:17]
	v_bfe_u32 v21, v20, 16, 1
	v_lshl_add_u64 v[16:17], v[30:31], 0, v[16:17]
	v_add3_u32 v20, v20, v21, s77
	global_store_short_d16_hi v[16:17], v20, off
	v_bfe_u32 v20, v19, 16, 1
	v_add_co_u32_e32 v16, vcc, s49, v16
	v_add3_u32 v19, v19, v20, s77
	s_nop 0
	v_addc_co_u32_e32 v17, vcc, 0, v17, vcc
	global_store_short_d16_hi v[16:17], v19, off
	v_cvt_f32_u32_e32 v16, v18
	v_mul_f32_e32 v16, 0x39000000, v16
	v_cos_f32_e32 v17, v16
	v_sin_f32_e32 v16, v16
	s_nop 0
	v_mul_f32_e32 v19, v16, v12
	v_fmac_f32_e32 v19, v17, v8
	v_mul_f32_e32 v8, v16, v8
	v_or_b32_e32 v16, s7, v41
	v_fma_f32 v8, v17, v12, -v8
	v_ashrrev_i32_e32 v17, 31, v16
	v_lshlrev_b64 v[16:17], 16, v[16:17]
	v_bfe_u32 v12, v19, 16, 1
	v_lshl_add_u64 v[16:17], v[30:31], 0, v[16:17]
	v_add3_u32 v12, v19, v12, s77
	global_store_short_d16_hi v[16:17], v12, off
	v_bfe_u32 v12, v8, 16, 1
	v_add_co_u32_e32 v16, vcc, s49, v16
	v_add3_u32 v8, v8, v12, s77
	s_nop 0
	v_addc_co_u32_e32 v17, vcc, 0, v17, vcc
	v_add_u32_e32 v12, s6, v18
	global_store_short_d16_hi v[16:17], v8, off
	v_cvt_f32_u32_e32 v8, v12
	v_add_u32_e32 v12, s6, v12
	v_mul_f32_e32 v8, 0x39000000, v8
	v_cos_f32_e32 v16, v8
	v_sin_f32_e32 v8, v8
	s_nop 0
	v_mul_f32_e32 v17, v8, v13
	v_mul_f32_e32 v8, v8, v9
	v_fma_f32 v13, v16, v13, -v8
	v_or_b32_e32 v8, s7, v42
	v_fmac_f32_e32 v17, v16, v9
	v_ashrrev_i32_e32 v9, 31, v8
	v_lshlrev_b64 v[8:9], 16, v[8:9]
	v_bfe_u32 v16, v17, 16, 1
	v_lshl_add_u64 v[8:9], v[30:31], 0, v[8:9]
	v_add3_u32 v16, v17, v16, s77
	global_store_short_d16_hi v[8:9], v16, off
	v_bfe_u32 v16, v13, 16, 1
	v_add_co_u32_e32 v8, vcc, s49, v8
	v_add3_u32 v13, v13, v16, s77
	s_nop 0
	v_addc_co_u32_e32 v9, vcc, 0, v9, vcc
	global_store_short_d16_hi v[8:9], v13, off
	v_cvt_f32_u32_e32 v8, v12
	v_mul_f32_e32 v8, 0x39000000, v8
	v_cos_f32_e32 v9, v8
	v_sin_f32_e32 v8, v8
	s_nop 0
	v_mul_f32_e32 v13, v8, v14
	v_mul_f32_e32 v8, v8, v10
	v_fmac_f32_e32 v13, v9, v10
	v_fma_f32 v10, v9, v14, -v8
	v_or_b32_e32 v8, s7, v43
	v_ashrrev_i32_e32 v9, 31, v8
	v_lshlrev_b64 v[8:9], 16, v[8:9]
	v_bfe_u32 v14, v13, 16, 1
	v_lshl_add_u64 v[8:9], v[30:31], 0, v[8:9]
	v_add3_u32 v13, v13, v14, s77
	global_store_short_d16_hi v[8:9], v13, off
	v_bfe_u32 v13, v10, 16, 1
	v_add_co_u32_e32 v8, vcc, s49, v8
	v_add3_u32 v10, v10, v13, s77
	s_nop 0
	v_addc_co_u32_e32 v9, vcc, 0, v9, vcc
	global_store_short_d16_hi v[8:9], v10, off
	v_add_u32_e32 v10, s6, v12
	v_cvt_f32_u32_e32 v8, v10
	v_add_u32_e32 v10, s8, v10
	v_mul_f32_e32 v8, 0x39000000, v8
	v_cos_f32_e32 v9, v8
	v_sin_f32_e32 v8, v8
	s_nop 0
	v_mul_f32_e32 v12, v8, v15
	v_mul_f32_e32 v8, v8, v11
	v_fmac_f32_e32 v12, v9, v11
	v_fma_f32 v11, v9, v15, -v8
	v_or_b32_e32 v8, s7, v44
	v_ashrrev_i32_e32 v9, 31, v8
	v_lshlrev_b64 v[8:9], 16, v[8:9]
	v_bfe_u32 v13, v12, 16, 1
	v_lshl_add_u64 v[8:9], v[30:31], 0, v[8:9]
	v_add3_u32 v12, v12, v13, s77
	global_store_short_d16_hi v[8:9], v12, off
	v_bfe_u32 v12, v11, 16, 1
	v_add_co_u32_e32 v8, vcc, s49, v8
	v_add3_u32 v11, v11, v12, s77
	s_nop 0
	v_addc_co_u32_e32 v9, vcc, 0, v9, vcc
	global_store_short_d16_hi v[8:9], v11, off
	v_cvt_f32_u32_e32 v8, v10
	v_mul_f32_e32 v8, 0x39000000, v8
	v_cos_f32_e32 v9, v8
	v_sin_f32_e32 v8, v8
	s_nop 0
	v_mul_f32_e32 v11, v8, v4
	v_fmac_f32_e32 v11, v9, v0
	v_mul_f32_e32 v0, v8, v0
	v_or_b32_e32 v8, s7, v45
	v_fma_f32 v0, v9, v4, -v0
	v_ashrrev_i32_e32 v9, 31, v8
	v_lshlrev_b64 v[8:9], 16, v[8:9]
	v_bfe_u32 v4, v11, 16, 1
	v_lshl_add_u64 v[8:9], v[30:31], 0, v[8:9]
	v_add3_u32 v4, v11, v4, s77
	global_store_short_d16_hi v[8:9], v4, off
	v_bfe_u32 v4, v0, 16, 1
	v_add_co_u32_e32 v8, vcc, s49, v8
	v_add3_u32 v0, v0, v4, s77
	s_nop 0
	v_addc_co_u32_e32 v9, vcc, 0, v9, vcc
	v_add_u32_e32 v4, s6, v10
	global_store_short_d16_hi v[8:9], v0, off
	v_cvt_f32_u32_e32 v0, v4
	v_add_u32_e32 v4, s6, v4
	v_mul_f32_e32 v0, 0x39000000, v0
	v_cos_f32_e32 v8, v0
	v_sin_f32_e32 v0, v0
	s_nop 0
	v_mul_f32_e32 v9, v0, v5
	v_mul_f32_e32 v0, v0, v1
	v_fma_f32 v5, v8, v5, -v0
	v_or_b32_e32 v0, s7, v46
	v_fmac_f32_e32 v9, v8, v1
	v_ashrrev_i32_e32 v1, 31, v0
	v_lshlrev_b64 v[0:1], 16, v[0:1]
	v_bfe_u32 v8, v9, 16, 1
	v_lshl_add_u64 v[0:1], v[30:31], 0, v[0:1]
	v_add3_u32 v8, v9, v8, s77
	global_store_short_d16_hi v[0:1], v8, off
	v_bfe_u32 v8, v5, 16, 1
	v_add_co_u32_e32 v0, vcc, s49, v0
	v_add3_u32 v5, v5, v8, s77
	s_nop 0
	v_addc_co_u32_e32 v1, vcc, 0, v1, vcc
	global_store_short_d16_hi v[0:1], v5, off
	v_cvt_f32_u32_e32 v0, v4
	v_mul_f32_e32 v0, 0x39000000, v0
	v_cos_f32_e32 v1, v0
	v_sin_f32_e32 v0, v0
	s_nop 0
	v_mul_f32_e32 v5, v0, v6
	v_mul_f32_e32 v0, v0, v2
	v_fmac_f32_e32 v5, v1, v2
	v_fma_f32 v2, v1, v6, -v0
	v_or_b32_e32 v0, s7, v47
	v_ashrrev_i32_e32 v1, 31, v0
	v_lshlrev_b64 v[0:1], 16, v[0:1]
	v_bfe_u32 v6, v5, 16, 1
	v_lshl_add_u64 v[0:1], v[30:31], 0, v[0:1]
	v_add3_u32 v5, v5, v6, s77
	global_store_short_d16_hi v[0:1], v5, off
	v_bfe_u32 v5, v2, 16, 1
	v_add_co_u32_e32 v0, vcc, s49, v0
	v_add3_u32 v2, v2, v5, s77
	s_nop 0
	v_addc_co_u32_e32 v1, vcc, 0, v1, vcc
	global_store_short_d16_hi v[0:1], v2, off
	v_add_u32_e32 v0, s6, v4
	v_cvt_f32_u32_e32 v0, v0
	v_mul_f32_e32 v0, 0x39000000, v0
	v_cos_f32_e32 v1, v0
	v_sin_f32_e32 v0, v0
	s_nop 0
	v_mul_f32_e32 v2, v0, v7
	v_mul_f32_e32 v0, v0, v3
	v_fmac_f32_e32 v2, v1, v3
	v_fma_f32 v3, v1, v7, -v0
	v_or_b32_e32 v0, s7, v48
	v_ashrrev_i32_e32 v1, 31, v0
	v_lshlrev_b64 v[0:1], 16, v[0:1]
	v_bfe_u32 v4, v2, 16, 1
	v_lshl_add_u64 v[0:1], v[30:31], 0, v[0:1]
	v_add3_u32 v2, v2, v4, s77
	global_store_short_d16_hi v[0:1], v2, off
	v_bfe_u32 v2, v3, 16, 1
	v_add_co_u32_e32 v0, vcc, 0x10000, v0
	v_add3_u32 v2, v3, v2, s77
	s_nop 0
	v_addc_co_u32_e32 v1, vcc, 0, v1, vcc
	global_store_short_d16_hi v[0:1], v2, off
	s_cbranch_scc1 .LBB0_334

.LBB0_338:
	s_add_i32 s6, s22, 0xf8
	s_and_b32 s6, s6, 0xff
	s_or_b32 s10, s6, 0x100
	s_cmpk_lt_i32 s22, 0x100
	s_cselect_b64 s[6:7], -1, 0
	s_and_b64 s[8:9], s[6:7], exec
	s_cselect_b32 s8, s22, s10
	s_mov_b32 s9, s51
	s_cmpk_lt_i32 s8, 0x108
	s_cselect_b64 s[10:11], -1, 0
	s_cmp_eq_u32 s9, 0
	v_cndmask_b32_e64 v0, 0, 1, s[6:7]
	v_cndmask_b32_e64 v1, 0, 1, s[10:11]
	s_cselect_b64 vcc, -1, 0
	v_cndmask_b32_e32 v0, v0, v1, vcc
	v_and_b32_e32 v0, 1, v0
	v_cmp_eq_u32_e32 vcc, 0, v0
	s_cbranch_vccnz .LBB0_337
	s_lshl_b32 s8, s8, 6
	s_add_i32 s9, s8, 0x7fffc000
	s_and_b32 s9, s9, 0x7fffff00
	s_addk_i32 s9, 0x4000
	s_and_b32 s10, s8, 0xc0
	s_and_b64 s[6:7], s[6:7], exec
	s_cselect_b32 s6, 0, s10
	s_cselect_b32 s24, 64, 0x100
	v_add_u32_e32 v129, s6, v107
	s_cselect_b32 s23, s8, s9
	v_add_u32_e32 v104, -1, v129
	s_add_i32 s8, s24, -1
	v_min_u32_e32 v0, s8, v104
	v_cmp_lt_i32_e32 vcc, 0, v129
	v_or_b32_e32 v127, 1, v129
	v_or_b32_e32 v125, 2, v129
	v_cndmask_b32_e32 v0, 0, v0, vcc
	v_add_u32_e32 v0, s23, v0
	v_mad_i64_i32 v[0:1], s[6:7], v0, s88, v[92:93]
	v_add_co_u32_e32 v2, vcc, s33, v0
	v_min_u32_e32 v4, s8, v125
	s_nop 0
	v_addc_co_u32_e32 v3, vcc, 0, v1, vcc
	flat_load_dwordx4 v[64:67], v[0:1] offset:3072
	flat_load_dwordx4 v[68:71], v[2:3]
	v_min_u32_e32 v0, s8, v129
	v_cmp_gt_i32_e32 vcc, 0, v129
	v_min_u32_e32 v2, s8, v127
	v_or_b32_e32 v123, 3, v129
	v_cndmask_b32_e64 v0, v0, 0, vcc
	v_add_u32_e32 v0, s23, v0
	v_mad_i64_i32 v[0:1], s[6:7], v0, s88, v[92:93]
	v_cndmask_b32_e64 v2, v2, 0, vcc
	v_add_co_u32_e64 v56, s[6:7], s33, v0
	v_add_u32_e32 v2, s23, v2
	s_nop 0
	v_addc_co_u32_e64 v57, s[6:7], 0, v1, s[6:7]
	v_mad_i64_i32 v[2:3], s[6:7], v2, s88, v[92:93]
	v_cndmask_b32_e64 v4, v4, 0, vcc
	v_add_co_u32_e64 v58, s[6:7], s33, v2
	v_add_u32_e32 v4, s23, v4
	v_min_u32_e32 v6, s8, v123
	v_addc_co_u32_e64 v59, s[6:7], 0, v3, s[6:7]
	v_mad_i64_i32 v[4:5], s[6:7], v4, s88, v[92:93]
	v_cndmask_b32_e64 v6, v6, 0, vcc
	v_add_co_u32_e64 v60, s[6:7], s33, v4
	v_add_u32_e32 v6, s23, v6
	s_nop 0
	v_addc_co_u32_e64 v61, s[6:7], 0, v5, s[6:7]
	v_mad_i64_i32 v[6:7], s[6:7], v6, s88, v[92:93]
	v_add_co_u32_e32 v62, vcc, s33, v6
	v_add_u32_e32 v120, 4, v129
	s_nop 0
	v_addc_co_u32_e32 v63, vcc, 0, v7, vcc
	v_min_u32_e32 v8, s8, v120
	v_cmp_lt_i32_e32 vcc, -5, v129
	flat_load_dwordx4 v[72:75], v[0:1] offset:3072
	flat_load_dwordx4 v[76:79], v[56:57]
	flat_load_dwordx4 v[80:83], v[2:3] offset:3072
	v_cndmask_b32_e32 v8, 0, v8, vcc
	v_add_u32_e32 v8, s23, v8
	v_mad_i64_i32 v[8:9], s[6:7], v8, s88, v[92:93]
	v_add_co_u32_e32 v10, vcc, s33, v8
	flat_load_dwordx4 v[84:87], v[58:59]
	flat_load_dwordx4 v[88:91], v[60:61]
	flat_load_dwordx4 v[96:99], v[6:7] offset:3072
	v_addc_co_u32_e32 v11, vcc, 0, v9, vcc
	flat_load_dwordx4 v[52:55], v[8:9] offset:3072
	flat_load_dwordx4 v[48:51], v[10:11]
	flat_load_dwordx4 v[44:47], v[0:1] offset:3584
	flat_load_dwordx4 v[40:43], v[2:3] offset:3584
	s_load_dwordx4 s[12:15], s[18:19], 0x68
	flat_load_dwordx4 v[100:103], v[4:5] offset:3072
	flat_load_dwordx4 v[36:39], v[4:5] offset:3584
	flat_load_dwordx4 v[110:113], v[62:63]
	s_nop 0
	flat_load_dwordx4 v[4:7], v[6:7] offset:3584
	v_cmp_gt_u32_e32 vcc, s24, v104
	s_mov_b32 s25, 0xffff0000
	s_waitcnt lgkmcnt(0)
	s_add_u32 s6, s12, s20
	s_addc_u32 s7, s13, s21
	global_load_dwordx4 v[0:3], v121, s[6:7] offset:16
	global_load_dwordx4 v[20:23], v121, s[6:7]
	global_load_dwordx4 v[8:11], v121, s[6:7] offset:1040
	global_load_dwordx4 v[24:27], v121, s[6:7] offset:1024
	global_load_dwordx4 v[12:15], v121, s[6:7] offset:2064
	global_load_dwordx4 v[28:31], v121, s[6:7] offset:2048
	s_lshl_b64 s[6:7], s[82:83], 2
	s_add_u32 s6, s14, s6
	s_addc_u32 s7, s15, s7
	global_load_dwordx4 v[16:19], v121, s[6:7] offset:16
	global_load_dwordx4 v[32:35], v121, s[6:7]
	v_cndmask_b32_e64 v106, 0, 1.0, vcc
	v_cmp_gt_u32_e32 vcc, s24, v129
	s_waitcnt vmcnt(0)
	v_lshlrev_b32_e32 v105, 16, v65
	v_lshlrev_b32_e32 v104, 16, v64
	v_lshlrev_b32_e32 v109, 16, v69
	v_lshlrev_b32_e32 v108, 16, v68
	v_and_b32_e32 v65, 0xffff0000, v65
	v_and_b32_e32 v64, 0xffff0000, v64
	v_and_b32_e32 v69, 0xffff0000, v69
	v_and_b32_e32 v68, 0xffff0000, v68
	v_pk_mul_f32 v[130:131], v[64:65], v[68:69]
	v_lshlrev_b32_e32 v65, 16, v67
	v_lshlrev_b32_e32 v64, 16, v66
	v_lshlrev_b32_e32 v69, 16, v71
	v_lshlrev_b32_e32 v68, 16, v70
	v_pk_mul_f32 v[132:133], v[64:65], v[68:69]
	v_and_b32_e32 v65, 0xffff0000, v67
	v_and_b32_e32 v64, 0xffff0000, v66
	v_and_b32_e32 v67, 0xffff0000, v71
	v_and_b32_e32 v66, 0xffff0000, v70
	v_pk_mul_f32 v[134:135], v[64:65], v[66:67]
	v_cndmask_b32_e64 v116, 0, 1.0, vcc
	v_cmp_gt_u32_e32 vcc, s24, v127
	v_pk_mul_f32 v[114:115], v[104:105], v[108:109]
	v_lshlrev_b32_e32 v65, 16, v73
	v_lshlrev_b32_e32 v64, 16, v72
	v_lshlrev_b32_e32 v67, 16, v77
	v_lshlrev_b32_e32 v66, 16, v76
	v_pk_mul_f32 v[136:137], v[64:65], v[66:67]
	v_and_b32_e32 v66, 0xffff0000, v76
	v_add_u32_e32 v76, s23, v129
	v_and_b32_e32 v65, 0xffff0000, v73
	v_and_b32_e32 v64, 0xffff0000, v72
	v_and_b32_e32 v67, 0xffff0000, v77
	v_lshlrev_b32_e32 v147, 16, v85
	v_lshlrev_b32_e32 v146, 16, v84
	v_and_b32_e32 v149, 0xffff0000, v81
	v_and_b32_e32 v148, 0xffff0000, v80
	v_and_b32_e32 v85, 0xffff0000, v85
	v_and_b32_e32 v84, 0xffff0000, v84
	v_ashrrev_i32_e32 v77, 31, v76
	v_pk_mul_f32 v[138:139], v[64:65], v[66:67]
	v_lshlrev_b32_e32 v65, 16, v75
	v_lshlrev_b32_e32 v64, 16, v74
	v_lshlrev_b32_e32 v67, 16, v79
	v_lshlrev_b32_e32 v66, 16, v78
	v_cndmask_b32_e64 v118, 0, 1.0, vcc
	v_lshlrev_b32_e32 v145, 16, v81
	v_lshlrev_b32_e32 v144, 16, v80
	v_lshlrev_b32_e32 v161, 16, v89
	v_lshlrev_b32_e32 v160, 16, v88
	v_and_b32_e32 v165, 0xffff0000, v89
	v_and_b32_e32 v164, 0xffff0000, v88
	v_lshlrev_b64 v[88:89], 11, v[76:77]
	v_pk_mul_f32 v[84:85], v[148:149], v[84:85]
	v_pk_mul_f32 v[140:141], v[64:65], v[66:67]
	v_and_b32_e32 v67, 0xffff0000, v79
	v_and_b32_e32 v66, 0xffff0000, v78
	v_lshlrev_b32_e32 v151, 16, v83
	v_lshlrev_b32_e32 v150, 16, v82
	v_lshlrev_b32_e32 v153, 16, v87
	v_lshlrev_b32_e32 v152, 16, v86
	v_and_b32_e32 v155, 0xffff0000, v83
	v_and_b32_e32 v154, 0xffff0000, v82
	v_and_b32_e32 v157, 0xffff0000, v87
	v_and_b32_e32 v156, 0xffff0000, v86
	v_lshlrev_b32_e32 v159, 16, v101
	v_lshlrev_b32_e32 v158, 16, v100
	v_and_b32_e32 v163, 0xffff0000, v101
	v_and_b32_e32 v162, 0xffff0000, v100
	v_lshlrev_b32_e32 v167, 16, v103
	v_lshlrev_b32_e32 v166, 16, v102
	v_and_b32_e32 v173, 0xffff0000, v103
	v_and_b32_e32 v172, 0xffff0000, v102
	v_lshlrev_b32_e32 v87, 16, v97
	v_lshlrev_b32_e32 v86, 16, v96
	v_lshlrev_b32_e32 v101, 16, v111
	v_lshlrev_b32_e32 v100, 16, v110
	v_and_b32_e32 v103, 0xffff0000, v97
	v_and_b32_e32 v102, 0xffff0000, v96
	v_and_b32_e32 v105, 0xffff0000, v111
	v_and_b32_e32 v104, 0xffff0000, v110
	v_lshlrev_b32_e32 v79, 16, v99
	v_lshlrev_b32_e32 v78, 16, v98
	v_and_b32_e32 v83, 0xffff0000, v99
	v_and_b32_e32 v82, 0xffff0000, v98
	v_lshl_add_u64 v[96:97], v[94:95], 0, v[88:89]
	v_pk_mul_f32 v[88:89], v[106:107], v[114:115] op_sel_hi:[0,1]
	v_pk_mul_f32 v[110:111], v[106:107], v[130:131] op_sel_hi:[0,1]
	v_pk_mul_f32 v[114:115], v[116:117], v[136:137] op_sel_hi:[0,1]
	v_pk_mul_f32 v[130:131], v[116:117], v[138:139] op_sel_hi:[0,1]
	v_pk_mul_f32 v[98:99], v[144:145], v[146:147]
	v_pk_mul_f32 v[138:139], v[118:119], v[84:85] op_sel_hi:[0,1]
	v_mov_b32_e32 v84, v24
	v_mov_b32_e32 v85, v26
	v_mov_b32_e32 v26, v25
	v_lshlrev_b32_e32 v171, 16, v91
	v_lshlrev_b32_e32 v170, 16, v90
	v_and_b32_e32 v175, 0xffff0000, v91
	v_and_b32_e32 v174, 0xffff0000, v90
	v_lshlrev_b32_e32 v81, 16, v113
	v_lshlrev_b32_e32 v80, 16, v112
	v_and_b32_e32 v91, 0xffff0000, v113
	v_and_b32_e32 v90, 0xffff0000, v112
	v_pk_mul_f32 v[136:137], v[118:119], v[98:99] op_sel_hi:[0,1]
	v_lshlrev_b32_e32 v113, 16, v45
	v_lshlrev_b32_e32 v112, 16, v44
	v_and_b32_e32 v145, 0xffff0000, v45
	v_and_b32_e32 v144, 0xffff0000, v44
	v_mov_b32_e32 v44, v20
	v_mov_b32_e32 v45, v22
	v_pk_mul_f32 v[98:99], v[114:115], v[84:85]
	v_mov_b32_e32 v22, v21
	v_pk_mul_f32 v[20:21], v[130:131], v[26:27]
	v_pk_fma_f32 v[98:99], v[88:89], v[44:45], v[98:99]
	v_mov_b32_e32 v88, v28
	v_mov_b32_e32 v89, v30
	v_pk_fma_f32 v[20:21], v[110:111], v[22:23], v[20:21]
	v_mov_b32_e32 v30, v29
	v_pk_fma_f32 v[146:147], v[136:137], v[88:89], v[98:99]
	v_mov_b32_e32 v99, v34
	v_pk_fma_f32 v[20:21], v[138:139], v[30:31], v[20:21]
	v_mov_b32_e32 v34, v33
	v_and_b32_e32 v65, 0xffff0000, v75
	v_and_b32_e32 v64, 0xffff0000, v74
	v_pk_add_f32 v[20:21], v[20:21], v[34:35]
	v_pk_mul_f32 v[142:143], v[64:65], v[66:67]
	v_mov_b32_e32 v98, v32
	v_pk_mul_f32 v[32:33], v[20:21], v[144:145]
	v_pk_mul_f32 v[20:21], v[150:151], v[152:153]
	v_pk_add_f32 v[146:147], v[146:147], v[98:99]
	v_pk_mul_f32 v[28:29], v[106:107], v[132:133] op_sel_hi:[0,1]
	v_pk_mul_f32 v[110:111], v[106:107], v[134:135] op_sel_hi:[0,1]
	v_pk_mul_f32 v[132:133], v[116:117], v[140:141] op_sel_hi:[0,1]
	v_pk_mul_f32 v[134:135], v[116:117], v[142:143] op_sel_hi:[0,1]
	v_pk_mul_f32 v[140:141], v[118:119], v[20:21] op_sel_hi:[0,1]
	v_pk_mul_f32 v[20:21], v[154:155], v[156:157]
	v_mov_b32_e32 v24, v8
	v_mov_b32_e32 v25, v10
	v_mov_b32_e32 v10, v9
	v_pk_mul_f32 v[112:113], v[146:147], v[112:113]
	v_pk_mul_f32 v[142:143], v[118:119], v[20:21] op_sel_hi:[0,1]
	v_mov_b32_e32 v20, v0
	v_mov_b32_e32 v21, v2
	v_pk_mul_f32 v[146:147], v[132:133], v[24:25]
	v_mov_b32_e32 v2, v1
	v_pk_mul_f32 v[0:1], v[134:135], v[10:11]
	v_pk_fma_f32 v[146:147], v[28:29], v[20:21], v[146:147]
	v_mov_b32_e32 v29, v14
	v_pk_fma_f32 v[0:1], v[110:111], v[2:3], v[0:1]
	v_mov_b32_e32 v14, v13
	v_mov_b32_e32 v28, v12
	v_mov_b32_e32 v149, v18
	v_pk_fma_f32 v[0:1], v[142:143], v[14:15], v[0:1]
	v_mov_b32_e32 v18, v17
	v_lshlrev_b32_e32 v145, 16, v47
	v_lshlrev_b32_e32 v144, 16, v46
	v_and_b32_e32 v47, 0xffff0000, v47
	v_and_b32_e32 v46, 0xffff0000, v46
	v_pk_fma_f32 v[146:147], v[140:141], v[28:29], v[146:147]
	v_mov_b32_e32 v148, v16
	v_pk_add_f32 v[0:1], v[0:1], v[18:19]
	v_pk_add_f32 v[146:147], v[146:147], v[148:149]
	v_pk_mul_f32 v[0:1], v[0:1], v[46:47]
	v_pk_mul_f32 v[144:145], v[146:147], v[144:145]
	v_bfe_u32 v8, v1, 16, 1
	v_bfe_u32 v9, v0, 16, 1
	v_add3_u32 v0, v0, v9, s77
	v_add3_u32 v1, v1, v8, s77
	v_bfe_u32 v8, v112, 16, 1
	v_bfe_u32 v9, v113, 16, 1
	v_bfe_u32 v16, v144, 16, 1
	v_bfe_u32 v17, v145, 16, 1
	v_bfe_u32 v12, v33, 16, 1
	v_bfe_u32 v13, v32, 16, 1
	v_add3_u32 v17, v145, v17, s77
	v_add3_u32 v16, v144, v16, s77
	v_add3_u32 v9, v113, v9, s77
	v_add3_u32 v8, v112, v8, s77
	v_cmp_gt_u32_e32 vcc, s24, v125
	v_add3_u32 v13, v32, v13, s77
	v_add3_u32 v12, v33, v12, s77
	v_lshrrev_b32_e32 v8, 16, v8
	v_lshrrev_b32_e32 v9, 16, v9
	v_lshrrev_b32_e32 v16, 16, v16
	v_lshrrev_b32_e32 v17, 16, v17
	v_cndmask_b32_e64 v108, 0, 1.0, vcc
	v_and_or_b32 v113, v1, s25, v17
	v_and_or_b32 v112, v0, s25, v16
	v_and_or_b32 v111, v12, s25, v9
	v_and_or_b32 v110, v13, s25, v8
	v_pk_mul_f32 v[8:9], v[158:159], v[160:161]
	v_lshlrev_b32_e32 v17, 16, v41
	v_lshlrev_b32_e32 v16, 16, v40
	v_and_b32_e32 v33, 0xffff0000, v41
	v_and_b32_e32 v32, 0xffff0000, v40
	v_pk_mul_f32 v[40:41], v[136:137], v[84:85]
	v_pk_mul_f32 v[8:9], v[108:109], v[8:9] op_sel_hi:[0,1]
	v_pk_fma_f32 v[40:41], v[114:115], v[44:45], v[40:41]
	v_pk_mul_f32 v[12:13], v[162:163], v[164:165]
	v_pk_fma_f32 v[40:41], v[8:9], v[88:89], v[40:41]
	v_pk_mul_f32 v[12:13], v[108:109], v[12:13] op_sel_hi:[0,1]
	v_pk_add_f32 v[40:41], v[40:41], v[98:99]
	global_store_dwordx4 v[96:97], v[110:113], off offset:1024
	v_pk_mul_f32 v[16:17], v[40:41], v[16:17]
	v_pk_mul_f32 v[40:41], v[138:139], v[26:27]
	v_pk_mul_f32 v[110:111], v[140:141], v[24:25]
	v_pk_fma_f32 v[40:41], v[130:131], v[22:23], v[40:41]
	v_pk_fma_f32 v[110:111], v[132:133], v[20:21], v[110:111]
	v_pk_fma_f32 v[40:41], v[12:13], v[30:31], v[40:41]
	v_or_b32_e32 v0, 1, v76
	v_pk_add_f32 v[40:41], v[40:41], v[34:35]
	v_ashrrev_i32_e32 v1, 31, v0
	v_pk_mul_f32 v[32:33], v[40:41], v[32:33]
	v_pk_mul_f32 v[40:41], v[166:167], v[170:171]
	v_bfe_u32 v77, v33, 16, 1
	v_pk_mul_f32 v[46:47], v[108:109], v[40:41] op_sel_hi:[0,1]
	v_pk_mul_f32 v[40:41], v[172:173], v[174:175]
	v_pk_fma_f32 v[110:111], v[46:47], v[28:29], v[110:111]
	v_pk_mul_f32 v[108:109], v[108:109], v[40:41] op_sel_hi:[0,1]
	v_lshlrev_b32_e32 v41, 16, v43
	v_lshlrev_b32_e32 v40, 16, v42
	v_pk_add_f32 v[110:111], v[110:111], v[148:149]
	v_and_b32_e32 v43, 0xffff0000, v43
	v_pk_mul_f32 v[40:41], v[110:111], v[40:41]
	v_pk_mul_f32 v[110:111], v[142:143], v[10:11]
	v_and_b32_e32 v42, 0xffff0000, v42
	v_pk_fma_f32 v[110:111], v[134:135], v[2:3], v[110:111]
	v_bfe_u32 v106, v32, 16, 1
	v_pk_fma_f32 v[110:111], v[108:109], v[14:15], v[110:111]
	v_add3_u32 v32, v32, v106, s77
	v_pk_add_f32 v[110:111], v[110:111], v[18:19]
	v_add3_u32 v33, v33, v77, s77
	v_pk_mul_f32 v[42:43], v[110:111], v[42:43]
	v_bfe_u32 v77, v40, 16, 1
	v_bfe_u32 v65, v43, 16, 1
	v_bfe_u32 v75, v42, 16, 1
	v_add3_u32 v42, v42, v75, s77
	v_add3_u32 v43, v43, v65, s77
	v_bfe_u32 v65, v16, 16, 1
	v_bfe_u32 v75, v17, 16, 1
	v_bfe_u32 v106, v41, 16, 1
	v_add3_u32 v41, v41, v106, s77
	v_add3_u32 v40, v40, v77, s77
	v_add3_u32 v17, v17, v75, s77
	v_add3_u32 v16, v16, v65, s77
	v_lshlrev_b64 v[0:1], 11, v[0:1]
	v_lshrrev_b32_e32 v16, 16, v16
	v_lshrrev_b32_e32 v17, 16, v17
	v_lshrrev_b32_e32 v40, 16, v40
	v_lshrrev_b32_e32 v41, 16, v41
	v_cmp_gt_u32_e32 vcc, s24, v123
	v_lshl_add_u64 v[0:1], v[94:95], 0, v[0:1]
	v_and_or_b32 v43, v43, s25, v41
	v_and_or_b32 v42, v42, s25, v40
	v_and_or_b32 v41, v33, s25, v17
	v_and_or_b32 v40, v32, s25, v16
	v_cndmask_b32_e64 v74, 0, 1.0, vcc
	global_store_dwordx4 v[0:1], v[40:43], off offset:1024
	v_pk_mul_f32 v[16:17], v[86:87], v[100:101]
	v_pk_mul_f32 v[32:33], v[102:103], v[104:105]
	v_pk_mul_f32 v[42:43], v[8:9], v[84:85]
	v_pk_mul_f32 v[16:17], v[74:75], v[16:17] op_sel_hi:[0,1]
	v_pk_fma_f32 v[42:43], v[136:137], v[44:45], v[42:43]
	v_lshlrev_b32_e32 v41, 16, v37
	v_pk_fma_f32 v[42:43], v[16:17], v[88:89], v[42:43]
	v_lshlrev_b32_e32 v40, 16, v36
	v_pk_add_f32 v[42:43], v[42:43], v[98:99]
	v_pk_mul_f32 v[32:33], v[74:75], v[32:33] op_sel_hi:[0,1]
	v_pk_mul_f32 v[40:41], v[42:43], v[40:41]
	v_pk_mul_f32 v[42:43], v[12:13], v[26:27]
	v_and_b32_e32 v37, 0xffff0000, v37
	v_pk_fma_f32 v[42:43], v[138:139], v[22:23], v[42:43]
	v_and_b32_e32 v36, 0xffff0000, v36
	v_pk_fma_f32 v[42:43], v[32:33], v[30:31], v[42:43]
	v_or_b32_e32 v0, 2, v76
	v_pk_add_f32 v[42:43], v[42:43], v[34:35]
	v_ashrrev_i32_e32 v1, 31, v0
	v_pk_mul_f32 v[36:37], v[42:43], v[36:37]
	v_pk_mul_f32 v[42:43], v[78:79], v[80:81]
	v_pk_mul_f32 v[80:81], v[46:47], v[24:25]
	v_pk_mul_f32 v[42:43], v[74:75], v[42:43] op_sel_hi:[0,1]
	v_pk_fma_f32 v[80:81], v[140:141], v[20:21], v[80:81]
	v_pk_mul_f32 v[78:79], v[82:83], v[90:91]
	v_pk_fma_f32 v[80:81], v[42:43], v[28:29], v[80:81]
	v_pk_mul_f32 v[74:75], v[74:75], v[78:79] op_sel_hi:[0,1]
	v_lshlrev_b32_e32 v79, 16, v39
	v_lshlrev_b32_e32 v78, 16, v38
	v_pk_add_f32 v[80:81], v[80:81], v[148:149]
	v_and_b32_e32 v39, 0xffff0000, v39
	v_pk_mul_f32 v[78:79], v[80:81], v[78:79]
	v_pk_mul_f32 v[80:81], v[108:109], v[10:11]
	v_and_b32_e32 v38, 0xffff0000, v38
	v_pk_fma_f32 v[80:81], v[142:143], v[2:3], v[80:81]
	v_lshlrev_b64 v[0:1], 11, v[0:1]
	v_pk_fma_f32 v[80:81], v[74:75], v[14:15], v[80:81]
	v_lshl_add_u64 v[0:1], v[94:95], 0, v[0:1]
	v_pk_add_f32 v[80:81], v[80:81], v[18:19]
	v_cmp_gt_u32_e32 vcc, s24, v120
	v_pk_mul_f32 v[38:39], v[80:81], v[38:39]
	v_bfe_u32 v80, v37, 16, 1
	v_bfe_u32 v65, v39, 16, 1
	v_bfe_u32 v77, v38, 16, 1
	v_bfe_u32 v81, v36, 16, 1
	v_add3_u32 v36, v36, v81, s77
	v_add3_u32 v37, v37, v80, s77
	v_add3_u32 v38, v38, v77, s77
	v_add3_u32 v39, v39, v65, s77
	v_bfe_u32 v65, v40, 16, 1
	v_bfe_u32 v77, v41, 16, 1
	v_bfe_u32 v80, v78, 16, 1
	v_bfe_u32 v81, v79, 16, 1
	v_add3_u32 v79, v79, v81, s77
	v_add3_u32 v78, v78, v80, s77
	v_add3_u32 v41, v41, v77, s77
	v_add3_u32 v40, v40, v65, s77
	v_lshrrev_b32_e32 v40, 16, v40
	v_lshrrev_b32_e32 v41, 16, v41
	v_lshrrev_b32_e32 v65, 16, v78
	v_lshrrev_b32_e32 v77, 16, v79
	v_and_or_b32 v39, v39, s25, v77
	v_and_or_b32 v38, v38, s25, v65
	v_and_or_b32 v37, v37, s25, v41
	v_and_or_b32 v36, v36, s25, v40
	global_store_dwordx4 v[0:1], v[36:39], off offset:1024
	v_or_b32_e32 v0, 3, v76
	v_ashrrev_i32_e32 v1, 31, v0
	v_lshlrev_b32_e32 v67, 16, v53
	v_lshlrev_b32_e32 v66, 16, v52
	v_lshlrev_b32_e32 v69, 16, v49
	v_lshlrev_b32_e32 v68, 16, v48
	v_lshlrev_b64 v[0:1], 11, v[0:1]
	v_cndmask_b32_e64 v64, 0, 1.0, vcc
	v_lshl_add_u64 v[36:37], v[94:95], 0, v[0:1]
	v_pk_mul_f32 v[0:1], v[66:67], v[68:69]
	v_pk_mul_f32 v[16:17], v[16:17], v[84:85]
	v_and_b32_e32 v71, 0xffff0000, v53
	v_and_b32_e32 v70, 0xffff0000, v52
	v_and_b32_e32 v73, 0xffff0000, v49
	v_and_b32_e32 v72, 0xffff0000, v48
	v_pk_mul_f32 v[0:1], v[64:65], v[0:1] op_sel_hi:[0,1]
	v_pk_fma_f32 v[8:9], v[8:9], v[44:45], v[16:17]
	v_pk_mul_f32 v[38:39], v[70:71], v[72:73]
	v_pk_fma_f32 v[0:1], v[0:1], v[88:89], v[8:9]
	v_pk_mul_f32 v[8:9], v[32:33], v[26:27]
	v_pk_mul_f32 v[38:39], v[64:65], v[38:39] op_sel_hi:[0,1]
	v_pk_fma_f32 v[8:9], v[12:13], v[22:23], v[8:9]
	v_lshlrev_b32_e32 v49, 16, v55
	v_lshlrev_b32_e32 v48, 16, v54
	v_lshlrev_b32_e32 v53, 16, v51
	v_lshlrev_b32_e32 v52, 16, v50
	v_and_b32_e32 v55, 0xffff0000, v55
	v_and_b32_e32 v54, 0xffff0000, v54
	v_and_b32_e32 v51, 0xffff0000, v51
	v_and_b32_e32 v50, 0xffff0000, v50
	v_pk_fma_f32 v[8:9], v[38:39], v[30:31], v[8:9]
	v_lshlrev_b32_e32 v41, 16, v5
	v_lshlrev_b32_e32 v40, 16, v4
	v_and_b32_e32 v5, 0xffff0000, v5
	v_and_b32_e32 v4, 0xffff0000, v4
	v_pk_add_f32 v[8:9], v[8:9], v[34:35]
	v_pk_mul_f32 v[12:13], v[54:55], v[50:51]
	v_pk_mul_f32 v[10:11], v[74:75], v[10:11]
	v_pk_mul_f32 v[4:5], v[8:9], v[4:5]
	v_pk_mul_f32 v[8:9], v[48:49], v[52:53]
	v_pk_mul_f32 v[12:13], v[64:65], v[12:13] op_sel_hi:[0,1]
	v_pk_mul_f32 v[22:23], v[42:43], v[24:25]
	v_pk_fma_f32 v[2:3], v[108:109], v[2:3], v[10:11]
	v_pk_mul_f32 v[8:9], v[64:65], v[8:9] op_sel_hi:[0,1]
	v_pk_fma_f32 v[20:21], v[46:47], v[20:21], v[22:23]
	v_pk_fma_f32 v[2:3], v[12:13], v[14:15], v[2:3]
	v_lshlrev_b32_e32 v17, 16, v7
	v_lshlrev_b32_e32 v16, 16, v6
	v_and_b32_e32 v7, 0xffff0000, v7
	v_and_b32_e32 v6, 0xffff0000, v6
	v_pk_fma_f32 v[8:9], v[8:9], v[28:29], v[20:21]
	v_pk_add_f32 v[2:3], v[2:3], v[18:19]
	v_pk_add_f32 v[0:1], v[0:1], v[98:99]
	v_pk_add_f32 v[8:9], v[8:9], v[148:149]
	v_pk_mul_f32 v[2:3], v[2:3], v[6:7]
	v_pk_mul_f32 v[0:1], v[0:1], v[40:41]
	v_pk_mul_f32 v[8:9], v[8:9], v[16:17]
	v_bfe_u32 v6, v3, 16, 1
	v_bfe_u32 v7, v2, 16, 1
	v_bfe_u32 v10, v5, 16, 1
	v_bfe_u32 v11, v4, 16, 1
	v_add3_u32 v4, v4, v11, s77
	v_add3_u32 v5, v5, v10, s77
	v_add3_u32 v2, v2, v7, s77
	v_add3_u32 v3, v3, v6, s77
	v_bfe_u32 v6, v0, 16, 1
	v_bfe_u32 v7, v1, 16, 1
	v_bfe_u32 v10, v8, 16, 1
	v_bfe_u32 v11, v9, 16, 1
	v_add3_u32 v9, v9, v11, s77
	v_add3_u32 v8, v8, v10, s77
	v_add3_u32 v1, v1, v7, s77
	v_add3_u32 v0, v0, v6, s77
	v_lshrrev_b32_e32 v0, 16, v0
	v_lshrrev_b32_e32 v1, 16, v1
	v_lshrrev_b32_e32 v6, 16, v8
	v_lshrrev_b32_e32 v7, 16, v9
	v_and_or_b32 v3, v3, s25, v7
	v_and_or_b32 v2, v2, s25, v6
	v_and_or_b32 v1, v5, s25, v1
	v_and_or_b32 v0, v4, s25, v0
	global_store_dwordx4 v[36:37], v[0:3], off offset:1024
	flat_load_dwordx4 v[12:15], v[56:57] offset:512
	flat_load_dwordx4 v[8:11], v[58:59] offset:512
	flat_load_dwordx4 v[4:7], v[60:61] offset:512
	s_nop 0
	flat_load_dwordx4 v[0:3], v[62:63] offset:512
	v_sub_u32_e32 v99, v129, v117
	v_min_u32_e32 v16, s8, v99
	v_cmp_lt_i32_e32 vcc, -1, v99
	v_add_u32_e32 v101, 1, v99
	v_min_u32_e32 v18, s8, v101
	v_cndmask_b32_e32 v16, 0, v16, vcc
	v_add_u32_e32 v16, s23, v16
	v_mad_i64_i32 v[16:17], s[6:7], v16, s88, v[92:93]
	v_add_co_u32_e32 v16, vcc, s33, v16
	v_add_u32_e32 v105, 2, v99
	s_nop 0
	v_addc_co_u32_e32 v17, vcc, 0, v17, vcc
	v_cmp_lt_i32_e32 vcc, -2, v99
	v_min_u32_e32 v24, s8, v105
	v_add_u32_e32 v102, 3, v99
	v_cndmask_b32_e32 v18, 0, v18, vcc
	v_add_u32_e32 v18, s23, v18
	v_mad_i64_i32 v[18:19], s[6:7], v18, s88, v[92:93]
	v_add_co_u32_e32 v20, vcc, s33, v18
	v_min_u32_e32 v26, s8, v102
	s_nop 0
	v_addc_co_u32_e32 v21, vcc, 0, v19, vcc
	v_cmp_lt_i32_e32 vcc, -3, v99
	v_add_u32_e32 v108, 4, v99
	v_min_u32_e32 v32, s8, v108
	v_cndmask_b32_e32 v24, 0, v24, vcc
	v_add_u32_e32 v24, s23, v24
	v_mad_i64_i32 v[24:25], s[6:7], v24, s88, v[92:93]
	v_add_co_u32_e32 v24, vcc, s33, v24
	v_add_u32_e32 v109, 5, v99
	s_nop 0
	v_addc_co_u32_e32 v25, vcc, 0, v25, vcc
	v_cmp_lt_i32_e32 vcc, -4, v99
	v_min_u32_e32 v34, s8, v109
	v_add_u32_e32 v110, 6, v99
	v_cndmask_b32_e32 v26, 0, v26, vcc
	v_add_u32_e32 v26, s23, v26
	v_mad_i64_i32 v[26:27], s[6:7], v26, s88, v[92:93]
	v_add_co_u32_e32 v28, vcc, s33, v26
	flat_load_dwordx4 v[16:19], v[16:17] offset:512
	s_nop 0
	flat_load_dwordx4 v[20:23], v[20:21] offset:512
	v_addc_co_u32_e32 v29, vcc, 0, v27, vcc
	v_cmp_lt_i32_e32 vcc, -5, v99
	flat_load_dwordx4 v[24:27], v[24:25] offset:512
	s_nop 0
	flat_load_dwordx4 v[28:31], v[28:29] offset:512
	v_cndmask_b32_e32 v32, 0, v32, vcc
	v_add_u32_e32 v32, s23, v32
	v_mad_i64_i32 v[32:33], s[6:7], v32, s88, v[92:93]
	v_add_co_u32_e32 v32, vcc, s33, v32
	s_nop 1
	v_addc_co_u32_e32 v33, vcc, 0, v33, vcc
	v_cmp_lt_i32_e32 vcc, -6, v99
	s_nop 1
	v_cndmask_b32_e32 v34, 0, v34, vcc
	v_add_u32_e32 v34, s23, v34
	v_mad_i64_i32 v[34:35], s[6:7], v34, s88, v[92:93]
	v_add_co_u32_e32 v34, vcc, s33, v34
	s_nop 1
	v_addc_co_u32_e32 v35, vcc, 0, v35, vcc
	flat_load_dwordx4 v[40:43], v[32:33] offset:512
	flat_load_dwordx4 v[72:75], v[34:35] offset:512
	v_min_u32_e32 v32, s8, v110
	v_cmp_lt_i32_e32 vcc, -7, v99
	s_nop 1
	v_cndmask_b32_e32 v32, 0, v32, vcc
	v_add_u32_e32 v32, s23, v32
	v_mad_i64_i32 v[32:33], s[6:7], v32, s88, v[92:93]
	v_add_co_u32_e32 v32, vcc, s33, v32
	s_nop 1
	v_addc_co_u32_e32 v33, vcc, 0, v33, vcc
	flat_load_dwordx4 v[76:79], v[32:33] offset:512
	v_add_u32_e32 v111, 7, v99
	v_min_u32_e32 v32, s8, v111
	v_cmp_lt_i32_e32 vcc, -8, v99
	v_add_u32_e32 v112, 8, v99
	v_min_u32_e32 v34, s8, v112
	v_cndmask_b32_e32 v32, 0, v32, vcc
	v_add_u32_e32 v32, s23, v32
	v_mad_i64_i32 v[32:33], s[6:7], v32, s88, v[92:93]
	v_add_co_u32_e32 v32, vcc, s33, v32
	v_add_u32_e32 v113, 9, v99
	s_nop 0
	v_addc_co_u32_e32 v33, vcc, 0, v33, vcc
	v_cmp_lt_i32_e32 vcc, -9, v99
	v_min_u32_e32 v44, s8, v113
	v_add_u32_e32 v114, 10, v99
	v_cndmask_b32_e32 v34, 0, v34, vcc
	v_add_u32_e32 v34, s23, v34
	v_mad_i64_i32 v[34:35], s[6:7], v34, s88, v[92:93]
	v_add_co_u32_e32 v36, vcc, s33, v34
	v_min_u32_e32 v46, s8, v114
	s_nop 0
	v_addc_co_u32_e32 v37, vcc, 0, v35, vcc
	v_cmp_lt_i32_e32 vcc, -10, v99
	v_add_u32_e32 v115, 11, v99
	v_min_u32_e32 v52, s8, v115
	v_cndmask_b32_e32 v44, 0, v44, vcc
	v_add_u32_e32 v44, s23, v44
	v_mad_i64_i32 v[44:45], s[6:7], v44, s88, v[92:93]
	v_add_co_u32_e32 v44, vcc, s33, v44
	v_add_u32_e32 v120, 12, v99
	s_nop 0
	v_addc_co_u32_e32 v45, vcc, 0, v45, vcc
	v_cmp_lt_i32_e32 vcc, -11, v99
	v_min_u32_e32 v54, s8, v120
	v_add_u32_e32 v118, 13, v99
	v_cndmask_b32_e32 v46, 0, v46, vcc
	v_add_u32_e32 v46, s23, v46
	v_mad_i64_i32 v[46:47], s[6:7], v46, s88, v[92:93]
	v_add_co_u32_e32 v48, vcc, s33, v46
	v_min_u32_e32 v60, s8, v118
	s_nop 0
	v_addc_co_u32_e32 v49, vcc, 0, v47, vcc
	v_cmp_lt_i32_e32 vcc, -12, v99
	flat_load_dwordx4 v[32:35], v[32:33] offset:512
	s_nop 0
	flat_load_dwordx4 v[36:39], v[36:37] offset:512
	v_cndmask_b32_e32 v52, 0, v52, vcc
	v_add_u32_e32 v52, s23, v52
	v_mad_i64_i32 v[52:53], s[6:7], v52, s88, v[92:93]
	v_add_co_u32_e32 v52, vcc, s33, v52
	flat_load_dwordx4 v[44:47], v[44:45] offset:512
	s_nop 0
	flat_load_dwordx4 v[48:51], v[48:49] offset:512
	v_addc_co_u32_e32 v53, vcc, 0, v53, vcc
	v_cmp_lt_i32_e32 vcc, -13, v99
	s_nop 1
	v_cndmask_b32_e32 v54, 0, v54, vcc
	v_add_u32_e32 v54, s23, v54
	v_mad_i64_i32 v[54:55], s[6:7], v54, s88, v[92:93]
	v_add_co_u32_e32 v54, vcc, s33, v54
	s_nop 1
	v_addc_co_u32_e32 v55, vcc, 0, v55, vcc
	v_cmp_lt_i32_e32 vcc, -14, v99
	flat_load_dwordx4 v[56:59], v[52:53] offset:512
	s_nop 0
	flat_load_dwordx4 v[52:55], v[54:55] offset:512
	v_cndmask_b32_e32 v60, 0, v60, vcc
	v_add_u32_e32 v60, s23, v60
	v_mad_i64_i32 v[60:61], s[6:7], v60, s88, v[92:93]
	v_add_co_u32_e32 v60, vcc, s33, v60
	s_nop 1
	v_addc_co_u32_e32 v61, vcc, 0, v61, vcc
	flat_load_dwordx4 v[60:63], v[60:61] offset:512
	v_add_u32_e32 v116, 14, v99
	v_min_u32_e32 v64, s8, v116
	v_cmp_lt_i32_e32 vcc, -15, v99
	v_add_u32_e32 v106, 15, v99
	v_min_u32_e32 v68, s8, v106
	v_cndmask_b32_e32 v64, 0, v64, vcc
	v_add_u32_e32 v64, s23, v64
	v_mad_i64_i32 v[64:65], s[6:7], v64, s88, v[92:93]
	v_add_co_u32_e32 v64, vcc, s33, v64
	v_add_u32_e32 v104, 16, v99
	s_nop 0
	v_addc_co_u32_e32 v65, vcc, 0, v65, vcc
	v_cmp_lt_i32_e32 vcc, -16, v99
	flat_load_dwordx4 v[64:67], v[64:65] offset:512
	v_add_u32_e32 v100, 17, v99
	v_cndmask_b32_e32 v68, 0, v68, vcc
	v_add_u32_e32 v68, s23, v68
	v_mad_i64_i32 v[68:69], s[6:7], v68, s88, v[92:93]
	v_add_co_u32_e32 v68, vcc, s33, v68
	s_movk_i32 s6, 0xffef
	s_nop 0
	v_addc_co_u32_e32 v69, vcc, 0, v69, vcc
	flat_load_dwordx4 v[80:83], v[68:69] offset:512
	v_min_u32_e32 v68, s8, v104
	v_cmp_lt_i32_e32 vcc, s6, v99
	v_add_u32_e32 v98, 18, v99
	v_cmp_gt_u32_e64 s[12:13], s24, v109
	v_cndmask_b32_e32 v68, 0, v68, vcc
	v_add_u32_e32 v68, s23, v68
	v_mad_i64_i32 v[68:69], s[6:7], v68, s88, v[92:93]
	v_add_co_u32_e32 v68, vcc, s33, v68
	s_movk_i32 s6, 0xffee
	s_nop 0
	v_addc_co_u32_e32 v69, vcc, 0, v69, vcc
	flat_load_dwordx4 v[84:87], v[68:69] offset:512
	v_min_u32_e32 v68, s8, v100
	v_cmp_lt_i32_e32 vcc, s6, v99
	s_waitcnt vmcnt(0) lgkmcnt(0)
	v_and_b32_e32 v183, 0xffff0000, v19
	v_and_b32_e32 v182, 0xffff0000, v18
	v_cndmask_b32_e32 v68, 0, v68, vcc
	v_add_u32_e32 v68, s23, v68
	v_mad_i64_i32 v[68:69], s[6:7], v68, s88, v[92:93]
	v_add_co_u32_e32 v68, vcc, s33, v68
	s_movk_i32 s6, 0xffed
	s_nop 0
	v_addc_co_u32_e32 v69, vcc, 0, v69, vcc
	flat_load_dwordx4 v[88:91], v[68:69] offset:512
	v_min_u32_e32 v68, s8, v98
	v_cmp_lt_i32_e32 vcc, s6, v99
	v_and_b32_e32 v159, 0xffff0000, v79
	v_lshlrev_b32_e32 v179, 16, v79
	v_cndmask_b32_e32 v68, 0, v68, vcc
	v_add_u32_e32 v68, s23, v68
	v_mad_i64_i32 v[68:69], s[6:7], v68, s88, v[92:93]
	v_add_co_u32_e32 v68, vcc, s33, v68
	v_and_b32_e32 v158, 0xffff0000, v78
	s_nop 0
	v_addc_co_u32_e32 v69, vcc, 0, v69, vcc
	flat_load_dwordx4 v[68:71], v[68:69] offset:512
	v_cmp_gt_u32_e32 vcc, s24, v98
	s_and_b64 s[6:7], s[0:1], vcc
	v_cmp_gt_u32_e32 vcc, s24, v100
	v_cndmask_b32_e64 v98, 0, 1.0, s[6:7]
	s_and_b64 s[6:7], s[0:1], vcc
	v_cmp_gt_u32_e32 vcc, s24, v104
	v_cndmask_b32_e64 v100, 0, 1.0, s[6:7]
	s_and_b64 s[6:7], s[0:1], vcc
	v_cmp_gt_u32_e32 vcc, s24, v106
	v_cndmask_b32_e64 v104, 0, 1.0, s[6:7]
	s_and_b64 s[6:7], s[0:1], vcc
	v_cmp_gt_u32_e32 vcc, s24, v116
	v_cndmask_b32_e64 v106, 0, 1.0, s[6:7]
	s_and_b64 s[6:7], s[0:1], vcc
	v_cmp_gt_u32_e32 vcc, s24, v118
	v_cndmask_b32_e64 v116, 0, 1.0, s[6:7]
	s_and_b64 s[6:7], s[0:1], vcc
	v_cmp_gt_u32_e32 vcc, s24, v120
	v_cndmask_b32_e64 v118, 0, 1.0, s[6:7]
	s_and_b64 s[6:7], s[0:1], vcc
	v_cmp_gt_u32_e32 vcc, s24, v115
	v_cndmask_b32_e64 v120, 0, 1.0, s[6:7]
	s_and_b64 s[6:7], s[0:1], vcc
	v_cmp_gt_u32_e32 vcc, s24, v114
	v_cndmask_b32_e64 v122, 0, 1.0, s[6:7]
	s_and_b64 s[6:7], vcc, s[2:3]
	v_cndmask_b32_e64 v126, 0, 1.0, s[6:7]
	v_cmp_gt_u32_e64 s[6:7], s24, v113
	s_and_b64 s[8:9], s[6:7], s[2:3]
	s_and_b64 s[26:27], s[0:1], vcc
	v_cmp_gt_u32_e32 vcc, s24, v105
	s_and_b64 s[6:7], s[0:1], s[6:7]
	v_cndmask_b32_e64 v130, 0, 1.0, s[8:9]
	v_cmp_gt_u32_e64 s[8:9], s24, v112
	v_cndmask_b32_e64 v164, 0, 1.0, vcc
	v_cndmask_b32_e64 v146, 0, 1.0, s[6:7]
	s_and_b64 s[6:7], s[12:13], s[2:3]
	v_cndmask_b32_e32 v168, 0, v119, vcc
	v_cmp_gt_u32_e32 vcc, s24, v99
	s_and_b64 s[10:11], s[8:9], s[2:3]
	v_and_b32_e32 v171, 0xffff0000, v75
	v_and_b32_e32 v170, 0xffff0000, v74
	v_lshlrev_b32_e32 v178, 16, v78
	v_lshlrev_b32_e32 v181, 16, v75
	v_lshlrev_b32_e32 v180, 16, v74
	v_cndmask_b32_e64 v148, 0, 1.0, s[6:7]
	v_cmp_gt_u32_e64 s[6:7], s24, v101
	v_cndmask_b32_e64 v174, 0, 1.0, vcc
	v_pk_fma_f32 v[184:185], v[182:183], 0, 0 op_sel_hi:[1,0,0]
	v_cndmask_b32_e64 v128, 0, 1.0, s[10:11]
	v_cmp_gt_u32_e64 s[10:11], s24, v111
	v_cmp_gt_u32_e64 s[16:17], s24, v102
	v_and_b32_e32 v161, 0xffff0000, v77
	v_lshlrev_b32_e32 v139, 16, v77
	v_and_b32_e32 v160, 0xffff0000, v76
	v_lshlrev_b32_e32 v138, 16, v76
	v_cndmask_b32_e64 v166, 0, 1.0, s[6:7]
	v_and_b32_e32 v77, 0xffff0000, v27
	v_and_b32_e32 v76, 0xffff0000, v26
	v_pk_fma_f32 v[182:183], v[174:175], v[182:183], 0 op_sel_hi:[0,1,0]
	s_and_b64 s[10:11], s[10:11], s[2:3]
	v_cmp_gt_u32_e64 s[14:15], s24, v108
	v_cndmask_b32_e64 v150, 0, 1.0, s[16:17]
	v_and_b32_e32 v177, 0xffff0000, v73
	v_and_b32_e32 v176, 0xffff0000, v72
	s_waitcnt vmcnt(0) lgkmcnt(0)
	v_and_b32_e32 v79, 0xffff0000, v89
	v_lshlrev_b32_e32 v75, 16, v89
	v_and_b32_e32 v78, 0xffff0000, v88
	v_lshlrev_b32_e32 v74, 16, v88
	v_and_b32_e32 v89, 0xffff0000, v23
	v_and_b32_e32 v88, 0xffff0000, v22
	v_pk_fma_f32 v[186:187], v[88:89], 0, v[184:185] op_sel_hi:[1,0,1]
	v_lshlrev_b32_e32 v143, 16, v73
	v_lshlrev_b32_e32 v142, 16, v72
	v_and_b32_e32 v73, 0xffff0000, v31
	v_and_b32_e32 v72, 0xffff0000, v30
	v_pk_fma_f32 v[188:189], v[76:77], 0, v[186:187] op_sel_hi:[1,0,1]
	v_pk_fma_f32 v[186:187], v[164:165], v[76:77], v[186:187] op_sel_hi:[0,1,1]
	v_pk_fma_f32 v[184:185], v[166:167], v[88:89], v[184:185] op_sel_hi:[0,1,1]
	v_pk_fma_f32 v[88:89], v[166:167], v[88:89], v[182:183] op_sel_hi:[0,1,1]
	v_cndmask_b32_e64 v124, 0, 1.0, s[10:11]
	v_cmp_gt_u32_e64 s[10:11], s24, v110
	v_cndmask_b32_e64 v156, 0, v119, s[14:15]
	v_cndmask_b32_e64 v162, 0, v119, s[16:17]
	v_and_b32_e32 v173, 0xffff0000, v43
	v_and_b32_e32 v172, 0xffff0000, v42
	v_pk_fma_f32 v[186:187], v[150:151], v[72:73], v[186:187] op_sel_hi:[0,1,1]
	v_pk_fma_f32 v[184:185], v[164:165], v[76:77], v[184:185] op_sel_hi:[0,1,1]
	v_pk_fma_f32 v[76:77], v[168:169], v[76:77], v[88:89] op_sel_hi:[0,1,1]
	v_cndmask_b32_e64 v132, 0, v119, s[10:11]
	v_cndmask_b32_e64 v134, 0, v119, s[12:13]
	s_and_b64 s[10:11], s[10:11], s[2:3]
	s_and_b64 s[6:7], s[0:1], s[8:9]
	v_pk_fma_f32 v[188:189], v[150:151], v[72:73], v[188:189] op_sel_hi:[0,1,1]
	v_pk_fma_f32 v[184:185], v[162:163], v[72:73], v[184:185] op_sel_hi:[0,1,1]
	v_pk_fma_f32 v[182:183], v[162:163], v[72:73], v[76:77] op_sel_hi:[0,1,1]
	v_pk_fma_f32 v[72:73], v[156:157], v[172:173], v[186:187] op_sel_hi:[0,1,1]
	v_cndmask_b32_e64 v144, 0, 1.0, s[10:11]
	v_cndmask_b32_e64 v152, 0, 1.0, s[6:7]
	s_and_b64 s[6:7], s[14:15], s[2:3]
	v_pk_fma_f32 v[72:73], v[134:135], v[170:171], v[72:73] op_sel_hi:[0,1,1]
	v_cndmask_b32_e64 v136, 0, 1.0, s[14:15]
	v_cndmask_b32_e64 v154, 0, 1.0, s[6:7]
	v_and_b32_e32 v197, 0xffff0000, v35
	v_and_b32_e32 v196, 0xffff0000, v34
	v_pk_fma_f32 v[72:73], v[144:145], v[158:159], v[72:73] op_sel_hi:[0,1,1]
	v_pk_fma_f32 v[88:89], v[156:157], v[172:173], v[184:185] op_sel_hi:[0,1,1]
	v_pk_fma_f32 v[76:77], v[124:125], v[196:197], v[72:73] op_sel_hi:[0,1,1]
	v_pk_fma_f32 v[72:73], v[136:137], v[172:173], v[188:189] op_sel_hi:[0,1,1]
	v_pk_fma_f32 v[172:173], v[154:155], v[172:173], v[182:183] op_sel_hi:[0,1,1]
	v_pk_fma_f32 v[72:73], v[134:135], v[170:171], v[72:73] op_sel_hi:[0,1,1]
	v_pk_fma_f32 v[88:89], v[148:149], v[170:171], v[88:89] op_sel_hi:[0,1,1]
	v_pk_fma_f32 v[170:171], v[148:149], v[170:171], v[172:173] op_sel_hi:[0,1,1]
	v_lshlrev_b32_e32 v19, 16, v19
	v_lshlrev_b32_e32 v18, 16, v18
	v_pk_fma_f32 v[72:73], v[132:133], v[158:159], v[72:73] op_sel_hi:[0,1,1]
	v_pk_fma_f32 v[88:89], v[144:145], v[158:159], v[88:89] op_sel_hi:[0,1,1]
	v_pk_fma_f32 v[158:159], v[144:145], v[158:159], v[170:171] op_sel_hi:[0,1,1]
	v_lshlrev_b32_e32 v23, 16, v23
	v_lshlrev_b32_e32 v22, 16, v22
	v_pk_fma_f32 v[170:171], v[18:19], 0, 0 op_sel_hi:[1,0,0]
	v_lshlrev_b32_e32 v27, 16, v27
	v_lshlrev_b32_e32 v26, 16, v26
	v_pk_fma_f32 v[172:173], v[22:23], 0, v[170:171] op_sel_hi:[1,0,1]
	v_pk_fma_f32 v[18:19], v[174:175], v[18:19], 0 op_sel_hi:[0,1,0]
	v_lshlrev_b32_e32 v31, 16, v31
	v_lshlrev_b32_e32 v30, 16, v30
	v_pk_fma_f32 v[182:183], v[26:27], 0, v[172:173] op_sel_hi:[1,0,1]
	v_pk_fma_f32 v[172:173], v[164:165], v[26:27], v[172:173] op_sel_hi:[0,1,1]
	v_pk_fma_f32 v[18:19], v[166:167], v[22:23], v[18:19] op_sel_hi:[0,1,1]
	v_lshlrev_b32_e32 v43, 16, v43
	v_lshlrev_b32_e32 v42, 16, v42
	v_pk_fma_f32 v[172:173], v[150:151], v[30:31], v[172:173] op_sel_hi:[0,1,1]
	v_pk_fma_f32 v[170:171], v[166:167], v[22:23], v[170:171] op_sel_hi:[0,1,1]
	v_pk_fma_f32 v[18:19], v[168:169], v[26:27], v[18:19] op_sel_hi:[0,1,1]
	v_pk_fma_f32 v[170:171], v[164:165], v[26:27], v[170:171] op_sel_hi:[0,1,1]
	v_pk_fma_f32 v[26:27], v[162:163], v[30:31], v[18:19] op_sel_hi:[0,1,1]
	v_pk_fma_f32 v[18:19], v[156:157], v[42:43], v[172:173] op_sel_hi:[0,1,1]
	v_pk_fma_f32 v[18:19], v[134:135], v[180:181], v[18:19] op_sel_hi:[0,1,1]
	v_pk_fma_f32 v[182:183], v[150:151], v[30:31], v[182:183] op_sel_hi:[0,1,1]
	v_pk_fma_f32 v[170:171], v[162:163], v[30:31], v[170:171] op_sel_hi:[0,1,1]
	v_lshlrev_b32_e32 v35, 16, v35
	v_lshlrev_b32_e32 v34, 16, v34
	v_pk_fma_f32 v[18:19], v[144:145], v[178:179], v[18:19] op_sel_hi:[0,1,1]
	v_pk_fma_f32 v[30:31], v[156:157], v[42:43], v[170:171] op_sel_hi:[0,1,1]
	v_pk_fma_f32 v[22:23], v[124:125], v[34:35], v[18:19] op_sel_hi:[0,1,1]
	v_pk_fma_f32 v[18:19], v[136:137], v[42:43], v[182:183] op_sel_hi:[0,1,1]
	v_pk_fma_f32 v[26:27], v[154:155], v[42:43], v[26:27] op_sel_hi:[0,1,1]
	v_pk_fma_f32 v[18:19], v[134:135], v[180:181], v[18:19] op_sel_hi:[0,1,1]
	v_pk_fma_f32 v[30:31], v[148:149], v[180:181], v[30:31] op_sel_hi:[0,1,1]
	v_pk_fma_f32 v[26:27], v[148:149], v[180:181], v[26:27] op_sel_hi:[0,1,1]
	v_pk_fma_f32 v[18:19], v[132:133], v[178:179], v[18:19] op_sel_hi:[0,1,1]
	v_pk_fma_f32 v[30:31], v[144:145], v[178:179], v[30:31] op_sel_hi:[0,1,1]
	v_pk_fma_f32 v[26:27], v[144:145], v[178:179], v[26:27] op_sel_hi:[0,1,1]
	v_and_b32_e32 v195, 0xffff0000, v39
	v_and_b32_e32 v194, 0xffff0000, v38
	v_lshlrev_b32_e32 v39, 16, v39
	v_lshlrev_b32_e32 v38, 16, v38
	v_pk_fma_f32 v[18:19], v[124:125], v[34:35], v[18:19] op_sel_hi:[0,1,1]
	v_pk_fma_f32 v[30:31], v[124:125], v[34:35], v[30:31] op_sel_hi:[0,1,1]
	v_pk_fma_f32 v[26:27], v[124:125], v[34:35], v[26:27] op_sel_hi:[0,1,1]
	v_and_b32_e32 v193, 0xffff0000, v47
	v_and_b32_e32 v192, 0xffff0000, v46
	v_lshlrev_b32_e32 v47, 16, v47
	v_lshlrev_b32_e32 v46, 16, v46
	v_pk_fma_f32 v[18:19], v[128:129], v[38:39], v[18:19] op_sel_hi:[0,1,1]
	v_pk_fma_f32 v[22:23], v[128:129], v[38:39], v[22:23] op_sel_hi:[0,1,1]
	v_pk_fma_f32 v[30:31], v[128:129], v[38:39], v[30:31] op_sel_hi:[0,1,1]
	v_pk_fma_f32 v[26:27], v[152:153], v[38:39], v[26:27] op_sel_hi:[0,1,1]
	v_cndmask_b32_e64 v140, 0, 1.0, s[26:27]
	v_and_b32_e32 v191, 0xffff0000, v51
	v_and_b32_e32 v190, 0xffff0000, v50
	v_lshlrev_b32_e32 v51, 16, v51
	v_lshlrev_b32_e32 v50, 16, v50
	v_pk_fma_f32 v[18:19], v[130:131], v[46:47], v[18:19] op_sel_hi:[0,1,1]
	v_pk_fma_f32 v[22:23], v[130:131], v[46:47], v[22:23] op_sel_hi:[0,1,1]
	v_pk_fma_f32 v[30:31], v[146:147], v[46:47], v[30:31] op_sel_hi:[0,1,1]
	v_pk_fma_f32 v[26:27], v[146:147], v[46:47], v[26:27] op_sel_hi:[0,1,1]
	v_and_b32_e32 v199, 0xffff0000, v59
	v_and_b32_e32 v198, 0xffff0000, v58
	v_lshlrev_b32_e32 v59, 16, v59
	v_lshlrev_b32_e32 v58, 16, v58
	v_pk_fma_f32 v[18:19], v[126:127], v[50:51], v[18:19] op_sel_hi:[0,1,1]
	v_pk_fma_f32 v[22:23], v[140:141], v[50:51], v[22:23] op_sel_hi:[0,1,1]
	v_pk_fma_f32 v[30:31], v[140:141], v[50:51], v[30:31] op_sel_hi:[0,1,1]
	v_pk_fma_f32 v[26:27], v[140:141], v[50:51], v[26:27] op_sel_hi:[0,1,1]
	v_and_b32_e32 v201, 0xffff0000, v55
	v_and_b32_e32 v200, 0xffff0000, v54
	v_lshlrev_b32_e32 v55, 16, v55
	v_lshlrev_b32_e32 v54, 16, v54
	v_pk_fma_f32 v[18:19], v[122:123], v[58:59], v[18:19] op_sel_hi:[0,1,1]
	v_pk_fma_f32 v[22:23], v[122:123], v[58:59], v[22:23] op_sel_hi:[0,1,1]
	v_pk_fma_f32 v[30:31], v[122:123], v[58:59], v[30:31] op_sel_hi:[0,1,1]
	v_pk_fma_f32 v[26:27], v[122:123], v[58:59], v[26:27] op_sel_hi:[0,1,1]
	v_and_b32_e32 v51, 0xffff0000, v17
	v_and_b32_e32 v50, 0xffff0000, v16
	v_and_b32_e32 v203, 0xffff0000, v63
	v_and_b32_e32 v202, 0xffff0000, v62
	v_lshlrev_b32_e32 v63, 16, v63
	v_lshlrev_b32_e32 v62, 16, v62
	v_pk_fma_f32 v[18:19], v[120:121], v[54:55], v[18:19] op_sel_hi:[0,1,1]
	v_pk_fma_f32 v[22:23], v[120:121], v[54:55], v[22:23] op_sel_hi:[0,1,1]
	v_pk_fma_f32 v[30:31], v[120:121], v[54:55], v[30:31] op_sel_hi:[0,1,1]
	v_pk_fma_f32 v[26:27], v[120:121], v[54:55], v[26:27] op_sel_hi:[0,1,1]
	v_and_b32_e32 v43, 0xffff0000, v21
	v_and_b32_e32 v42, 0xffff0000, v20
	v_pk_fma_f32 v[54:55], v[50:51], 0, 0 op_sel_hi:[1,0,0]
	v_and_b32_e32 v205, 0xffff0000, v67
	v_and_b32_e32 v204, 0xffff0000, v66
	v_lshlrev_b32_e32 v67, 16, v67
	v_lshlrev_b32_e32 v66, 16, v66
	v_pk_fma_f32 v[26:27], v[118:119], v[62:63], v[26:27] op_sel_hi:[0,1,1]
	v_and_b32_e32 v35, 0xffff0000, v25
	v_and_b32_e32 v34, 0xffff0000, v24
	v_pk_fma_f32 v[58:59], v[42:43], 0, v[54:55] op_sel_hi:[1,0,1]
	v_pk_fma_f32 v[50:51], v[174:175], v[50:51], 0 op_sel_hi:[0,1,0]
	v_pk_fma_f32 v[18:19], v[118:119], v[62:63], v[18:19] op_sel_hi:[0,1,1]
	v_pk_fma_f32 v[22:23], v[118:119], v[62:63], v[22:23] op_sel_hi:[0,1,1]
	v_pk_fma_f32 v[30:31], v[118:119], v[62:63], v[30:31] op_sel_hi:[0,1,1]
	v_pk_fma_f32 v[38:39], v[116:117], v[66:67], v[26:27] op_sel_hi:[0,1,1]
	v_and_b32_e32 v27, 0xffff0000, v29
	v_and_b32_e32 v26, 0xffff0000, v28
	v_pk_fma_f32 v[62:63], v[34:35], 0, v[58:59] op_sel_hi:[1,0,1]
	v_pk_fma_f32 v[58:59], v[164:165], v[34:35], v[58:59] op_sel_hi:[0,1,1]
	v_pk_fma_f32 v[54:55], v[166:167], v[42:43], v[54:55] op_sel_hi:[0,1,1]
	v_pk_fma_f32 v[42:43], v[166:167], v[42:43], v[50:51] op_sel_hi:[0,1,1]
	v_and_b32_e32 v47, 0xffff0000, v41
	v_and_b32_e32 v46, 0xffff0000, v40
	v_pk_fma_f32 v[58:59], v[150:151], v[26:27], v[58:59] op_sel_hi:[0,1,1]
	v_pk_fma_f32 v[54:55], v[164:165], v[34:35], v[54:55] op_sel_hi:[0,1,1]
	v_pk_fma_f32 v[34:35], v[168:169], v[34:35], v[42:43] op_sel_hi:[0,1,1]
	v_pk_fma_f32 v[62:63], v[150:151], v[26:27], v[62:63] op_sel_hi:[0,1,1]
	v_pk_fma_f32 v[54:55], v[162:163], v[26:27], v[54:55] op_sel_hi:[0,1,1]
	v_pk_fma_f32 v[50:51], v[162:163], v[26:27], v[34:35] op_sel_hi:[0,1,1]
	v_pk_fma_f32 v[26:27], v[156:157], v[46:47], v[58:59] op_sel_hi:[0,1,1]
	v_pk_fma_f32 v[26:27], v[134:135], v[176:177], v[26:27] op_sel_hi:[0,1,1]
	v_and_b32_e32 v179, 0xffff0000, v33
	v_and_b32_e32 v178, 0xffff0000, v32
	v_pk_fma_f32 v[26:27], v[144:145], v[160:161], v[26:27] op_sel_hi:[0,1,1]
	v_lshlrev_b32_e32 v17, 16, v17
	v_lshlrev_b32_e32 v16, 16, v16
	v_pk_fma_f32 v[42:43], v[156:157], v[46:47], v[54:55] op_sel_hi:[0,1,1]
	v_pk_fma_f32 v[34:35], v[124:125], v[178:179], v[26:27] op_sel_hi:[0,1,1]
	v_pk_fma_f32 v[26:27], v[136:137], v[46:47], v[62:63] op_sel_hi:[0,1,1]
	v_pk_fma_f32 v[46:47], v[154:155], v[46:47], v[50:51] op_sel_hi:[0,1,1]
	v_lshlrev_b32_e32 v21, 16, v21
	v_lshlrev_b32_e32 v20, 16, v20
	v_pk_fma_f32 v[50:51], v[16:17], 0, 0 op_sel_hi:[1,0,0]
	v_lshlrev_b32_e32 v25, 16, v25
	v_lshlrev_b32_e32 v24, 16, v24
	v_pk_fma_f32 v[54:55], v[20:21], 0, v[50:51] op_sel_hi:[1,0,1]
	v_pk_fma_f32 v[16:17], v[174:175], v[16:17], 0 op_sel_hi:[0,1,0]
	v_lshlrev_b32_e32 v29, 16, v29
	v_lshlrev_b32_e32 v28, 16, v28
	v_pk_fma_f32 v[58:59], v[24:25], 0, v[54:55] op_sel_hi:[1,0,1]
	v_pk_fma_f32 v[54:55], v[164:165], v[24:25], v[54:55] op_sel_hi:[0,1,1]
	v_pk_fma_f32 v[16:17], v[166:167], v[20:21], v[16:17] op_sel_hi:[0,1,1]
	v_lshlrev_b32_e32 v41, 16, v41
	v_lshlrev_b32_e32 v40, 16, v40
	v_pk_fma_f32 v[54:55], v[150:151], v[28:29], v[54:55] op_sel_hi:[0,1,1]
	v_pk_fma_f32 v[16:17], v[168:169], v[24:25], v[16:17] op_sel_hi:[0,1,1]
	v_pk_fma_f32 v[50:51], v[166:167], v[20:21], v[50:51] op_sel_hi:[0,1,1]
	v_pk_fma_f32 v[20:21], v[162:163], v[28:29], v[16:17] op_sel_hi:[0,1,1]
	v_pk_fma_f32 v[16:17], v[156:157], v[40:41], v[54:55] op_sel_hi:[0,1,1]
	v_pk_fma_f32 v[50:51], v[164:165], v[24:25], v[50:51] op_sel_hi:[0,1,1]
	v_pk_fma_f32 v[16:17], v[134:135], v[142:143], v[16:17] op_sel_hi:[0,1,1]
	v_and_b32_e32 v171, 0xffff0000, v45
	v_and_b32_e32 v170, 0xffff0000, v44
	v_pk_fma_f32 v[58:59], v[150:151], v[28:29], v[58:59] op_sel_hi:[0,1,1]
	v_pk_fma_f32 v[50:51], v[162:163], v[28:29], v[50:51] op_sel_hi:[0,1,1]
	v_lshlrev_b32_e32 v29, 16, v45
	v_lshlrev_b32_e32 v28, 16, v44
	v_lshlrev_b32_e32 v45, 16, v33
	v_lshlrev_b32_e32 v44, 16, v32
	v_pk_fma_f32 v[16:17], v[144:145], v[138:139], v[16:17] op_sel_hi:[0,1,1]
	v_pk_fma_f32 v[50:51], v[156:157], v[40:41], v[50:51] op_sel_hi:[0,1,1]
	v_pk_fma_f32 v[32:33], v[124:125], v[44:45], v[16:17] op_sel_hi:[0,1,1]
	v_pk_fma_f32 v[16:17], v[136:137], v[40:41], v[58:59] op_sel_hi:[0,1,1]
	v_pk_fma_f32 v[20:21], v[154:155], v[40:41], v[20:21] op_sel_hi:[0,1,1]
	v_pk_fma_f32 v[26:27], v[134:135], v[176:177], v[26:27] op_sel_hi:[0,1,1]
	v_pk_fma_f32 v[42:43], v[148:149], v[176:177], v[42:43] op_sel_hi:[0,1,1]
	v_pk_fma_f32 v[46:47], v[148:149], v[176:177], v[46:47] op_sel_hi:[0,1,1]
	v_pk_fma_f32 v[16:17], v[134:135], v[142:143], v[16:17] op_sel_hi:[0,1,1]
	v_pk_fma_f32 v[50:51], v[148:149], v[142:143], v[50:51] op_sel_hi:[0,1,1]
	v_pk_fma_f32 v[20:21], v[148:149], v[142:143], v[20:21] op_sel_hi:[0,1,1]
	v_pk_fma_f32 v[26:27], v[132:133], v[160:161], v[26:27] op_sel_hi:[0,1,1]
	v_pk_fma_f32 v[42:43], v[144:145], v[160:161], v[42:43] op_sel_hi:[0,1,1]
	v_pk_fma_f32 v[46:47], v[144:145], v[160:161], v[46:47] op_sel_hi:[0,1,1]
	v_pk_fma_f32 v[16:17], v[132:133], v[138:139], v[16:17] op_sel_hi:[0,1,1]
	v_pk_fma_f32 v[50:51], v[144:145], v[138:139], v[50:51] op_sel_hi:[0,1,1]
	v_pk_fma_f32 v[20:21], v[144:145], v[138:139], v[20:21] op_sel_hi:[0,1,1]
	v_pk_fma_f32 v[72:73], v[124:125], v[196:197], v[72:73] op_sel_hi:[0,1,1]
	v_pk_fma_f32 v[88:89], v[124:125], v[196:197], v[88:89] op_sel_hi:[0,1,1]
	v_pk_fma_f32 v[158:159], v[124:125], v[196:197], v[158:159] op_sel_hi:[0,1,1]
	v_and_b32_e32 v173, 0xffff0000, v37
	v_and_b32_e32 v172, 0xffff0000, v36
	v_pk_fma_f32 v[26:27], v[124:125], v[178:179], v[26:27] op_sel_hi:[0,1,1]
	v_pk_fma_f32 v[42:43], v[124:125], v[178:179], v[42:43] op_sel_hi:[0,1,1]
	v_pk_fma_f32 v[46:47], v[124:125], v[178:179], v[46:47] op_sel_hi:[0,1,1]
	v_lshlrev_b32_e32 v37, 16, v37
	v_lshlrev_b32_e32 v36, 16, v36
	v_pk_fma_f32 v[16:17], v[124:125], v[44:45], v[16:17] op_sel_hi:[0,1,1]
	v_pk_fma_f32 v[50:51], v[124:125], v[44:45], v[50:51] op_sel_hi:[0,1,1]
	v_pk_fma_f32 v[20:21], v[124:125], v[44:45], v[20:21] op_sel_hi:[0,1,1]
	v_pk_fma_f32 v[72:73], v[128:129], v[194:195], v[72:73] op_sel_hi:[0,1,1]
	v_pk_fma_f32 v[76:77], v[128:129], v[194:195], v[76:77] op_sel_hi:[0,1,1]
	v_pk_fma_f32 v[88:89], v[128:129], v[194:195], v[88:89] op_sel_hi:[0,1,1]
	v_pk_fma_f32 v[158:159], v[152:153], v[194:195], v[158:159] op_sel_hi:[0,1,1]
	v_pk_fma_f32 v[26:27], v[128:129], v[172:173], v[26:27] op_sel_hi:[0,1,1]
	v_pk_fma_f32 v[34:35], v[128:129], v[172:173], v[34:35] op_sel_hi:[0,1,1]
	v_pk_fma_f32 v[42:43], v[128:129], v[172:173], v[42:43] op_sel_hi:[0,1,1]
	v_pk_fma_f32 v[46:47], v[152:153], v[172:173], v[46:47] op_sel_hi:[0,1,1]
	v_pk_fma_f32 v[16:17], v[128:129], v[36:37], v[16:17] op_sel_hi:[0,1,1]
	v_pk_fma_f32 v[32:33], v[128:129], v[36:37], v[32:33] op_sel_hi:[0,1,1]
	v_pk_fma_f32 v[50:51], v[128:129], v[36:37], v[50:51] op_sel_hi:[0,1,1]
	v_pk_fma_f32 v[20:21], v[152:153], v[36:37], v[20:21] op_sel_hi:[0,1,1]
	v_pk_fma_f32 v[72:73], v[130:131], v[192:193], v[72:73] op_sel_hi:[0,1,1]
	v_pk_fma_f32 v[76:77], v[130:131], v[192:193], v[76:77] op_sel_hi:[0,1,1]
	v_pk_fma_f32 v[88:89], v[146:147], v[192:193], v[88:89] op_sel_hi:[0,1,1]
	v_pk_fma_f32 v[158:159], v[146:147], v[192:193], v[158:159] op_sel_hi:[0,1,1]
	v_pk_fma_f32 v[18:19], v[116:117], v[66:67], v[18:19] op_sel_hi:[0,1,1]
	v_pk_fma_f32 v[22:23], v[116:117], v[66:67], v[22:23] op_sel_hi:[0,1,1]
	v_pk_fma_f32 v[30:31], v[116:117], v[66:67], v[30:31] op_sel_hi:[0,1,1]
	v_and_b32_e32 v67, 0xffff0000, v49
	v_and_b32_e32 v66, 0xffff0000, v48
	v_pk_fma_f32 v[26:27], v[130:131], v[170:171], v[26:27] op_sel_hi:[0,1,1]
	v_pk_fma_f32 v[34:35], v[130:131], v[170:171], v[34:35] op_sel_hi:[0,1,1]
	v_pk_fma_f32 v[42:43], v[146:147], v[170:171], v[42:43] op_sel_hi:[0,1,1]
	v_pk_fma_f32 v[46:47], v[146:147], v[170:171], v[46:47] op_sel_hi:[0,1,1]
	v_lshlrev_b32_e32 v25, 16, v49
	v_lshlrev_b32_e32 v24, 16, v48
	v_pk_fma_f32 v[16:17], v[130:131], v[28:29], v[16:17] op_sel_hi:[0,1,1]
	v_pk_fma_f32 v[32:33], v[130:131], v[28:29], v[32:33] op_sel_hi:[0,1,1]
	v_pk_fma_f32 v[50:51], v[146:147], v[28:29], v[50:51] op_sel_hi:[0,1,1]
	v_pk_fma_f32 v[20:21], v[146:147], v[28:29], v[20:21] op_sel_hi:[0,1,1]
	v_pk_fma_f32 v[72:73], v[126:127], v[190:191], v[72:73] op_sel_hi:[0,1,1]
	v_pk_fma_f32 v[76:77], v[140:141], v[190:191], v[76:77] op_sel_hi:[0,1,1]
	v_pk_fma_f32 v[88:89], v[140:141], v[190:191], v[88:89] op_sel_hi:[0,1,1]
	v_pk_fma_f32 v[158:159], v[140:141], v[190:191], v[158:159] op_sel_hi:[0,1,1]
	v_and_b32_e32 v181, 0xffff0000, v57
	v_and_b32_e32 v180, 0xffff0000, v56
	v_pk_fma_f32 v[26:27], v[126:127], v[66:67], v[26:27] op_sel_hi:[0,1,1]
	v_pk_fma_f32 v[34:35], v[140:141], v[66:67], v[34:35] op_sel_hi:[0,1,1]
	v_pk_fma_f32 v[42:43], v[140:141], v[66:67], v[42:43] op_sel_hi:[0,1,1]
	v_pk_fma_f32 v[46:47], v[140:141], v[66:67], v[46:47] op_sel_hi:[0,1,1]
	v_lshlrev_b32_e32 v49, 16, v57
	v_lshlrev_b32_e32 v48, 16, v56
	v_pk_fma_f32 v[16:17], v[126:127], v[24:25], v[16:17] op_sel_hi:[0,1,1]
	v_pk_fma_f32 v[32:33], v[140:141], v[24:25], v[32:33] op_sel_hi:[0,1,1]
	v_pk_fma_f32 v[50:51], v[140:141], v[24:25], v[50:51] op_sel_hi:[0,1,1]
	v_pk_fma_f32 v[20:21], v[140:141], v[24:25], v[20:21] op_sel_hi:[0,1,1]
	v_pk_fma_f32 v[72:73], v[122:123], v[198:199], v[72:73] op_sel_hi:[0,1,1]
	v_pk_fma_f32 v[76:77], v[122:123], v[198:199], v[76:77] op_sel_hi:[0,1,1]
	v_pk_fma_f32 v[88:89], v[122:123], v[198:199], v[88:89] op_sel_hi:[0,1,1]
	v_pk_fma_f32 v[158:159], v[122:123], v[198:199], v[158:159] op_sel_hi:[0,1,1]
	v_and_b32_e32 v183, 0xffff0000, v53
	v_and_b32_e32 v182, 0xffff0000, v52
	v_pk_fma_f32 v[26:27], v[122:123], v[180:181], v[26:27] op_sel_hi:[0,1,1]
	v_pk_fma_f32 v[34:35], v[122:123], v[180:181], v[34:35] op_sel_hi:[0,1,1]
	v_pk_fma_f32 v[42:43], v[122:123], v[180:181], v[42:43] op_sel_hi:[0,1,1]
	v_pk_fma_f32 v[46:47], v[122:123], v[180:181], v[46:47] op_sel_hi:[0,1,1]
	v_lshlrev_b32_e32 v53, 16, v53
	v_lshlrev_b32_e32 v52, 16, v52
	v_pk_fma_f32 v[16:17], v[122:123], v[48:49], v[16:17] op_sel_hi:[0,1,1]
	v_pk_fma_f32 v[32:33], v[122:123], v[48:49], v[32:33] op_sel_hi:[0,1,1]
	v_pk_fma_f32 v[50:51], v[122:123], v[48:49], v[50:51] op_sel_hi:[0,1,1]
	v_pk_fma_f32 v[20:21], v[122:123], v[48:49], v[20:21] op_sel_hi:[0,1,1]
	v_pk_fma_f32 v[72:73], v[120:121], v[200:201], v[72:73] op_sel_hi:[0,1,1]
	v_pk_fma_f32 v[76:77], v[120:121], v[200:201], v[76:77] op_sel_hi:[0,1,1]
	v_pk_fma_f32 v[88:89], v[120:121], v[200:201], v[88:89] op_sel_hi:[0,1,1]
	v_pk_fma_f32 v[158:159], v[120:121], v[200:201], v[158:159] op_sel_hi:[0,1,1]
	v_and_b32_e32 v185, 0xffff0000, v61
	v_and_b32_e32 v184, 0xffff0000, v60
	v_pk_fma_f32 v[26:27], v[120:121], v[182:183], v[26:27] op_sel_hi:[0,1,1]
	v_pk_fma_f32 v[34:35], v[120:121], v[182:183], v[34:35] op_sel_hi:[0,1,1]
	v_pk_fma_f32 v[42:43], v[120:121], v[182:183], v[42:43] op_sel_hi:[0,1,1]
	v_pk_fma_f32 v[46:47], v[120:121], v[182:183], v[46:47] op_sel_hi:[0,1,1]
	v_lshlrev_b32_e32 v57, 16, v61
	v_lshlrev_b32_e32 v56, 16, v60
	v_pk_fma_f32 v[16:17], v[120:121], v[52:53], v[16:17] op_sel_hi:[0,1,1]
	v_pk_fma_f32 v[32:33], v[120:121], v[52:53], v[32:33] op_sel_hi:[0,1,1]
	v_pk_fma_f32 v[50:51], v[120:121], v[52:53], v[50:51] op_sel_hi:[0,1,1]
	v_pk_fma_f32 v[20:21], v[120:121], v[52:53], v[20:21] op_sel_hi:[0,1,1]
	v_pk_fma_f32 v[72:73], v[118:119], v[202:203], v[72:73] op_sel_hi:[0,1,1]
	v_pk_fma_f32 v[76:77], v[118:119], v[202:203], v[76:77] op_sel_hi:[0,1,1]
	v_pk_fma_f32 v[88:89], v[118:119], v[202:203], v[88:89] op_sel_hi:[0,1,1]
	v_pk_fma_f32 v[158:159], v[118:119], v[202:203], v[158:159] op_sel_hi:[0,1,1]
	v_and_b32_e32 v187, 0xffff0000, v65
	v_and_b32_e32 v186, 0xffff0000, v64
	v_pk_fma_f32 v[26:27], v[118:119], v[184:185], v[26:27] op_sel_hi:[0,1,1]
	v_pk_fma_f32 v[34:35], v[118:119], v[184:185], v[34:35] op_sel_hi:[0,1,1]
	v_pk_fma_f32 v[42:43], v[118:119], v[184:185], v[42:43] op_sel_hi:[0,1,1]
	v_pk_fma_f32 v[46:47], v[118:119], v[184:185], v[46:47] op_sel_hi:[0,1,1]
	v_lshlrev_b32_e32 v61, 16, v65
	v_lshlrev_b32_e32 v60, 16, v64
	v_pk_fma_f32 v[16:17], v[118:119], v[56:57], v[16:17] op_sel_hi:[0,1,1]
	v_pk_fma_f32 v[32:33], v[118:119], v[56:57], v[32:33] op_sel_hi:[0,1,1]
	v_pk_fma_f32 v[50:51], v[118:119], v[56:57], v[50:51] op_sel_hi:[0,1,1]
	v_pk_fma_f32 v[20:21], v[118:119], v[56:57], v[20:21] op_sel_hi:[0,1,1]
	v_and_b32_e32 v103, 0xffff0000, v91
	v_lshlrev_b32_e32 v91, 16, v91
	v_and_b32_e32 v102, 0xffff0000, v90
	v_and_b32_e32 v109, 0xffff0000, v87
	v_and_b32_e32 v108, 0xffff0000, v86
	v_and_b32_e32 v111, 0xffff0000, v83
	v_and_b32_e32 v110, 0xffff0000, v82
	v_lshlrev_b32_e32 v90, 16, v90
	v_lshlrev_b32_e32 v87, 16, v87
	v_lshlrev_b32_e32 v86, 16, v86
	v_lshlrev_b32_e32 v83, 16, v83
	v_lshlrev_b32_e32 v82, 16, v82
	v_and_b32_e32 v113, 0xffff0000, v85
	v_and_b32_e32 v112, 0xffff0000, v84
	v_and_b32_e32 v115, 0xffff0000, v81
	v_and_b32_e32 v114, 0xffff0000, v80
	v_lshlrev_b32_e32 v85, 16, v85
	v_lshlrev_b32_e32 v84, 16, v84
	v_lshlrev_b32_e32 v81, 16, v81
	v_lshlrev_b32_e32 v80, 16, v80
	v_pk_fma_f32 v[72:73], v[116:117], v[204:205], v[72:73] op_sel_hi:[0,1,1]
	v_pk_fma_f32 v[76:77], v[116:117], v[204:205], v[76:77] op_sel_hi:[0,1,1]
	v_pk_fma_f32 v[88:89], v[116:117], v[204:205], v[88:89] op_sel_hi:[0,1,1]
	v_pk_fma_f32 v[158:159], v[116:117], v[204:205], v[158:159] op_sel_hi:[0,1,1]
	v_pk_fma_f32 v[26:27], v[116:117], v[186:187], v[26:27] op_sel_hi:[0,1,1]
	v_pk_fma_f32 v[34:35], v[116:117], v[186:187], v[34:35] op_sel_hi:[0,1,1]
	v_pk_fma_f32 v[42:43], v[116:117], v[186:187], v[42:43] op_sel_hi:[0,1,1]
	v_pk_fma_f32 v[46:47], v[116:117], v[186:187], v[46:47] op_sel_hi:[0,1,1]
	v_pk_fma_f32 v[16:17], v[116:117], v[60:61], v[16:17] op_sel_hi:[0,1,1]
	v_pk_fma_f32 v[32:33], v[116:117], v[60:61], v[32:33] op_sel_hi:[0,1,1]
	v_pk_fma_f32 v[50:51], v[116:117], v[60:61], v[50:51] op_sel_hi:[0,1,1]
	v_pk_fma_f32 v[28:29], v[116:117], v[60:61], v[20:21] op_sel_hi:[0,1,1]
	v_add_u32_e32 v21, v129, v117
	v_max_i32_e32 v20, 0, v99
	v_min_i32_e32 v21, s24, v21
	v_sub_u32_e32 v20, v21, v20
	v_cvt_f32_i32_e32 v20, v20
	v_and_b32_e32 v21, 0xffff0000, v69
	v_pk_fma_f32 v[28:29], v[106:107], v[80:81], v[28:29] op_sel_hi:[0,1,1]
	v_pk_fma_f32 v[28:29], v[84:85], 0, v[28:29] op_sel_hi:[1,0,1]
	v_div_scale_f32 v24, s[6:7], v20, v20, 1.0
	v_rcp_f32_e32 v25, v24
	v_div_scale_f32 v36, vcc, 1.0, v20, 1.0
	v_and_b32_e32 v45, 0xffff0000, v13
	v_fma_f32 v37, -v24, v25, 1.0
	v_fmac_f32_e32 v25, v37, v25
	v_mul_f32_e32 v37, v36, v25
	v_fma_f32 v40, -v24, v37, v36
	v_fmac_f32_e32 v37, v40, v25
	v_fma_f32 v24, -v24, v37, v36
	v_pk_fma_f32 v[40:41], v[106:107], v[114:115], v[46:47] op_sel_hi:[0,1,1]
	v_div_fmas_f32 v24, v24, v25, v37
	v_pk_fma_f32 v[40:41], v[112:113], 0, v[40:41] op_sel_hi:[1,0,1]
	v_div_fixup_f32 v36, v24, v20, 1.0
	v_and_b32_e32 v20, 0xffff0000, v68
	v_pk_fma_f32 v[40:41], v[78:79], 0, v[40:41] op_sel_hi:[1,0,1]
	v_and_b32_e32 v44, 0xffff0000, v12
	v_pk_fma_f32 v[40:41], v[20:21], 0, v[40:41] op_sel_hi:[1,0,1]
	v_lshlrev_b32_e32 v25, 16, v69
	v_lshlrev_b32_e32 v24, 16, v68
	v_pk_fma_f32 v[28:29], v[74:75], 0, v[28:29] op_sel_hi:[1,0,1]
	v_pk_fma_f32 v[40:41], v[36:37], v[40:41], v[44:45] op_sel_hi:[0,1,1] neg_lo:[0,0,1] neg_hi:[0,0,1]
	v_pk_fma_f32 v[44:45], v[106:107], v[110:111], v[158:159] op_sel_hi:[0,1,1]
	v_pk_fma_f32 v[38:39], v[106:107], v[82:83], v[38:39] op_sel_hi:[0,1,1]
	v_pk_fma_f32 v[28:29], v[24:25], 0, v[28:29] op_sel_hi:[1,0,1]
	v_lshlrev_b32_e32 v13, 16, v13
	v_lshlrev_b32_e32 v12, 16, v12
	v_pk_fma_f32 v[44:45], v[108:109], 0, v[44:45] op_sel_hi:[1,0,1]
	v_pk_fma_f32 v[38:39], v[86:87], 0, v[38:39] op_sel_hi:[1,0,1]
	v_pk_fma_f32 v[46:47], v[36:37], v[28:29], v[12:13] op_sel_hi:[0,1,1] neg_lo:[0,0,1] neg_hi:[0,0,1]
	v_and_b32_e32 v13, 0xffff0000, v71
	v_and_b32_e32 v12, 0xffff0000, v70
	v_lshlrev_b32_e32 v29, 16, v71
	v_lshlrev_b32_e32 v28, 16, v70
	v_pk_fma_f32 v[44:45], v[102:103], 0, v[44:45] op_sel_hi:[1,0,1]
	v_pk_fma_f32 v[38:39], v[90:91], 0, v[38:39] op_sel_hi:[1,0,1]
	v_pk_fma_f32 v[44:45], v[12:13], 0, v[44:45] op_sel_hi:[1,0,1]
	v_pk_fma_f32 v[38:39], v[28:29], 0, v[38:39] op_sel_hi:[1,0,1]
	v_and_b32_e32 v49, 0xffff0000, v15
	v_and_b32_e32 v48, 0xffff0000, v14
	v_lshlrev_b32_e32 v15, 16, v15
	v_lshlrev_b32_e32 v14, 16, v14
	v_pk_fma_f32 v[14:15], v[36:37], v[38:39], v[14:15] op_sel_hi:[0,1,1] neg_lo:[0,0,1] neg_hi:[0,0,1]
	v_pk_fma_f32 v[36:37], v[36:37], v[44:45], v[48:49] op_sel_hi:[0,1,1] neg_lo:[0,0,1] neg_hi:[0,0,1]
	v_bfe_u32 v38, v37, 16, 1
	v_bfe_u32 v39, v36, 16, 1
	v_bfe_u32 v44, v41, 16, 1
	v_bfe_u32 v45, v40, 16, 1
	v_add3_u32 v36, v36, v39, s77
	v_add3_u32 v37, v37, v38, s77
	v_bfe_u32 v38, v46, 16, 1
	v_bfe_u32 v39, v47, 16, 1
	v_add3_u32 v40, v40, v45, s77
	v_add3_u32 v41, v41, v44, s77
	v_bfe_u32 v44, v14, 16, 1
	v_bfe_u32 v45, v15, 16, 1
	v_add3_u32 v39, v47, v39, s77
	v_add3_u32 v38, v46, v38, s77
	v_add3_u32 v15, v15, v45, s77
	v_add3_u32 v14, v14, v44, s77
	v_lshrrev_b32_e32 v44, 16, v38
	v_lshrrev_b32_e32 v45, 16, v39
	v_sub_u32_e32 v38, v127, v117
	v_add_u32_e32 v39, v127, v117
	v_max_i32_e32 v38, 0, v38
	v_min_i32_e32 v39, s24, v39
	v_sub_u32_e32 v38, v39, v38
	v_cvt_f32_i32_e32 v46, v38
	v_lshrrev_b32_e32 v14, 16, v14
	v_lshrrev_b32_e32 v15, 16, v15
	v_and_or_b32 v38, v36, s25, v14
	v_div_scale_f32 v14, s[6:7], v46, v46, 1.0
	v_and_or_b32 v39, v37, s25, v15
	v_rcp_f32_e32 v15, v14
	v_and_or_b32 v37, v41, s25, v45
	v_and_or_b32 v36, v40, s25, v44
	global_store_dwordx4 v[96:97], v[36:39], off offset:1536
	v_pk_fma_f32 v[40:41], v[106:107], v[80:81], v[50:51] op_sel_hi:[0,1,1]
	v_pk_fma_f32 v[40:41], v[104:105], v[84:85], v[40:41] op_sel_hi:[0,1,1]
	v_fma_f32 v36, -v14, v15, 1.0
	v_fmac_f32_e32 v15, v36, v15
	v_div_scale_f32 v36, vcc, 1.0, v46, 1.0
	v_mul_f32_e32 v37, v36, v15
	v_fma_f32 v38, -v14, v37, v36
	v_fmac_f32_e32 v37, v38, v15
	v_fma_f32 v14, -v14, v37, v36
	v_div_fmas_f32 v14, v14, v15, v37
	v_pk_fma_f32 v[40:41], v[74:75], 0, v[40:41] op_sel_hi:[1,0,1]
	v_div_fixup_f32 v14, v14, v46, 1.0
	v_pk_fma_f32 v[38:39], v[106:107], v[114:115], v[42:43] op_sel_hi:[0,1,1]
	v_and_b32_e32 v43, 0xffff0000, v9
	v_and_b32_e32 v42, 0xffff0000, v8
	v_lshlrev_b32_e32 v9, 16, v9
	v_lshlrev_b32_e32 v8, 16, v8
	v_pk_fma_f32 v[40:41], v[24:25], 0, v[40:41] op_sel_hi:[1,0,1]
	v_pk_fma_f32 v[38:39], v[104:105], v[112:113], v[38:39] op_sel_hi:[0,1,1]
	v_pk_fma_f32 v[8:9], v[14:15], v[40:41], v[8:9] op_sel_hi:[0,1,1] neg_lo:[0,0,1] neg_hi:[0,0,1]
	v_pk_fma_f32 v[40:41], v[106:107], v[110:111], v[88:89] op_sel_hi:[0,1,1]
	v_pk_fma_f32 v[30:31], v[106:107], v[82:83], v[30:31] op_sel_hi:[0,1,1]
	v_pk_fma_f32 v[38:39], v[78:79], 0, v[38:39] op_sel_hi:[1,0,1]
	v_pk_fma_f32 v[40:41], v[104:105], v[108:109], v[40:41] op_sel_hi:[0,1,1]
	v_pk_fma_f32 v[30:31], v[104:105], v[86:87], v[30:31] op_sel_hi:[0,1,1]
	v_pk_fma_f32 v[38:39], v[20:21], 0, v[38:39] op_sel_hi:[1,0,1]
	v_pk_fma_f32 v[40:41], v[102:103], 0, v[40:41] op_sel_hi:[1,0,1]
	v_pk_fma_f32 v[30:31], v[90:91], 0, v[30:31] op_sel_hi:[1,0,1]
	v_pk_fma_f32 v[38:39], v[14:15], v[38:39], v[42:43] op_sel_hi:[0,1,1] neg_lo:[0,0,1] neg_hi:[0,0,1]
	v_and_b32_e32 v43, 0xffff0000, v11
	v_and_b32_e32 v42, 0xffff0000, v10
	v_lshlrev_b32_e32 v11, 16, v11
	v_lshlrev_b32_e32 v10, 16, v10
	v_pk_fma_f32 v[40:41], v[12:13], 0, v[40:41] op_sel_hi:[1,0,1]
	v_pk_fma_f32 v[30:31], v[28:29], 0, v[30:31] op_sel_hi:[1,0,1]
	v_add_u32_e32 v36, s23, v127
	v_pk_fma_f32 v[10:11], v[14:15], v[30:31], v[10:11] op_sel_hi:[0,1,1] neg_lo:[0,0,1] neg_hi:[0,0,1]
	v_pk_fma_f32 v[14:15], v[14:15], v[40:41], v[42:43] op_sel_hi:[0,1,1] neg_lo:[0,0,1] neg_hi:[0,0,1]
	v_bfe_u32 v30, v15, 16, 1
	v_bfe_u32 v31, v14, 16, 1
	v_add3_u32 v14, v14, v31, s77
	v_add3_u32 v15, v15, v30, s77
	v_bfe_u32 v30, v8, 16, 1
	v_bfe_u32 v31, v9, 16, 1
	v_add3_u32 v9, v9, v31, s77
	v_add3_u32 v8, v8, v30, s77
	v_sub_u32_e32 v30, v125, v117
	v_add_u32_e32 v31, v125, v117
	v_max_i32_e32 v30, 0, v30
	v_min_i32_e32 v31, s24, v31
	v_sub_u32_e32 v30, v31, v30
	v_bfe_u32 v40, v39, 16, 1
	v_cvt_f32_i32_e32 v30, v30
	v_bfe_u32 v41, v38, 16, 1
	v_add3_u32 v39, v39, v40, s77
	v_bfe_u32 v40, v10, 16, 1
	v_add3_u32 v38, v38, v41, s77
	v_bfe_u32 v41, v11, 16, 1
	v_add3_u32 v10, v10, v40, s77
	v_add3_u32 v11, v11, v41, s77
	v_lshrrev_b32_e32 v10, 16, v10
	v_lshrrev_b32_e32 v11, 16, v11
	v_and_or_b32 v10, v14, s25, v10
	v_div_scale_f32 v14, s[6:7], v30, v30, 1.0
	v_and_or_b32 v11, v15, s25, v11
	v_rcp_f32_e32 v15, v14
	v_ashrrev_i32_e32 v37, 31, v36
	v_lshlrev_b64 v[36:37], 11, v[36:37]
	v_lshrrev_b32_e32 v8, 16, v8
	v_lshrrev_b32_e32 v9, 16, v9
	v_lshl_add_u64 v[36:37], v[94:95], 0, v[36:37]
	v_and_or_b32 v9, v39, s25, v9
	v_and_or_b32 v8, v38, s25, v8
	global_store_dwordx4 v[36:37], v[8:11], off offset:1536
	v_pk_fma_f32 v[22:23], v[106:107], v[82:83], v[22:23] op_sel_hi:[0,1,1]
	v_pk_fma_f32 v[22:23], v[104:105], v[86:87], v[22:23] op_sel_hi:[0,1,1]
	v_fma_f32 v8, -v14, v15, 1.0
	v_fmac_f32_e32 v15, v8, v15
	v_div_scale_f32 v8, vcc, 1.0, v30, 1.0
	v_mul_f32_e32 v9, v8, v15
	v_fma_f32 v10, -v14, v9, v8
	v_fmac_f32_e32 v9, v10, v15
	v_fma_f32 v8, -v14, v9, v8
	v_div_fmas_f32 v8, v8, v15, v9
	v_div_fixup_f32 v8, v8, v30, 1.0
	v_pk_fma_f32 v[30:31], v[106:107], v[80:81], v[32:33] op_sel_hi:[0,1,1]
	v_pk_fma_f32 v[30:31], v[104:105], v[84:85], v[30:31] op_sel_hi:[0,1,1]
	v_pk_fma_f32 v[30:31], v[100:101], v[74:75], v[30:31] op_sel_hi:[0,1,1]
	v_pk_fma_f32 v[14:15], v[106:107], v[114:115], v[34:35] op_sel_hi:[0,1,1]
	v_and_b32_e32 v33, 0xffff0000, v5
	v_and_b32_e32 v32, 0xffff0000, v4
	v_lshlrev_b32_e32 v5, 16, v5
	v_lshlrev_b32_e32 v4, 16, v4
	v_pk_fma_f32 v[30:31], v[24:25], 0, v[30:31] op_sel_hi:[1,0,1]
	v_pk_fma_f32 v[14:15], v[104:105], v[112:113], v[14:15] op_sel_hi:[0,1,1]
	v_pk_fma_f32 v[4:5], v[8:9], v[30:31], v[4:5] op_sel_hi:[0,1,1] neg_lo:[0,0,1] neg_hi:[0,0,1]
	v_pk_fma_f32 v[30:31], v[106:107], v[110:111], v[76:77] op_sel_hi:[0,1,1]
	v_pk_fma_f32 v[14:15], v[100:101], v[78:79], v[14:15] op_sel_hi:[0,1,1]
	v_pk_fma_f32 v[30:31], v[104:105], v[108:109], v[30:31] op_sel_hi:[0,1,1]
	v_pk_fma_f32 v[14:15], v[20:21], 0, v[14:15] op_sel_hi:[1,0,1]
	v_pk_fma_f32 v[30:31], v[100:101], v[102:103], v[30:31] op_sel_hi:[0,1,1]
	v_pk_fma_f32 v[22:23], v[100:101], v[90:91], v[22:23] op_sel_hi:[0,1,1]
	v_pk_fma_f32 v[14:15], v[8:9], v[14:15], v[32:33] op_sel_hi:[0,1,1] neg_lo:[0,0,1] neg_hi:[0,0,1]
	v_and_b32_e32 v33, 0xffff0000, v7
	v_and_b32_e32 v32, 0xffff0000, v6
	v_lshlrev_b32_e32 v7, 16, v7
	v_lshlrev_b32_e32 v6, 16, v6
	v_pk_fma_f32 v[30:31], v[12:13], 0, v[30:31] op_sel_hi:[1,0,1]
	v_pk_fma_f32 v[22:23], v[28:29], 0, v[22:23] op_sel_hi:[1,0,1]
	v_add_u32_e32 v10, s23, v125
	v_pk_fma_f32 v[6:7], v[8:9], v[22:23], v[6:7] op_sel_hi:[0,1,1] neg_lo:[0,0,1] neg_hi:[0,0,1]
	v_pk_fma_f32 v[8:9], v[8:9], v[30:31], v[32:33] op_sel_hi:[0,1,1] neg_lo:[0,0,1] neg_hi:[0,0,1]
	v_bfe_u32 v22, v9, 16, 1
	v_bfe_u32 v23, v8, 16, 1
	v_add3_u32 v8, v8, v23, s77
	v_add3_u32 v9, v9, v22, s77
	v_bfe_u32 v22, v4, 16, 1
	v_bfe_u32 v23, v5, 16, 1
	v_add3_u32 v5, v5, v23, s77
	v_add3_u32 v4, v4, v22, s77
	v_sub_u32_e32 v22, v123, v117
	v_add_u32_e32 v23, v123, v117
	v_max_i32_e32 v22, 0, v22
	v_min_i32_e32 v23, s24, v23
	v_sub_u32_e32 v22, v23, v22
	v_bfe_u32 v30, v15, 16, 1
	v_cvt_f32_i32_e32 v22, v22
	v_bfe_u32 v31, v14, 16, 1
	v_add3_u32 v15, v15, v30, s77
	v_bfe_u32 v30, v6, 16, 1
	v_add3_u32 v14, v14, v31, s77
	v_bfe_u32 v31, v7, 16, 1
	v_add3_u32 v6, v6, v30, s77
	v_add3_u32 v7, v7, v31, s77
	v_lshrrev_b32_e32 v6, 16, v6
	v_lshrrev_b32_e32 v7, 16, v7
	v_and_or_b32 v6, v8, s25, v6
	v_div_scale_f32 v8, s[6:7], v22, v22, 1.0
	v_and_or_b32 v7, v9, s25, v7
	v_rcp_f32_e32 v9, v8
	v_ashrrev_i32_e32 v11, 31, v10
	v_lshlrev_b64 v[10:11], 11, v[10:11]
	v_lshrrev_b32_e32 v4, 16, v4
	v_lshrrev_b32_e32 v5, 16, v5
	v_lshl_add_u64 v[10:11], v[94:95], 0, v[10:11]
	v_and_or_b32 v5, v15, s25, v5
	v_and_or_b32 v4, v14, s25, v4
	global_store_dwordx4 v[10:11], v[4:7], off offset:1536
	v_pk_fma_f32 v[10:11], v[106:107], v[80:81], v[16:17] op_sel_hi:[0,1,1]
	v_pk_fma_f32 v[10:11], v[104:105], v[84:85], v[10:11] op_sel_hi:[0,1,1]
	v_fma_f32 v4, -v8, v9, 1.0
	v_fmac_f32_e32 v9, v4, v9
	v_div_scale_f32 v4, vcc, 1.0, v22, 1.0
	v_mul_f32_e32 v5, v4, v9
	v_fma_f32 v6, -v8, v5, v4
	v_fmac_f32_e32 v5, v6, v9
	v_fma_f32 v4, -v8, v5, v4
	v_div_fmas_f32 v4, v4, v9, v5
	v_pk_fma_f32 v[8:9], v[106:107], v[114:115], v[26:27] op_sel_hi:[0,1,1]
	v_pk_fma_f32 v[8:9], v[104:105], v[112:113], v[8:9] op_sel_hi:[0,1,1]
	v_pk_fma_f32 v[10:11], v[100:101], v[74:75], v[10:11] op_sel_hi:[0,1,1]
	v_div_fixup_f32 v4, v4, v22, 1.0
	v_and_b32_e32 v15, 0xffff0000, v1
	v_and_b32_e32 v14, 0xffff0000, v0
	v_lshlrev_b32_e32 v1, 16, v1
	v_lshlrev_b32_e32 v0, 16, v0
	v_pk_fma_f32 v[8:9], v[100:101], v[78:79], v[8:9] op_sel_hi:[0,1,1]
	v_pk_fma_f32 v[10:11], v[98:99], v[24:25], v[10:11] op_sel_hi:[0,1,1]
	v_pk_fma_f32 v[8:9], v[98:99], v[20:21], v[8:9] op_sel_hi:[0,1,1]
	v_pk_fma_f32 v[0:1], v[4:5], v[10:11], v[0:1] op_sel_hi:[0,1,1] neg_lo:[0,0,1] neg_hi:[0,0,1]
	v_pk_fma_f32 v[10:11], v[106:107], v[110:111], v[72:73] op_sel_hi:[0,1,1]
	v_pk_fma_f32 v[8:9], v[4:5], v[8:9], v[14:15] op_sel_hi:[0,1,1] neg_lo:[0,0,1] neg_hi:[0,0,1]
	v_pk_fma_f32 v[14:15], v[106:107], v[82:83], v[18:19] op_sel_hi:[0,1,1]
	v_pk_fma_f32 v[10:11], v[104:105], v[108:109], v[10:11] op_sel_hi:[0,1,1]
	v_pk_fma_f32 v[14:15], v[104:105], v[86:87], v[14:15] op_sel_hi:[0,1,1]
	v_pk_fma_f32 v[10:11], v[100:101], v[102:103], v[10:11] op_sel_hi:[0,1,1]
	v_pk_fma_f32 v[10:11], v[98:99], v[12:13], v[10:11] op_sel_hi:[0,1,1]
	v_pk_fma_f32 v[12:13], v[100:101], v[90:91], v[14:15] op_sel_hi:[0,1,1]
	v_and_b32_e32 v17, 0xffff0000, v3
	v_and_b32_e32 v16, 0xffff0000, v2
	v_lshlrev_b32_e32 v3, 16, v3
	v_lshlrev_b32_e32 v2, 16, v2
	v_pk_fma_f32 v[12:13], v[98:99], v[28:29], v[12:13] op_sel_hi:[0,1,1]
	v_pk_fma_f32 v[2:3], v[4:5], v[12:13], v[2:3] op_sel_hi:[0,1,1] neg_lo:[0,0,1] neg_hi:[0,0,1]
	v_pk_fma_f32 v[4:5], v[4:5], v[10:11], v[16:17] op_sel_hi:[0,1,1] neg_lo:[0,0,1] neg_hi:[0,0,1]
	v_bfe_u32 v10, v5, 16, 1
	v_bfe_u32 v11, v4, 16, 1
	v_bfe_u32 v12, v9, 16, 1
	v_bfe_u32 v13, v8, 16, 1
	v_add_u32_e32 v6, s23, v123
	v_add3_u32 v8, v8, v13, s77
	v_add3_u32 v9, v9, v12, s77
	v_add3_u32 v4, v4, v11, s77
	v_add3_u32 v5, v5, v10, s77
	v_bfe_u32 v10, v0, 16, 1
	v_bfe_u32 v11, v1, 16, 1
	v_bfe_u32 v12, v2, 16, 1
	v_bfe_u32 v13, v3, 16, 1
	v_ashrrev_i32_e32 v7, 31, v6
	v_add3_u32 v3, v3, v13, s77
	v_add3_u32 v2, v2, v12, s77
	v_add3_u32 v1, v1, v11, s77
	v_add3_u32 v0, v0, v10, s77
	v_lshlrev_b64 v[6:7], 11, v[6:7]
	v_lshrrev_b32_e32 v0, 16, v0
	v_lshrrev_b32_e32 v1, 16, v1
	v_lshrrev_b32_e32 v2, 16, v2
	v_lshrrev_b32_e32 v3, 16, v3
	v_lshl_add_u64 v[6:7], v[94:95], 0, v[6:7]
	v_and_or_b32 v3, v5, s25, v3
	v_and_or_b32 v2, v4, s25, v2
	v_and_or_b32 v1, v9, s25, v1
	v_and_or_b32 v0, v8, s25, v0
	global_store_dwordx4 v[6:7], v[0:3], off offset:1536
	s_branch .LBB0_337

.LBB0_389:
	s_bfe_u32 s1, s2, 0x60004
	s_ashr_i32 s7, s2, 10
	s_lshl_b32 s8, s7, 7
	s_lshl_b32 s9, s1, 1
	s_or_b32 s8, s9, s8
	s_ashr_i32 s9, s8, 31
	s_lshl_b64 s[8:9], s[8:9], 16
	s_add_u32 s8, s3, s8
	s_addc_u32 s9, s6, s9
	s_and_b32 s10, s0, 0xf0
	s_lshl_b32 s82, s10, 1
	s_add_u32 s8, s8, s82
	s_addc_u32 s9, s9, 0
	v_lshl_add_u64 v[0:1], s[8:9], 0, v[36:37]
	v_lshl_add_u64 v[4:5], v[0:1], 0, v[168:169]
	flat_load_ushort v6, v[4:5]
	flat_load_ushort v7, v[4:5] offset:512
	flat_load_ushort v8, v[4:5] offset:1024
	flat_load_ushort v9, v[4:5] offset:1536
	flat_load_ushort v10, v[4:5] offset:2048
	flat_load_ushort v11, v[4:5] offset:2560
	flat_load_ushort v12, v[4:5] offset:3072
	flat_load_ushort v13, v[4:5] offset:3584
	v_add_co_u32_e32 v2, vcc, s71, v4
	s_mov_b64 s[8:9], 0x4000
	s_nop 0
	v_addc_co_u32_e32 v3, vcc, 0, v5, vcc
	v_lshl_add_u64 v[0:1], v[4:5], 0, s[8:9]
	flat_load_ushort v34, v[2:3]
	flat_load_ushort v35, v[0:1] offset:512
	flat_load_ushort v46, v[0:1] offset:1024
	flat_load_ushort v47, v[0:1] offset:1536
	flat_load_ushort v48, v[0:1] offset:2048
	flat_load_ushort v49, v[0:1] offset:2560
	flat_load_ushort v50, v[0:1] offset:3072
	flat_load_ushort v51, v[0:1] offset:3584
	s_mov_b64 s[8:9], 0x8000
	v_add_co_u32_e32 v2, vcc, s50, v4
	v_lshl_add_u64 v[0:1], v[4:5], 0, s[8:9]
	s_nop 0
	v_addc_co_u32_e32 v3, vcc, 0, v5, vcc
	s_mov_b64 s[8:9], 0xc000
	flat_load_ushort v52, v[2:3]
	flat_load_ushort v53, v[0:1] offset:512
	flat_load_ushort v54, v[0:1] offset:1024
	flat_load_ushort v55, v[0:1] offset:1536
	flat_load_ushort v56, v[0:1] offset:2048
	flat_load_ushort v57, v[0:1] offset:2560
	flat_load_ushort v58, v[0:1] offset:3072
	flat_load_ushort v59, v[0:1] offset:3584
	v_lshl_add_u64 v[0:1], v[4:5], 0, s[8:9]
	s_mov_b32 s8, 0xc000
	v_add_co_u32_e32 v2, vcc, s8, v4
	s_mov_b64 s[8:9], 0x10000
	s_nop 0
	v_addc_co_u32_e32 v3, vcc, 0, v5, vcc
	flat_load_ushort v60, v[2:3]
	flat_load_ushort v61, v[0:1] offset:512
	flat_load_ushort v62, v[0:1] offset:1024
	flat_load_ushort v63, v[0:1] offset:1536
	flat_load_ushort v64, v[0:1] offset:2048
	flat_load_ushort v65, v[0:1] offset:2560
	flat_load_ushort v66, v[0:1] offset:3072
	flat_load_ushort v67, v[0:1] offset:3584
	ds_read_b128 v[14:17], v40 offset:16896
	ds_read_b128 v[18:21], v40 offset:25344
	ds_read_b128 v[22:25], v40 offset:33792
	ds_read_b128 v[26:29], v40 offset:42240
	ds_read_b128 v[30:33], v40 offset:50688
	ds_read_b128 v[42:45], v40 offset:59136
	s_add_i32 s2, s2, s70
	s_add_i32 s0, s0, s81
	s_cmpk_lt_i32 s2, 0x800
	s_waitcnt vmcnt(0) lgkmcnt(0)
	v_perm_b32 v0, v7, v6, s89
	v_perm_b32 v1, v9, v8, s89
	ds_read_b128 v[6:9], v40
	v_perm_b32 v2, v11, v10, s89
	v_perm_b32 v3, v13, v12, s89
	ds_read_b128 v[10:13], v40 offset:8448
	s_waitcnt lgkmcnt(1)
	v_mfma_f32_16x16x32_bf16 v[6:9], v[6:9], v[0:3], 0
	s_waitcnt lgkmcnt(0)
	v_mfma_f32_16x16x32_bf16 v[10:13], v[10:13], v[0:3], 0
	v_mfma_f32_16x16x32_bf16 v[14:17], v[14:17], v[0:3], 0
	v_mfma_f32_16x16x32_bf16 v[18:21], v[18:21], v[0:3], 0
	v_mfma_f32_16x16x32_bf16 v[22:25], v[22:25], v[0:3], 0
	v_mfma_f32_16x16x32_bf16 v[26:29], v[26:29], v[0:3], 0
	v_mfma_f32_16x16x32_bf16 v[30:33], v[30:33], v[0:3], 0
	v_mfma_f32_16x16x32_bf16 v[0:3], v[42:45], v[0:3], 0
	v_perm_b32 v44, v49, v48, s89
	v_perm_b32 v43, v47, v46, s89
	ds_read_b128 v[46:49], v40 offset:64
	v_perm_b32 v45, v51, v50, s89
	v_perm_b32 v42, v35, v34, s89
	s_waitcnt lgkmcnt(0)
	s_nop 0
	v_mfma_f32_16x16x32_bf16 v[6:9], v[46:49], v[42:45], v[6:9]
	ds_read_b128 v[46:49], v40 offset:8512
	s_waitcnt lgkmcnt(0)
	v_mfma_f32_16x16x32_bf16 v[10:13], v[46:49], v[42:45], v[10:13]
	ds_read_b128 v[46:49], v40 offset:16960
	s_waitcnt lgkmcnt(0)
	v_mfma_f32_16x16x32_bf16 v[14:17], v[46:49], v[42:45], v[14:17]
	ds_read_b128 v[46:49], v40 offset:25408
	s_waitcnt lgkmcnt(0)
	v_mfma_f32_16x16x32_bf16 v[18:21], v[46:49], v[42:45], v[18:21]
	ds_read_b128 v[46:49], v40 offset:33856
	s_waitcnt lgkmcnt(0)
	v_mfma_f32_16x16x32_bf16 v[22:25], v[46:49], v[42:45], v[22:25]
	ds_read_b128 v[46:49], v40 offset:42304
	s_waitcnt lgkmcnt(0)
	v_mfma_f32_16x16x32_bf16 v[26:29], v[46:49], v[42:45], v[26:29]
	ds_read_b128 v[46:49], v40 offset:50752
	s_waitcnt lgkmcnt(0)
	v_mfma_f32_16x16x32_bf16 v[30:33], v[46:49], v[42:45], v[30:33]
	ds_read_b128 v[46:49], v40 offset:59200
	s_waitcnt lgkmcnt(0)
	v_mfma_f32_16x16x32_bf16 v[0:3], v[46:49], v[42:45], v[0:3]
	ds_read_b128 v[46:49], v40 offset:128
	v_perm_b32 v45, v59, v58, s89
	v_perm_b32 v44, v57, v56, s89
	v_perm_b32 v43, v55, v54, s89
	v_perm_b32 v42, v53, v52, s89
	s_waitcnt lgkmcnt(0)
	s_nop 0
	v_mfma_f32_16x16x32_bf16 v[6:9], v[46:49], v[42:45], v[6:9]
	ds_read_b128 v[46:49], v40 offset:8576
	s_waitcnt lgkmcnt(0)
	v_mfma_f32_16x16x32_bf16 v[10:13], v[46:49], v[42:45], v[10:13]
	ds_read_b128 v[46:49], v40 offset:17024
	s_waitcnt lgkmcnt(0)
	v_mfma_f32_16x16x32_bf16 v[14:17], v[46:49], v[42:45], v[14:17]
	ds_read_b128 v[46:49], v40 offset:25472
	s_waitcnt lgkmcnt(0)
	v_mfma_f32_16x16x32_bf16 v[18:21], v[46:49], v[42:45], v[18:21]
	ds_read_b128 v[46:49], v40 offset:33920
	s_waitcnt lgkmcnt(0)
	v_mfma_f32_16x16x32_bf16 v[22:25], v[46:49], v[42:45], v[22:25]
	ds_read_b128 v[46:49], v40 offset:42368
	s_waitcnt lgkmcnt(0)
	v_mfma_f32_16x16x32_bf16 v[26:29], v[46:49], v[42:45], v[26:29]
	ds_read_b128 v[46:49], v40 offset:50816
	s_waitcnt lgkmcnt(0)
	v_mfma_f32_16x16x32_bf16 v[30:33], v[46:49], v[42:45], v[30:33]
	ds_read_b128 v[46:49], v40 offset:59264
	s_waitcnt lgkmcnt(0)
	v_mfma_f32_16x16x32_bf16 v[0:3], v[46:49], v[42:45], v[0:3]
	ds_read_b128 v[46:49], v40 offset:192
	v_perm_b32 v45, v67, v66, s89
	v_perm_b32 v44, v65, v64, s89
	v_perm_b32 v43, v63, v62, s89
	v_perm_b32 v42, v61, v60, s89
	s_waitcnt lgkmcnt(0)
	s_nop 0
	v_mfma_f32_16x16x32_bf16 v[50:53], v[46:49], v[42:45], v[6:9]
	s_nop 2
	ds_read_b128 v[6:9], v40 offset:8640
	s_waitcnt lgkmcnt(0)
	v_mfma_f32_16x16x32_bf16 v[54:57], v[6:9], v[42:45], v[10:13]
	ds_read_b128 v[6:9], v40 offset:17088
	s_waitcnt lgkmcnt(0)
	v_mfma_f32_16x16x32_bf16 v[58:61], v[6:9], v[42:45], v[14:17]
	ds_read_b128 v[6:9], v40 offset:25536
	s_nop 1
	ds_read_b128 v[12:15], v40 offset:50880
	s_waitcnt lgkmcnt(1)
	v_mfma_f32_16x16x32_bf16 v[16:19], v[6:9], v[42:45], v[18:21]
	ds_read_b128 v[6:9], v40 offset:33984
	s_waitcnt lgkmcnt(0)
	v_mfma_f32_16x16x32_bf16 v[62:65], v[6:9], v[42:45], v[22:25]
	ds_read_b128 v[6:9], v40 offset:42432
	s_nop 1
	ds_read_b128 v[20:23], v40 offset:59328
	s_waitcnt lgkmcnt(0)
	v_mfma_f32_16x16x32_bf16 v[0:3], v[20:23], v[42:45], v[0:3]
	v_add_co_u32_e32 v20, vcc, s49, v4
	s_nop 1
	v_addc_co_u32_e32 v21, vcc, 0, v5, vcc
	v_mfma_f32_16x16x32_bf16 v[8:11], v[6:9], v[42:45], v[26:29]
	v_lshl_add_u64 v[6:7], v[4:5], 0, s[8:9]
	flat_load_ushort v22, v[20:21]
	flat_load_ushort v23, v[6:7] offset:512
	flat_load_ushort v24, v[6:7] offset:1024
	flat_load_ushort v25, v[6:7] offset:1536
	flat_load_ushort v26, v[6:7] offset:2048
	flat_load_ushort v27, v[6:7] offset:2560
	flat_load_ushort v28, v[6:7] offset:3072
	flat_load_ushort v29, v[6:7] offset:3584
	s_mov_b64 s[8:9], 0x14000
	v_lshl_add_u64 v[6:7], v[4:5], 0, s[8:9]
	s_mov_b32 s8, 0x14000
	v_add_co_u32_e32 v20, vcc, s8, v4
	s_mov_b64 s[8:9], 0x18000
	s_nop 0
	v_addc_co_u32_e32 v21, vcc, 0, v5, vcc
	flat_load_ushort v66, v[20:21]
	flat_load_ushort v67, v[6:7] offset:512
	flat_load_ushort v68, v[6:7] offset:1024
	flat_load_ushort v69, v[6:7] offset:1536
	flat_load_ushort v70, v[6:7] offset:2048
	flat_load_ushort v71, v[6:7] offset:2560
	flat_load_ushort v72, v[6:7] offset:3072
	flat_load_ushort v73, v[6:7] offset:3584
	v_lshl_add_u64 v[6:7], v[4:5], 0, s[8:9]
	s_mov_b32 s8, 0x18000
	v_add_co_u32_e32 v20, vcc, s8, v4
	s_mov_b64 s[8:9], 0x1c000
	s_nop 0
	v_addc_co_u32_e32 v21, vcc, 0, v5, vcc
	flat_load_ushort v74, v[20:21]
	flat_load_ushort v75, v[6:7] offset:512
	flat_load_ushort v76, v[6:7] offset:1024
	flat_load_ushort v77, v[6:7] offset:1536
	flat_load_ushort v78, v[6:7] offset:2048
	flat_load_ushort v79, v[6:7] offset:2560
	flat_load_ushort v80, v[6:7] offset:3072
	flat_load_ushort v81, v[6:7] offset:3584
	v_lshl_add_u64 v[6:7], v[4:5], 0, s[8:9]
	s_mov_b32 s8, 0x1c000
	v_add_co_u32_e32 v4, vcc, s8, v4
	v_mfma_f32_16x16x32_bf16 v[12:15], v[12:15], v[42:45], v[30:33]
	s_nop 0
	v_addc_co_u32_e32 v5, vcc, 0, v5, vcc
	flat_load_ushort v42, v[4:5]
	flat_load_ushort v43, v[6:7] offset:512
	flat_load_ushort v44, v[6:7] offset:1024
	flat_load_ushort v45, v[6:7] offset:1536
	flat_load_ushort v46, v[6:7] offset:2048
	flat_load_ushort v47, v[6:7] offset:2560
	flat_load_ushort v48, v[6:7] offset:3072
	flat_load_ushort v49, v[6:7] offset:3584
	ds_read_b128 v[4:7], v40 offset:256
	s_waitcnt vmcnt(0) lgkmcnt(0)
	v_perm_b32 v32, v23, v22, s89
	v_perm_b32 v33, v25, v24, s89
	v_perm_b32 v34, v27, v26, s89
	v_perm_b32 v35, v29, v28, s89
	s_nop 1
	v_mfma_f32_16x16x32_bf16 v[28:31], v[4:7], v[32:35], v[50:53]
	ds_read_b128 v[4:7], v40 offset:8704
	s_waitcnt lgkmcnt(0)
	v_mfma_f32_16x16x32_bf16 v[24:27], v[4:7], v[32:35], v[54:57]
	ds_read_b128 v[4:7], v40 offset:17152
	ds_read_b128 v[50:53], v40 offset:42496
	s_waitcnt lgkmcnt(1)
	v_mfma_f32_16x16x32_bf16 v[20:23], v[4:7], v[32:35], v[58:61]
	ds_read_b128 v[4:7], v40 offset:25600
	s_waitcnt lgkmcnt(0)
	v_mfma_f32_16x16x32_bf16 v[16:19], v[4:7], v[32:35], v[16:19]
	ds_read_b128 v[4:7], v40 offset:34048
	v_mfma_f32_16x16x32_bf16 v[8:11], v[50:53], v[32:35], v[8:11]
	ds_read_b128 v[50:53], v40 offset:50944
	s_waitcnt lgkmcnt(0)
	v_mfma_f32_16x16x32_bf16 v[12:15], v[50:53], v[32:35], v[12:15]
	ds_read_b128 v[50:53], v40 offset:59392
	s_waitcnt lgkmcnt(0)
	v_mfma_f32_16x16x32_bf16 v[0:3], v[50:53], v[32:35], v[0:3]
	ds_read_b128 v[50:53], v40 offset:320
	v_mfma_f32_16x16x32_bf16 v[4:7], v[4:7], v[32:35], v[62:65]
	v_perm_b32 v35, v73, v72, s89
	v_perm_b32 v34, v71, v70, s89
	v_perm_b32 v33, v69, v68, s89
	v_perm_b32 v32, v67, v66, s89
	s_waitcnt lgkmcnt(0)
	s_nop 0
	v_mfma_f32_16x16x32_bf16 v[28:31], v[50:53], v[32:35], v[28:31]
	ds_read_b128 v[50:53], v40 offset:8768
	s_waitcnt lgkmcnt(0)
	v_mfma_f32_16x16x32_bf16 v[24:27], v[50:53], v[32:35], v[24:27]
	ds_read_b128 v[50:53], v40 offset:17216
	s_waitcnt lgkmcnt(0)
	v_mfma_f32_16x16x32_bf16 v[20:23], v[50:53], v[32:35], v[20:23]
	ds_read_b128 v[50:53], v40 offset:25664
	s_waitcnt lgkmcnt(0)
	v_mfma_f32_16x16x32_bf16 v[16:19], v[50:53], v[32:35], v[16:19]
	ds_read_b128 v[50:53], v40 offset:34112
	s_waitcnt lgkmcnt(0)
	v_mfma_f32_16x16x32_bf16 v[4:7], v[50:53], v[32:35], v[4:7]
	ds_read_b128 v[50:53], v40 offset:42560
	s_waitcnt lgkmcnt(0)
	v_mfma_f32_16x16x32_bf16 v[8:11], v[50:53], v[32:35], v[8:11]
	ds_read_b128 v[50:53], v40 offset:51008
	s_waitcnt lgkmcnt(0)
	v_mfma_f32_16x16x32_bf16 v[12:15], v[50:53], v[32:35], v[12:15]
	ds_read_b128 v[50:53], v40 offset:59456
	s_waitcnt lgkmcnt(0)
	v_mfma_f32_16x16x32_bf16 v[0:3], v[50:53], v[32:35], v[0:3]
	ds_read_b128 v[50:53], v40 offset:384
	v_perm_b32 v35, v81, v80, s89
	v_perm_b32 v34, v79, v78, s89
	v_perm_b32 v33, v77, v76, s89
	v_perm_b32 v32, v75, v74, s89
	s_waitcnt lgkmcnt(0)
	s_nop 0
	v_mfma_f32_16x16x32_bf16 v[28:31], v[50:53], v[32:35], v[28:31]
	ds_read_b128 v[50:53], v40 offset:8832
	s_waitcnt lgkmcnt(0)
	v_mfma_f32_16x16x32_bf16 v[24:27], v[50:53], v[32:35], v[24:27]
	ds_read_b128 v[50:53], v40 offset:17280
	s_waitcnt lgkmcnt(0)
	v_mfma_f32_16x16x32_bf16 v[20:23], v[50:53], v[32:35], v[20:23]
	ds_read_b128 v[50:53], v40 offset:25728
	s_waitcnt lgkmcnt(0)
	v_mfma_f32_16x16x32_bf16 v[16:19], v[50:53], v[32:35], v[16:19]
	ds_read_b128 v[50:53], v40 offset:34176
	s_waitcnt lgkmcnt(0)
	v_mfma_f32_16x16x32_bf16 v[4:7], v[50:53], v[32:35], v[4:7]
	ds_read_b128 v[50:53], v40 offset:42624
	s_waitcnt lgkmcnt(0)
	v_mfma_f32_16x16x32_bf16 v[8:11], v[50:53], v[32:35], v[8:11]
	ds_read_b128 v[50:53], v40 offset:51072
	s_waitcnt lgkmcnt(0)
	v_mfma_f32_16x16x32_bf16 v[50:53], v[50:53], v[32:35], v[12:15]
	s_nop 2
	ds_read_b128 v[12:15], v40 offset:59520
	s_waitcnt lgkmcnt(0)
	v_mfma_f32_16x16x32_bf16 v[0:3], v[12:15], v[32:35], v[0:3]
	ds_read_b128 v[12:15], v40 offset:448
	v_perm_b32 v35, v49, v48, s89
	v_perm_b32 v34, v47, v46, s89
	v_perm_b32 v33, v45, v44, s89
	v_perm_b32 v32, v43, v42, s89
	s_waitcnt lgkmcnt(0)
	s_nop 0
	v_mfma_f32_16x16x32_bf16 v[42:45], v[12:15], v[32:35], v[28:31]
	ds_read_b128 v[12:15], v40 offset:8896
	s_nop 1
	ds_read_b128 v[28:31], v40 offset:59584
	s_waitcnt lgkmcnt(1)
	v_mfma_f32_16x16x32_bf16 v[24:27], v[12:15], v[32:35], v[24:27]
	ds_read_b128 v[12:15], v40 offset:17344
	s_waitcnt lgkmcnt(0)
	v_mfma_f32_16x16x32_bf16 v[20:23], v[12:15], v[32:35], v[20:23]
	ds_read_b128 v[12:15], v40 offset:25792
	s_waitcnt lgkmcnt(0)
	v_mfma_f32_16x16x32_bf16 v[16:19], v[12:15], v[32:35], v[16:19]
	ds_read_b128 v[12:15], v40 offset:34240
	s_waitcnt lgkmcnt(0)
	v_mfma_f32_16x16x32_bf16 v[12:15], v[12:15], v[32:35], v[4:7]
	s_nop 2
	ds_read_b128 v[4:7], v40 offset:42688
	s_waitcnt lgkmcnt(0)
	v_mfma_f32_16x16x32_bf16 v[8:11], v[4:7], v[32:35], v[8:11]
	ds_read_b128 v[4:7], v40 offset:51136
	v_mfma_f32_16x16x32_bf16 v[0:3], v[28:31], v[32:35], v[0:3]
	v_bfe_u32 v30, v42, 16, 1
	v_lshl_add_u64 v[28:29], v[38:39], 0, s[82:83]
	s_waitcnt lgkmcnt(0)
	v_mfma_f32_16x16x32_bf16 v[4:7], v[4:7], v[32:35], v[50:53]
	v_add3_u32 v34, v42, v30, s77
	v_lshl_or_b32 v30, s7, 13, v41
	v_or_b32_e32 v30, s1, v30
	v_ashrrev_i32_e32 v31, 31, v30
	v_lshlrev_b64 v[32:33], 11, v[30:31]
	v_lshl_add_u64 v[32:33], v[28:29], 0, v[32:33]
	global_store_short_d16_hi v[32:33], v34, off offset:512
	v_or_b32_e32 v32, 64, v30
	v_ashrrev_i32_e32 v33, 31, v32
	v_bfe_u32 v31, v43, 16, 1
	v_lshlrev_b64 v[32:33], 11, v[32:33]
	v_add3_u32 v31, v43, v31, s77
	v_lshl_add_u64 v[32:33], v[28:29], 0, v[32:33]
	global_store_short_d16_hi v[32:33], v31, off offset:512
	v_or_b32_e32 v32, 0x80, v30
	v_ashrrev_i32_e32 v33, 31, v32
	v_bfe_u32 v31, v44, 16, 1
	v_lshlrev_b64 v[32:33], 11, v[32:33]
	v_add3_u32 v31, v44, v31, s77
	v_lshl_add_u64 v[32:33], v[28:29], 0, v[32:33]
	global_store_short_d16_hi v[32:33], v31, off offset:512
	v_or_b32_e32 v32, 0xc0, v30
	v_ashrrev_i32_e32 v33, 31, v32
	v_bfe_u32 v31, v45, 16, 1
	v_lshlrev_b64 v[32:33], 11, v[32:33]
	v_add3_u32 v31, v45, v31, s77
	v_lshl_add_u64 v[32:33], v[28:29], 0, v[32:33]
	global_store_short_d16_hi v[32:33], v31, off offset:512
	v_or_b32_e32 v32, 0x400, v30
	v_ashrrev_i32_e32 v33, 31, v32
	v_bfe_u32 v31, v24, 16, 1
	v_lshlrev_b64 v[32:33], 11, v[32:33]
	v_add3_u32 v24, v24, v31, s77
	v_lshl_add_u64 v[32:33], v[28:29], 0, v[32:33]
	global_store_short_d16_hi v[32:33], v24, off offset:512
	v_bfe_u32 v24, v25, 16, 1
	v_add3_u32 v31, v25, v24, s77
	v_or_b32_e32 v24, 0x440, v30
	v_ashrrev_i32_e32 v25, 31, v24
	v_lshlrev_b64 v[24:25], 11, v[24:25]
	v_lshl_add_u64 v[24:25], v[28:29], 0, v[24:25]
	global_store_short_d16_hi v[24:25], v31, off offset:512
	v_bfe_u32 v24, v26, 16, 1
	v_add3_u32 v26, v26, v24, s77
	v_or_b32_e32 v24, 0x480, v30
	v_ashrrev_i32_e32 v25, 31, v24
	v_lshlrev_b64 v[24:25], 11, v[24:25]
	v_lshl_add_u64 v[24:25], v[28:29], 0, v[24:25]
	global_store_short_d16_hi v[24:25], v26, off offset:512
	v_bfe_u32 v24, v27, 16, 1
	v_add3_u32 v26, v27, v24, s77
	v_or_b32_e32 v24, 0x4c0, v30
	v_ashrrev_i32_e32 v25, 31, v24
	v_lshlrev_b64 v[24:25], 11, v[24:25]
	v_lshl_add_u64 v[24:25], v[28:29], 0, v[24:25]
	global_store_short_d16_hi v[24:25], v26, off offset:512
	v_bfe_u32 v24, v20, 16, 1
	v_add3_u32 v20, v20, v24, s77
	v_or_b32_e32 v24, 0x800, v30
	v_ashrrev_i32_e32 v25, 31, v24
	v_lshlrev_b64 v[24:25], 11, v[24:25]
	v_lshl_add_u64 v[24:25], v[28:29], 0, v[24:25]
	global_store_short_d16_hi v[24:25], v20, off offset:512
	v_bfe_u32 v20, v21, 16, 1
	v_add3_u32 v24, v21, v20, s77
	v_or_b32_e32 v20, 0x840, v30
	v_ashrrev_i32_e32 v21, 31, v20
	v_lshlrev_b64 v[20:21], 11, v[20:21]
	v_lshl_add_u64 v[20:21], v[28:29], 0, v[20:21]
	global_store_short_d16_hi v[20:21], v24, off offset:512
	v_bfe_u32 v20, v22, 16, 1
	v_add3_u32 v22, v22, v20, s77
	v_or_b32_e32 v20, 0x880, v30
	v_ashrrev_i32_e32 v21, 31, v20
	v_lshlrev_b64 v[20:21], 11, v[20:21]
	v_lshl_add_u64 v[20:21], v[28:29], 0, v[20:21]
	global_store_short_d16_hi v[20:21], v22, off offset:512
	v_bfe_u32 v20, v23, 16, 1
	v_add3_u32 v22, v23, v20, s77
	v_or_b32_e32 v20, 0x8c0, v30
	v_ashrrev_i32_e32 v21, 31, v20
	v_lshlrev_b64 v[20:21], 11, v[20:21]
	v_lshl_add_u64 v[20:21], v[28:29], 0, v[20:21]
	global_store_short_d16_hi v[20:21], v22, off offset:512
	v_bfe_u32 v20, v16, 16, 1
	v_add3_u32 v16, v16, v20, s77
	v_or_b32_e32 v20, 0xc00, v30
	v_ashrrev_i32_e32 v21, 31, v20
	v_lshlrev_b64 v[20:21], 11, v[20:21]
	v_lshl_add_u64 v[20:21], v[28:29], 0, v[20:21]
	global_store_short_d16_hi v[20:21], v16, off offset:512
	v_bfe_u32 v16, v17, 16, 1
	v_add3_u32 v20, v17, v16, s77
	v_or_b32_e32 v16, 0xc40, v30
	v_ashrrev_i32_e32 v17, 31, v16
	v_lshlrev_b64 v[16:17], 11, v[16:17]
	v_lshl_add_u64 v[16:17], v[28:29], 0, v[16:17]
	global_store_short_d16_hi v[16:17], v20, off offset:512
	v_bfe_u32 v16, v18, 16, 1
	v_add3_u32 v18, v18, v16, s77
	v_or_b32_e32 v16, 0xc80, v30
	v_ashrrev_i32_e32 v17, 31, v16
	v_lshlrev_b64 v[16:17], 11, v[16:17]
	v_lshl_add_u64 v[16:17], v[28:29], 0, v[16:17]
	global_store_short_d16_hi v[16:17], v18, off offset:512
	v_bfe_u32 v16, v19, 16, 1
	v_add3_u32 v18, v19, v16, s77
	v_or_b32_e32 v16, 0xcc0, v30
	v_ashrrev_i32_e32 v17, 31, v16
	v_lshlrev_b64 v[16:17], 11, v[16:17]
	v_lshl_add_u64 v[16:17], v[28:29], 0, v[16:17]
	global_store_short_d16_hi v[16:17], v18, off offset:512
	v_bfe_u32 v16, v12, 16, 1
	v_add3_u32 v12, v12, v16, s77
	v_or_b32_e32 v16, 0x1000, v30
	v_ashrrev_i32_e32 v17, 31, v16
	v_lshlrev_b64 v[16:17], 11, v[16:17]
	v_lshl_add_u64 v[16:17], v[28:29], 0, v[16:17]
	global_store_short_d16_hi v[16:17], v12, off offset:512
	v_bfe_u32 v12, v13, 16, 1
	v_add3_u32 v16, v13, v12, s77
	v_or_b32_e32 v12, 0x1040, v30
	v_ashrrev_i32_e32 v13, 31, v12
	v_lshlrev_b64 v[12:13], 11, v[12:13]
	v_lshl_add_u64 v[12:13], v[28:29], 0, v[12:13]
	global_store_short_d16_hi v[12:13], v16, off offset:512
	v_bfe_u32 v12, v14, 16, 1
	v_add3_u32 v14, v14, v12, s77
	v_or_b32_e32 v12, 0x1080, v30
	v_ashrrev_i32_e32 v13, 31, v12
	v_lshlrev_b64 v[12:13], 11, v[12:13]
	v_lshl_add_u64 v[12:13], v[28:29], 0, v[12:13]
	global_store_short_d16_hi v[12:13], v14, off offset:512
	v_bfe_u32 v12, v15, 16, 1
	v_add3_u32 v14, v15, v12, s77
	v_or_b32_e32 v12, 0x10c0, v30
	v_ashrrev_i32_e32 v13, 31, v12
	v_lshlrev_b64 v[12:13], 11, v[12:13]
	v_lshl_add_u64 v[12:13], v[28:29], 0, v[12:13]
	global_store_short_d16_hi v[12:13], v14, off offset:512
	v_bfe_u32 v12, v8, 16, 1
	v_add3_u32 v8, v8, v12, s77
	v_or_b32_e32 v12, 0x1400, v30
	v_ashrrev_i32_e32 v13, 31, v12
	v_lshlrev_b64 v[12:13], 11, v[12:13]
	v_lshl_add_u64 v[12:13], v[28:29], 0, v[12:13]
	global_store_short_d16_hi v[12:13], v8, off offset:512
	v_bfe_u32 v8, v9, 16, 1
	v_add3_u32 v12, v9, v8, s77
	v_or_b32_e32 v8, 0x1440, v30
	v_ashrrev_i32_e32 v9, 31, v8
	v_lshlrev_b64 v[8:9], 11, v[8:9]
	v_lshl_add_u64 v[8:9], v[28:29], 0, v[8:9]
	global_store_short_d16_hi v[8:9], v12, off offset:512
	v_bfe_u32 v8, v10, 16, 1
	v_add3_u32 v10, v10, v8, s77
	v_or_b32_e32 v8, 0x1480, v30
	v_ashrrev_i32_e32 v9, 31, v8
	v_lshlrev_b64 v[8:9], 11, v[8:9]
	v_lshl_add_u64 v[8:9], v[28:29], 0, v[8:9]
	global_store_short_d16_hi v[8:9], v10, off offset:512
	v_bfe_u32 v8, v11, 16, 1
	v_add3_u32 v10, v11, v8, s77
	v_or_b32_e32 v8, 0x14c0, v30
	v_ashrrev_i32_e32 v9, 31, v8
	v_lshlrev_b64 v[8:9], 11, v[8:9]
	v_lshl_add_u64 v[8:9], v[28:29], 0, v[8:9]
	global_store_short_d16_hi v[8:9], v10, off offset:512
	v_bfe_u32 v8, v4, 16, 1
	v_add3_u32 v4, v4, v8, s77
	v_or_b32_e32 v8, 0x1800, v30
	v_ashrrev_i32_e32 v9, 31, v8
	v_lshlrev_b64 v[8:9], 11, v[8:9]
	v_lshl_add_u64 v[8:9], v[28:29], 0, v[8:9]
	global_store_short_d16_hi v[8:9], v4, off offset:512
	v_bfe_u32 v4, v5, 16, 1
	v_add3_u32 v8, v5, v4, s77
	v_or_b32_e32 v4, 0x1840, v30
	v_ashrrev_i32_e32 v5, 31, v4
	v_lshlrev_b64 v[4:5], 11, v[4:5]
	v_lshl_add_u64 v[4:5], v[28:29], 0, v[4:5]
	global_store_short_d16_hi v[4:5], v8, off offset:512
	v_bfe_u32 v4, v6, 16, 1
	v_add3_u32 v6, v6, v4, s77
	v_or_b32_e32 v4, 0x1880, v30
	v_ashrrev_i32_e32 v5, 31, v4
	v_lshlrev_b64 v[4:5], 11, v[4:5]
	v_lshl_add_u64 v[4:5], v[28:29], 0, v[4:5]
	global_store_short_d16_hi v[4:5], v6, off offset:512
	v_bfe_u32 v4, v7, 16, 1
	v_add3_u32 v6, v7, v4, s77
	v_or_b32_e32 v4, 0x18c0, v30
	v_ashrrev_i32_e32 v5, 31, v4
	v_lshlrev_b64 v[4:5], 11, v[4:5]
	v_lshl_add_u64 v[4:5], v[28:29], 0, v[4:5]
	global_store_short_d16_hi v[4:5], v6, off offset:512
	v_bfe_u32 v4, v0, 16, 1
	v_add3_u32 v0, v0, v4, s77
	v_or_b32_e32 v4, 0x1c00, v30
	v_ashrrev_i32_e32 v5, 31, v4
	v_lshlrev_b64 v[4:5], 11, v[4:5]
	v_lshl_add_u64 v[4:5], v[28:29], 0, v[4:5]
	global_store_short_d16_hi v[4:5], v0, off offset:512
	v_bfe_u32 v0, v1, 16, 1
	v_add3_u32 v4, v1, v0, s77
	v_or_b32_e32 v0, 0x1c40, v30
	v_ashrrev_i32_e32 v1, 31, v0
	v_lshlrev_b64 v[0:1], 11, v[0:1]
	v_lshl_add_u64 v[0:1], v[28:29], 0, v[0:1]
	global_store_short_d16_hi v[0:1], v4, off offset:512
	v_bfe_u32 v0, v2, 16, 1
	v_add3_u32 v2, v2, v0, s77
	v_or_b32_e32 v0, 0x1c80, v30
	v_ashrrev_i32_e32 v1, 31, v0
	v_lshlrev_b64 v[0:1], 11, v[0:1]
	v_lshl_add_u64 v[0:1], v[28:29], 0, v[0:1]
	global_store_short_d16_hi v[0:1], v2, off offset:512
	v_bfe_u32 v0, v3, 16, 1
	v_add3_u32 v2, v3, v0, s77
	v_or_b32_e32 v0, 0x1cc0, v30
	v_ashrrev_i32_e32 v1, 31, v0
	v_lshlrev_b64 v[0:1], 11, v[0:1]
	v_lshl_add_u64 v[0:1], v[28:29], 0, v[0:1]
	global_store_short_d16_hi v[0:1], v2, off offset:512
	s_cbranch_scc1 .LBB0_389

.LBB0_411:
	v_cndmask_b32_e64 v110, v59, v8, s[4:5]
	v_ashrrev_i32_e32 v111, 31, v110
	v_lshlrev_b64 v[110:111], 13, v[110:111]
	v_lshl_add_u64 v[110:111], v[2:3], 0, v[110:111]
	global_store_dword v[110:111], v108, off
	s_or_b64 exec, exec, s[6:7]
	v_fmac_f32_e32 v105, v107, v108
	s_and_saveexec_b64 s[6:7], vcc
	s_cbranch_execz .LBB0_396
.LBB0_412:
	v_cndmask_b32_e64 v108, v60, v11, s[4:5]
	v_ashrrev_i32_e32 v109, 31, v108
	v_lshlrev_b64 v[108:109], 13, v[108:109]
	v_lshl_add_u64 v[108:109], v[2:3], 0, v[108:109]
	global_store_dword v[108:109], v105, off
	s_or_b64 exec, exec, s[6:7]
	v_fmac_f32_e32 v103, v106, v105
	s_and_saveexec_b64 s[6:7], vcc
	s_cbranch_execz .LBB0_397
.LBB0_413:
	v_cndmask_b32_e64 v106, v61, v14, s[4:5]
	v_ashrrev_i32_e32 v107, 31, v106
	v_lshlrev_b64 v[106:107], 13, v[106:107]
	v_lshl_add_u64 v[106:107], v[2:3], 0, v[106:107]
	global_store_dword v[106:107], v103, off
	s_or_b64 exec, exec, s[6:7]
	v_fmac_f32_e32 v101, v104, v103
	s_and_saveexec_b64 s[6:7], vcc
	s_cbranch_execz .LBB0_398
.LBB0_414:
	v_cndmask_b32_e64 v104, v62, v17, s[4:5]
	v_ashrrev_i32_e32 v105, 31, v104
	v_lshlrev_b64 v[104:105], 13, v[104:105]
	v_lshl_add_u64 v[104:105], v[2:3], 0, v[104:105]
	global_store_dword v[104:105], v101, off
	s_or_b64 exec, exec, s[6:7]
	v_fmac_f32_e32 v99, v102, v101
	s_and_saveexec_b64 s[6:7], vcc
	s_cbranch_execz .LBB0_399
.LBB0_415:
	v_cndmask_b32_e64 v102, v63, v20, s[4:5]
	v_ashrrev_i32_e32 v103, 31, v102
	v_lshlrev_b64 v[102:103], 13, v[102:103]
	v_lshl_add_u64 v[102:103], v[2:3], 0, v[102:103]
	global_store_dword v[102:103], v99, off
	s_or_b64 exec, exec, s[6:7]
	v_fmac_f32_e32 v97, v100, v99
	s_and_saveexec_b64 s[6:7], vcc
	s_cbranch_execz .LBB0_400
.LBB0_416:
	v_cndmask_b32_e64 v100, v64, v23, s[4:5]
	v_ashrrev_i32_e32 v101, 31, v100
	v_lshlrev_b64 v[100:101], 13, v[100:101]
	v_lshl_add_u64 v[100:101], v[2:3], 0, v[100:101]
	global_store_dword v[100:101], v97, off
	s_or_b64 exec, exec, s[6:7]
	v_fmac_f32_e32 v95, v98, v97
	s_and_saveexec_b64 s[6:7], vcc
	s_cbranch_execz .LBB0_401
.LBB0_417:
	v_cndmask_b32_e64 v98, v65, v26, s[4:5]
	v_ashrrev_i32_e32 v99, 31, v98
	v_lshlrev_b64 v[98:99], 13, v[98:99]
	v_lshl_add_u64 v[98:99], v[2:3], 0, v[98:99]
	global_store_dword v[98:99], v95, off
	s_or_b64 exec, exec, s[6:7]
	v_fmac_f32_e32 v93, v96, v95
	s_and_saveexec_b64 s[6:7], vcc
	s_cbranch_execz .LBB0_402
.LBB0_418:
	v_cndmask_b32_e64 v96, v66, v29, s[4:5]
	v_ashrrev_i32_e32 v97, 31, v96
	v_lshlrev_b64 v[96:97], 13, v[96:97]
	v_lshl_add_u64 v[96:97], v[2:3], 0, v[96:97]
	global_store_dword v[96:97], v93, off
	s_or_b64 exec, exec, s[6:7]
	v_fmac_f32_e32 v91, v94, v93
	s_and_saveexec_b64 s[6:7], vcc
	s_cbranch_execz .LBB0_403
.LBB0_419:
	v_cndmask_b32_e64 v94, v67, v32, s[4:5]
	v_ashrrev_i32_e32 v95, 31, v94
	v_lshlrev_b64 v[94:95], 13, v[94:95]
	v_lshl_add_u64 v[94:95], v[2:3], 0, v[94:95]
	global_store_dword v[94:95], v91, off
	s_or_b64 exec, exec, s[6:7]
	v_fmac_f32_e32 v89, v92, v91
	s_and_saveexec_b64 s[6:7], vcc
	s_cbranch_execz .LBB0_404
.LBB0_420:
	v_cndmask_b32_e64 v92, v68, v35, s[4:5]
	v_ashrrev_i32_e32 v93, 31, v92
	v_lshlrev_b64 v[92:93], 13, v[92:93]
	v_lshl_add_u64 v[92:93], v[2:3], 0, v[92:93]
	global_store_dword v[92:93], v89, off
	s_or_b64 exec, exec, s[6:7]
	v_fmac_f32_e32 v87, v90, v89
	s_and_saveexec_b64 s[6:7], vcc
	s_cbranch_execz .LBB0_405
.LBB0_421:
	v_cndmask_b32_e64 v90, v69, v38, s[4:5]
	v_ashrrev_i32_e32 v91, 31, v90
	v_lshlrev_b64 v[90:91], 13, v[90:91]
	v_lshl_add_u64 v[90:91], v[2:3], 0, v[90:91]
	global_store_dword v[90:91], v87, off
	s_or_b64 exec, exec, s[6:7]
	v_fmac_f32_e32 v5, v88, v87
	s_and_saveexec_b64 s[6:7], vcc
	s_cbranch_execz .LBB0_406
.LBB0_422:
	v_cndmask_b32_e64 v88, v70, v41, s[4:5]
	v_ashrrev_i32_e32 v89, 31, v88
	v_lshlrev_b64 v[88:89], 13, v[88:89]
	v_lshl_add_u64 v[88:89], v[2:3], 0, v[88:89]
	global_store_dword v[88:89], v5, off
	s_or_b64 exec, exec, s[6:7]
	v_fmac_f32_e32 v4, v86, v5
	s_and_saveexec_b64 s[6:7], vcc
	s_cbranch_execz .LBB0_407
.LBB0_423:
	v_cndmask_b32_e64 v86, v71, v44, s[4:5]
	v_ashrrev_i32_e32 v87, 31, v86
	v_lshlrev_b64 v[86:87], 13, v[86:87]
	v_lshl_add_u64 v[86:87], v[2:3], 0, v[86:87]
	global_store_dword v[86:87], v4, off
	s_or_b64 exec, exec, s[6:7]
	s_and_saveexec_b64 s[6:7], s[0:1]
	s_cbranch_execz .LBB0_392
.LBB0_424:
	v_fmac_f32_e32 v78, v80, v4
	v_cndmask_b32_e64 v4, v72, v47, s[4:5]
	v_ashrrev_i32_e32 v5, 31, v4
	v_lshlrev_b64 v[4:5], 13, v[4:5]
	v_lshl_add_u64 v[4:5], v[2:3], 0, v[4:5]
	global_store_dword v[4:5], v78, off
	v_cndmask_b32_e64 v4, v73, v50, s[4:5]
	v_ashrrev_i32_e32 v5, 31, v4
	v_lshlrev_b64 v[4:5], 13, v[4:5]
	v_fmac_f32_e32 v79, v82, v78
	v_lshl_add_u64 v[4:5], v[2:3], 0, v[4:5]
	global_store_dword v[4:5], v79, off
	v_cndmask_b32_e64 v4, v74, v53, s[4:5]
	v_ashrrev_i32_e32 v5, 31, v4
	v_lshlrev_b64 v[4:5], 13, v[4:5]
	v_lshl_add_u64 v[4:5], v[2:3], 0, v[4:5]
	v_fmac_f32_e32 v81, v83, v79
	global_store_dword v[4:5], v81, off
	v_cndmask_b32_e64 v4, v75, v56, s[4:5]
	v_ashrrev_i32_e32 v5, 31, v4
	v_lshlrev_b64 v[4:5], 13, v[4:5]
	v_fmac_f32_e32 v84, v85, v81
	v_lshl_add_u64 v[2:3], v[2:3], 0, v[4:5]
	global_store_dword v[2:3], v84, off
	s_branch .LBB0_392

.LBB0_471:
	s_nop 1
	ds_read_b128 v[28:31], v123 offset:33792
	ds_read_b128 v[40:43], v123 offset:33808
	s_mov_b32 s73, s83
	v_lshl_add_u64 v[66:67], v[152:153], 0, s[72:73]
	v_mov_b32_e32 v145, v169
	s_waitcnt lgkmcnt(1)
	v_mul_f32_e32 v28, 0xbfb8aa3b, v28
	v_mul_f32_e32 v29, 0xbfb8aa3b, v29
	v_mul_f32_e32 v30, 0xbfb8aa3b, v30
	v_mul_f32_e32 v31, 0xbfb8aa3b, v31
	v_exp_f32_e32 v28, v28
	v_exp_f32_e32 v29, v29
	v_exp_f32_e32 v30, v30
	v_exp_f32_e32 v31, v31
	ds_read_b128 v[48:51], v123 offset:50448
	v_pk_mul_f32 v[28:29], v[28:29], v[198:199]
	s_waitcnt lgkmcnt(1)
	v_mul_f32_e32 v40, 0xbfb8aa3b, v40
	v_pk_mul_f32 v[30:31], v[30:31], v[200:201]
	v_cvt_pk_bf16_f32 v44, v28, v29
	v_cvt_pk_bf16_f32 v45, v30, v31
	ds_read_b128 v[28:31], v123 offset:50432
	v_mul_f32_e32 v41, 0xbfb8aa3b, v41
	v_mul_f32_e32 v42, 0xbfb8aa3b, v42
	v_mul_f32_e32 v43, 0xbfb8aa3b, v43
	s_waitcnt lgkmcnt(1)
	v_mul_f32_e32 v48, 0xbfb8aa3b, v48
	s_waitcnt lgkmcnt(0)
	v_mul_f32_e32 v28, 0xbfb8aa3b, v28
	v_mul_f32_e32 v29, 0xbfb8aa3b, v29
	v_mul_f32_e32 v30, 0xbfb8aa3b, v30
	v_mul_f32_e32 v31, 0xbfb8aa3b, v31
	v_mul_f32_e32 v49, 0xbfb8aa3b, v49
	v_mul_f32_e32 v50, 0xbfb8aa3b, v50
	v_mul_f32_e32 v51, 0xbfb8aa3b, v51
	v_exp_f32_e32 v40, v40
	v_exp_f32_e32 v41, v41
	v_exp_f32_e32 v42, v42
	v_exp_f32_e32 v43, v43
	v_exp_f32_e32 v28, v28
	v_exp_f32_e32 v29, v29
	v_exp_f32_e32 v30, v30
	v_exp_f32_e32 v31, v31
	v_exp_f32_e32 v48, v48
	v_exp_f32_e32 v49, v49
	v_exp_f32_e32 v50, v50
	v_exp_f32_e32 v51, v51
	v_pk_mul_f32 v[40:41], v[40:41], v[202:203]
	v_pk_mul_f32 v[42:43], v[42:43], v[196:197]
	v_pk_mul_f32 v[28:29], v[28:29], v[114:115]
	v_pk_mul_f32 v[30:31], v[30:31], v[188:189]
	v_pk_mul_f32 v[48:49], v[48:49], v[190:191]
	v_pk_mul_f32 v[50:51], v[50:51], v[112:113]
	v_cvt_pk_bf16_f32 v46, v40, v41
	v_cvt_pk_bf16_f32 v47, v42, v43
	v_cvt_pk_bf16_f32 v52, v28, v29
	v_cvt_pk_bf16_f32 v53, v30, v31
	v_cvt_pk_bf16_f32 v54, v48, v49
	v_cvt_pk_bf16_f32 v55, v50, v51
	v_mfma_f32_16x16x32_bf16 v[40:43], v[44:47], v[72:75], 0
	v_lshl_add_u64 v[66:67], v[66:67], 0, v[144:145]
	flat_load_dwordx2 v[68:69], v[66:67] offset:1536
	s_mov_b32 s92, 0xf800000
	v_mfma_f32_16x16x32_bf16 v[28:31], v[52:55], v[72:75], 0
	v_ashrrev_i32_e32 v151, 31, v150
	s_nop 2
	v_cndmask_b32_e64 v40, v40, 0, s[4:5]
	v_cndmask_b32_e64 v41, v41, 0, s[42:43]
	v_cndmask_b32_e64 v42, v42, 0, s[0:1]
	v_cndmask_b32_e64 v43, v43, 0, s[44:45]
	v_cndmask_b32_e64 v48, v28, 0, s[54:55]
	v_cndmask_b32_e64 v49, v29, 0, s[56:57]
	v_cndmask_b32_e64 v50, v30, 0, s[58:59]
	v_cndmask_b32_e64 v31, v31, 0, s[60:61]
	v_cvt_pk_bf16_f32 v28, v40, v41
	v_cvt_pk_bf16_f32 v29, v42, v43
	v_cvt_pk_bf16_f32 v30, v48, v49
	v_cvt_pk_bf16_f32 v31, v50, v31
	v_mfma_f32_16x16x32_bf16 v[44:47], v[44:47], v[20:23], 0
	v_ashrrev_i32_e32 v147, 31, v146
	s_waitcnt vmcnt(0) lgkmcnt(0)
	v_lshlrev_b32_e32 v77, 16, v69
	v_mfma_f32_16x16x32_bf16 v[56:59], v[12:15], v[28:31], v[88:91]
	v_lshlrev_b32_e32 v76, 16, v68
	v_and_b32_e32 v68, 0xffff0000, v68
	v_mul_f32_e32 v78, 0xbfb8aa3b, v68
	v_mfma_f32_16x16x32_bf16 v[48:51], v[8:11], v[28:31], v[92:95]
	v_exp_f32_e32 v79, v78
	s_nop 2
	v_pk_mul_f32 v[60:61], v[58:59], v[58:59]
	v_pk_mul_f32 v[62:63], v[56:57], v[56:57]
	v_mfma_f32_16x16x32_bf16 v[40:43], v[4:7], v[28:31], v[96:99]
	v_pk_mov_b32 v[64:65], v[62:63], v[60:61] op_sel:[1,0]
	v_mov_b32_e32 v63, v61
	v_pk_add_f32 v[60:61], v[64:65], v[62:63]
	v_mfma_f32_16x16x32_bf16 v[28:31], v[0:3], v[28:31], v[100:103]
	v_mul_f32_e64 v62, v50, v50
	v_mul_f32_e64 v63, v51, v51
	v_pk_mul_f32 v[64:65], v[48:49], v[48:49]
	v_pk_add_f32 v[60:61], v[60:61], v[60:61] op_sel:[0,1] op_sel_hi:[1,0]
	v_pk_mov_b32 v[70:71], v[64:65], v[62:63] op_sel:[1,0]
	v_mov_b32_e32 v65, v63
	v_pk_add_f32 v[62:63], v[70:71], v[64:65]
	s_nop 0
	v_mul_f32_e32 v64, v28, v28
	v_mul_f32_e32 v65, v29, v29
	v_pk_add_f32 v[62:63], v[62:63], v[62:63] op_sel:[0,1] op_sel_hi:[1,0]
	v_mov_b32_e32 v61, v64
	v_mov_b32_e32 v63, v65
	v_pk_add_f32 v[64:65], v[60:61], v[62:63]
	global_load_dwordx4 v[60:63], v[132:133], off
	v_mul_f32_e32 v70, v41, v41
	v_mul_f32_e32 v72, v30, v30
	v_pk_fma_f32 v[70:71], v[40:41], v[40:41], v[70:71] op_sel_hi:[1,1,0]
	v_mul_f32_e32 v74, v31, v31
	v_mov_b32_e32 v71, v72
	v_mul_f32_e32 v72, v43, v43
	v_pk_fma_f32 v[72:73], v[42:43], v[42:43], v[72:73] op_sel_hi:[1,1,0]
	v_mov_b32_e32 v82, v56
	v_mov_b32_e32 v73, v74
	v_pk_add_f32 v[70:71], v[70:71], v[72:73]
	v_mul_f32_e32 v56, 0xbfb8aa3b, v77
	v_pk_add_f32 v[64:65], v[64:65], v[70:71]
	v_exp_f32_e32 v56, v56
	v_add_f32_e32 v64, v64, v65
	ds_bpermute_b32 v65, v219, v64
	v_and_b32_e32 v69, 0xffff0000, v69
	v_add_f32_e32 v56, 1.0, v56
	v_mov_b32_e32 v83, v58
	v_mov_b32_e32 v58, v57
	s_waitcnt lgkmcnt(0)
	v_add_f32_e32 v64, v64, v65
	ds_bpermute_b32 v65, v220, v64
	v_mfma_f32_16x16x32_bf16 v[20:23], v[52:55], v[20:23], 0
	v_cndmask_b32_e64 v44, v44, 0, s[46:47]
	v_cndmask_b32_e64 v45, v45, 0, s[48:49]
	v_cndmask_b32_e64 v46, v46, 0, s[50:51]
	s_waitcnt lgkmcnt(0)
	v_add_f32_e32 v64, v64, v65
	v_fmamk_f32 v64, v64, 0x3c800000, v206
	v_mul_f32_e32 v65, 0x4f800000, v64
	v_cmp_gt_f32_e64 s[70:71], s92, v64
	v_cndmask_b32_e64 v47, v47, 0, s[52:53]
	v_cndmask_b32_e64 v52, v20, 0, s[62:63]
	v_cndmask_b32_e64 v64, v64, v65, s[70:71]
	v_sqrt_f32_e32 v65, v64
	v_cndmask_b32_e64 v53, v21, 0, s[64:65]
	v_cndmask_b32_e64 v54, v22, 0, s[66:67]
	v_cndmask_b32_e64 v23, v23, 0, s[68:69]
	v_add_u32_e32 v70, -1, v65
	v_fma_f32 v71, -v70, v65, v64
	v_cmp_ge_f32_e32 vcc, 0, v71
	v_add_u32_e32 v71, 1, v65
	v_cvt_pk_bf16_f32 v20, v44, v45
	v_cndmask_b32_e32 v70, v65, v70, vcc
	v_fma_f32 v65, -v71, v65, v64
	v_cmp_lt_f32_e32 vcc, 0, v65
	v_cvt_pk_bf16_f32 v21, v46, v47
	v_cvt_pk_bf16_f32 v22, v52, v53
	v_cndmask_b32_e32 v65, v70, v71, vcc
	v_mul_f32_e32 v70, 0x37800000, v65
	v_cndmask_b32_e64 v65, v65, v70, s[70:71]
	v_cmp_class_f32_e32 vcc, v64, v207
	v_cvt_pk_bf16_f32 v23, v54, v23
	v_mov_b32_e32 v52, v48
	v_cndmask_b32_e32 v64, v65, v64, vcc
	v_div_scale_f32 v65, s[70:71], v64, v64, 1.0
	v_rcp_f32_e32 v70, v65
	v_mfma_f32_16x16x32_bf16 v[12:15], v[12:15], v[20:23], v[36:39]
	v_mov_b32_e32 v53, v50
	v_mov_b32_e32 v50, v49
	v_fma_f32 v71, -v65, v70, 1.0
	v_fmac_f32_e32 v70, v71, v70
	v_div_scale_f32 v71, vcc, 1.0, v64, 1.0
	v_mul_f32_e32 v72, v71, v70
	v_fma_f32 v73, -v65, v72, v71
	v_fmac_f32_e32 v72, v73, v70
	v_fma_f32 v65, -v65, v72, v71
	v_div_fmas_f32 v65, v65, v70, v72
	v_div_fixup_f32 v64, v65, v64, 1.0
	v_mul_f32_e32 v65, 0xbfb8aa3b, v76
	v_exp_f32_e32 v65, v65
	flat_load_dwordx2 v[74:75], v[66:67] offset:1568
	flat_load_dwordx2 v[70:71], v[66:67] offset:1600
	s_nop 0
	flat_load_dwordx2 v[66:67], v[66:67] offset:1632
	v_lshlrev_b64 v[72:73], 11, v[150:151]
	v_mfma_f32_16x16x32_bf16 v[8:11], v[8:11], v[20:23], v[32:35]
	v_add_f32_e32 v65, 1.0, v65
	v_rcp_f32_e32 v78, v65
	v_add_f32_e32 v65, 1.0, v79
	v_rcp_f32_e32 v79, v56
	v_mul_f32_e32 v56, 0xbfb8aa3b, v69
	v_exp_f32_e32 v56, v56
	v_rcp_f32_e32 v80, v65
	v_pk_mul_f32 v[82:83], v[82:83], v[64:65] op_sel_hi:[1,0]
	s_waitcnt vmcnt(0)
	v_mov_b32_e32 v84, v60
	v_add_f32_e32 v56, 1.0, v56
	v_rcp_f32_e32 v81, v56
	v_mov_b32_e32 v85, v62
	v_pk_mul_f32 v[82:83], v[84:85], v[82:83]
	v_pk_mul_f32 v[76:77], v[78:79], v[76:77]
	v_pk_mul_f32 v[56:57], v[58:59], v[64:65] op_sel_hi:[1,0]
	v_mov_b32_e32 v62, v61
	v_pk_mul_f32 v[76:77], v[82:83], v[76:77]
	v_pk_mul_f32 v[56:57], v[62:63], v[56:57]
	v_pk_mul_f32 v[58:59], v[80:81], v[68:69]
	v_pk_mul_f32 v[52:53], v[52:53], v[64:65] op_sel_hi:[1,0]
	v_pk_mul_f32 v[56:57], v[56:57], v[58:59]
	v_and_b32_sdwa v59, v76, v209 dst_sel:DWORD dst_unused:UNUSED_PAD src0_sel:WORD_1 src1_sel:DWORD
	v_add3_u32 v60, v76, v59, s77
	v_and_b32_sdwa v59, v57, v209 dst_sel:DWORD dst_unused:UNUSED_PAD src0_sel:WORD_1 src1_sel:DWORD
	v_and_b32_sdwa v61, v56, v209 dst_sel:DWORD dst_unused:UNUSED_PAD src0_sel:WORD_1 src1_sel:DWORD
	v_and_b32_sdwa v58, v77, v209 dst_sel:DWORD dst_unused:UNUSED_PAD src0_sel:WORD_1 src1_sel:DWORD
	v_add3_u32 v57, v57, v59, s77
	v_add3_u32 v56, v56, v61, s77
	v_add3_u32 v58, v77, v58, s77
	v_and_b32_e32 v57, 0xffff0000, v57
	v_and_b32_e32 v56, 0xffff0000, v56
	v_or_b32_sdwa v59, v57, v58 dst_sel:DWORD dst_unused:UNUSED_PAD src0_sel:DWORD src1_sel:WORD_1
	v_or_b32_sdwa v58, v56, v60 dst_sel:DWORD dst_unused:UNUSED_PAD src0_sel:DWORD src1_sel:WORD_1
	v_lshl_add_u64 v[56:57], v[134:135], 0, v[72:73]
	global_store_dwordx2 v[56:57], v[58:59], off
	global_load_dwordx4 v[58:61], v[132:133], off offset:64
	v_mov_b32_e32 v48, v40
	v_mov_b32_e32 v49, v42
	v_pk_mul_f32 v[48:49], v[48:49], v[64:65] op_sel_hi:[1,0]
	v_mov_b32_e32 v42, v41
	v_mfma_f32_16x16x32_bf16 v[4:7], v[4:7], v[20:23], v[24:27]
	s_waitcnt lgkmcnt(0)
	v_lshlrev_b32_e32 v36, 16, v74
	v_mul_f32_e32 v38, 0xbfb8aa3b, v36
	v_exp_f32_e32 v39, v38
	v_and_b32_e32 v38, 0xffff0000, v74
	v_mul_f32_e32 v44, 0xbfb8aa3b, v38
	v_exp_f32_e32 v45, v44
	v_lshlrev_b32_e32 v37, 16, v75
	v_add_f32_e32 v39, 1.0, v39
	v_rcp_f32_e32 v44, v39
	v_add_f32_e32 v45, 1.0, v45
	v_rcp_f32_e32 v46, v45
	v_mul_f32_e32 v45, 0xbfb8aa3b, v37
	v_exp_f32_e32 v45, v45
	v_and_b32_e32 v39, 0xffff0000, v75
	v_mul_f32_e32 v47, 0xbfb8aa3b, v39
	v_exp_f32_e32 v47, v47
	v_add_f32_e32 v45, 1.0, v45
	v_rcp_f32_e32 v45, v45
	v_lshlrev_b32_e32 v32, 16, v70
	v_mul_f32_e32 v34, 0xbfb8aa3b, v32
	v_lshlrev_b32_e32 v33, 16, v71
	v_pk_mul_f32 v[36:37], v[44:45], v[36:37]
	v_add_f32_e32 v44, 1.0, v47
	v_rcp_f32_e32 v47, v44
	v_pk_mul_f32 v[44:45], v[50:51], v[64:65] op_sel_hi:[1,0]
	v_exp_f32_e32 v35, v34
	v_and_b32_e32 v34, 0xffff0000, v70
	v_pk_mul_f32 v[38:39], v[46:47], v[38:39]
	v_mul_f32_e32 v40, 0xbfb8aa3b, v33
	v_exp_f32_e32 v40, v40
	v_add_f32_e32 v35, 1.0, v35
	v_mfma_f32_16x16x32_bf16 v[0:3], v[0:3], v[20:23], v[16:19]
	v_mul_f32_e64 v20, v12, v12
	v_mul_f32_e64 v21, v13, v13
	v_pk_mul_f32 v[22:23], v[10:11], v[10:11]
	v_pk_mul_f32 v[26:27], v[8:9], v[8:9]
	v_pk_mul_f32 v[18:19], v[14:15], v[14:15]
	v_mov_b32_e32 v16, v28
	v_mov_b32_e32 v17, v30
	v_mov_b32_e32 v30, v29
	v_pk_mov_b32 v[28:29], v[20:21], v[18:19] op_sel:[1,0]
	s_waitcnt vmcnt(0)
	v_mov_b32_e32 v54, v58
	v_mov_b32_e32 v55, v60
	v_pk_mul_f32 v[52:53], v[54:55], v[52:53]
	v_mov_b32_e32 v60, v59
	v_pk_mul_f32 v[36:37], v[52:53], v[36:37]
	v_pk_mul_f32 v[44:45], v[60:61], v[44:45]
	v_mov_b32_e32 v21, v19
	v_pk_mul_f32 v[38:39], v[44:45], v[38:39]
	v_and_b32_sdwa v44, v37, v209 dst_sel:DWORD dst_unused:UNUSED_PAD src0_sel:WORD_1 src1_sel:DWORD
	v_and_b32_sdwa v45, v36, v209 dst_sel:DWORD dst_unused:UNUSED_PAD src0_sel:WORD_1 src1_sel:DWORD
	v_add3_u32 v36, v36, v45, s77
	v_add3_u32 v37, v37, v44, s77
	v_and_b32_sdwa v44, v39, v209 dst_sel:DWORD dst_unused:UNUSED_PAD src0_sel:WORD_1 src1_sel:DWORD
	v_and_b32_sdwa v45, v38, v209 dst_sel:DWORD dst_unused:UNUSED_PAD src0_sel:WORD_1 src1_sel:DWORD
	v_add3_u32 v39, v39, v44, s77
	v_add3_u32 v38, v38, v45, s77
	v_and_b32_e32 v39, 0xffff0000, v39
	v_and_b32_e32 v38, 0xffff0000, v38
	v_or_b32_sdwa v37, v39, v37 dst_sel:DWORD dst_unused:UNUSED_PAD src0_sel:DWORD src1_sel:WORD_1
	v_or_b32_sdwa v36, v38, v36 dst_sel:DWORD dst_unused:UNUSED_PAD src0_sel:DWORD src1_sel:WORD_1
	global_store_dwordx2 v[56:57], v[36:37], off offset:32
	global_load_dwordx4 v[36:39], v[132:133], off offset:128
	v_mul_f32_e32 v44, 0xbfb8aa3b, v34
	v_exp_f32_e32 v45, v44
	v_rcp_f32_e32 v44, v35
	v_and_b32_e32 v35, 0xffff0000, v71
	v_pk_add_f32 v[20:21], v[28:29], v[20:21]
	v_add_f32_e32 v45, 1.0, v45
	v_rcp_f32_e32 v46, v45
	v_lshlrev_b32_e32 v29, 16, v67
	v_lshlrev_b32_e32 v28, 16, v66
	v_pk_mov_b32 v[18:19], v[26:27], v[22:23] op_sel:[1,0]
	v_mul_f32_e32 v22, 0xbfb8aa3b, v28
	v_exp_f32_e32 v22, v22
	v_lshl_add_u64 v[24:25], v[148:149], 0, s[72:73]
	v_pk_mul_f32 v[16:17], v[16:17], v[64:65] op_sel_hi:[1,0]
	v_pk_mul_f32 v[30:31], v[30:31], v[64:65] op_sel_hi:[1,0]
	v_add_f32_e32 v22, 1.0, v22
	v_pk_add_f32 v[20:21], v[20:21], v[20:21] op_sel:[0,1] op_sel_hi:[1,0]
	s_waitcnt vmcnt(0)
	v_mov_b32_e32 v50, v36
	v_add_f32_e32 v36, 1.0, v40
	v_rcp_f32_e32 v45, v36
	v_mul_f32_e32 v36, 0xbfb8aa3b, v35
	v_exp_f32_e32 v36, v36
	v_mov_b32_e32 v51, v38
	v_pk_mul_f32 v[48:49], v[48:49], v[50:51]
	v_pk_mul_f32 v[32:33], v[44:45], v[32:33]
	v_add_f32_e32 v36, 1.0, v36
	v_rcp_f32_e32 v47, v36
	v_pk_mul_f32 v[40:41], v[42:43], v[64:65] op_sel_hi:[1,0]
	v_mov_b32_e32 v38, v37
	v_pk_mul_f32 v[32:33], v[48:49], v[32:33]
	v_pk_mul_f32 v[36:37], v[40:41], v[38:39]
	v_pk_mul_f32 v[34:35], v[46:47], v[34:35]
	v_and_b32_e32 v39, 0xffff0000, v67
	v_pk_mul_f32 v[34:35], v[36:37], v[34:35]
	v_and_b32_sdwa v36, v33, v209 dst_sel:DWORD dst_unused:UNUSED_PAD src0_sel:WORD_1 src1_sel:DWORD
	v_and_b32_sdwa v37, v32, v209 dst_sel:DWORD dst_unused:UNUSED_PAD src0_sel:WORD_1 src1_sel:DWORD
	v_add3_u32 v32, v32, v37, s77
	v_add3_u32 v33, v33, v36, s77
	v_and_b32_sdwa v36, v35, v209 dst_sel:DWORD dst_unused:UNUSED_PAD src0_sel:WORD_1 src1_sel:DWORD
	v_and_b32_sdwa v37, v34, v209 dst_sel:DWORD dst_unused:UNUSED_PAD src0_sel:WORD_1 src1_sel:DWORD
	v_add3_u32 v35, v35, v36, s77
	v_add3_u32 v34, v34, v37, s77
	v_and_b32_e32 v35, 0xffff0000, v35
	v_and_b32_e32 v34, 0xffff0000, v34
	v_or_b32_sdwa v33, v35, v33 dst_sel:DWORD dst_unused:UNUSED_PAD src0_sel:DWORD src1_sel:WORD_1
	v_or_b32_sdwa v32, v34, v32 dst_sel:DWORD dst_unused:UNUSED_PAD src0_sel:DWORD src1_sel:WORD_1
	global_store_dwordx2 v[56:57], v[32:33], off offset:64
	global_load_dwordx4 v[32:35], v[132:133], off offset:192
	v_and_b32_e32 v38, 0xffff0000, v66
	v_mul_f32_e32 v40, 0xbfb8aa3b, v29
	v_mul_f32_e32 v27, 0xbfb8aa3b, v38
	v_mul_f32_e32 v41, 0xbfb8aa3b, v39
	v_exp_f32_e32 v40, v40
	v_exp_f32_e32 v27, v27
	v_exp_f32_e32 v41, v41
	v_lshl_add_u64 v[36:37], v[24:25], 0, v[144:145]
	v_add_f32_e32 v43, 1.0, v40
	v_add_f32_e32 v27, 1.0, v27
	v_add_f32_e32 v44, 1.0, v41
	v_rcp_f32_e32 v40, v22
	v_rcp_f32_e32 v41, v43
	v_rcp_f32_e32 v42, v27
	v_rcp_f32_e32 v43, v44
	flat_load_dwordx2 v[24:25], v[36:37] offset:1536
	v_pk_mul_f32 v[28:29], v[40:41], v[28:29]
	v_pk_mul_f32 v[38:39], v[42:43], v[38:39]
	s_waitcnt vmcnt(0)
	v_mov_b32_e32 v40, v32
	v_mov_b32_e32 v41, v34
	v_mov_b32_e32 v34, v33
	v_pk_mul_f32 v[16:17], v[16:17], v[40:41]
	v_pk_mul_f32 v[30:31], v[30:31], v[34:35]
	v_pk_mul_f32 v[16:17], v[16:17], v[28:29]
	v_pk_mul_f32 v[28:29], v[30:31], v[38:39]
	v_and_b32_sdwa v22, v17, v209 dst_sel:DWORD dst_unused:UNUSED_PAD src0_sel:WORD_1 src1_sel:DWORD
	v_and_b32_sdwa v27, v16, v209 dst_sel:DWORD dst_unused:UNUSED_PAD src0_sel:WORD_1 src1_sel:DWORD
	v_and_b32_sdwa v30, v29, v209 dst_sel:DWORD dst_unused:UNUSED_PAD src0_sel:WORD_1 src1_sel:DWORD
	v_and_b32_sdwa v31, v28, v209 dst_sel:DWORD dst_unused:UNUSED_PAD src0_sel:WORD_1 src1_sel:DWORD
	v_add3_u32 v16, v16, v27, s77
	v_add3_u32 v17, v17, v22, s77
	v_add3_u32 v22, v29, v30, s77
	v_add3_u32 v27, v28, v31, s77
	v_and_b32_e32 v22, 0xffff0000, v22
	v_and_b32_e32 v27, 0xffff0000, v27
	v_or_b32_sdwa v17, v22, v17 dst_sel:DWORD dst_unused:UNUSED_PAD src0_sel:DWORD src1_sel:WORD_1
	v_or_b32_sdwa v16, v27, v16 dst_sel:DWORD dst_unused:UNUSED_PAD src0_sel:DWORD src1_sel:WORD_1
	global_store_dwordx2 v[56:57], v[16:17], off offset:96
	v_mov_b32_e32 v27, v23
	v_pk_add_f32 v[22:23], v[18:19], v[26:27]
	global_load_dwordx4 v[16:19], v[132:133], off
	v_mul_f32_e32 v26, v0, v0
	v_mul_f32_e32 v27, v1, v1
	v_pk_add_f32 v[22:23], v[22:23], v[22:23] op_sel:[0,1] op_sel_hi:[1,0]
	v_mov_b32_e32 v21, v26
	v_mov_b32_e32 v23, v27
	v_pk_add_f32 v[20:21], v[20:21], v[22:23]
	v_mul_f32_e32 v22, v5, v5
	v_mul_f32_e32 v26, v7, v7
	v_mul_f32_e32 v28, v2, v2
	v_mul_f32_e32 v29, v3, v3
	v_pk_fma_f32 v[22:23], v[4:5], v[4:5], v[22:23] op_sel_hi:[1,1,0]
	v_pk_fma_f32 v[26:27], v[6:7], v[6:7], v[26:27] op_sel_hi:[1,1,0]
	v_mov_b32_e32 v23, v28
	v_mov_b32_e32 v27, v29
	v_pk_add_f32 v[22:23], v[22:23], v[26:27]
	v_mov_b32_e32 v30, v12
	v_pk_add_f32 v[20:21], v[20:21], v[22:23]
	v_lshlrev_b64 v[22:23], 11, v[146:147]
	v_add_f32_e32 v20, v20, v21
	ds_bpermute_b32 v21, v219, v20
	s_waitcnt lgkmcnt(0)
	v_add_f32_e32 v20, v20, v21
	ds_bpermute_b32 v21, v220, v20
	s_waitcnt lgkmcnt(0)
	v_add_f32_e32 v20, v20, v21
	v_fmamk_f32 v20, v20, 0x3c800000, v206
	v_mul_f32_e32 v21, 0x4f800000, v20
	v_cmp_gt_f32_e32 vcc, s92, v20
	v_readlane_b32 s92, v253, 9
	v_readlane_b32 s94, v253, 11
	v_cndmask_b32_e32 v31, v20, v21, vcc
	v_sqrt_f32_e32 v32, v31
	flat_load_dwordx2 v[28:29], v[36:37] offset:1568
	flat_load_dwordx2 v[26:27], v[36:37] offset:1600
	flat_load_dwordx2 v[20:21], v[36:37] offset:1632
	s_add_i32 s91, s91, s94
	s_cmpk_gt_i32 s91, 0xff
	v_add_u32_e32 v12, -1, v32
	v_add_u32_e32 v33, 1, v32
	v_fma_f32 v34, -v12, v32, v31
	v_fma_f32 v35, -v33, v32, v31
	v_cmp_ge_f32_e64 s[70:71], 0, v34
	v_readlane_b32 s93, v253, 10
	v_readlane_b32 s95, v253, 12
	v_cndmask_b32_e64 v12, v32, v12, s[70:71]
	v_cmp_lt_f32_e64 s[70:71], 0, v35
	s_waitcnt vmcnt(0)
	v_mov_b32_e32 v38, v16
	v_cndmask_b32_e64 v12, v12, v33, s[70:71]
	v_mul_f32_e32 v32, 0x37800000, v12
	v_cndmask_b32_e32 v12, v12, v32, vcc
	v_cmp_class_f32_e32 vcc, v31, v207
	v_mov_b32_e32 v39, v18
	v_mov_b32_e32 v18, v17
	v_cndmask_b32_e32 v12, v12, v31, vcc
	v_div_scale_f32 v32, s[70:71], v12, v12, 1.0
	v_rcp_f32_e32 v33, v32
	v_mov_b32_e32 v31, v14
	v_div_scale_f32 v14, vcc, 1.0, v12, 1.0
	v_fma_f32 v34, -v32, v33, 1.0
	v_fmac_f32_e32 v33, v34, v33
	v_mul_f32_e32 v34, v14, v33
	v_fma_f32 v35, -v32, v34, v14
	v_fmac_f32_e32 v34, v35, v33
	v_fma_f32 v14, -v32, v34, v14
	v_div_fmas_f32 v14, v14, v33, v34
	v_lshlrev_b32_e32 v32, 16, v24
	v_div_fixup_f32 v12, v14, v12, 1.0
	v_and_b32_e32 v24, 0xffff0000, v24
	v_mul_f32_e32 v14, 0xbfb8aa3b, v32
	v_mul_f32_e32 v34, 0xbfb8aa3b, v24
	v_exp_f32_e32 v14, v14
	v_exp_f32_e32 v34, v34
	v_lshlrev_b32_e32 v33, 16, v25
	v_and_b32_e32 v25, 0xffff0000, v25
	v_add_f32_e32 v14, 1.0, v14
	v_add_f32_e32 v36, 1.0, v34
	v_rcp_f32_e32 v34, v14
	v_mul_f32_e32 v14, 0xbfb8aa3b, v25
	v_mul_f32_e32 v35, 0xbfb8aa3b, v33
	v_exp_f32_e32 v16, v14
	v_exp_f32_e32 v35, v35
	v_pk_mul_f32 v[30:31], v[30:31], v[12:13] op_sel_hi:[1,0]
	v_mov_b32_e32 v14, v13
	v_add_f32_e32 v13, 1.0, v16
	v_add_f32_e32 v35, 1.0, v35
	v_rcp_f32_e32 v36, v36
	v_rcp_f32_e32 v37, v13
	v_rcp_f32_e32 v35, v35
	v_pk_mul_f32 v[14:15], v[14:15], v[12:13] op_sel_hi:[1,0]
	v_pk_mul_f32 v[30:31], v[38:39], v[30:31]
	v_pk_mul_f32 v[14:15], v[18:19], v[14:15]
	v_pk_mul_f32 v[16:17], v[36:37], v[24:25]
	v_pk_mul_f32 v[32:33], v[34:35], v[32:33]
	v_pk_mul_f32 v[14:15], v[14:15], v[16:17]
	v_pk_mul_f32 v[30:31], v[30:31], v[32:33]
	v_and_b32_sdwa v17, v15, v209 dst_sel:DWORD dst_unused:UNUSED_PAD src0_sel:WORD_1 src1_sel:DWORD
	v_and_b32_sdwa v18, v14, v209 dst_sel:DWORD dst_unused:UNUSED_PAD src0_sel:WORD_1 src1_sel:DWORD
	v_and_b32_sdwa v13, v31, v209 dst_sel:DWORD dst_unused:UNUSED_PAD src0_sel:WORD_1 src1_sel:DWORD
	v_and_b32_sdwa v16, v30, v209 dst_sel:DWORD dst_unused:UNUSED_PAD src0_sel:WORD_1 src1_sel:DWORD
	v_add3_u32 v15, v15, v17, s77
	v_add3_u32 v14, v14, v18, s77
	v_add3_u32 v16, v30, v16, s77
	v_add3_u32 v13, v31, v13, s77
	v_and_b32_e32 v15, 0xffff0000, v15
	v_and_b32_e32 v14, 0xffff0000, v14
	v_or_b32_sdwa v15, v15, v13 dst_sel:DWORD dst_unused:UNUSED_PAD src0_sel:DWORD src1_sel:WORD_1
	v_or_b32_sdwa v14, v14, v16 dst_sel:DWORD dst_unused:UNUSED_PAD src0_sel:DWORD src1_sel:WORD_1
	v_lshl_add_u64 v[18:19], v[134:135], 0, v[22:23]
	global_store_dwordx2 v[18:19], v[14:15], off
	global_load_dwordx4 v[14:17], v[132:133], off offset:64
	v_mov_b32_e32 v22, v8
	v_mov_b32_e32 v23, v10
	v_mov_b32_e32 v10, v9
	s_waitcnt lgkmcnt(0)
	v_lshlrev_b32_e32 v9, 16, v29
	v_lshlrev_b32_e32 v8, 16, v28
	v_and_b32_e32 v25, 0xffff0000, v29
	v_and_b32_e32 v24, 0xffff0000, v28
	v_mul_f32_e32 v13, 0xbfb8aa3b, v8
	v_mul_f32_e32 v29, 0xbfb8aa3b, v9
	v_mul_f32_e32 v28, 0xbfb8aa3b, v24
	v_mul_f32_e32 v30, 0xbfb8aa3b, v25
	v_exp_f32_e32 v13, v13
	v_exp_f32_e32 v29, v29
	v_exp_f32_e32 v28, v28
	v_exp_f32_e32 v30, v30
	v_add_f32_e32 v13, 1.0, v13
	v_add_f32_e32 v29, 1.0, v29
	v_add_f32_e32 v31, 1.0, v28
	v_add_f32_e32 v32, 1.0, v30
	v_rcp_f32_e32 v28, v13
	v_rcp_f32_e32 v29, v29
	v_rcp_f32_e32 v30, v31
	v_rcp_f32_e32 v31, v32
	v_pk_mul_f32 v[10:11], v[10:11], v[12:13] op_sel_hi:[1,0]
	v_pk_mul_f32 v[8:9], v[28:29], v[8:9]
	v_pk_mul_f32 v[22:23], v[22:23], v[12:13] op_sel_hi:[1,0]
	v_pk_mul_f32 v[24:25], v[30:31], v[24:25]
	s_waitcnt vmcnt(0)
	v_mov_b32_e32 v29, v16
	v_mov_b32_e32 v16, v15
	v_mov_b32_e32 v28, v14
	v_pk_mul_f32 v[10:11], v[16:17], v[10:11]
	v_pk_mul_f32 v[14:15], v[28:29], v[22:23]
	v_pk_mul_f32 v[10:11], v[10:11], v[24:25]
	v_pk_mul_f32 v[8:9], v[14:15], v[8:9]
	v_and_b32_sdwa v15, v11, v209 dst_sel:DWORD dst_unused:UNUSED_PAD src0_sel:WORD_1 src1_sel:DWORD
	v_and_b32_sdwa v16, v10, v209 dst_sel:DWORD dst_unused:UNUSED_PAD src0_sel:WORD_1 src1_sel:DWORD
	v_and_b32_sdwa v13, v9, v209 dst_sel:DWORD dst_unused:UNUSED_PAD src0_sel:WORD_1 src1_sel:DWORD
	v_and_b32_sdwa v14, v8, v209 dst_sel:DWORD dst_unused:UNUSED_PAD src0_sel:WORD_1 src1_sel:DWORD
	v_add3_u32 v11, v11, v15, s77
	v_add3_u32 v10, v10, v16, s77
	v_add3_u32 v8, v8, v14, s77
	v_add3_u32 v9, v9, v13, s77
	v_and_b32_e32 v11, 0xffff0000, v11
	v_and_b32_e32 v10, 0xffff0000, v10
	v_or_b32_sdwa v9, v11, v9 dst_sel:DWORD dst_unused:UNUSED_PAD src0_sel:DWORD src1_sel:WORD_1
	v_or_b32_sdwa v8, v10, v8 dst_sel:DWORD dst_unused:UNUSED_PAD src0_sel:DWORD src1_sel:WORD_1
	global_store_dwordx2 v[18:19], v[8:9], off offset:32
	global_load_dwordx4 v[8:11], v[132:133], off offset:128
	v_mov_b32_e32 v14, v4
	v_mov_b32_e32 v15, v6
	v_mov_b32_e32 v6, v5
	v_lshlrev_b32_e32 v5, 16, v27
	v_lshlrev_b32_e32 v4, 16, v26
	v_and_b32_e32 v17, 0xffff0000, v27
	v_and_b32_e32 v16, 0xffff0000, v26
	v_mul_f32_e32 v13, 0xbfb8aa3b, v4
	v_mul_f32_e32 v23, 0xbfb8aa3b, v5
	v_mul_f32_e32 v22, 0xbfb8aa3b, v16
	v_mul_f32_e32 v24, 0xbfb8aa3b, v17
	v_exp_f32_e32 v13, v13
	v_exp_f32_e32 v23, v23
	v_exp_f32_e32 v22, v22
	v_exp_f32_e32 v24, v24
	v_add_f32_e32 v13, 1.0, v13
	v_add_f32_e32 v23, 1.0, v23
	v_add_f32_e32 v25, 1.0, v22
	v_add_f32_e32 v26, 1.0, v24
	v_rcp_f32_e32 v22, v13
	v_rcp_f32_e32 v23, v23
	v_rcp_f32_e32 v24, v25
	v_rcp_f32_e32 v25, v26
	v_pk_mul_f32 v[6:7], v[6:7], v[12:13] op_sel_hi:[1,0]
	v_pk_mul_f32 v[4:5], v[22:23], v[4:5]
	v_pk_mul_f32 v[14:15], v[14:15], v[12:13] op_sel_hi:[1,0]
	v_pk_mul_f32 v[16:17], v[24:25], v[16:17]
	s_waitcnt vmcnt(0)
	v_mov_b32_e32 v23, v10
	v_mov_b32_e32 v10, v9
	v_mov_b32_e32 v22, v8
	v_pk_mul_f32 v[6:7], v[6:7], v[10:11]
	v_pk_mul_f32 v[8:9], v[14:15], v[22:23]
	v_pk_mul_f32 v[6:7], v[6:7], v[16:17]
	v_pk_mul_f32 v[4:5], v[8:9], v[4:5]
	v_and_b32_sdwa v10, v7, v209 dst_sel:DWORD dst_unused:UNUSED_PAD src0_sel:WORD_1 src1_sel:DWORD
	v_and_b32_sdwa v11, v6, v209 dst_sel:DWORD dst_unused:UNUSED_PAD src0_sel:WORD_1 src1_sel:DWORD
	v_and_b32_sdwa v8, v5, v209 dst_sel:DWORD dst_unused:UNUSED_PAD src0_sel:WORD_1 src1_sel:DWORD
	v_and_b32_sdwa v9, v4, v209 dst_sel:DWORD dst_unused:UNUSED_PAD src0_sel:WORD_1 src1_sel:DWORD
	v_add3_u32 v7, v7, v10, s77
	v_add3_u32 v6, v6, v11, s77
	v_add3_u32 v4, v4, v9, s77
	v_add3_u32 v5, v5, v8, s77
	v_and_b32_e32 v7, 0xffff0000, v7
	v_and_b32_e32 v6, 0xffff0000, v6
	v_or_b32_sdwa v5, v7, v5 dst_sel:DWORD dst_unused:UNUSED_PAD src0_sel:DWORD src1_sel:WORD_1
	v_or_b32_sdwa v4, v6, v4 dst_sel:DWORD dst_unused:UNUSED_PAD src0_sel:DWORD src1_sel:WORD_1
	global_store_dwordx2 v[18:19], v[4:5], off offset:64
	global_load_dwordx4 v[4:7], v[132:133], off offset:192
	v_and_b32_e32 v11, 0xffff0000, v21
	v_and_b32_e32 v10, 0xffff0000, v20
	v_mov_b32_e32 v8, v0
	v_mov_b32_e32 v9, v2
	v_mov_b32_e32 v2, v1
	v_lshlrev_b32_e32 v1, 16, v21
	v_lshlrev_b32_e32 v0, 16, v20
	v_mul_f32_e32 v14, 0xbfb8aa3b, v10
	v_mul_f32_e32 v16, 0xbfb8aa3b, v11
	v_mul_f32_e32 v13, 0xbfb8aa3b, v0
	v_mul_f32_e32 v15, 0xbfb8aa3b, v1
	v_exp_f32_e32 v14, v14
	v_exp_f32_e32 v16, v16
	v_exp_f32_e32 v13, v13
	v_exp_f32_e32 v15, v15
	v_add_f32_e32 v17, 1.0, v14
	v_add_f32_e32 v20, 1.0, v16
	v_add_f32_e32 v13, 1.0, v13
	v_add_f32_e32 v15, 1.0, v15
	v_rcp_f32_e32 v16, v17
	v_rcp_f32_e32 v17, v20
	v_rcp_f32_e32 v14, v13
	v_rcp_f32_e32 v15, v15
	v_pk_mul_f32 v[8:9], v[8:9], v[12:13] op_sel_hi:[1,0]
	v_pk_mul_f32 v[2:3], v[2:3], v[12:13] op_sel_hi:[1,0]
	v_pk_mul_f32 v[10:11], v[16:17], v[10:11]
	v_pk_mul_f32 v[0:1], v[14:15], v[0:1]
	s_waitcnt vmcnt(0)
	v_mov_b32_e32 v13, v6
	v_mov_b32_e32 v6, v5
	v_mov_b32_e32 v12, v4
	v_pk_mul_f32 v[2:3], v[2:3], v[6:7]
	v_pk_mul_f32 v[4:5], v[8:9], v[12:13]
	v_pk_mul_f32 v[2:3], v[2:3], v[10:11]
	v_pk_mul_f32 v[0:1], v[4:5], v[0:1]
	v_and_b32_sdwa v6, v3, v209 dst_sel:DWORD dst_unused:UNUSED_PAD src0_sel:WORD_1 src1_sel:DWORD
	v_and_b32_sdwa v7, v2, v209 dst_sel:DWORD dst_unused:UNUSED_PAD src0_sel:WORD_1 src1_sel:DWORD
	v_and_b32_sdwa v4, v1, v209 dst_sel:DWORD dst_unused:UNUSED_PAD src0_sel:WORD_1 src1_sel:DWORD
	v_and_b32_sdwa v5, v0, v209 dst_sel:DWORD dst_unused:UNUSED_PAD src0_sel:WORD_1 src1_sel:DWORD
	v_add3_u32 v3, v3, v6, s77
	v_add3_u32 v2, v2, v7, s77
	v_add3_u32 v0, v0, v5, s77
	v_add3_u32 v1, v1, v4, s77
	v_and_b32_e32 v3, 0xffff0000, v3
	v_and_b32_e32 v2, 0xffff0000, v2
	v_or_b32_sdwa v1, v3, v1 dst_sel:DWORD dst_unused:UNUSED_PAD src0_sel:DWORD src1_sel:WORD_1
	v_or_b32_sdwa v0, v2, v0 dst_sel:DWORD dst_unused:UNUSED_PAD src0_sel:DWORD src1_sel:WORD_1
	global_store_dwordx2 v[18:19], v[0:1], off offset:96
	s_waitcnt lgkmcnt(0)
	s_barrier
	s_cbranch_scc1 .LBB0_483

.LBB0_485:
	ds_read_b128 v[12:15], v184 offset:33792
	ds_read_b128 v[20:23], v184 offset:33808
	v_cmp_ge_i32_e32 vcc, v175, v119
	s_mov_b32 s7, s83
	v_ashrrev_i32_e32 v121, 31, v120
	s_waitcnt lgkmcnt(1)
	v_mul_f32_e32 v12, 0xbfb8aa3b, v12
	v_mul_f32_e32 v13, 0xbfb8aa3b, v13
	v_mul_f32_e32 v14, 0xbfb8aa3b, v14
	v_mul_f32_e32 v15, 0xbfb8aa3b, v15
	s_waitcnt lgkmcnt(0)
	v_mul_f32_e32 v20, 0xbfb8aa3b, v20
	v_mul_f32_e32 v21, 0xbfb8aa3b, v21
	v_mul_f32_e32 v22, 0xbfb8aa3b, v22
	v_mul_f32_e32 v23, 0xbfb8aa3b, v23
	v_exp_f32_e32 v12, v12
	v_exp_f32_e32 v13, v13
	v_exp_f32_e32 v14, v14
	v_exp_f32_e32 v15, v15
	v_exp_f32_e32 v20, v20
	v_exp_f32_e32 v21, v21
	v_exp_f32_e32 v22, v22
	v_exp_f32_e32 v23, v23
	v_pk_mul_f32 v[12:13], v[12:13], v[130:131]
	v_pk_mul_f32 v[14:15], v[14:15], v[132:133]
	v_pk_mul_f32 v[20:21], v[20:21], v[134:135]
	v_pk_mul_f32 v[22:23], v[22:23], v[128:129]
	v_cvt_pk_bf16_f32 v12, v12, v13
	v_cvt_pk_bf16_f32 v13, v14, v15
	v_cvt_pk_bf16_f32 v14, v20, v21
	v_cvt_pk_bf16_f32 v15, v22, v23
	ds_read_b128 v[20:23], v184 offset:50432
	ds_read_b128 v[28:31], v184 offset:50448
	v_mfma_f32_16x16x32_bf16 v[12:15], v[12:15], v[68:71], 0
	s_add_i32 s12, s12, s66
	s_add_i32 s11, s11, s80
	s_cmp_lt_i32 s12, 16
	s_nop 4
	v_cndmask_b32_e32 v32, 0, v12, vcc
	v_cmp_ge_i32_e32 vcc, v176, v119
	s_waitcnt lgkmcnt(1)
	v_mul_f32_e32 v12, 0xbfb8aa3b, v20
	v_mul_f32_e32 v20, 0xbfb8aa3b, v22
	v_cndmask_b32_e32 v33, 0, v13, vcc
	v_mul_f32_e32 v13, 0xbfb8aa3b, v21
	v_mul_f32_e32 v21, 0xbfb8aa3b, v23
	s_waitcnt lgkmcnt(0)
	v_mul_f32_e32 v22, 0xbfb8aa3b, v28
	v_mul_f32_e32 v23, 0xbfb8aa3b, v29
	v_mul_f32_e32 v28, 0xbfb8aa3b, v30
	v_mul_f32_e32 v29, 0xbfb8aa3b, v31
	v_exp_f32_e32 v12, v12
	v_exp_f32_e32 v13, v13
	v_exp_f32_e32 v20, v20
	v_exp_f32_e32 v21, v21
	v_exp_f32_e32 v22, v22
	v_exp_f32_e32 v23, v23
	v_exp_f32_e32 v28, v28
	v_exp_f32_e32 v29, v29
	v_pk_mul_f32 v[12:13], v[12:13], v[86:87]
	v_pk_mul_f32 v[30:31], v[20:21], v[124:125]
	v_pk_mul_f32 v[22:23], v[22:23], v[126:127]
	v_pk_mul_f32 v[28:29], v[28:29], v[84:85]
	v_cvt_pk_bf16_f32 v20, v12, v13
	v_cvt_pk_bf16_f32 v21, v30, v31
	v_cvt_pk_bf16_f32 v22, v22, v23
	v_cvt_pk_bf16_f32 v23, v28, v29
	v_cmp_ge_i32_e32 vcc, v177, v119
	s_nop 1
	v_cndmask_b32_e32 v28, 0, v14, vcc
	v_cmp_ge_i32_e32 vcc, v178, v119
	s_nop 1
	v_cndmask_b32_e32 v29, 0, v15, vcc
	v_mfma_f32_16x16x32_bf16 v[12:15], v[20:23], v[68:71], 0
	v_cmp_ge_i32_e32 vcc, v179, v119
	v_cvt_pk_bf16_f32 v20, v32, v33
	v_cvt_pk_bf16_f32 v21, v28, v29
	s_nop 4
	v_cndmask_b32_e32 v12, 0, v12, vcc
	v_cmp_ge_i32_e32 vcc, v180, v119
	s_nop 1
	v_cndmask_b32_e32 v13, 0, v13, vcc
	v_cmp_ge_i32_e32 vcc, v181, v119
	v_cvt_pk_bf16_f32 v22, v12, v13
	s_nop 0
	v_cndmask_b32_e32 v14, 0, v14, vcc
	v_cmp_ge_i32_e32 vcc, v182, v119
	v_mov_b32_e32 v119, v169
	s_nop 0
	v_cndmask_b32_e32 v15, 0, v15, vcc
	v_cvt_pk_bf16_f32 v23, v14, v15
	s_nop 1
	v_mfma_f32_16x16x32_bf16 v[16:19], v[0:3], v[20:23], v[16:19]
	v_mfma_f32_16x16x32_bf16 v[12:15], v[4:7], v[20:23], v[24:27]
	v_mfma_f32_16x16x32_bf16 v[4:7], v[8:11], v[20:23], v[40:43]
	s_nop 5
	v_mul_f32_e64 v8, v18, v18
	v_mul_f32_e64 v9, v19, v19
	v_pk_mul_f32 v[10:11], v[16:17], v[16:17]
	v_mfma_f32_16x16x32_bf16 v[0:3], v[36:39], v[20:23], v[44:47]
	v_lshl_add_u64 v[20:21], v[122:123], 0, s[6:7]
	v_lshl_add_u64 v[22:23], v[20:21], 0, v[118:119]
	flat_load_dwordx2 v[24:25], v[22:23] offset:1536
	v_pk_mov_b32 v[20:21], v[10:11], v[8:9] op_sel:[1,0]
	v_mov_b32_e32 v11, v9
	v_pk_add_f32 v[8:9], v[20:21], v[10:11]
	v_pk_mul_f32 v[10:11], v[14:15], v[14:15]
	v_pk_mul_f32 v[20:21], v[12:13], v[12:13]
	v_mul_f32_e32 v28, v1, v1
	v_pk_mov_b32 v[26:27], v[20:21], v[10:11] op_sel:[1,0]
	v_mov_b32_e32 v21, v11
	v_pk_add_f32 v[10:11], v[26:27], v[20:21]
	v_mul_f32_e32 v26, v0, v0
	v_pk_add_f32 v[20:21], v[8:9], v[8:9] op_sel:[0,1] op_sel_hi:[1,0]
	v_mul_f32_e32 v29, v2, v2
	v_mov_b32_e32 v21, v26
	v_pk_add_f32 v[26:27], v[10:11], v[10:11] op_sel:[0,1] op_sel_hi:[1,0]
	global_load_dwordx4 v[8:11], v[104:105], off
	v_mov_b32_e32 v27, v28
	v_pk_add_f32 v[20:21], v[20:21], v[26:27]
	v_mul_f32_e32 v26, v5, v5
	v_pk_fma_f32 v[26:27], v[4:5], v[4:5], v[26:27] op_sel_hi:[1,1,0]
	v_mul_f32_e32 v28, v7, v7
	v_mul_f32_e32 v30, v3, v3
	v_mov_b32_e32 v27, v29
	v_pk_fma_f32 v[28:29], v[6:7], v[6:7], v[28:29] op_sel_hi:[1,1,0]
	v_mov_b32_e32 v38, v16
	v_mov_b32_e32 v29, v30
	v_pk_add_f32 v[26:27], v[26:27], v[28:29]
	v_mov_b32_e32 v39, v18
	v_pk_add_f32 v[20:21], v[20:21], v[26:27]
	v_mov_b32_e32 v18, v17
	v_add_f32_e32 v20, v20, v21
	ds_bpermute_b32 v21, v219, v20
	s_waitcnt lgkmcnt(0)
	v_add_f32_e32 v20, v20, v21
	ds_bpermute_b32 v21, v220, v20
	s_waitcnt lgkmcnt(0)
	v_add_f32_e32 v20, v20, v21
	v_fmamk_f32 v20, v20, 0x3c800000, v206
	v_mul_f32_e32 v21, 0x4f800000, v20
	v_cmp_gt_f32_e32 vcc, s57, v20
	s_waitcnt vmcnt(0)
	v_lshlrev_b32_e32 v33, 16, v25
	v_cndmask_b32_e32 v20, v20, v21, vcc
	v_sqrt_f32_e32 v21, v20
	v_lshlrev_b32_e32 v32, 16, v24
	v_and_b32_e32 v24, 0xffff0000, v24
	v_mul_f32_e32 v16, 0xbfb8aa3b, v33
	v_add_u32_e32 v26, -1, v21
	v_fma_f32 v27, -v26, v21, v20
	v_cmp_ge_f32_e64 s[4:5], 0, v27
	v_add_u32_e32 v27, 1, v21
	v_mul_f32_e32 v34, 0xbfb8aa3b, v24
	v_cndmask_b32_e64 v26, v21, v26, s[4:5]
	v_fma_f32 v21, -v27, v21, v20
	v_cmp_lt_f32_e64 s[4:5], 0, v21
	v_exp_f32_e32 v16, v16
	v_exp_f32_e32 v35, v34
	v_cndmask_b32_e64 v21, v26, v27, s[4:5]
	v_mul_f32_e32 v26, 0x37800000, v21
	v_cndmask_b32_e32 v21, v21, v26, vcc
	v_cmp_class_f32_e32 vcc, v20, v207
	v_and_b32_e32 v25, 0xffff0000, v25
	v_mov_b32_e32 v40, v8
	v_cndmask_b32_e32 v20, v21, v20, vcc
	v_div_scale_f32 v21, s[4:5], v20, v20, 1.0
	v_rcp_f32_e32 v28, v21
	v_add_f32_e32 v8, 1.0, v16
	v_mov_b32_e32 v41, v10
	v_mov_b32_e32 v10, v9
	v_fma_f32 v29, -v21, v28, 1.0
	v_fmac_f32_e32 v28, v29, v28
	v_div_scale_f32 v29, vcc, 1.0, v20, 1.0
	v_mul_f32_e32 v30, v29, v28
	v_fma_f32 v31, -v21, v30, v29
	v_fmac_f32_e32 v30, v31, v28
	v_fma_f32 v21, -v21, v30, v29
	v_div_fmas_f32 v21, v21, v28, v30
	v_div_fixup_f32 v20, v21, v20, 1.0
	v_mul_f32_e32 v21, 0xbfb8aa3b, v32
	v_exp_f32_e32 v21, v21
	flat_load_dwordx2 v[28:29], v[22:23] offset:1568
	flat_load_dwordx2 v[30:31], v[22:23] offset:1600
	s_nop 0
	flat_load_dwordx2 v[22:23], v[22:23] offset:1632
	v_lshlrev_b64 v[26:27], 11, v[120:121]
	v_add_f32_e32 v21, 1.0, v21
	v_rcp_f32_e32 v34, v21
	v_add_f32_e32 v21, 1.0, v35
	v_rcp_f32_e32 v35, v8
	v_mul_f32_e32 v8, 0xbfb8aa3b, v25
	v_exp_f32_e32 v8, v8
	v_rcp_f32_e32 v36, v21
	v_pk_mul_f32 v[16:17], v[18:19], v[20:21] op_sel_hi:[1,0]
	v_pk_mul_f32 v[38:39], v[38:39], v[20:21] op_sel_hi:[1,0]
	v_add_f32_e32 v8, 1.0, v8
	v_rcp_f32_e32 v37, v8
	v_pk_mul_f32 v[8:9], v[10:11], v[16:17]
	v_pk_mul_f32 v[38:39], v[40:41], v[38:39]
	v_pk_mul_f32 v[32:33], v[34:35], v[32:33]
	v_pk_mul_f32 v[10:11], v[36:37], v[24:25]
	v_pk_mul_f32 v[32:33], v[38:39], v[32:33]
	v_pk_mul_f32 v[8:9], v[8:9], v[10:11]
	v_and_b32_sdwa v10, v33, v209 dst_sel:DWORD dst_unused:UNUSED_PAD src0_sel:WORD_1 src1_sel:DWORD
	v_and_b32_sdwa v16, v9, v209 dst_sel:DWORD dst_unused:UNUSED_PAD src0_sel:WORD_1 src1_sel:DWORD
	v_and_b32_sdwa v17, v8, v209 dst_sel:DWORD dst_unused:UNUSED_PAD src0_sel:WORD_1 src1_sel:DWORD
	v_and_b32_sdwa v11, v32, v209 dst_sel:DWORD dst_unused:UNUSED_PAD src0_sel:WORD_1 src1_sel:DWORD
	v_add3_u32 v9, v9, v16, s77
	v_add3_u32 v8, v8, v17, s77
	v_add3_u32 v11, v32, v11, s77
	v_add3_u32 v10, v33, v10, s77
	v_and_b32_e32 v9, 0xffff0000, v9
	v_and_b32_e32 v8, 0xffff0000, v8
	v_or_b32_sdwa v9, v9, v10 dst_sel:DWORD dst_unused:UNUSED_PAD src0_sel:DWORD src1_sel:WORD_1
	v_or_b32_sdwa v8, v8, v11 dst_sel:DWORD dst_unused:UNUSED_PAD src0_sel:DWORD src1_sel:WORD_1
	v_lshl_add_u64 v[16:17], v[108:109], 0, v[26:27]
	global_store_dwordx2 v[16:17], v[8:9], off
	global_load_dwordx4 v[8:11], v[104:105], off offset:64
	v_mov_b32_e32 v32, v12
	v_mov_b32_e32 v33, v14
	v_mov_b32_e32 v14, v13
	s_waitcnt vmcnt(0) lgkmcnt(0)
	v_lshlrev_b32_e32 v19, 16, v29
	v_lshlrev_b32_e32 v18, 16, v28
	v_mul_f32_e32 v21, 0xbfb8aa3b, v18
	v_and_b32_e32 v24, 0xffff0000, v28
	v_mul_f32_e32 v12, 0xbfb8aa3b, v19
	v_exp_f32_e32 v21, v21
	v_mul_f32_e32 v25, 0xbfb8aa3b, v24
	v_exp_f32_e32 v12, v12
	v_exp_f32_e32 v27, v25
	v_add_f32_e32 v21, 1.0, v21
	v_and_b32_e32 v25, 0xffff0000, v29
	v_rcp_f32_e32 v26, v21
	v_add_f32_e32 v21, 1.0, v27
	v_rcp_f32_e32 v28, v21
	v_pk_mul_f32 v[32:33], v[32:33], v[20:21] op_sel_hi:[1,0]
	v_mov_b32_e32 v34, v8
	v_add_f32_e32 v8, 1.0, v12
	v_rcp_f32_e32 v27, v8
	v_mul_f32_e32 v8, 0xbfb8aa3b, v25
	v_exp_f32_e32 v8, v8
	v_mov_b32_e32 v35, v10
	v_pk_mul_f32 v[12:13], v[14:15], v[20:21] op_sel_hi:[1,0]
	v_mov_b32_e32 v10, v9
	v_add_f32_e32 v8, 1.0, v8
	v_rcp_f32_e32 v29, v8
	v_pk_mul_f32 v[8:9], v[10:11], v[12:13]
	v_pk_mul_f32 v[32:33], v[34:35], v[32:33]
	v_pk_mul_f32 v[18:19], v[26:27], v[18:19]
	v_pk_mul_f32 v[10:11], v[28:29], v[24:25]
	v_pk_mul_f32 v[18:19], v[32:33], v[18:19]
	v_pk_mul_f32 v[8:9], v[8:9], v[10:11]
	v_and_b32_sdwa v10, v19, v209 dst_sel:DWORD dst_unused:UNUSED_PAD src0_sel:WORD_1 src1_sel:DWORD
	v_and_b32_sdwa v12, v9, v209 dst_sel:DWORD dst_unused:UNUSED_PAD src0_sel:WORD_1 src1_sel:DWORD
	v_and_b32_sdwa v13, v8, v209 dst_sel:DWORD dst_unused:UNUSED_PAD src0_sel:WORD_1 src1_sel:DWORD
	v_and_b32_sdwa v11, v18, v209 dst_sel:DWORD dst_unused:UNUSED_PAD src0_sel:WORD_1 src1_sel:DWORD
	v_add3_u32 v9, v9, v12, s77
	v_add3_u32 v8, v8, v13, s77
	v_add3_u32 v11, v18, v11, s77
	v_add3_u32 v10, v19, v10, s77
	v_and_b32_e32 v9, 0xffff0000, v9
	v_and_b32_e32 v8, 0xffff0000, v8
	v_or_b32_sdwa v9, v9, v10 dst_sel:DWORD dst_unused:UNUSED_PAD src0_sel:DWORD src1_sel:WORD_1
	v_or_b32_sdwa v8, v8, v11 dst_sel:DWORD dst_unused:UNUSED_PAD src0_sel:DWORD src1_sel:WORD_1
	global_store_dwordx2 v[16:17], v[8:9], off offset:32
	global_load_dwordx4 v[8:11], v[104:105], off offset:128
	v_lshlrev_b32_e32 v14, 16, v30
	v_and_b32_e32 v18, 0xffff0000, v30
	v_mov_b32_e32 v12, v4
	v_mov_b32_e32 v13, v6
	v_mul_f32_e32 v4, 0xbfb8aa3b, v14
	v_mul_f32_e32 v6, 0xbfb8aa3b, v18
	v_exp_f32_e32 v4, v4
	v_exp_f32_e32 v6, v6
	v_lshlrev_b32_e32 v15, 16, v31
	v_mul_f32_e32 v19, 0xbfb8aa3b, v15
	v_pk_mul_f32 v[12:13], v[12:13], v[20:21] op_sel_hi:[1,0]
	v_exp_f32_e32 v21, v19
	v_and_b32_e32 v19, 0xffff0000, v31
	v_add_f32_e32 v4, 1.0, v4
	v_add_f32_e32 v6, 1.0, v6
	v_rcp_f32_e32 v24, v4
	v_rcp_f32_e32 v4, v6
	v_mul_f32_e32 v6, 0xbfb8aa3b, v19
	v_add_f32_e32 v21, 1.0, v21
	v_rcp_f32_e32 v25, v21
	s_waitcnt vmcnt(0)
	v_mov_b32_e32 v26, v8
	v_exp_f32_e32 v8, v6
	v_mov_b32_e32 v6, v5
	v_mov_b32_e32 v27, v10
	v_pk_mul_f32 v[6:7], v[6:7], v[20:21] op_sel_hi:[1,0]
	v_add_f32_e32 v5, 1.0, v8
	v_rcp_f32_e32 v5, v5
	v_mov_b32_e32 v10, v9
	v_pk_mul_f32 v[6:7], v[10:11], v[6:7]
	v_pk_mul_f32 v[12:13], v[26:27], v[12:13]
	v_pk_mul_f32 v[4:5], v[4:5], v[18:19]
	v_pk_mul_f32 v[14:15], v[24:25], v[14:15]
	v_pk_mul_f32 v[4:5], v[6:7], v[4:5]
	v_pk_mul_f32 v[12:13], v[12:13], v[14:15]
	v_and_b32_sdwa v8, v5, v209 dst_sel:DWORD dst_unused:UNUSED_PAD src0_sel:WORD_1 src1_sel:DWORD
	v_and_b32_sdwa v9, v4, v209 dst_sel:DWORD dst_unused:UNUSED_PAD src0_sel:WORD_1 src1_sel:DWORD
	v_and_b32_sdwa v6, v13, v209 dst_sel:DWORD dst_unused:UNUSED_PAD src0_sel:WORD_1 src1_sel:DWORD
	v_and_b32_sdwa v7, v12, v209 dst_sel:DWORD dst_unused:UNUSED_PAD src0_sel:WORD_1 src1_sel:DWORD
	v_add3_u32 v5, v5, v8, s77
	v_add3_u32 v4, v4, v9, s77
	v_add3_u32 v7, v12, v7, s77
	v_add3_u32 v6, v13, v6, s77
	v_and_b32_e32 v5, 0xffff0000, v5
	v_and_b32_e32 v4, 0xffff0000, v4
	v_or_b32_sdwa v5, v5, v6 dst_sel:DWORD dst_unused:UNUSED_PAD src0_sel:DWORD src1_sel:WORD_1
	v_or_b32_sdwa v4, v4, v7 dst_sel:DWORD dst_unused:UNUSED_PAD src0_sel:DWORD src1_sel:WORD_1
	global_store_dwordx2 v[16:17], v[4:5], off offset:64
	global_load_dwordx4 v[4:7], v[104:105], off offset:192
	v_mov_b32_e32 v8, v0
	v_mov_b32_e32 v9, v2
	v_mov_b32_e32 v2, v1
	v_lshlrev_b32_e32 v1, 16, v23
	v_lshlrev_b32_e32 v0, 16, v22
	v_and_b32_e32 v10, 0xffff0000, v22
	v_and_b32_e32 v11, 0xffff0000, v23
	v_mul_f32_e32 v12, 0xbfb8aa3b, v0
	v_mul_f32_e32 v13, 0xbfb8aa3b, v10
	v_mul_f32_e32 v14, 0xbfb8aa3b, v1
	v_mul_f32_e32 v15, 0xbfb8aa3b, v11
	v_exp_f32_e32 v12, v12
	v_exp_f32_e32 v13, v13
	v_exp_f32_e32 v14, v14
	v_exp_f32_e32 v15, v15
	v_add_f32_e32 v12, 1.0, v12
	v_add_f32_e32 v13, 1.0, v13
	v_add_f32_e32 v18, 1.0, v14
	v_add_f32_e32 v15, 1.0, v15
	v_rcp_f32_e32 v12, v12
	v_rcp_f32_e32 v14, v13
	v_rcp_f32_e32 v13, v18
	v_rcp_f32_e32 v15, v15
	v_pk_mul_f32 v[2:3], v[2:3], v[20:21] op_sel_hi:[1,0]
	v_pk_mul_f32 v[8:9], v[8:9], v[20:21] op_sel_hi:[1,0]
	v_pk_mul_f32 v[0:1], v[12:13], v[0:1]
	v_pk_mul_f32 v[10:11], v[14:15], v[10:11]
	s_waitcnt vmcnt(0)
	v_mov_b32_e32 v13, v6
	v_mov_b32_e32 v6, v5
	v_mov_b32_e32 v12, v4
	v_pk_mul_f32 v[2:3], v[2:3], v[6:7]
	v_pk_mul_f32 v[4:5], v[8:9], v[12:13]
	v_pk_mul_f32 v[2:3], v[2:3], v[10:11]
	v_pk_mul_f32 v[0:1], v[4:5], v[0:1]
	v_and_b32_sdwa v6, v3, v209 dst_sel:DWORD dst_unused:UNUSED_PAD src0_sel:WORD_1 src1_sel:DWORD
	v_and_b32_sdwa v7, v2, v209 dst_sel:DWORD dst_unused:UNUSED_PAD src0_sel:WORD_1 src1_sel:DWORD
	v_and_b32_sdwa v4, v1, v209 dst_sel:DWORD dst_unused:UNUSED_PAD src0_sel:WORD_1 src1_sel:DWORD
	v_and_b32_sdwa v5, v0, v209 dst_sel:DWORD dst_unused:UNUSED_PAD src0_sel:WORD_1 src1_sel:DWORD
	v_add3_u32 v3, v3, v6, s77
	v_add3_u32 v2, v2, v7, s77
	v_add3_u32 v0, v0, v5, s77
	v_add3_u32 v1, v1, v4, s77
	v_and_b32_e32 v3, 0xffff0000, v3
	v_and_b32_e32 v2, 0xffff0000, v2
	v_or_b32_sdwa v1, v3, v1 dst_sel:DWORD dst_unused:UNUSED_PAD src0_sel:DWORD src1_sel:WORD_1
	v_or_b32_sdwa v0, v2, v0 dst_sel:DWORD dst_unused:UNUSED_PAD src0_sel:DWORD src1_sel:WORD_1
	global_store_dwordx2 v[16:17], v[0:1], off offset:96
	s_waitcnt lgkmcnt(0)
	s_barrier
	s_cbranch_scc0 .LBB0_495

.LBB0_500:
	s_and_b32 s10, s8, 0x100
	s_bitset1_b32 s10, 14
	s_mul_i32 s2, s10, 0x1400
	s_add_u32 s2, s78, s2
	s_addc_u32 s3, s79, 0
	s_and_b32 s4, s8, 0xf0
	s_lshl_b32 s82, s4, 1
	s_add_u32 s2, s2, s82
	s_addc_u32 s3, s3, 0
	v_lshl_add_u64 v[0:1], s[2:3], 0, v[16:17]
	v_lshlrev_b32_e32 v168, 1, v12
	v_lshl_add_u64 v[66:67], v[0:1], 0, v[168:169]
	v_add_co_u32_e32 v68, vcc, s33, v66
	s_add_u32 s4, s2, 0x800
	s_nop 0
	v_addc_co_u32_e32 v69, vcc, 0, v67, vcc
	v_add_co_u32_e32 v70, vcc, s14, v66
	s_addc_u32 s5, s3, 0
	s_nop 0
	v_addc_co_u32_e32 v71, vcc, 0, v67, vcc
	v_add_co_u32_e32 v72, vcc, s12, v66
	v_lshl_add_u64 v[0:1], s[4:5], 0, v[18:19]
	s_nop 0
	v_addc_co_u32_e32 v73, vcc, 0, v67, vcc
	v_add_co_u32_e32 v74, vcc, s19, v66
	v_lshl_add_u64 v[0:1], v[0:1], 0, v[168:169]
	s_nop 0
	v_addc_co_u32_e32 v75, vcc, 0, v67, vcc
	v_add_co_u32_e32 v76, vcc, s15, v66
	flat_load_ushort v10, v[70:71]
	s_nop 0
	v_addc_co_u32_e32 v77, vcc, 0, v67, vcc
	v_add_co_u32_e32 v78, vcc, s16, v66
	s_and_b32 s11, s7, 0xe0
	s_nop 0
	v_addc_co_u32_e32 v79, vcc, 0, v67, vcc
	v_add_co_u32_e32 v80, vcc, s20, v66
	v_or_b32_e32 v4, s11, v12
	s_nop 0
	v_addc_co_u32_e32 v81, vcc, 0, v67, vcc
	v_add_co_u32_e32 v2, vcc, s33, v0
	v_lshlrev_b32_e32 v82, 10, v4
	s_nop 0
	v_addc_co_u32_e32 v3, vcc, 0, v1, vcc
	flat_load_ushort v93, v[2:3] offset:1024
	v_add_co_u32_e32 v2, vcc, s13, v0
	v_or_b32_e32 v64, 0x4000, v82
	s_nop 0
	v_addc_co_u32_e32 v3, vcc, 0, v1, vcc
	flat_load_ushort v97, v[2:3] offset:2048
	v_add_co_u32_e32 v2, vcc, s14, v0
	v_mov_b32_e32 v65, v169
	s_nop 0
	v_addc_co_u32_e32 v3, vcc, 0, v1, vcc
	flat_load_ushort v101, v[2:3] offset:3072
	v_add_co_u32_e32 v2, vcc, s19, v0
	v_lshl_add_u64 v[4:5], v[14:15], 0, v[64:65]
	s_nop 0
	v_addc_co_u32_e32 v3, vcc, 0, v1, vcc
	flat_load_ushort v90, v[0:1]
	flat_load_ushort v104, v[2:3]
	flat_load_ushort v11, v[72:73] offset:1024
	flat_load_ushort v110, v[74:75] offset:2048
	flat_load_ushort v8, v[66:67] offset:2048
	flat_load_ushort v111, v[76:77] offset:3072
	flat_load_ushort v112, v[78:79]
	flat_load_ushort v9, v[68:69] offset:3072
	flat_load_ushort v113, v[80:81] offset:1024
	v_mov_b32_e32 v83, v169
	flat_load_dwordx4 v[4:7], v[4:5]
	v_add_co_u32_e32 v2, vcc, s15, v0
	v_lshl_add_u64 v[84:85], v[14:15], 0, v[82:83]
	s_nop 0
	v_addc_co_u32_e32 v3, vcc, 0, v1, vcc
	flat_load_ushort v107, v[2:3] offset:1024
	v_add_co_u32_e32 v2, vcc, s21, v0
	s_waitcnt vmcnt(0) lgkmcnt(0)
	v_perm_b32 v119, v101, v97, s89
	v_addc_co_u32_e32 v3, vcc, 0, v1, vcc
	v_add_co_u32_e32 v0, vcc, s16, v0
	flat_load_ushort v108, v[2:3] offset:2048
	s_nop 0
	v_addc_co_u32_e32 v1, vcc, 0, v1, vcc
	flat_load_ushort v109, v[0:1] offset:3072
	v_lshl_add_u64 v[0:1], s[4:5], 0, v[20:21]
	v_lshl_add_u64 v[0:1], v[0:1], 0, v[168:169]
	v_add_co_u32_e32 v2, vcc, s33, v0
	flat_load_ushort v94, v[0:1]
	s_nop 0
	v_addc_co_u32_e32 v3, vcc, 0, v1, vcc
	flat_load_ushort v96, v[2:3] offset:1024
	v_add_co_u32_e32 v2, vcc, s13, v0
	v_perm_b32 v118, v93, v90, s89
	s_nop 0
	v_addc_co_u32_e32 v3, vcc, 0, v1, vcc
	flat_load_ushort v99, v[2:3] offset:2048
	v_add_co_u32_e32 v2, vcc, s14, v0
	v_perm_b32 v120, v107, v104, s89
	s_nop 0
	v_addc_co_u32_e32 v3, vcc, 0, v1, vcc
	flat_load_ushort v100, v[2:3] offset:3072
	v_add_co_u32_e32 v2, vcc, s19, v0
	s_waitcnt vmcnt(0) lgkmcnt(0)
	v_perm_b32 v121, v109, v108, s89
	v_addc_co_u32_e32 v3, vcc, 0, v1, vcc
	flat_load_ushort v102, v[2:3]
	v_add_co_u32_e32 v2, vcc, s15, v0
	s_nop 1
	v_addc_co_u32_e32 v3, vcc, 0, v1, vcc
	flat_load_ushort v103, v[2:3] offset:1024
	v_add_co_u32_e32 v2, vcc, s21, v0
	s_nop 1
	v_addc_co_u32_e32 v3, vcc, 0, v1, vcc
	v_add_co_u32_e32 v0, vcc, s16, v0
	flat_load_ushort v105, v[2:3] offset:2048
	s_nop 0
	v_addc_co_u32_e32 v1, vcc, 0, v1, vcc
	flat_load_ushort v106, v[0:1] offset:3072
	v_lshl_add_u64 v[0:1], s[4:5], 0, v[22:23]
	v_lshl_add_u64 v[0:1], v[0:1], 0, v[168:169]
	v_add_co_u32_e32 v2, vcc, s33, v0
	flat_load_ushort v86, v[0:1]
	s_nop 0
	v_addc_co_u32_e32 v3, vcc, 0, v1, vcc
	flat_load_ushort v87, v[2:3] offset:1024
	v_add_co_u32_e32 v2, vcc, s13, v0
	s_nop 1
	v_addc_co_u32_e32 v3, vcc, 0, v1, vcc
	flat_load_ushort v88, v[2:3] offset:2048
	v_add_co_u32_e32 v2, vcc, s14, v0
	s_nop 1
	v_addc_co_u32_e32 v3, vcc, 0, v1, vcc
	flat_load_ushort v89, v[2:3] offset:3072
	v_add_co_u32_e32 v2, vcc, s19, v0
	s_nop 1
	v_addc_co_u32_e32 v3, vcc, 0, v1, vcc
	flat_load_ushort v91, v[2:3]
	v_add_co_u32_e32 v2, vcc, s15, v0
	s_nop 1
	v_addc_co_u32_e32 v3, vcc, 0, v1, vcc
	flat_load_ushort v92, v[2:3] offset:1024
	v_add_co_u32_e32 v2, vcc, s21, v0
	v_perm_b32 v113, v113, v112, s89
	s_nop 0
	v_addc_co_u32_e32 v3, vcc, 0, v1, vcc
	v_add_co_u32_e32 v0, vcc, s16, v0
	flat_load_ushort v95, v[2:3] offset:2048
	s_nop 0
	v_addc_co_u32_e32 v1, vcc, 0, v1, vcc
	flat_load_ushort v98, v[0:1] offset:3072
	v_perm_b32 v112, v111, v110, s89
	flat_load_dwordx4 v[0:3], v[84:85]
	v_perm_b32 v111, v11, v10, s89
	v_perm_b32 v110, v9, v8, s89
	s_waitcnt vmcnt(0) lgkmcnt(0)
	s_nop 0
	v_mfma_f32_16x16x32_bf16 v[8:11], v[0:3], v[110:113], 0
	v_mfma_f32_16x16x32_bf16 v[0:3], v[4:7], v[110:113], 0
	v_lshl_add_u64 v[4:5], v[24:25], 0, v[64:65]
	flat_load_dwordx4 v[4:7], v[4:5]
	s_nop 0
	flat_load_dwordx4 v[110:113], v[84:85] offset:64
	s_waitcnt vmcnt(0) lgkmcnt(0)
	v_mfma_f32_16x16x32_bf16 v[8:11], v[110:113], v[118:121], v[8:11]
	v_mfma_f32_16x16x32_bf16 v[0:3], v[4:7], v[118:121], v[0:3]
	v_lshl_add_u64 v[108:109], v[26:27], 0, v[64:65]
	flat_load_dwordx4 v[4:7], v[84:85] offset:128
	v_perm_b32 v105, v106, v105, s89
	flat_load_dwordx4 v[108:111], v[108:109]
	v_perm_b32 v104, v103, v102, s89
	v_perm_b32 v103, v100, v99, s89
	v_perm_b32 v102, v96, v94, s89
	v_perm_b32 v93, v98, v95, s89
	v_perm_b32 v92, v92, v91, s89
	v_perm_b32 v91, v89, v88, s89
	v_perm_b32 v90, v87, v86, s89
	s_waitcnt vmcnt(0) lgkmcnt(0)
	v_mfma_f32_16x16x32_bf16 v[4:7], v[4:7], v[102:105], v[8:11]
	v_mfma_f32_16x16x32_bf16 v[8:11], v[108:111], v[102:105], v[0:3]
	s_nop 2
	v_lshl_add_u64 v[0:1], v[28:29], 0, v[64:65]
	flat_load_dwordx4 v[100:103], v[0:1]
	s_nop 0
	flat_load_dwordx4 v[0:3], v[84:85] offset:192
	s_waitcnt vmcnt(0) lgkmcnt(0)
	v_mfma_f32_16x16x32_bf16 v[0:3], v[0:3], v[90:93], v[4:7]
	v_mfma_f32_16x16x32_bf16 v[4:7], v[100:103], v[90:93], v[8:11]
	s_nop 2
	v_lshl_add_u64 v[8:9], s[4:5], 0, v[30:31]
	v_lshl_add_u64 v[8:9], v[8:9], 0, v[168:169]
	v_add_co_u32_e32 v10, vcc, s33, v8
	flat_load_ushort v114, v[8:9]
	s_nop 0
	v_addc_co_u32_e32 v11, vcc, 0, v9, vcc
	flat_load_ushort v115, v[10:11] offset:1024
	v_add_co_u32_e32 v10, vcc, s13, v8
	v_lshl_add_u64 v[110:111], v[38:39], 0, v[64:65]
	s_nop 0
	v_addc_co_u32_e32 v11, vcc, 0, v9, vcc
	flat_load_ushort v116, v[10:11] offset:2048
	v_add_co_u32_e32 v10, vcc, s14, v8
	s_nop 1
	v_addc_co_u32_e32 v11, vcc, 0, v9, vcc
	flat_load_ushort v118, v[10:11] offset:3072
	v_add_co_u32_e32 v10, vcc, s19, v8
	s_nop 1
	v_addc_co_u32_e32 v11, vcc, 0, v9, vcc
	flat_load_ushort v119, v[10:11]
	v_add_co_u32_e32 v10, vcc, s15, v8
	s_nop 1
	v_addc_co_u32_e32 v11, vcc, 0, v9, vcc
	flat_load_ushort v120, v[10:11] offset:1024
	v_add_co_u32_e32 v10, vcc, s21, v8
	s_waitcnt vmcnt(0) lgkmcnt(0)
	v_perm_b32 v120, v120, v119, s89
	v_addc_co_u32_e32 v11, vcc, 0, v9, vcc
	v_add_co_u32_e32 v8, vcc, s16, v8
	flat_load_ushort v121, v[10:11] offset:2048
	s_nop 0
	v_addc_co_u32_e32 v9, vcc, 0, v9, vcc
	flat_load_ushort v122, v[8:9] offset:3072
	v_lshl_add_u64 v[8:9], s[4:5], 0, v[32:33]
	v_lshl_add_u64 v[8:9], v[8:9], 0, v[168:169]
	v_add_co_u32_e32 v10, vcc, s33, v8
	flat_load_ushort v90, v[8:9]
	s_nop 0
	v_addc_co_u32_e32 v11, vcc, 0, v9, vcc
	flat_load_ushort v93, v[10:11] offset:1024
	v_add_co_u32_e32 v10, vcc, s13, v8
	v_perm_b32 v119, v118, v116, s89
	s_nop 0
	v_addc_co_u32_e32 v11, vcc, 0, v9, vcc
	flat_load_ushort v97, v[10:11] offset:2048
	v_add_co_u32_e32 v10, vcc, s14, v8
	v_perm_b32 v118, v115, v114, s89
	s_nop 0
	v_addc_co_u32_e32 v11, vcc, 0, v9, vcc
	flat_load_ushort v101, v[10:11] offset:3072
	v_add_co_u32_e32 v10, vcc, s19, v8
	s_waitcnt vmcnt(0) lgkmcnt(0)
	v_perm_b32 v121, v122, v121, s89
	v_addc_co_u32_e32 v11, vcc, 0, v9, vcc
	flat_load_ushort v104, v[10:11]
	v_add_co_u32_e32 v10, vcc, s15, v8
	s_nop 1
	v_addc_co_u32_e32 v11, vcc, 0, v9, vcc
	flat_load_ushort v107, v[10:11] offset:1024
	v_add_co_u32_e32 v10, vcc, s21, v8
	s_nop 1
	v_addc_co_u32_e32 v11, vcc, 0, v9, vcc
	v_add_co_u32_e32 v8, vcc, s16, v8
	flat_load_ushort v108, v[10:11] offset:2048
	s_nop 0
	v_addc_co_u32_e32 v9, vcc, 0, v9, vcc
	flat_load_ushort v109, v[8:9] offset:3072
	v_lshl_add_u64 v[8:9], s[4:5], 0, v[34:35]
	v_lshl_add_u64 v[8:9], v[8:9], 0, v[168:169]
	v_add_co_u32_e32 v10, vcc, s33, v8
	flat_load_ushort v94, v[8:9]
	s_nop 0
	v_addc_co_u32_e32 v11, vcc, 0, v9, vcc
	flat_load_ushort v96, v[10:11] offset:1024
	v_add_co_u32_e32 v10, vcc, s13, v8
	s_nop 1
	v_addc_co_u32_e32 v11, vcc, 0, v9, vcc
	flat_load_ushort v99, v[10:11] offset:2048
	v_add_co_u32_e32 v10, vcc, s14, v8
	s_nop 1
	v_addc_co_u32_e32 v11, vcc, 0, v9, vcc
	flat_load_ushort v100, v[10:11] offset:3072
	v_add_co_u32_e32 v10, vcc, s19, v8
	s_nop 1
	v_addc_co_u32_e32 v11, vcc, 0, v9, vcc
	flat_load_ushort v102, v[10:11]
	v_add_co_u32_e32 v10, vcc, s15, v8
	s_nop 1
	v_addc_co_u32_e32 v11, vcc, 0, v9, vcc
	flat_load_ushort v103, v[10:11] offset:1024
	v_add_co_u32_e32 v10, vcc, s21, v8
	s_nop 1
	v_addc_co_u32_e32 v11, vcc, 0, v9, vcc
	v_add_co_u32_e32 v8, vcc, s16, v8
	flat_load_ushort v105, v[10:11] offset:2048
	s_nop 0
	v_addc_co_u32_e32 v9, vcc, 0, v9, vcc
	flat_load_ushort v106, v[8:9] offset:3072
	v_lshl_add_u64 v[8:9], s[4:5], 0, v[36:37]
	v_lshl_add_u64 v[8:9], v[8:9], 0, v[168:169]
	v_add_co_u32_e32 v10, vcc, s33, v8
	flat_load_ushort v86, v[8:9]
	s_nop 0
	v_addc_co_u32_e32 v11, vcc, 0, v9, vcc
	flat_load_ushort v87, v[10:11] offset:1024
	v_add_co_u32_e32 v10, vcc, s13, v8
	s_nop 1
	v_addc_co_u32_e32 v11, vcc, 0, v9, vcc
	flat_load_ushort v88, v[10:11] offset:2048
	v_add_co_u32_e32 v10, vcc, s14, v8
	s_nop 1
	v_addc_co_u32_e32 v11, vcc, 0, v9, vcc
	flat_load_ushort v89, v[10:11] offset:3072
	v_add_co_u32_e32 v10, vcc, s19, v8
	s_nop 1
	v_addc_co_u32_e32 v11, vcc, 0, v9, vcc
	flat_load_ushort v91, v[10:11]
	v_add_co_u32_e32 v10, vcc, s15, v8
	s_nop 1
	v_addc_co_u32_e32 v11, vcc, 0, v9, vcc
	flat_load_ushort v92, v[10:11] offset:1024
	v_add_co_u32_e32 v10, vcc, s21, v8
	s_nop 1
	v_addc_co_u32_e32 v11, vcc, 0, v9, vcc
	v_add_co_u32_e32 v8, vcc, s16, v8
	flat_load_ushort v95, v[10:11] offset:2048
	s_nop 0
	v_addc_co_u32_e32 v9, vcc, 0, v9, vcc
	flat_load_ushort v98, v[8:9] offset:3072
	s_nop 0
	flat_load_dwordx4 v[8:11], v[84:85] offset:256
	s_waitcnt vmcnt(0) lgkmcnt(0)
	v_mfma_f32_16x16x32_bf16 v[8:11], v[8:11], v[118:121], v[0:3]
	flat_load_dwordx4 v[110:113], v[110:111]
	s_waitcnt vmcnt(0) lgkmcnt(0)
	v_mfma_f32_16x16x32_bf16 v[0:3], v[110:113], v[118:121], v[4:7]
	s_nop 2
	v_lshl_add_u64 v[4:5], v[40:41], 0, v[64:65]
	flat_load_dwordx4 v[4:7], v[4:5]
	s_nop 0
	flat_load_dwordx4 v[110:113], v[84:85] offset:320
	v_perm_b32 v121, v109, v108, s89
	v_perm_b32 v120, v107, v104, s89
	v_perm_b32 v119, v101, v97, s89
	v_perm_b32 v118, v93, v90, s89
	s_waitcnt vmcnt(0) lgkmcnt(0)
	s_nop 0
	v_mfma_f32_16x16x32_bf16 v[8:11], v[110:113], v[118:121], v[8:11]
	v_mfma_f32_16x16x32_bf16 v[0:3], v[4:7], v[118:121], v[0:3]
	v_lshl_add_u64 v[108:109], v[42:43], 0, v[64:65]
	flat_load_dwordx4 v[4:7], v[84:85] offset:384
	v_perm_b32 v105, v106, v105, s89
	flat_load_dwordx4 v[108:111], v[108:109]
	v_perm_b32 v104, v103, v102, s89
	v_perm_b32 v103, v100, v99, s89
	v_perm_b32 v102, v96, v94, s89
	v_perm_b32 v93, v98, v95, s89
	v_perm_b32 v92, v92, v91, s89
	v_perm_b32 v91, v89, v88, s89
	v_perm_b32 v90, v87, v86, s89
	s_waitcnt vmcnt(0) lgkmcnt(0)
	v_mfma_f32_16x16x32_bf16 v[4:7], v[4:7], v[102:105], v[8:11]
	v_mfma_f32_16x16x32_bf16 v[8:11], v[108:111], v[102:105], v[0:3]
	s_nop 2
	v_lshl_add_u64 v[0:1], v[44:45], 0, v[64:65]
	flat_load_dwordx4 v[100:103], v[0:1]
	s_nop 0
	flat_load_dwordx4 v[0:3], v[84:85] offset:448
	s_waitcnt vmcnt(0) lgkmcnt(0)
	v_mfma_f32_16x16x32_bf16 v[0:3], v[0:3], v[90:93], v[4:7]
	v_mfma_f32_16x16x32_bf16 v[4:7], v[100:103], v[90:93], v[8:11]
	s_add_u32 s2, s2, 0xa00
	s_addc_u32 s3, s3, 0
	s_nop 0
	v_lshl_add_u64 v[8:9], s[2:3], 0, v[18:19]
	v_lshl_add_u64 v[8:9], v[8:9], 0, v[168:169]
	v_add_co_u32_e32 v10, vcc, s33, v8
	flat_load_ushort v98, v[66:67] offset:2560
	flat_load_ushort v102, v[68:69] offset:3584
	flat_load_ushort v99, v[70:71] offset:512
	flat_load_ushort v103, v[72:73] offset:1536
	flat_load_ushort v100, v[74:75] offset:2560
	flat_load_ushort v104, v[76:77] offset:3584
	flat_load_ushort v101, v[78:79] offset:512
	flat_load_ushort v105, v[80:81] offset:1536
	v_addc_co_u32_e32 v11, vcc, 0, v9, vcc
	flat_load_ushort v75, v[10:11] offset:1024
	v_add_co_u32_e32 v10, vcc, s13, v8
	v_lshl_add_u64 v[66:67], v[46:47], 0, v[82:83]
	s_nop 0
	v_addc_co_u32_e32 v11, vcc, 0, v9, vcc
	flat_load_ushort v79, v[10:11] offset:2048
	v_add_co_u32_e32 v10, vcc, s14, v8
	v_lshl_add_u64 v[82:83], v[46:47], 0, v[64:65]
	s_nop 0
	v_addc_co_u32_e32 v11, vcc, 0, v9, vcc
	flat_load_ushort v85, v[10:11] offset:3072
	v_add_co_u32_e32 v10, vcc, s19, v8
	flat_load_ushort v72, v[8:9]
	flat_load_dwordx4 v[94:97], v[82:83]
	v_addc_co_u32_e32 v11, vcc, 0, v9, vcc
	flat_load_ushort v88, v[10:11]
	v_add_co_u32_e32 v10, vcc, s15, v8
	s_waitcnt vmcnt(0) lgkmcnt(0)
	v_perm_b32 v98, v102, v98, s89
	v_addc_co_u32_e32 v11, vcc, 0, v9, vcc
	flat_load_ushort v91, v[10:11] offset:1024
	v_add_co_u32_e32 v10, vcc, s21, v8
	v_perm_b32 v101, v105, v101, s89
	s_nop 0
	v_addc_co_u32_e32 v11, vcc, 0, v9, vcc
	v_add_co_u32_e32 v8, vcc, s16, v8
	flat_load_ushort v92, v[10:11] offset:2048
	s_nop 0
	v_addc_co_u32_e32 v9, vcc, 0, v9, vcc
	flat_load_ushort v93, v[8:9] offset:3072
	v_lshl_add_u64 v[8:9], s[2:3], 0, v[20:21]
	v_lshl_add_u64 v[8:9], v[8:9], 0, v[168:169]
	v_add_co_u32_e32 v10, vcc, s33, v8
	flat_load_ushort v76, v[8:9]
	s_nop 0
	v_addc_co_u32_e32 v11, vcc, 0, v9, vcc
	flat_load_ushort v78, v[10:11] offset:1024
	v_add_co_u32_e32 v10, vcc, s13, v8
	v_perm_b32 v100, v104, v100, s89
	s_nop 0
	v_addc_co_u32_e32 v11, vcc, 0, v9, vcc
	flat_load_ushort v81, v[10:11] offset:2048
	v_add_co_u32_e32 v10, vcc, s14, v8
	v_perm_b32 v99, v103, v99, s89
	s_nop 0
	v_addc_co_u32_e32 v11, vcc, 0, v9, vcc
	flat_load_ushort v84, v[10:11] offset:3072
	v_add_co_u32_e32 v10, vcc, s19, v8
	s_nop 1
	v_addc_co_u32_e32 v11, vcc, 0, v9, vcc
	flat_load_ushort v86, v[10:11]
	v_add_co_u32_e32 v10, vcc, s15, v8
	s_nop 1
	v_addc_co_u32_e32 v11, vcc, 0, v9, vcc
	flat_load_ushort v87, v[10:11] offset:1024
	v_add_co_u32_e32 v10, vcc, s21, v8
	s_nop 1
	v_addc_co_u32_e32 v11, vcc, 0, v9, vcc
	v_add_co_u32_e32 v8, vcc, s16, v8
	flat_load_ushort v89, v[10:11] offset:2048
	s_nop 0
	v_addc_co_u32_e32 v9, vcc, 0, v9, vcc
	flat_load_ushort v90, v[8:9] offset:3072
	v_lshl_add_u64 v[8:9], s[2:3], 0, v[22:23]
	v_lshl_add_u64 v[8:9], v[8:9], 0, v[168:169]
	v_add_co_u32_e32 v10, vcc, s33, v8
	flat_load_ushort v68, v[8:9]
	s_nop 0
	v_addc_co_u32_e32 v11, vcc, 0, v9, vcc
	flat_load_ushort v69, v[10:11] offset:1024
	v_add_co_u32_e32 v10, vcc, s13, v8
	s_nop 1
	v_addc_co_u32_e32 v11, vcc, 0, v9, vcc
	flat_load_ushort v70, v[10:11] offset:2048
	v_add_co_u32_e32 v10, vcc, s14, v8
	s_nop 1
	v_addc_co_u32_e32 v11, vcc, 0, v9, vcc
	flat_load_ushort v71, v[10:11] offset:3072
	v_add_co_u32_e32 v10, vcc, s19, v8
	s_nop 1
	v_addc_co_u32_e32 v11, vcc, 0, v9, vcc
	flat_load_ushort v73, v[10:11]
	v_add_co_u32_e32 v10, vcc, s15, v8
	s_nop 1
	v_addc_co_u32_e32 v11, vcc, 0, v9, vcc
	flat_load_ushort v74, v[10:11] offset:1024
	v_add_co_u32_e32 v10, vcc, s21, v8
	s_nop 1
	v_addc_co_u32_e32 v11, vcc, 0, v9, vcc
	v_add_co_u32_e32 v8, vcc, s16, v8
	flat_load_ushort v77, v[10:11] offset:2048
	s_nop 0
	v_addc_co_u32_e32 v9, vcc, 0, v9, vcc
	flat_load_ushort v80, v[8:9] offset:3072
	s_nop 0
	flat_load_dwordx4 v[8:11], v[66:67]
	s_waitcnt vmcnt(0) lgkmcnt(0)
	v_mfma_f32_16x16x32_bf16 v[8:11], v[8:11], v[98:101], v[0:3]
	v_mfma_f32_16x16x32_bf16 v[0:3], v[94:97], v[98:101], v[4:7]
	v_perm_b32 v101, v93, v92, s89
	v_perm_b32 v100, v91, v88, s89
	v_perm_b32 v99, v85, v79, s89
	v_lshl_add_u64 v[4:5], v[48:49], 0, v[64:65]
	flat_load_dwordx4 v[4:7], v[4:5]
	s_nop 0
	flat_load_dwordx4 v[94:97], v[66:67] offset:64
	v_perm_b32 v98, v75, v72, s89
	s_waitcnt vmcnt(0) lgkmcnt(0)
	s_nop 0
	v_mfma_f32_16x16x32_bf16 v[8:11], v[94:97], v[98:101], v[8:11]
	v_mfma_f32_16x16x32_bf16 v[0:3], v[4:7], v[98:101], v[0:3]
	v_lshl_add_u64 v[82:83], v[50:51], 0, v[64:65]
	flat_load_dwordx4 v[4:7], v[66:67] offset:128
	flat_load_dwordx4 v[92:95], v[82:83]
	v_perm_b32 v89, v90, v89, s89
	v_perm_b32 v88, v87, v86, s89
	v_perm_b32 v87, v84, v81, s89
	v_perm_b32 v86, v78, v76, s89
	v_perm_b32 v75, v80, v77, s89
	v_perm_b32 v74, v74, v73, s89
	v_perm_b32 v73, v71, v70, s89
	v_perm_b32 v72, v69, v68, s89
	s_waitcnt vmcnt(0) lgkmcnt(0)
	v_mfma_f32_16x16x32_bf16 v[4:7], v[4:7], v[86:89], v[8:11]
	v_mfma_f32_16x16x32_bf16 v[8:11], v[92:95], v[86:89], v[0:3]
	s_nop 2
	v_lshl_add_u64 v[0:1], v[52:53], 0, v[64:65]
	flat_load_dwordx4 v[82:85], v[0:1]
	s_nop 0
	flat_load_dwordx4 v[0:3], v[66:67] offset:192
	s_waitcnt vmcnt(0) lgkmcnt(0)
	v_mfma_f32_16x16x32_bf16 v[0:3], v[0:3], v[72:75], v[4:7]
	v_mfma_f32_16x16x32_bf16 v[4:7], v[82:85], v[72:75], v[8:11]
	s_nop 2
	v_lshl_add_u64 v[8:9], s[2:3], 0, v[30:31]
	v_lshl_add_u64 v[8:9], v[8:9], 0, v[168:169]
	v_add_co_u32_e32 v10, vcc, s33, v8
	flat_load_ushort v96, v[8:9]
	s_nop 0
	v_addc_co_u32_e32 v11, vcc, 0, v9, vcc
	flat_load_ushort v100, v[10:11] offset:1024
	v_add_co_u32_e32 v10, vcc, s13, v8
	v_lshl_add_u64 v[92:93], v[54:55], 0, v[64:65]
	s_nop 0
	v_addc_co_u32_e32 v11, vcc, 0, v9, vcc
	flat_load_ushort v97, v[10:11] offset:2048
	v_add_co_u32_e32 v10, vcc, s14, v8
	s_nop 1
	v_addc_co_u32_e32 v11, vcc, 0, v9, vcc
	flat_load_ushort v101, v[10:11] offset:3072
	v_add_co_u32_e32 v10, vcc, s19, v8
	s_waitcnt vmcnt(0) lgkmcnt(0)
	v_perm_b32 v97, v101, v97, s89
	v_addc_co_u32_e32 v11, vcc, 0, v9, vcc
	flat_load_ushort v98, v[10:11]
	v_add_co_u32_e32 v10, vcc, s15, v8
	v_perm_b32 v96, v100, v96, s89
	s_nop 0
	v_addc_co_u32_e32 v11, vcc, 0, v9, vcc
	flat_load_ushort v102, v[10:11] offset:1024
	v_add_co_u32_e32 v10, vcc, s21, v8
	s_waitcnt vmcnt(0) lgkmcnt(0)
	v_perm_b32 v98, v102, v98, s89
	v_addc_co_u32_e32 v11, vcc, 0, v9, vcc
	v_add_co_u32_e32 v8, vcc, s16, v8
	flat_load_ushort v99, v[10:11] offset:2048
	s_nop 0
	v_addc_co_u32_e32 v9, vcc, 0, v9, vcc
	flat_load_ushort v103, v[8:9] offset:3072
	v_lshl_add_u64 v[8:9], s[2:3], 0, v[32:33]
	v_lshl_add_u64 v[8:9], v[8:9], 0, v[168:169]
	v_add_co_u32_e32 v10, vcc, s33, v8
	flat_load_ushort v72, v[8:9]
	s_nop 0
	v_addc_co_u32_e32 v11, vcc, 0, v9, vcc
	flat_load_ushort v75, v[10:11] offset:1024
	v_add_co_u32_e32 v10, vcc, s13, v8
	s_waitcnt vmcnt(0) lgkmcnt(0)
	v_perm_b32 v99, v103, v99, s89
	v_addc_co_u32_e32 v11, vcc, 0, v9, vcc
	flat_load_ushort v79, v[10:11] offset:2048
	v_add_co_u32_e32 v10, vcc, s14, v8
	s_nop 1
	v_addc_co_u32_e32 v11, vcc, 0, v9, vcc
	flat_load_ushort v83, v[10:11] offset:3072
	v_add_co_u32_e32 v10, vcc, s19, v8
	s_nop 1
	v_addc_co_u32_e32 v11, vcc, 0, v9, vcc
	flat_load_ushort v86, v[10:11]
	v_add_co_u32_e32 v10, vcc, s15, v8
	s_nop 1
	v_addc_co_u32_e32 v11, vcc, 0, v9, vcc
	flat_load_ushort v89, v[10:11] offset:1024
	v_add_co_u32_e32 v10, vcc, s21, v8
	s_nop 1
	v_addc_co_u32_e32 v11, vcc, 0, v9, vcc
	v_add_co_u32_e32 v8, vcc, s16, v8
	flat_load_ushort v90, v[10:11] offset:2048
	s_nop 0
	v_addc_co_u32_e32 v9, vcc, 0, v9, vcc
	flat_load_ushort v91, v[8:9] offset:3072
	v_lshl_add_u64 v[8:9], s[2:3], 0, v[34:35]
	v_lshl_add_u64 v[8:9], v[8:9], 0, v[168:169]
	v_add_co_u32_e32 v10, vcc, s33, v8
	flat_load_ushort v76, v[8:9]
	s_nop 0
	v_addc_co_u32_e32 v11, vcc, 0, v9, vcc
	flat_load_ushort v78, v[10:11] offset:1024
	v_add_co_u32_e32 v10, vcc, s13, v8
	s_nop 1
	v_addc_co_u32_e32 v11, vcc, 0, v9, vcc
	flat_load_ushort v81, v[10:11] offset:2048
	v_add_co_u32_e32 v10, vcc, s14, v8
	s_nop 1
	v_addc_co_u32_e32 v11, vcc, 0, v9, vcc
	flat_load_ushort v82, v[10:11] offset:3072
	v_add_co_u32_e32 v10, vcc, s19, v8
	s_nop 1
	v_addc_co_u32_e32 v11, vcc, 0, v9, vcc
	flat_load_ushort v84, v[10:11]
	v_add_co_u32_e32 v10, vcc, s15, v8
	s_nop 1
	v_addc_co_u32_e32 v11, vcc, 0, v9, vcc
	flat_load_ushort v85, v[10:11] offset:1024
	v_add_co_u32_e32 v10, vcc, s21, v8
	s_nop 1
	v_addc_co_u32_e32 v11, vcc, 0, v9, vcc
	v_add_co_u32_e32 v8, vcc, s16, v8
	flat_load_ushort v87, v[10:11] offset:2048
	s_nop 0
	v_addc_co_u32_e32 v9, vcc, 0, v9, vcc
	flat_load_ushort v88, v[8:9] offset:3072
	v_lshl_add_u64 v[8:9], s[2:3], 0, v[36:37]
	v_lshl_add_u64 v[8:9], v[8:9], 0, v[168:169]
	v_add_co_u32_e32 v10, vcc, s33, v8
	flat_load_ushort v68, v[8:9]
	s_nop 0
	v_addc_co_u32_e32 v11, vcc, 0, v9, vcc
	flat_load_ushort v69, v[10:11] offset:1024
	v_add_co_u32_e32 v10, vcc, s13, v8
	s_nop 1
	v_addc_co_u32_e32 v11, vcc, 0, v9, vcc
	flat_load_ushort v70, v[10:11] offset:2048
	v_add_co_u32_e32 v10, vcc, s14, v8
	s_nop 1
	v_addc_co_u32_e32 v11, vcc, 0, v9, vcc
	flat_load_ushort v71, v[10:11] offset:3072
	v_add_co_u32_e32 v10, vcc, s19, v8
	s_nop 1
	v_addc_co_u32_e32 v11, vcc, 0, v9, vcc
	flat_load_ushort v73, v[10:11]
	v_add_co_u32_e32 v10, vcc, s15, v8
	s_nop 1
	v_addc_co_u32_e32 v11, vcc, 0, v9, vcc
	flat_load_ushort v74, v[10:11] offset:1024
	v_add_co_u32_e32 v10, vcc, s21, v8
	s_nop 1
	v_addc_co_u32_e32 v11, vcc, 0, v9, vcc
	v_add_co_u32_e32 v8, vcc, s16, v8
	flat_load_ushort v77, v[10:11] offset:2048
	s_nop 0
	v_addc_co_u32_e32 v9, vcc, 0, v9, vcc
	flat_load_ushort v80, v[8:9] offset:3072
	s_nop 0
	flat_load_dwordx4 v[8:11], v[66:67] offset:256
	s_waitcnt vmcnt(0) lgkmcnt(0)
	v_mfma_f32_16x16x32_bf16 v[8:11], v[8:11], v[96:99], v[0:3]
	flat_load_dwordx4 v[92:95], v[92:93]
	s_waitcnt vmcnt(0) lgkmcnt(0)
	v_mfma_f32_16x16x32_bf16 v[0:3], v[92:95], v[96:99], v[4:7]
	s_nop 2
	v_lshl_add_u64 v[4:5], v[56:57], 0, v[64:65]
	flat_load_dwordx4 v[4:7], v[4:5]
	s_nop 0
	flat_load_dwordx4 v[92:95], v[66:67] offset:320
	v_perm_b32 v99, v91, v90, s89
	v_perm_b32 v98, v89, v86, s89
	v_perm_b32 v97, v83, v79, s89
	v_perm_b32 v96, v75, v72, s89
	s_waitcnt vmcnt(0) lgkmcnt(0)
	s_nop 0
	v_mfma_f32_16x16x32_bf16 v[8:11], v[92:95], v[96:99], v[8:11]
	v_mfma_f32_16x16x32_bf16 v[0:3], v[4:7], v[96:99], v[0:3]
	flat_load_dwordx4 v[4:7], v[66:67] offset:384
	v_lshl_add_u64 v[90:91], v[58:59], 0, v[64:65]
	flat_load_dwordx4 v[90:93], v[90:91]
	v_perm_b32 v87, v88, v87, s89
	v_perm_b32 v86, v85, v84, s89
	v_perm_b32 v85, v82, v81, s89
	v_perm_b32 v84, v78, v76, s89
	v_perm_b32 v75, v80, v77, s89
	v_perm_b32 v74, v74, v73, s89
	v_perm_b32 v73, v71, v70, s89
	v_perm_b32 v72, v69, v68, s89
	s_waitcnt vmcnt(0) lgkmcnt(0)
	v_mfma_f32_16x16x32_bf16 v[4:7], v[4:7], v[84:87], v[8:11]
	s_nop 2
	v_lshl_add_u64 v[8:9], v[60:61], 0, v[64:65]
	flat_load_dwordx4 v[8:11], v[8:9]
	s_nop 0
	flat_load_dwordx4 v[64:67], v[66:67] offset:448
	v_mfma_f32_16x16x32_bf16 v[0:3], v[90:93], v[84:87], v[0:3]
	s_waitcnt vmcnt(0) lgkmcnt(0)
	v_mfma_f32_16x16x32_bf16 v[0:3], v[8:11], v[72:75], v[0:3]
	v_mfma_f32_16x16x32_bf16 v[4:7], v[64:67], v[72:75], v[4:7]
	v_or_b32_e32 v8, s11, v13
	v_or_b32_e32 v10, s10, v8
	v_lshl_add_u64 v[8:9], v[62:63], 0, s[82:83]
	s_nop 4
	v_bfe_u32 v11, v4, 16, 1
	v_lshlrev_b32_e32 v168, 11, v10
	v_add3_u32 v4, v4, v11, s77
	v_lshl_add_u64 v[8:9], v[8:9], 0, v[168:169]
	global_store_short_d16_hi v[8:9], v4, off offset:512
	v_bfe_u32 v4, v5, 16, 1
	v_add3_u32 v4, v5, v4, s77
	global_store_short_d16_hi v[8:9], v4, off offset:2560
	v_bfe_u32 v4, v6, 16, 1
	v_add3_u32 v6, v6, v4, s77
	v_add_co_u32_e32 v4, vcc, s33, v8
	s_add_i32 s9, s9, s70
	s_nop 0
	v_addc_co_u32_e32 v5, vcc, 0, v9, vcc
	global_store_short_d16_hi v[4:5], v6, off offset:512
	v_bfe_u32 v6, v7, 16, 1
	v_add3_u32 v6, v7, v6, s77
	global_store_short_d16_hi v[4:5], v6, off offset:2560
	v_bfe_u32 v4, v0, 16, 1
	v_add3_u32 v0, v0, v4, s77
	v_add_co_u32_e32 v4, vcc, s16, v8
	s_add_i32 s7, s7, s93
	s_nop 0
	v_addc_co_u32_e32 v5, vcc, 0, v9, vcc
	global_store_short_d16_hi v[4:5], v0, off offset:512
	v_bfe_u32 v0, v1, 16, 1
	v_add3_u32 v0, v1, v0, s77
	global_store_short_d16_hi v[4:5], v0, off offset:2560
	v_bfe_u32 v0, v2, 16, 1
	v_add3_u32 v2, v2, v0, s77
	v_add_co_u32_e32 v0, vcc, 0x9000, v8
	s_add_i32 s8, s8, s67
	s_nop 0
	v_addc_co_u32_e32 v1, vcc, 0, v9, vcc
	global_store_short_d16_hi v[0:1], v2, off offset:512
	v_bfe_u32 v2, v3, 16, 1
	v_add3_u32 v2, v3, v2, s77
	s_cmpk_lt_u32 s9, 0x100
	global_store_short_d16_hi v[0:1], v2, off offset:2560
	s_cbranch_scc1 .LBB0_500

.LBB0_502:
	s_andn2_b64 vcc, exec, s[2:3]
	s_cbranch_vccnz .LBB0_505
	s_add_i32 s7, s6, 0xffffff00
	s_cmpk_gt_u32 s7, 0xff
	s_cbranch_scc1 .LBB0_505
	s_lshl_b32 s2, s7, 1
	s_and_b32 s6, s2, 0x100
	s_bitset1_b32 s6, 14
	s_mul_i32 s2, s6, 0x1400
	s_add_u32 s2, s78, s2
	s_addc_u32 s3, s79, 0
	s_lshl_b32 s4, s7, 2
	s_and_b32 s82, s4, 0x1e0
	v_lshrrev_b32_e32 v0, 1, v117
	s_add_u32 s2, s2, s82
	v_and_b32_e32 v46, 24, v0
	v_and_b32_e32 v4, 15, v117
	s_addc_u32 s3, s3, 0
	v_mul_u32_u24_e32 v40, 0x1400, v46
	v_mov_b32_e32 v41, v169
	v_lshl_add_u64 v[2:3], s[2:3], 0, v[40:41]
	v_lshlrev_b32_e32 v12, 1, v4
	v_mov_b32_e32 v13, v169
	v_lshl_add_u64 v[14:15], v[2:3], 0, v[12:13]
	v_add_co_u32_e32 v16, vcc, s33, v14
	s_movk_i32 s9, 0x3000
	s_nop 0
	v_addc_co_u32_e32 v17, vcc, 0, v15, vcc
	v_lshlrev_b32_e32 v168, 1, v46
	v_add_co_u32_e32 v18, vcc, s9, v14
	v_lshl_add_u64 v[0:1], s[0:1], 0, v[168:169]
	s_nop 0
	v_addc_co_u32_e32 v19, vcc, 0, v15, vcc
	s_movk_i32 s0, 0x4000
	v_add_co_u32_e32 v20, vcc, s0, v14
	s_mov_b32 s10, 0x8000
	s_nop 0
	v_addc_co_u32_e32 v21, vcc, 0, v15, vcc
	v_add_co_u32_e32 v22, vcc, s19, v14
	s_add_u32 s4, s2, 0x800
	s_nop 0
	v_addc_co_u32_e32 v23, vcc, 0, v15, vcc
	v_add_co_u32_e32 v24, vcc, s15, v14
	v_mov_b32_e32 v2, 0x28000
	s_nop 0
	v_addc_co_u32_e32 v25, vcc, 0, v15, vcc
	v_add_co_u32_e32 v26, vcc, s10, v14
	s_addc_u32 s5, s3, 0
	s_nop 0
	v_addc_co_u32_e32 v27, vcc, 0, v15, vcc
	v_mad_u32_u24 v30, v46, s88, v2
	v_mov_b32_e32 v31, v169
	s_lshl_b32 s7, s7, 5
	v_add_co_u32_e32 v28, vcc, s20, v14
	v_lshl_add_u64 v[2:3], s[4:5], 0, v[30:31]
	s_and_b32 s7, s7, 0xe0
	v_addc_co_u32_e32 v29, vcc, 0, v15, vcc
	v_lshl_add_u64 v[2:3], v[2:3], 0, v[12:13]
	v_or_b32_e32 v6, s7, v4
	v_add_co_u32_e32 v4, vcc, s33, v2
	s_movk_i32 s8, 0x2000
	s_nop 0
	v_addc_co_u32_e32 v5, vcc, 0, v3, vcc
	flat_load_ushort v10, v[20:21] offset:1024
	flat_load_ushort v44, v[4:5] offset:1024
	v_add_co_u32_e32 v4, vcc, s8, v2
	flat_load_ushort v7, v[14:15] offset:2048
	flat_load_ushort v42, v[2:3]
	v_addc_co_u32_e32 v5, vcc, 0, v3, vcc
	flat_load_ushort v54, v[4:5] offset:2048
	v_add_co_u32_e32 v4, vcc, s9, v2
	flat_load_ushort v11, v[22:23] offset:2048
	s_nop 0
	v_addc_co_u32_e32 v5, vcc, 0, v3, vcc
	flat_load_ushort v58, v[4:5] offset:3072
	v_add_co_u32_e32 v4, vcc, s19, v2
	v_mov_b32_e32 v33, v169
	s_nop 0
	v_addc_co_u32_e32 v5, vcc, 0, v3, vcc
	flat_load_ushort v64, v[4:5]
	v_add_co_u32_e32 v4, vcc, s15, v2
	flat_load_ushort v71, v[24:25] offset:3072
	s_nop 0
	v_addc_co_u32_e32 v5, vcc, 0, v3, vcc
	flat_load_ushort v67, v[4:5] offset:1024
	v_add_co_u32_e32 v4, vcc, s21, v2
	flat_load_ushort v8, v[16:17] offset:3072
	s_nop 0
	v_addc_co_u32_e32 v5, vcc, 0, v3, vcc
	v_add_co_u32_e32 v2, vcc, s10, v2
	flat_load_ushort v69, v[4:5] offset:2048
	s_nop 0
	v_addc_co_u32_e32 v3, vcc, 0, v3, vcc
	flat_load_ushort v70, v[2:3] offset:3072
	v_mov_b32_e32 v2, 0x50000
	v_mad_u32_u24 v32, v46, s88, v2
	v_lshl_add_u64 v[2:3], s[4:5], 0, v[32:33]
	v_lshl_add_u64 v[2:3], v[2:3], 0, v[12:13]
	v_add_co_u32_e32 v4, vcc, s33, v2
	flat_load_ushort v56, v[2:3]
	s_nop 0
	v_addc_co_u32_e32 v5, vcc, 0, v3, vcc
	flat_load_ushort v57, v[4:5] offset:1024
	v_add_co_u32_e32 v4, vcc, s8, v2
	flat_load_ushort v76, v[26:27]
	s_nop 0
	v_addc_co_u32_e32 v5, vcc, 0, v3, vcc
	flat_load_ushort v60, v[4:5] offset:2048
	v_add_co_u32_e32 v4, vcc, s9, v2
	v_mov_b32_e32 v37, v169
	s_nop 0
	v_addc_co_u32_e32 v5, vcc, 0, v3, vcc
	flat_load_ushort v62, v[4:5] offset:3072
	v_add_co_u32_e32 v4, vcc, s19, v2
	flat_load_ushort v77, v[28:29] offset:1024
	s_nop 0
	v_addc_co_u32_e32 v5, vcc, 0, v3, vcc
	flat_load_ushort v63, v[4:5]
	v_add_co_u32_e32 v4, vcc, s15, v2
	v_lshlrev_b32_e32 v38, 10, v6
	s_nop 0
	v_addc_co_u32_e32 v5, vcc, 0, v3, vcc
	flat_load_ushort v65, v[4:5] offset:1024
	v_add_co_u32_e32 v4, vcc, s21, v2
	flat_load_ushort v9, v[18:19]
	s_nop 0
	v_addc_co_u32_e32 v5, vcc, 0, v3, vcc
	v_add_co_u32_e32 v2, vcc, s10, v2
	flat_load_ushort v66, v[4:5] offset:2048
	s_nop 0
	v_addc_co_u32_e32 v3, vcc, 0, v3, vcc
	flat_load_ushort v68, v[2:3] offset:3072
	v_mov_b32_e32 v2, 0x78000
	v_mad_u32_u24 v36, v46, s88, v2
	v_lshl_add_u64 v[2:3], s[4:5], 0, v[36:37]
	v_lshl_add_u64 v[2:3], v[2:3], 0, v[12:13]
	v_add_co_u32_e32 v4, vcc, s33, v2
	flat_load_ushort v41, v[2:3]
	s_nop 0
	v_addc_co_u32_e32 v5, vcc, 0, v3, vcc
	flat_load_ushort v43, v[4:5] offset:1024
	v_add_co_u32_e32 v4, vcc, s8, v2
	v_or_b32_e32 v34, 0x4000, v38
	s_nop 0
	v_addc_co_u32_e32 v5, vcc, 0, v3, vcc
	flat_load_ushort v45, v[4:5] offset:2048
	v_add_co_u32_e32 v4, vcc, s9, v2
	v_mov_b32_e32 v35, v169
	s_nop 0
	v_addc_co_u32_e32 v5, vcc, 0, v3, vcc
	flat_load_ushort v47, v[4:5] offset:3072
	v_add_co_u32_e32 v4, vcc, s19, v2
	v_lshl_add_u64 v[50:51], v[0:1], 0, v[34:35]
	s_nop 0
	v_addc_co_u32_e32 v5, vcc, 0, v3, vcc
	flat_load_ushort v53, v[4:5]
	v_add_co_u32_e32 v4, vcc, s15, v2
	flat_load_dwordx4 v[72:75], v[50:51]
	s_nop 0
	v_addc_co_u32_e32 v5, vcc, 0, v3, vcc
	flat_load_ushort v55, v[4:5] offset:1024
	v_add_co_u32_e32 v4, vcc, s21, v2
	v_mov_b32_e32 v39, v169
	s_nop 0
	v_addc_co_u32_e32 v5, vcc, 0, v3, vcc
	v_add_co_u32_e32 v2, vcc, s10, v2
	v_lshl_add_u64 v[48:49], v[0:1], 0, v[38:39]
	s_nop 0
	v_addc_co_u32_e32 v3, vcc, 0, v3, vcc
	flat_load_ushort v59, v[4:5] offset:2048
	flat_load_ushort v61, v[2:3] offset:3072
	s_waitcnt vmcnt(0) lgkmcnt(0)
	v_perm_b32 v78, v71, v11, s89
	flat_load_dwordx4 v[2:5], v[48:49]
	v_lshrrev_b32_e32 v52, 2, v117
	v_perm_b32 v79, v77, v76, s89
	v_perm_b32 v76, v8, v7, s89
	v_perm_b32 v77, v10, v9, s89
	s_waitcnt vmcnt(0) lgkmcnt(0)
	s_nop 0
	v_mfma_f32_16x16x32_bf16 v[8:11], v[2:5], v[76:79], 0
	v_mfma_f32_16x16x32_bf16 v[0:3], v[72:75], v[76:79], 0
	flat_load_dwordx4 v[4:7], v[50:51] offset:64
	flat_load_dwordx4 v[72:75], v[48:49] offset:64
	v_perm_b32 v79, v70, v69, s89
	v_perm_b32 v78, v67, v64, s89
	v_perm_b32 v77, v58, v54, s89
	v_perm_b32 v76, v44, v42, s89
	s_waitcnt vmcnt(0) lgkmcnt(0)
	s_nop 0
	v_mfma_f32_16x16x32_bf16 v[8:11], v[72:75], v[76:79], v[8:11]
	v_mfma_f32_16x16x32_bf16 v[0:3], v[4:7], v[76:79], v[0:3]
	flat_load_dwordx4 v[4:7], v[48:49] offset:128
	flat_load_dwordx4 v[70:73], v[50:51] offset:128
	v_perm_b32 v67, v68, v66, s89
	v_perm_b32 v66, v65, v63, s89
	v_perm_b32 v65, v62, v60, s89
	v_perm_b32 v64, v57, v56, s89
	v_perm_b32 v57, v61, v59, s89
	v_perm_b32 v56, v55, v53, s89
	v_perm_b32 v55, v47, v45, s89
	v_perm_b32 v54, v43, v41, s89
	s_waitcnt vmcnt(0) lgkmcnt(0)
	v_mfma_f32_16x16x32_bf16 v[4:7], v[4:7], v[64:67], v[8:11]
	v_mfma_f32_16x16x32_bf16 v[8:11], v[70:73], v[64:67], v[0:3]
	flat_load_dwordx4 v[62:65], v[50:51] offset:192
	s_nop 1
	flat_load_dwordx4 v[0:3], v[48:49] offset:192
	s_waitcnt vmcnt(0) lgkmcnt(0)
	v_mfma_f32_16x16x32_bf16 v[0:3], v[0:3], v[54:57], v[4:7]
	v_mfma_f32_16x16x32_bf16 v[4:7], v[62:65], v[54:57], v[8:11]
	v_or_b32_e32 v40, 0xa0000, v40
	v_mov_b32_e32 v41, v169
	s_nop 0
	v_lshl_add_u64 v[8:9], s[4:5], 0, v[40:41]
	v_lshl_add_u64 v[8:9], v[8:9], 0, v[12:13]
	v_add_co_u32_e32 v10, vcc, s33, v8
	flat_load_ushort v77, v[8:9]
	s_nop 0
	v_addc_co_u32_e32 v11, vcc, 0, v9, vcc
	flat_load_ushort v82, v[10:11] offset:1024
	v_add_co_u32_e32 v10, vcc, s8, v8
	v_mov_b32_e32 v43, v169
	s_nop 0
	v_addc_co_u32_e32 v11, vcc, 0, v9, vcc
	flat_load_ushort v83, v[10:11] offset:2048
	v_add_co_u32_e32 v10, vcc, s9, v8
	v_mov_b32_e32 v45, v169
	s_nop 0
	v_addc_co_u32_e32 v11, vcc, 0, v9, vcc
	flat_load_ushort v86, v[10:11] offset:3072
	v_add_co_u32_e32 v10, vcc, s19, v8
	v_mov_b32_e32 v47, v169
	s_nop 0
	v_addc_co_u32_e32 v11, vcc, 0, v9, vcc
	flat_load_ushort v84, v[10:11]
	v_add_co_u32_e32 v10, vcc, s15, v8
	s_waitcnt vmcnt(0) lgkmcnt(0)
	v_perm_b32 v82, v82, v77, s89
	v_addc_co_u32_e32 v11, vcc, 0, v9, vcc
	flat_load_ushort v87, v[10:11] offset:1024
	v_add_co_u32_e32 v10, vcc, s21, v8
	v_perm_b32 v83, v86, v83, s89
	s_nop 0
	v_addc_co_u32_e32 v11, vcc, 0, v9, vcc
	v_add_co_u32_e32 v8, vcc, s10, v8
	flat_load_ushort v85, v[10:11] offset:2048
	s_nop 0
	v_addc_co_u32_e32 v9, vcc, 0, v9, vcc
	flat_load_ushort v88, v[8:9] offset:3072
	v_mov_b32_e32 v8, 0xc8000
	v_mad_u32_u24 v42, v46, s88, v8
	v_lshl_add_u64 v[8:9], s[4:5], 0, v[42:43]
	v_lshl_add_u64 v[8:9], v[8:9], 0, v[12:13]
	v_add_co_u32_e32 v10, vcc, s33, v8
	flat_load_ushort v54, v[8:9]
	s_nop 0
	v_addc_co_u32_e32 v11, vcc, 0, v9, vcc
	flat_load_ushort v57, v[10:11] offset:1024
	v_add_co_u32_e32 v10, vcc, s8, v8
	s_waitcnt vmcnt(0) lgkmcnt(0)
	v_perm_b32 v84, v87, v84, s89
	v_addc_co_u32_e32 v11, vcc, 0, v9, vcc
	flat_load_ushort v61, v[10:11] offset:2048
	v_add_co_u32_e32 v10, vcc, s9, v8
	v_perm_b32 v85, v88, v85, s89
	s_nop 0
	v_addc_co_u32_e32 v11, vcc, 0, v9, vcc
	flat_load_ushort v65, v[10:11] offset:3072
	v_add_co_u32_e32 v10, vcc, s19, v8
	s_nop 1
	v_addc_co_u32_e32 v11, vcc, 0, v9, vcc
	flat_load_ushort v70, v[10:11]
	v_add_co_u32_e32 v10, vcc, s15, v8
	s_nop 1
	v_addc_co_u32_e32 v11, vcc, 0, v9, vcc
	flat_load_ushort v73, v[10:11] offset:1024
	v_add_co_u32_e32 v10, vcc, s21, v8
	s_nop 1
	v_addc_co_u32_e32 v11, vcc, 0, v9, vcc
	v_add_co_u32_e32 v8, vcc, s10, v8
	flat_load_ushort v75, v[10:11] offset:2048
	s_nop 0
	v_addc_co_u32_e32 v9, vcc, 0, v9, vcc
	flat_load_ushort v76, v[8:9] offset:3072
	v_mov_b32_e32 v8, 0xf0000
	v_mad_u32_u24 v44, v46, s88, v8
	v_lshl_add_u64 v[8:9], s[4:5], 0, v[44:45]
	v_lshl_add_u64 v[8:9], v[8:9], 0, v[12:13]
	v_add_co_u32_e32 v10, vcc, s33, v8
	flat_load_ushort v62, v[8:9]
	s_nop 0
	v_addc_co_u32_e32 v11, vcc, 0, v9, vcc
	flat_load_ushort v63, v[10:11] offset:1024
	v_add_co_u32_e32 v10, vcc, s8, v8
	s_nop 1
	v_addc_co_u32_e32 v11, vcc, 0, v9, vcc
	flat_load_ushort v66, v[10:11] offset:2048
	v_add_co_u32_e32 v10, vcc, s9, v8
	s_nop 1
	v_addc_co_u32_e32 v11, vcc, 0, v9, vcc
	flat_load_ushort v68, v[10:11] offset:3072
	v_add_co_u32_e32 v10, vcc, s19, v8
	s_nop 1
	v_addc_co_u32_e32 v11, vcc, 0, v9, vcc
	flat_load_ushort v69, v[10:11]
	v_add_co_u32_e32 v10, vcc, s15, v8
	s_nop 1
	v_addc_co_u32_e32 v11, vcc, 0, v9, vcc
	flat_load_ushort v71, v[10:11] offset:1024
	v_add_co_u32_e32 v10, vcc, s21, v8
	s_nop 1
	v_addc_co_u32_e32 v11, vcc, 0, v9, vcc
	v_add_co_u32_e32 v8, vcc, s10, v8
	flat_load_ushort v72, v[10:11] offset:2048
	s_nop 0
	v_addc_co_u32_e32 v9, vcc, 0, v9, vcc
	flat_load_ushort v74, v[8:9] offset:3072
	v_mov_b32_e32 v8, 0x118000
	v_mad_u32_u24 v46, v46, s88, v8
	v_lshl_add_u64 v[8:9], s[4:5], 0, v[46:47]
	v_lshl_add_u64 v[8:9], v[8:9], 0, v[12:13]
	v_add_co_u32_e32 v10, vcc, s33, v8
	flat_load_ushort v53, v[8:9]
	s_nop 0
	v_addc_co_u32_e32 v11, vcc, 0, v9, vcc
	flat_load_ushort v55, v[10:11] offset:1024
	v_add_co_u32_e32 v10, vcc, s8, v8
	s_nop 1
	v_addc_co_u32_e32 v11, vcc, 0, v9, vcc
	flat_load_ushort v56, v[10:11] offset:2048
	v_add_co_u32_e32 v10, vcc, s9, v8
	s_nop 1
	v_addc_co_u32_e32 v11, vcc, 0, v9, vcc
	flat_load_ushort v58, v[10:11] offset:3072
	v_add_co_u32_e32 v10, vcc, s19, v8
	s_nop 1
	v_addc_co_u32_e32 v11, vcc, 0, v9, vcc
	flat_load_ushort v59, v[10:11]
	v_add_co_u32_e32 v10, vcc, s15, v8
	s_nop 1
	v_addc_co_u32_e32 v11, vcc, 0, v9, vcc
	flat_load_ushort v60, v[10:11] offset:1024
	v_add_co_u32_e32 v10, vcc, s21, v8
	s_nop 1
	v_addc_co_u32_e32 v11, vcc, 0, v9, vcc
	v_add_co_u32_e32 v8, vcc, s10, v8
	flat_load_ushort v64, v[10:11] offset:2048
	s_nop 0
	v_addc_co_u32_e32 v9, vcc, 0, v9, vcc
	flat_load_ushort v67, v[8:9] offset:3072
	s_nop 0
	flat_load_dwordx4 v[8:11], v[48:49] offset:256
	flat_load_dwordx4 v[78:81], v[50:51] offset:256
	s_waitcnt vmcnt(0) lgkmcnt(0)
	v_mfma_f32_16x16x32_bf16 v[8:11], v[8:11], v[82:85], v[0:3]
	v_mfma_f32_16x16x32_bf16 v[0:3], v[78:81], v[82:85], v[4:7]
	s_nop 2
	flat_load_dwordx4 v[4:7], v[50:51] offset:320
	flat_load_dwordx4 v[78:81], v[48:49] offset:320
	v_perm_b32 v85, v76, v75, s89
	v_perm_b32 v84, v73, v70, s89
	v_perm_b32 v83, v65, v61, s89
	v_perm_b32 v82, v57, v54, s89
	s_waitcnt vmcnt(0) lgkmcnt(0)
	s_nop 0
	v_mfma_f32_16x16x32_bf16 v[8:11], v[78:81], v[82:85], v[8:11]
	v_mfma_f32_16x16x32_bf16 v[0:3], v[4:7], v[82:85], v[0:3]
	flat_load_dwordx4 v[4:7], v[48:49] offset:384
	flat_load_dwordx4 v[76:79], v[50:51] offset:384
	v_perm_b32 v73, v74, v72, s89
	v_perm_b32 v72, v71, v69, s89
	v_perm_b32 v71, v68, v66, s89
	v_perm_b32 v70, v63, v62, s89
	s_waitcnt vmcnt(0) lgkmcnt(0)
	s_nop 0
	v_mfma_f32_16x16x32_bf16 v[4:7], v[4:7], v[70:73], v[8:11]
	v_mfma_f32_16x16x32_bf16 v[8:11], v[76:79], v[70:73], v[0:3]
	flat_load_dwordx4 v[68:71], v[50:51] offset:448
	s_nop 1
	flat_load_dwordx4 v[0:3], v[48:49] offset:448
	v_perm_b32 v51, v67, v64, s89
	v_perm_b32 v50, v60, v59, s89
	v_perm_b32 v49, v58, v56, s89
	v_perm_b32 v48, v55, v53, s89
	s_waitcnt vmcnt(0) lgkmcnt(0)
	s_nop 0
	v_mfma_f32_16x16x32_bf16 v[0:3], v[0:3], v[48:51], v[4:7]
	v_mfma_f32_16x16x32_bf16 v[4:7], v[68:71], v[48:51], v[8:11]
	s_add_u32 s0, s2, 0xa00
	s_addc_u32 s1, s3, 0
	s_nop 0
	v_lshl_add_u64 v[10:11], s[0:1], 0, v[30:31]
	v_lshl_add_u64 v[10:11], v[10:11], 0, v[12:13]
	flat_load_ushort v57, v[14:15] offset:2560
	flat_load_ushort v62, v[16:17] offset:3584
	flat_load_ushort v63, v[18:19] offset:512
	flat_load_ushort v66, v[20:21] offset:1536
	flat_load_ushort v64, v[22:23] offset:2560
	flat_load_ushort v67, v[24:25] offset:3584
	flat_load_ushort v65, v[26:27] offset:512
	flat_load_ushort v68, v[28:29] offset:1536
	v_add_co_u32_e32 v14, vcc, s33, v10
	v_readlane_b32 s2, v254, 59
	s_nop 0
	v_addc_co_u32_e32 v15, vcc, 0, v11, vcc
	flat_load_ushort v23, v[14:15] offset:1024
	v_add_co_u32_e32 v14, vcc, s8, v10
	v_readlane_b32 s3, v254, 60
	s_nop 0
	v_addc_co_u32_e32 v15, vcc, 0, v11, vcc
	flat_load_ushort v27, v[14:15] offset:2048
	v_add_co_u32_e32 v14, vcc, s9, v10
	v_lshl_add_u64 v[8:9], s[2:3], 0, v[168:169]
	s_mov_b64 s[2:3], 0x198200
	v_addc_co_u32_e32 v15, vcc, 0, v11, vcc
	v_lshl_add_u64 v[8:9], v[8:9], 0, s[2:3]
	flat_load_ushort v48, v[14:15] offset:3072
	v_add_co_u32_e32 v14, vcc, s19, v10
	v_lshl_add_u64 v[16:17], v[8:9], 0, v[34:35]
	s_nop 0
	v_addc_co_u32_e32 v15, vcc, 0, v11, vcc
	flat_load_ushort v20, v[10:11]
	flat_load_ushort v50, v[14:15]
	flat_load_dwordx4 v[58:61], v[16:17]
	v_add_co_u32_e32 v14, vcc, s15, v10
	s_waitcnt vmcnt(0) lgkmcnt(0)
	v_perm_b32 v62, v62, v57, s89
	v_addc_co_u32_e32 v15, vcc, 0, v11, vcc
	flat_load_ushort v54, v[14:15] offset:1024
	v_add_co_u32_e32 v14, vcc, s21, v10
	v_perm_b32 v65, v68, v65, s89
	s_nop 0
	v_addc_co_u32_e32 v15, vcc, 0, v11, vcc
	v_add_co_u32_e32 v10, vcc, s10, v10
	flat_load_ushort v55, v[14:15] offset:2048
	s_nop 0
	v_addc_co_u32_e32 v11, vcc, 0, v11, vcc
	flat_load_ushort v56, v[10:11] offset:3072
	v_lshl_add_u64 v[10:11], s[0:1], 0, v[32:33]
	v_lshl_add_u64 v[10:11], v[10:11], 0, v[12:13]
	v_add_co_u32_e32 v14, vcc, s33, v10
	flat_load_ushort v26, v[10:11]
	s_nop 0
	v_addc_co_u32_e32 v15, vcc, 0, v11, vcc
	flat_load_ushort v28, v[14:15] offset:1024
	v_add_co_u32_e32 v14, vcc, s8, v10
	v_perm_b32 v64, v67, v64, s89
	s_nop 0
	v_addc_co_u32_e32 v15, vcc, 0, v11, vcc
	flat_load_ushort v30, v[14:15] offset:2048
	v_add_co_u32_e32 v14, vcc, s9, v10
	v_perm_b32 v63, v66, v63, s89
	s_nop 0
	v_addc_co_u32_e32 v15, vcc, 0, v11, vcc
	flat_load_ushort v32, v[14:15] offset:3072
	v_add_co_u32_e32 v14, vcc, s19, v10
	s_waitcnt vmcnt(0) lgkmcnt(0)
	v_perm_b32 v57, v56, v55, s89
	v_addc_co_u32_e32 v15, vcc, 0, v11, vcc
	flat_load_ushort v33, v[14:15]
	v_add_co_u32_e32 v14, vcc, s15, v10
	v_perm_b32 v56, v54, v50, s89
	s_nop 0
	v_addc_co_u32_e32 v15, vcc, 0, v11, vcc
	flat_load_ushort v49, v[14:15] offset:1024
	v_add_co_u32_e32 v14, vcc, s21, v10
	v_perm_b32 v55, v48, v27, s89
	s_nop 0
	v_addc_co_u32_e32 v15, vcc, 0, v11, vcc
	v_add_co_u32_e32 v10, vcc, s10, v10
	flat_load_ushort v51, v[14:15] offset:2048
	s_nop 0
	v_addc_co_u32_e32 v11, vcc, 0, v11, vcc
	flat_load_ushort v53, v[10:11] offset:3072
	v_lshl_add_u64 v[10:11], s[0:1], 0, v[36:37]
	v_lshl_add_u64 v[10:11], v[10:11], 0, v[12:13]
	v_add_co_u32_e32 v14, vcc, s33, v10
	flat_load_ushort v18, v[10:11]
	s_nop 0
	v_addc_co_u32_e32 v15, vcc, 0, v11, vcc
	flat_load_ushort v19, v[14:15] offset:1024
	v_add_co_u32_e32 v14, vcc, s8, v10
	v_perm_b32 v54, v23, v20, s89
	s_nop 0
	v_addc_co_u32_e32 v15, vcc, 0, v11, vcc
	flat_load_ushort v21, v[14:15] offset:2048
	v_add_co_u32_e32 v14, vcc, s9, v10
	s_nop 1
	v_addc_co_u32_e32 v15, vcc, 0, v11, vcc
	flat_load_ushort v22, v[14:15] offset:3072
	v_add_co_u32_e32 v14, vcc, s19, v10
	s_nop 1
	v_addc_co_u32_e32 v15, vcc, 0, v11, vcc
	flat_load_ushort v24, v[14:15]
	v_add_co_u32_e32 v14, vcc, s15, v10
	s_nop 1
	v_addc_co_u32_e32 v15, vcc, 0, v11, vcc
	flat_load_ushort v25, v[14:15] offset:1024
	v_add_co_u32_e32 v14, vcc, s21, v10
	s_nop 1
	v_addc_co_u32_e32 v15, vcc, 0, v11, vcc
	v_add_co_u32_e32 v10, vcc, s10, v10
	flat_load_ushort v29, v[14:15] offset:2048
	s_nop 0
	v_addc_co_u32_e32 v11, vcc, 0, v11, vcc
	v_lshl_add_u64 v[14:15], v[8:9], 0, v[38:39]
	flat_load_ushort v31, v[10:11] offset:3072
	flat_load_dwordx4 v[36:39], v[14:15]
	s_waitcnt vmcnt(0) lgkmcnt(0)
	v_mfma_f32_16x16x32_bf16 v[8:11], v[36:39], v[62:65], v[0:3]
	v_mfma_f32_16x16x32_bf16 v[0:3], v[58:61], v[62:65], v[4:7]
	s_nop 2
	flat_load_dwordx4 v[4:7], v[16:17] offset:64
	flat_load_dwordx4 v[34:37], v[14:15] offset:64
	s_waitcnt vmcnt(0) lgkmcnt(0)
	v_mfma_f32_16x16x32_bf16 v[8:11], v[34:37], v[54:57], v[8:11]
	v_mfma_f32_16x16x32_bf16 v[0:3], v[4:7], v[54:57], v[0:3]
	flat_load_dwordx4 v[4:7], v[14:15] offset:128
	flat_load_dwordx4 v[34:37], v[16:17] offset:128
	v_perm_b32 v51, v53, v51, s89
	v_perm_b32 v50, v49, v33, s89
	v_perm_b32 v49, v32, v30, s89
	v_perm_b32 v48, v28, v26, s89
	v_perm_b32 v27, v31, v29, s89
	v_perm_b32 v26, v25, v24, s89
	v_perm_b32 v25, v22, v21, s89
	v_perm_b32 v24, v19, v18, s89
	s_waitcnt vmcnt(0) lgkmcnt(0)
	v_mfma_f32_16x16x32_bf16 v[4:7], v[4:7], v[48:51], v[8:11]
	v_mfma_f32_16x16x32_bf16 v[8:11], v[34:37], v[48:51], v[0:3]
	flat_load_dwordx4 v[32:35], v[16:17] offset:192
	s_nop 1
	flat_load_dwordx4 v[0:3], v[14:15] offset:192
	s_waitcnt vmcnt(0) lgkmcnt(0)
	v_mfma_f32_16x16x32_bf16 v[0:3], v[0:3], v[24:27], v[4:7]
	v_mfma_f32_16x16x32_bf16 v[4:7], v[32:35], v[24:27], v[8:11]
	s_nop 2
	v_lshl_add_u64 v[8:9], s[0:1], 0, v[40:41]
	v_lshl_add_u64 v[8:9], v[8:9], 0, v[12:13]
	v_add_co_u32_e32 v10, vcc, s33, v8
	flat_load_ushort v50, v[8:9]
	s_nop 0
	v_addc_co_u32_e32 v11, vcc, 0, v9, vcc
	flat_load_ushort v51, v[10:11] offset:1024
	v_add_co_u32_e32 v10, vcc, s8, v8
	s_nop 1
	v_addc_co_u32_e32 v11, vcc, 0, v9, vcc
	flat_load_ushort v53, v[10:11] offset:2048
	v_add_co_u32_e32 v10, vcc, s9, v8
	s_nop 1
	v_addc_co_u32_e32 v11, vcc, 0, v9, vcc
	flat_load_ushort v54, v[10:11] offset:3072
	v_add_co_u32_e32 v10, vcc, s19, v8
	s_nop 1
	v_addc_co_u32_e32 v11, vcc, 0, v9, vcc
	flat_load_ushort v48, v[10:11]
	v_add_co_u32_e32 v10, vcc, s15, v8
	s_nop 1
	v_addc_co_u32_e32 v11, vcc, 0, v9, vcc
	flat_load_ushort v55, v[10:11] offset:1024
	v_add_co_u32_e32 v10, vcc, s21, v8
	s_waitcnt vmcnt(0) lgkmcnt(0)
	v_perm_b32 v48, v55, v48, s89
	v_addc_co_u32_e32 v11, vcc, 0, v9, vcc
	v_add_co_u32_e32 v8, vcc, s10, v8
	flat_load_ushort v49, v[10:11] offset:2048
	s_nop 0
	v_addc_co_u32_e32 v9, vcc, 0, v9, vcc
	flat_load_ushort v56, v[8:9] offset:3072
	v_lshl_add_u64 v[8:9], s[0:1], 0, v[42:43]
	v_lshl_add_u64 v[8:9], v[8:9], 0, v[12:13]
	v_add_co_u32_e32 v10, vcc, s33, v8
	flat_load_ushort v20, v[8:9]
	s_nop 0
	v_addc_co_u32_e32 v11, vcc, 0, v9, vcc
	flat_load_ushort v23, v[10:11] offset:1024
	v_add_co_u32_e32 v10, vcc, s8, v8
	s_waitcnt vmcnt(0) lgkmcnt(0)
	v_perm_b32 v49, v56, v49, s89
	v_addc_co_u32_e32 v11, vcc, 0, v9, vcc
	flat_load_ushort v27, v[10:11] offset:2048
	v_add_co_u32_e32 v10, vcc, s9, v8
	s_nop 1
	v_addc_co_u32_e32 v11, vcc, 0, v9, vcc
	flat_load_ushort v31, v[10:11] offset:3072
	v_add_co_u32_e32 v10, vcc, s19, v8
	s_nop 1
	v_addc_co_u32_e32 v11, vcc, 0, v9, vcc
	flat_load_ushort v36, v[10:11]
	v_add_co_u32_e32 v10, vcc, s15, v8
	s_nop 1
	v_addc_co_u32_e32 v11, vcc, 0, v9, vcc
	flat_load_ushort v39, v[10:11] offset:1024
	v_add_co_u32_e32 v10, vcc, s21, v8
	s_nop 1
	v_addc_co_u32_e32 v11, vcc, 0, v9, vcc
	v_add_co_u32_e32 v8, vcc, s10, v8
	flat_load_ushort v40, v[10:11] offset:2048
	s_nop 0
	v_addc_co_u32_e32 v9, vcc, 0, v9, vcc
	flat_load_ushort v41, v[8:9] offset:3072
	v_lshl_add_u64 v[8:9], s[0:1], 0, v[44:45]
	v_lshl_add_u64 v[8:9], v[8:9], 0, v[12:13]
	v_add_co_u32_e32 v10, vcc, s33, v8
	flat_load_ushort v26, v[8:9]
	s_nop 0
	v_addc_co_u32_e32 v11, vcc, 0, v9, vcc
	flat_load_ushort v28, v[10:11] offset:1024
	v_add_co_u32_e32 v10, vcc, s8, v8
	s_nop 1
	v_addc_co_u32_e32 v11, vcc, 0, v9, vcc
	flat_load_ushort v30, v[10:11] offset:2048
	v_add_co_u32_e32 v10, vcc, s9, v8
	s_nop 1
	v_addc_co_u32_e32 v11, vcc, 0, v9, vcc
	flat_load_ushort v33, v[10:11] offset:3072
	v_add_co_u32_e32 v10, vcc, s19, v8
	s_nop 1
	v_addc_co_u32_e32 v11, vcc, 0, v9, vcc
	flat_load_ushort v34, v[10:11]
	v_add_co_u32_e32 v10, vcc, s15, v8
	s_nop 1
	v_addc_co_u32_e32 v11, vcc, 0, v9, vcc
	flat_load_ushort v35, v[10:11] offset:1024
	v_add_co_u32_e32 v10, vcc, s21, v8
	s_nop 1
	v_addc_co_u32_e32 v11, vcc, 0, v9, vcc
	v_add_co_u32_e32 v8, vcc, s10, v8
	flat_load_ushort v37, v[10:11] offset:2048
	s_nop 0
	v_addc_co_u32_e32 v9, vcc, 0, v9, vcc
	flat_load_ushort v38, v[8:9] offset:3072
	v_lshl_add_u64 v[8:9], s[0:1], 0, v[46:47]
	v_lshl_add_u64 v[8:9], v[8:9], 0, v[12:13]
	v_add_co_u32_e32 v10, vcc, s33, v8
	flat_load_ushort v18, v[8:9]
	s_nop 0
	v_addc_co_u32_e32 v11, vcc, 0, v9, vcc
	flat_load_ushort v19, v[10:11] offset:1024
	v_add_co_u32_e32 v10, vcc, s8, v8
	v_perm_b32 v47, v54, v53, s89
	s_nop 0
	v_addc_co_u32_e32 v11, vcc, 0, v9, vcc
	flat_load_ushort v21, v[10:11] offset:2048
	v_add_co_u32_e32 v10, vcc, s9, v8
	v_perm_b32 v46, v51, v50, s89
	s_nop 0
	v_addc_co_u32_e32 v11, vcc, 0, v9, vcc
	flat_load_ushort v22, v[10:11] offset:3072
	v_add_co_u32_e32 v10, vcc, s19, v8
	s_nop 1
	v_addc_co_u32_e32 v11, vcc, 0, v9, vcc
	flat_load_ushort v24, v[10:11]
	v_add_co_u32_e32 v10, vcc, s15, v8
	s_nop 1
	v_addc_co_u32_e32 v11, vcc, 0, v9, vcc
	flat_load_ushort v25, v[10:11] offset:1024
	v_add_co_u32_e32 v10, vcc, s21, v8
	s_nop 1
	v_addc_co_u32_e32 v11, vcc, 0, v9, vcc
	v_add_co_u32_e32 v8, vcc, s10, v8
	flat_load_ushort v29, v[10:11] offset:2048
	s_nop 0
	v_addc_co_u32_e32 v9, vcc, 0, v9, vcc
	flat_load_ushort v32, v[8:9] offset:3072
	s_nop 0
	flat_load_dwordx4 v[8:11], v[14:15] offset:256
	flat_load_dwordx4 v[42:45], v[16:17] offset:256
	s_waitcnt vmcnt(0) lgkmcnt(0)
	v_mfma_f32_16x16x32_bf16 v[8:11], v[8:11], v[46:49], v[0:3]
	v_mfma_f32_16x16x32_bf16 v[0:3], v[42:45], v[46:49], v[4:7]
	s_nop 2
	flat_load_dwordx4 v[4:7], v[16:17] offset:320
	flat_load_dwordx4 v[42:45], v[14:15] offset:320
	v_perm_b32 v49, v41, v40, s89
	v_perm_b32 v48, v39, v36, s89
	v_perm_b32 v47, v31, v27, s89
	v_perm_b32 v46, v23, v20, s89
	s_waitcnt vmcnt(0) lgkmcnt(0)
	s_nop 0
	v_mfma_f32_16x16x32_bf16 v[8:11], v[42:45], v[46:49], v[8:11]
	v_mfma_f32_16x16x32_bf16 v[0:3], v[4:7], v[46:49], v[0:3]
	flat_load_dwordx4 v[4:7], v[14:15] offset:384
	flat_load_dwordx4 v[40:43], v[16:17] offset:384
	v_perm_b32 v37, v38, v37, s89
	v_perm_b32 v36, v35, v34, s89
	v_perm_b32 v35, v33, v30, s89
	v_perm_b32 v34, v28, v26, s89
	v_perm_b32 v27, v32, v29, s89
	v_perm_b32 v26, v25, v24, s89
	v_perm_b32 v25, v22, v21, s89
	v_perm_b32 v24, v19, v18, s89
	s_waitcnt vmcnt(0) lgkmcnt(0)
	v_mfma_f32_16x16x32_bf16 v[4:7], v[4:7], v[34:37], v[8:11]
	s_nop 2
	flat_load_dwordx4 v[8:11], v[16:17] offset:448
	s_nop 0
	flat_load_dwordx4 v[14:17], v[14:15] offset:448
	v_mfma_f32_16x16x32_bf16 v[0:3], v[40:43], v[34:37], v[0:3]
	s_waitcnt vmcnt(0) lgkmcnt(0)
	v_mfma_f32_16x16x32_bf16 v[0:3], v[8:11], v[24:27], v[0:3]
	v_mfma_f32_16x16x32_bf16 v[4:7], v[14:17], v[24:27], v[4:7]
	v_readlane_b32 s0, v254, 57
	v_and_or_b32 v8, v52, 12, s7
	v_readlane_b32 s1, v254, 58
	v_or_b32_e32 v10, s6, v8
	s_nop 3
	v_bfe_u32 v11, v4, 16, 1
	v_lshl_add_u64 v[8:9], s[0:1], 0, v[12:13]
	v_lshl_add_u64 v[8:9], v[8:9], 0, s[82:83]
	v_lshlrev_b32_e32 v168, 11, v10
	v_add3_u32 v4, v4, v11, s77
	v_lshl_add_u64 v[8:9], v[8:9], 0, v[168:169]
	global_store_short_d16_hi v[8:9], v4, off offset:512
	v_bfe_u32 v4, v5, 16, 1
	v_add3_u32 v4, v5, v4, s77
	global_store_short_d16_hi v[8:9], v4, off offset:2560
	v_bfe_u32 v4, v6, 16, 1
	v_add3_u32 v6, v6, v4, s77
	v_add_co_u32_e32 v4, vcc, s33, v8
	s_nop 1
	v_addc_co_u32_e32 v5, vcc, 0, v9, vcc
	global_store_short_d16_hi v[4:5], v6, off offset:512
	v_bfe_u32 v6, v7, 16, 1
	v_add3_u32 v6, v7, v6, s77
	global_store_short_d16_hi v[4:5], v6, off offset:2560
	v_bfe_u32 v4, v0, 16, 1
	v_add3_u32 v0, v0, v4, s77
	v_add_co_u32_e32 v4, vcc, s10, v8
	s_nop 1
	v_addc_co_u32_e32 v5, vcc, 0, v9, vcc
	global_store_short_d16_hi v[4:5], v0, off offset:512
	v_bfe_u32 v0, v1, 16, 1
	v_add3_u32 v0, v1, v0, s77
	global_store_short_d16_hi v[4:5], v0, off offset:2560
	v_bfe_u32 v0, v2, 16, 1
	v_add3_u32 v2, v2, v0, s77
	v_add_co_u32_e32 v0, vcc, 0x9000, v8
	s_nop 1
	v_addc_co_u32_e32 v1, vcc, 0, v9, vcc
	global_store_short_d16_hi v[0:1], v2, off offset:512
	v_bfe_u32 v2, v3, 16, 1
	v_add3_u32 v2, v3, v2, s77
	global_store_short_d16_hi v[0:1], v2, off offset:2560

.LBB0_640:
	s_or_b64 exec, exec, s[8:9]
	v_readlane_b32 s0, v254, 48
	v_readlane_b32 s1, v254, 49
	s_add_u32 s8, s12, s0
	s_addc_u32 s9, s13, s1
	s_add_u32 s0, s6, 0x3200000
	s_addc_u32 s1, s7, 0
	s_add_u32 s6, s18, s2
	s_addc_u32 s7, s19, s3
	s_add_u32 s2, s6, 0x4000
	v_lshlrev_b64 v[0:1], 2, v[176:177]
	s_addc_u32 s3, s7, 0
	s_waitcnt vmcnt(0) lgkmcnt(0)
	s_barrier
	v_lshl_add_u64 v[2:3], s[8:9], 0, v[0:1]
	v_lshl_add_u64 v[4:5], s[2:3], 0, v[0:1]
	global_load_dwordx4 v[34:37], v[2:3], off offset:16
	global_load_dwordx4 v[18:21], v[2:3], off
	flat_load_dwordx4 v[22:25], v[4:5]
	v_or_b32_e32 v4, 4, v176
	v_ashrrev_i32_e32 v5, 31, v4
	v_lshlrev_b64 v[4:5], 2, v[4:5]
	v_lshl_add_u64 v[6:7], s[2:3], 0, v[4:5]
	flat_load_dwordx4 v[26:29], v[6:7]
	v_or_b32_e32 v6, 0x80, v176
	v_ashrrev_i32_e32 v7, 31, v6
	v_lshlrev_b64 v[6:7], 2, v[6:7]
	v_lshl_add_u64 v[8:9], s[2:3], 0, v[6:7]
	flat_load_dwordx4 v[38:41], v[8:9]
	v_or_b32_e32 v8, 0x84, v176
	v_ashrrev_i32_e32 v9, 31, v8
	v_lshlrev_b64 v[30:31], 2, v[8:9]
	v_lshl_add_u64 v[8:9], s[2:3], 0, v[30:31]
	s_add_u32 s2, s6, 0x3000
	s_addc_u32 s3, s7, 0
	v_lshl_add_u64 v[0:1], s[2:3], 0, v[0:1]
	flat_load_dwordx4 v[42:45], v[8:9]
	flat_load_dwordx4 v[12:15], v[0:1]
	v_lshl_add_u64 v[0:1], s[2:3], 0, v[4:5]
	flat_load_dwordx4 v[8:11], v[0:1]
	global_load_dwordx4 v[50:53], v[2:3], off offset:512
	v_lshl_add_u64 v[0:1], s[2:3], 0, v[6:7]
	flat_load_dwordx4 v[4:7], v[0:1]
	global_load_dwordx4 v[170:173], v[2:3], off offset:528
	v_lshl_add_u64 v[0:1], s[2:3], 0, v[30:31]
	flat_load_dwordx4 v[0:3], v[0:1]
	v_lshl_add_u32 v129, v180, 2, 0
	ds_read_b32 v131, v129 offset:4096
	v_lshl_add_u64 v[30:31], s[0:1], 0, v[192:193]
	v_lshl_add_u64 v[134:135], v[30:31], 0, v[174:175]
	v_lshl_add_u64 v[96:97], s[0:1], 0, v[96:97]
	v_lshl_add_u64 v[96:97], v[96:97], 0, v[174:175]
	s_waitcnt lgkmcnt(0)
	v_mov_b32_e32 v47, v131
	v_mov_b32_e32 v139, v131
	v_mov_b32_e32 v143, v131
	v_mov_b32_e32 v193, v131
	v_mov_b32_e32 v177, v131
	v_mov_b32_e32 v213, v131
	v_mov_b32_e32 v215, v131
	v_mov_b32_e32 v217, v131
	v_mov_b32_e32 v243, v131
	v_mov_b32_e32 v245, v131
	v_mov_b32_e32 v247, v131
	v_mov_b32_e32 v249, v131
	v_mov_b32_e32 v251, v131
	v_lshl_add_u64 v[92:93], s[0:1], 0, v[92:93]
	v_lshl_add_u64 v[92:93], v[92:93], 0, v[174:175]
	v_lshl_add_u64 v[48:49], s[0:1], 0, v[48:49]
	v_lshl_add_u64 v[48:49], v[48:49], 0, v[174:175]
	v_lshl_add_u64 v[32:33], s[0:1], 0, v[32:33]
	v_lshl_add_u64 v[32:33], v[32:33], 0, v[174:175]
	v_lshl_add_u64 v[16:17], s[0:1], 0, v[16:17]
	v_lshl_add_u64 v[16:17], v[16:17], 0, v[174:175]
	s_waitcnt vmcnt(0)
	v_mov_b32_e32 v194, v35
	v_mov_b32_e32 v180, v18
	v_mov_b32_e32 v182, v19
	v_mov_b32_e32 v184, v20
	v_mov_b32_e32 v186, v21
	v_add_f32_e32 v130, 1.0, v22
	v_add_f32_e32 v46, 1.0, v23
	v_add_f32_e32 v138, 1.0, v24
	v_add_f32_e32 v142, 1.0, v25
	v_add_f32_e32 v192, 1.0, v27
	v_mov_b32_e32 v190, v34
	v_mov_b32_e32 v198, v36
	v_add_f32_e32 v176, 1.0, v26
	v_add_f32_e32 v212, 1.0, v28
	v_add_f32_e32 v34, 1.0, v29
	v_pk_mul_f32 v[30:31], v[180:181], v[130:131]
	v_pk_mul_f32 v[28:29], v[182:183], v[46:47]
	v_pk_mul_f32 v[26:27], v[184:185], v[138:139]
	v_pk_mul_f32 v[24:25], v[186:187], v[142:143]
	v_pk_mul_f32 v[20:21], v[194:195], v[192:193]
	v_mov_b32_e32 v178, v37
	v_mov_b32_e32 v35, v131
	v_add_f32_e32 v36, 1.0, v38
	v_add_f32_e32 v214, 1.0, v39
	v_pk_mul_f32 v[22:23], v[190:191], v[176:177]
	v_pk_mul_f32 v[18:19], v[198:199], v[212:213]
	v_fma_f32 v31, v30, v31, v12
	v_fma_f32 v29, v28, v29, v13
	v_fma_f32 v27, v26, v27, v14
	v_fma_f32 v25, v24, v25, v15
	v_fma_f32 v21, v20, v21, v9
	v_cvt_pk_bf16_f32 v38, v31, v29
	v_cvt_pk_bf16_f32 v39, v27, v25
	v_pk_mul_f32 v[34:35], v[178:179], v[34:35]
	v_mov_b32_e32 v200, v50
	v_mov_b32_e32 v37, v131
	v_mov_b32_e32 v196, v51
	v_add_f32_e32 v216, 1.0, v40
	v_add_f32_e32 v242, 1.0, v41
	v_fma_f32 v23, v22, v23, v8
	v_cvt_pk_bf16_f32 v40, v23, v21
	v_fma_f32 v19, v18, v19, v10
	v_fma_f32 v21, v34, v35, v11
	v_cvt_pk_bf16_f32 v41, v19, v21
	global_store_dwordx4 v[134:135], v[38:41], off
	v_pk_mul_f32 v[36:37], v[200:201], v[36:37]
	v_mov_b32_e32 v188, v52
	v_pk_mul_f32 v[38:39], v[196:197], v[214:215]
	v_mov_b32_e32 v122, v53
	v_add_f32_e32 v244, 1.0, v42
	v_add_f32_e32 v246, 1.0, v43
	v_fma_f32 v19, v36, v37, v4
	v_fma_f32 v21, v38, v39, v5
	v_pk_mul_f32 v[40:41], v[188:189], v[216:217]
	v_pk_mul_f32 v[42:43], v[122:123], v[242:243]
	v_mov_b32_e32 v120, v170
	v_mov_b32_e32 v118, v171
	v_add_f32_e32 v248, 1.0, v44
	v_add_f32_e32 v250, 1.0, v45
	v_cvt_pk_bf16_f32 v176, v19, v21
	v_fma_f32 v19, v40, v41, v6
	v_fma_f32 v21, v42, v43, v7
	v_pk_mul_f32 v[44:45], v[120:121], v[244:245]
	v_pk_mul_f32 v[46:47], v[118:119], v[246:247]
	v_mov_b32_e32 v116, v172
	v_mov_b32_e32 v112, v173
	v_cvt_pk_bf16_f32 v177, v19, v21
	v_fma_f32 v19, v44, v45, v0
	v_fma_f32 v21, v46, v47, v1
	v_pk_mul_f32 v[50:51], v[116:117], v[248:249]
	v_pk_mul_f32 v[52:53], v[112:113], v[250:251]
	v_cvt_pk_bf16_f32 v178, v19, v21
	v_fma_f32 v19, v50, v51, v2
	v_fma_f32 v21, v52, v53, v3
	v_cvt_pk_bf16_f32 v179, v19, v21
	global_store_dwordx4 v[134:135], v[176:179], off offset:256
	ds_read_b32 v19, v129 offset:4160
	v_lshl_add_u64 v[112:113], s[0:1], 0, v[114:115]
	v_lshl_add_u64 v[112:113], v[112:113], 0, v[174:175]
	s_waitcnt lgkmcnt(0)
	v_mul_f32_e32 v21, v124, v19
	v_fma_f32 v21, v30, v21, v12
	v_mul_f32_e32 v23, v108, v19
	v_fma_f32 v23, v28, v23, v13
	v_cvt_pk_bf16_f32 v108, v21, v23
	v_mul_f32_e32 v21, v109, v19
	v_fma_f32 v21, v26, v21, v14
	v_mul_f32_e32 v23, v110, v19
	v_fma_f32 v23, v24, v23, v15
	v_cvt_pk_bf16_f32 v109, v21, v23
	v_mul_f32_e32 v21, v111, v19
	v_fma_f32 v21, v22, v21, v8
	v_mul_f32_e32 v23, v104, v19
	v_fma_f32 v23, v20, v23, v9
	v_cvt_pk_bf16_f32 v110, v21, v23
	v_mul_f32_e32 v21, v105, v19
	v_fma_f32 v21, v18, v21, v10
	v_mul_f32_e32 v23, v106, v19
	v_fma_f32 v23, v34, v23, v11
	v_cvt_pk_bf16_f32 v111, v21, v23
	v_mul_f32_e32 v21, v107, v19
	v_fma_f32 v21, v36, v21, v4
	v_mul_f32_e32 v23, v100, v19
	global_store_dwordx4 v[112:113], v[108:111], off
	v_fma_f32 v23, v38, v23, v5
	v_cvt_pk_bf16_f32 v100, v21, v23
	v_mul_f32_e32 v21, v101, v19
	v_fma_f32 v21, v40, v21, v6
	v_mul_f32_e32 v23, v102, v19
	v_fma_f32 v23, v42, v23, v7
	v_cvt_pk_bf16_f32 v101, v21, v23
	v_mul_f32_e32 v21, v103, v19
	v_fma_f32 v21, v44, v21, v0
	v_mul_f32_e32 v23, v125, v19
	v_fma_f32 v23, v46, v23, v1
	v_cvt_pk_bf16_f32 v102, v21, v23
	v_mul_f32_e32 v21, v126, v19
	v_mul_f32_e32 v19, v127, v19
	v_fma_f32 v21, v50, v21, v2
	v_fma_f32 v19, v52, v19, v3
	v_cvt_pk_bf16_f32 v103, v21, v19
	global_store_dwordx4 v[112:113], v[100:103], off offset:256
	ds_read_b32 v19, v129 offset:4224
	s_waitcnt lgkmcnt(0)
	v_mul_f32_e32 v21, v160, v19
	v_fma_f32 v21, v30, v21, v12
	v_mul_f32_e32 v23, v156, v19
	v_fma_f32 v23, v28, v23, v13
	v_cvt_pk_bf16_f32 v100, v21, v23
	v_mul_f32_e32 v21, v161, v19
	v_fma_f32 v21, v26, v21, v14
	v_mul_f32_e32 v23, v157, v19
	v_fma_f32 v23, v24, v23, v15
	v_cvt_pk_bf16_f32 v101, v21, v23
	v_mul_f32_e32 v21, v162, v19
	v_fma_f32 v21, v22, v21, v8
	v_mul_f32_e32 v23, v158, v19
	v_fma_f32 v23, v20, v23, v9
	v_cvt_pk_bf16_f32 v102, v21, v23
	v_mul_f32_e32 v21, v163, v19
	v_fma_f32 v21, v18, v21, v10
	v_mul_f32_e32 v23, v159, v19
	v_fma_f32 v23, v34, v23, v11
	v_cvt_pk_bf16_f32 v103, v21, v23
	v_mul_f32_e32 v21, v164, v19
	v_fma_f32 v21, v36, v21, v4
	v_mul_f32_e32 v23, v152, v19
	global_store_dwordx4 v[96:97], v[100:103], off
	v_fma_f32 v23, v38, v23, v5
	s_nop 0
	v_cvt_pk_bf16_f32 v100, v21, v23
	v_mul_f32_e32 v21, v165, v19
	v_fma_f32 v21, v40, v21, v6
	v_mul_f32_e32 v23, v153, v19
	v_fma_f32 v23, v42, v23, v7
	v_cvt_pk_bf16_f32 v101, v21, v23
	v_mul_f32_e32 v21, v166, v19
	v_fma_f32 v21, v44, v21, v0
	v_mul_f32_e32 v23, v154, v19
	v_fma_f32 v23, v46, v23, v1
	v_cvt_pk_bf16_f32 v102, v21, v23
	v_mul_f32_e32 v21, v167, v19
	v_mul_f32_e32 v19, v155, v19
	v_fma_f32 v21, v50, v21, v2
	v_fma_f32 v19, v52, v19, v3
	v_cvt_pk_bf16_f32 v103, v21, v19
	global_store_dwordx4 v[96:97], v[100:103], off offset:256
	ds_read_b32 v19, v129 offset:4288
	s_waitcnt lgkmcnt(0)
	v_mul_f32_e32 v21, v168, v19
	v_fma_f32 v21, v30, v21, v12
	v_mul_f32_e32 v23, v148, v19
	v_fma_f32 v23, v28, v23, v13
	v_cvt_pk_bf16_f32 v100, v21, v23
	v_mul_f32_e32 v21, v220, v19
	v_fma_f32 v21, v26, v21, v14
	v_mul_f32_e32 v23, v149, v19
	v_fma_f32 v23, v24, v23, v15
	v_cvt_pk_bf16_f32 v101, v21, v23
	v_mul_f32_e32 v21, v221, v19
	v_fma_f32 v21, v22, v21, v8
	v_mul_f32_e32 v23, v150, v19
	v_fma_f32 v23, v20, v23, v9
	v_cvt_pk_bf16_f32 v102, v21, v23
	v_mul_f32_e32 v21, v222, v19
	v_fma_f32 v21, v18, v21, v10
	v_mul_f32_e32 v23, v151, v19
	v_fma_f32 v23, v34, v23, v11
	v_cvt_pk_bf16_f32 v103, v21, v23
	v_mul_f32_e32 v21, v223, v19
	v_fma_f32 v21, v36, v21, v4
	v_mul_f32_e32 v23, v144, v19
	global_store_dwordx4 v[92:93], v[100:103], off
	v_fma_f32 v23, v38, v23, v5
	s_nop 0
	v_cvt_pk_bf16_f32 v100, v21, v23
	v_mul_f32_e32 v21, v224, v19
	v_fma_f32 v21, v40, v21, v6
	v_mul_f32_e32 v23, v145, v19
	v_fma_f32 v23, v42, v23, v7
	v_cvt_pk_bf16_f32 v101, v21, v23
	v_mul_f32_e32 v21, v225, v19
	v_fma_f32 v21, v44, v21, v0
	v_mul_f32_e32 v23, v146, v19
	v_fma_f32 v23, v46, v23, v1
	v_cvt_pk_bf16_f32 v102, v21, v23
	v_mul_f32_e32 v21, v226, v19
	v_mul_f32_e32 v19, v147, v19
	v_fma_f32 v21, v50, v21, v2
	v_fma_f32 v19, v52, v19, v3
	v_cvt_pk_bf16_f32 v103, v21, v19
	global_store_dwordx4 v[92:93], v[100:103], off offset:256
	ds_read_b32 v19, v129 offset:4608
	v_lshl_add_u64 v[92:93], s[0:1], 0, v[94:95]
	v_lshl_add_u64 v[92:93], v[92:93], 0, v[174:175]
	s_waitcnt lgkmcnt(0)
	v_mul_f32_e32 v21, v204, v19
	v_fma_f32 v21, v30, v21, v12
	v_mul_f32_e32 v23, v60, v19
	v_fma_f32 v23, v28, v23, v13
	v_cvt_pk_bf16_f32 v60, v21, v23
	v_mul_f32_e32 v21, v61, v19
	v_fma_f32 v21, v26, v21, v14
	v_mul_f32_e32 v23, v62, v19
	v_fma_f32 v23, v24, v23, v15
	v_cvt_pk_bf16_f32 v61, v21, v23
	v_mul_f32_e32 v21, v63, v19
	v_fma_f32 v21, v22, v21, v8
	v_mul_f32_e32 v23, v56, v19
	v_fma_f32 v23, v20, v23, v9
	v_cvt_pk_bf16_f32 v62, v21, v23
	v_mul_f32_e32 v21, v57, v19
	v_fma_f32 v21, v18, v21, v10
	v_mul_f32_e32 v23, v58, v19
	v_fma_f32 v23, v34, v23, v11
	v_cvt_pk_bf16_f32 v63, v21, v23
	v_mul_f32_e32 v21, v59, v19
	v_fma_f32 v21, v36, v21, v4
	v_mul_f32_e32 v23, v88, v19
	global_store_dwordx4 v[92:93], v[60:63], off
	v_fma_f32 v23, v38, v23, v5
	v_cvt_pk_bf16_f32 v56, v21, v23
	v_mul_f32_e32 v21, v205, v19
	v_fma_f32 v21, v40, v21, v6
	v_mul_f32_e32 v23, v54, v19
	v_fma_f32 v23, v42, v23, v7
	v_cvt_pk_bf16_f32 v57, v21, v23
	v_mul_f32_e32 v21, v55, v19
	v_fma_f32 v21, v44, v21, v0
	v_mul_f32_e32 v23, v89, v19
	v_fma_f32 v23, v46, v23, v1
	v_cvt_pk_bf16_f32 v58, v21, v23
	v_mul_f32_e32 v21, v90, v19
	v_mul_f32_e32 v19, v91, v19
	v_fma_f32 v21, v50, v21, v2
	v_fma_f32 v19, v52, v19, v3
	v_cvt_pk_bf16_f32 v59, v21, v19
	global_store_dwordx4 v[92:93], v[56:59], off offset:256
	ds_read_b32 v19, v129 offset:4672
	s_waitcnt lgkmcnt(0)
	v_mul_f32_e32 v21, v98, v19
	v_fma_f32 v21, v30, v21, v12
	v_mul_f32_e32 v23, v84, v19
	v_fma_f32 v23, v28, v23, v13
	v_cvt_pk_bf16_f32 v54, v21, v23
	v_mul_f32_e32 v21, v99, v19
	v_fma_f32 v21, v26, v21, v14
	v_mul_f32_e32 v23, v85, v19
	v_fma_f32 v23, v24, v23, v15
	v_cvt_pk_bf16_f32 v55, v21, v23
	v_mul_f32_e32 v21, v227, v19
	v_fma_f32 v21, v22, v21, v8
	v_mul_f32_e32 v23, v86, v19
	v_fma_f32 v23, v20, v23, v9
	v_cvt_pk_bf16_f32 v56, v21, v23
	v_mul_f32_e32 v21, v228, v19
	v_fma_f32 v21, v18, v21, v10
	v_mul_f32_e32 v23, v87, v19
	v_fma_f32 v23, v34, v23, v11
	v_cvt_pk_bf16_f32 v57, v21, v23
	v_mul_f32_e32 v21, v229, v19
	v_fma_f32 v21, v36, v21, v4
	v_mul_f32_e32 v23, v80, v19
	global_store_dwordx4 v[48:49], v[54:57], off
	v_fma_f32 v23, v38, v23, v5
	s_nop 0
	v_cvt_pk_bf16_f32 v54, v21, v23
	v_mul_f32_e32 v21, v230, v19
	v_fma_f32 v21, v40, v21, v6
	v_mul_f32_e32 v23, v81, v19
	v_fma_f32 v23, v42, v23, v7
	v_cvt_pk_bf16_f32 v55, v21, v23
	v_mul_f32_e32 v21, v231, v19
	v_fma_f32 v21, v44, v21, v0
	v_mul_f32_e32 v23, v82, v19
	v_fma_f32 v23, v46, v23, v1
	v_cvt_pk_bf16_f32 v56, v21, v23
	v_mul_f32_e32 v21, v232, v19
	v_mul_f32_e32 v19, v83, v19
	v_fma_f32 v21, v50, v21, v2
	v_fma_f32 v19, v52, v19, v3
	v_cvt_pk_bf16_f32 v57, v21, v19
	global_store_dwordx4 v[48:49], v[54:57], off offset:256
	ds_read_b32 v19, v129 offset:4736
	s_waitcnt lgkmcnt(0)
	v_mul_f32_e32 v21, v233, v19
	v_fma_f32 v21, v30, v21, v12
	v_mul_f32_e32 v23, v76, v19
	v_fma_f32 v23, v28, v23, v13
	v_cvt_pk_bf16_f32 v54, v21, v23
	v_mul_f32_e32 v21, v234, v19
	v_fma_f32 v21, v26, v21, v14
	v_mul_f32_e32 v23, v77, v19
	v_fma_f32 v23, v24, v23, v15
	v_cvt_pk_bf16_f32 v55, v21, v23
	v_mul_f32_e32 v21, v235, v19
	v_fma_f32 v21, v22, v21, v8
	v_mul_f32_e32 v23, v78, v19
	v_fma_f32 v23, v20, v23, v9
	v_cvt_pk_bf16_f32 v56, v21, v23
	v_mul_f32_e32 v21, v236, v19
	v_fma_f32 v21, v18, v21, v10
	v_mul_f32_e32 v23, v79, v19
	v_fma_f32 v23, v34, v23, v11
	v_cvt_pk_bf16_f32 v57, v21, v23
	v_mul_f32_e32 v21, v237, v19
	v_fma_f32 v21, v36, v21, v4
	v_mul_f32_e32 v23, v72, v19
	global_store_dwordx4 v[32:33], v[54:57], off
	v_fma_f32 v23, v38, v23, v5
	s_nop 0
	v_cvt_pk_bf16_f32 v54, v21, v23
	v_mul_f32_e32 v21, v238, v19
	v_fma_f32 v21, v40, v21, v6
	v_mul_f32_e32 v23, v73, v19
	v_fma_f32 v23, v42, v23, v7
	v_cvt_pk_bf16_f32 v55, v21, v23
	v_mul_f32_e32 v21, v239, v19
	v_fma_f32 v21, v44, v21, v0
	v_mul_f32_e32 v23, v74, v19
	v_fma_f32 v23, v46, v23, v1
	v_cvt_pk_bf16_f32 v56, v21, v23
	v_mul_f32_e32 v21, v240, v19
	v_mul_f32_e32 v19, v75, v19
	v_fma_f32 v21, v50, v21, v2
	v_fma_f32 v19, v52, v19, v3
	v_cvt_pk_bf16_f32 v57, v21, v19
	global_store_dwordx4 v[32:33], v[54:57], off offset:256
	ds_read_b32 v19, v129 offset:4800
	s_waitcnt lgkmcnt(0)
	v_mul_f32_e32 v21, v202, v19
	v_fma_f32 v12, v30, v21, v12
	v_mul_f32_e32 v21, v68, v19
	v_fma_f32 v13, v28, v21, v13
	v_cvt_pk_bf16_f32 v12, v12, v13
	v_mul_f32_e32 v13, v140, v19
	v_fma_f32 v13, v26, v13, v14
	v_mul_f32_e32 v14, v141, v19
	v_fmac_f32_e32 v15, v24, v14
	v_mul_f32_e32 v14, v69, v19
	v_fma_f32 v8, v22, v14, v8
	v_mul_f32_e32 v14, v70, v19
	v_cvt_pk_bf16_f32 v13, v13, v15
	v_fma_f32 v9, v20, v14, v9
	v_cvt_pk_bf16_f32 v14, v8, v9
	v_mul_f32_e32 v8, v136, v19
	v_fma_f32 v8, v18, v8, v10
	v_mul_f32_e32 v9, v71, v19
	v_fmac_f32_e32 v11, v34, v9
	v_cvt_pk_bf16_f32 v15, v8, v11
	v_mul_f32_e32 v8, v137, v19
	v_fma_f32 v4, v36, v8, v4
	v_mul_f32_e32 v8, v64, v19
	v_fma_f32 v5, v38, v8, v5
	global_store_dwordx4 v[16:17], v[12:15], off
	v_cvt_pk_bf16_f32 v4, v4, v5
	v_mul_f32_e32 v5, v132, v19
	v_fma_f32 v5, v40, v5, v6
	v_mul_f32_e32 v6, v133, v19
	v_fmac_f32_e32 v7, v42, v6
	v_mul_f32_e32 v6, v65, v19
	v_fma_f32 v0, v44, v6, v0
	v_mul_f32_e32 v6, v66, v19
	v_fma_f32 v1, v46, v6, v1
	v_cvt_pk_bf16_f32 v5, v5, v7
	v_cvt_pk_bf16_f32 v6, v0, v1
	v_mul_f32_e32 v0, v128, v19
	v_mul_f32_e32 v1, v67, v19
	v_fma_f32 v0, v50, v0, v2
	v_fmac_f32_e32 v3, v52, v1
	v_cvt_pk_bf16_f32 v7, v0, v3
	global_store_dwordx4 v[16:17], v[4:7], off offset:256

.LBB0_714:
	s_add_i32 s34, s70, s9
	s_cmpk_lt_i32 s34, 0x4000
	s_cselect_b32 s0, s34, 0x3fff
	s_ashr_i32 s1, s0, 31
	s_lshl_b64 s[22:23], s[0:1], 11
	s_add_i32 s16, s67, s9
	s_cmpk_lt_i32 s16, 0x4000
	s_cselect_b64 s[24:25], -1, 0
	s_and_b64 s[0:1], s[24:25], exec
	v_lshl_add_u64 v[0:1], s[14:15], 0, v[56:57]
	s_cselect_b32 s0, s16, 0x3fff
	global_load_dwordx2 v[46:47], v[0:1], off offset:512
	global_load_dwordx2 v[48:49], v[0:1], off offset:1024
	s_ashr_i32 s1, s0, 31
	s_add_i32 s16, s72, s9
	s_lshl_b64 s[20:21], s[0:1], 11
	v_lshl_add_u64 v[2:3], v[36:37], 0, s[22:23]
	s_cmpk_lt_i32 s16, 0x4000
	global_load_dwordx2 v[54:55], v[2:3], off
	global_load_dwordx4 v[50:53], v[34:35], off
	global_load_dwordx4 v[24:27], v[34:35], off offset:1024
	global_load_dwordx2 v[70:71], v[2:3], off offset:512
	global_load_dwordx4 v[20:23], v[34:35], off offset:2048
	global_load_dwordx4 v[16:19], v[34:35], off offset:3072
	global_load_dwordx2 v[108:109], v[0:1], off offset:1536
	global_load_dwordx2 v[112:113], v[0:1], off
	global_load_dwordx2 v[72:73], v[2:3], off offset:1024
	s_cselect_b64 s[18:19], -1, 0
	global_load_dwordx2 v[74:75], v[2:3], off offset:1536
	s_and_b64 s[0:1], s[18:19], exec
	s_cselect_b32 s0, s16, 0x3fff
	s_ashr_i32 s16, s9, 13
	v_lshl_add_u64 v[0:1], v[36:37], 0, s[20:21]
	s_mul_i32 s30, s16, 0x1800
	global_load_dwordx2 v[76:77], v[0:1], off
	global_load_dwordx2 v[78:79], v[0:1], off offset:512
	global_load_dwordx2 v[126:127], v[0:1], off offset:1024
	global_load_dwordx2 v[128:129], v[0:1], off offset:1536
	s_ashr_i32 s1, s0, 31
	s_ashr_i32 s31, s30, 31
	s_lshl_b64 s[16:17], s[0:1], 11
	s_lshl_b64 s[0:1], s[30:31], 2
	s_add_u32 s30, s28, s0
	s_addc_u32 s31, s29, s1
	v_lshl_add_u64 v[0:1], v[36:37], 0, s[16:17]
	s_add_u32 s0, s30, 0x3000
	global_load_dwordx2 v[130:131], v[0:1], off
	global_load_dwordx2 v[132:133], v[0:1], off offset:512
	global_load_dwordx2 v[134:135], v[0:1], off offset:1024
	global_load_dwordx2 v[136:137], v[0:1], off offset:1536
	s_addc_u32 s1, s31, 0
	s_add_u32 s30, s30, 0x4000
	s_waitcnt lgkmcnt(0)
	v_mov_b32_e32 v41, v169
	v_mov_b32_e32 v43, v169
	v_mov_b32_e32 v45, v169
	s_addc_u32 s31, s31, 0
	v_lshl_add_u64 v[0:1], s[0:1], 0, v[168:169]
	v_lshl_add_u64 v[2:3], s[0:1], 0, v[40:41]
	v_lshl_add_u64 v[4:5], s[0:1], 0, v[42:43]
	v_lshl_add_u64 v[6:7], s[30:31], 0, v[168:169]
	v_lshl_add_u64 v[8:9], s[30:31], 0, v[40:41]
	v_lshl_add_u64 v[28:29], s[30:31], 0, v[42:43]
	v_lshl_add_u64 v[30:31], s[30:31], 0, v[44:45]
	v_lshl_add_u64 v[80:81], s[0:1], 0, v[44:45]
	flat_load_dwordx4 v[58:61], v[6:7]
	flat_load_dwordx4 v[12:15], v[0:1]
	flat_load_dwordx4 v[62:65], v[8:9]
	s_nop 0
	flat_load_dwordx4 v[8:11], v[2:3]
	flat_load_dwordx4 v[66:69], v[28:29]
	s_nop 0
	flat_load_dwordx4 v[4:7], v[4:5]
	s_nop 0
	flat_load_dwordx4 v[28:31], v[30:31]
	s_nop 0
	flat_load_dwordx4 v[0:3], v[80:81]
	s_cmpk_gt_i32 s34, 0x3fff
	s_waitcnt vmcnt(0)
	v_and_b32_e32 v105, 0xffff0000, v47
	v_and_b32_e32 v104, 0xffff0000, v46
	v_lshlrev_b32_e32 v107, 16, v47
	v_lshlrev_b32_e32 v106, 16, v46
	v_pk_mul_f32 v[46:47], v[104:105], v[104:105]
	v_and_b32_e32 v111, 0xffff0000, v48
	v_pk_fma_f32 v[46:47], v[106:107], v[106:107], v[46:47]
	v_and_b32_e32 v103, 0xffff0000, v49
	v_lshlrev_b32_e32 v110, 16, v48
	v_lshlrev_b32_e32 v102, 16, v49
	v_mul_f32_e32 v48, v111, v111
	v_pk_add_f32 v[114:115], v[46:47], v[46:47] op_sel:[0,1] op_sel_hi:[1,0]
	v_mul_f32_e32 v46, v103, v103
	v_and_b32_e32 v99, 0xffff0000, v55
	v_and_b32_e32 v98, 0xffff0000, v54
	v_and_b32_e32 v95, 0xffff0000, v71
	v_and_b32_e32 v94, 0xffff0000, v70
	v_pk_fma_f32 v[116:117], v[110:111], v[110:111], v[48:49] op_sel_hi:[1,1,0]
	v_pk_fma_f32 v[118:119], v[102:103], v[102:103], v[46:47] op_sel_hi:[1,1,0]
	v_lshlrev_b32_e32 v101, 16, v55
	v_lshlrev_b32_e32 v100, 16, v54
	v_pk_mul_f32 v[46:47], v[98:99], v[98:99]
	v_lshlrev_b32_e32 v97, 16, v71
	v_lshlrev_b32_e32 v96, 16, v70
	v_pk_mul_f32 v[48:49], v[94:95], v[94:95]
	v_and_b32_e32 v91, 0xffff0000, v73
	v_and_b32_e32 v90, 0xffff0000, v72
	v_pk_fma_f32 v[46:47], v[100:101], v[100:101], v[46:47]
	v_pk_fma_f32 v[48:49], v[96:97], v[96:97], v[48:49]
	v_lshlrev_b32_e32 v93, 16, v73
	v_lshlrev_b32_e32 v92, 16, v72
	v_pk_mul_f32 v[54:55], v[90:91], v[90:91]
	v_and_b32_e32 v87, 0xffff0000, v75
	v_and_b32_e32 v86, 0xffff0000, v74
	v_pk_fma_f32 v[54:55], v[92:93], v[92:93], v[54:55]
	v_lshlrev_b32_e32 v89, 16, v75
	v_lshlrev_b32_e32 v88, 16, v74
	v_pk_mul_f32 v[70:71], v[86:87], v[86:87]
	v_add_f32_e32 v33, v48, v49
	v_add_f32_e32 v41, v46, v47
	v_and_b32_e32 v83, 0xffff0000, v77
	v_and_b32_e32 v82, 0xffff0000, v76
	v_lshlrev_b32_e32 v81, 16, v79
	v_lshlrev_b32_e32 v80, 16, v78
	v_and_b32_e32 v79, 0xffff0000, v79
	v_and_b32_e32 v78, 0xffff0000, v78
	v_pk_fma_f32 v[70:71], v[88:89], v[88:89], v[70:71]
	v_add_f32_e32 v33, v41, v33
	v_add_f32_e32 v41, v54, v55
	v_lshlrev_b32_e32 v85, 16, v77
	v_lshlrev_b32_e32 v84, 16, v76
	v_pk_mul_f32 v[46:47], v[82:83], v[82:83]
	v_pk_mul_f32 v[48:49], v[78:79], v[78:79]
	v_and_b32_e32 v75, 0xffff0000, v127
	v_and_b32_e32 v74, 0xffff0000, v126
	v_add_f32_e32 v33, v33, v41
	v_add_f32_e32 v41, v70, v71
	v_pk_fma_f32 v[46:47], v[84:85], v[84:85], v[46:47]
	v_pk_fma_f32 v[48:49], v[80:81], v[80:81], v[48:49]
	v_lshlrev_b32_e32 v77, 16, v127
	v_lshlrev_b32_e32 v76, 16, v126
	v_pk_mul_f32 v[54:55], v[74:75], v[74:75]
	v_and_b32_e32 v71, 0xffff0000, v129
	v_and_b32_e32 v70, 0xffff0000, v128
	v_add_f32_e32 v33, v33, v41
	v_pk_fma_f32 v[54:55], v[76:77], v[76:77], v[54:55]
	v_lshlrev_b32_e32 v73, 16, v129
	v_lshlrev_b32_e32 v72, 16, v128
	v_pk_mul_f32 v[126:127], v[70:71], v[70:71]
	v_add_f32_e32 v41, v48, v49
	v_add_f32_e32 v43, v46, v47
	v_pk_fma_f32 v[126:127], v[72:73], v[72:73], v[126:127]
	v_add_f32_e32 v41, v43, v41
	v_add_f32_e32 v43, v54, v55
	v_and_b32_e32 v47, 0xffff0000, v131
	v_and_b32_e32 v46, 0xffff0000, v130
	s_waitcnt lgkmcnt(0)
	v_mov_b32_e32 v54, v58
	v_mov_b32_e32 v55, v60
	v_add_f32_e32 v41, v41, v43
	v_add_f32_e32 v43, v126, v127
	v_lshlrev_b32_e32 v49, 16, v131
	v_lshlrev_b32_e32 v48, 16, v130
	v_pk_add_f32 v[54:55], v[54:55], 1.0 op_sel_hi:[1,0]
	v_mov_b32_e32 v126, v50
	v_mov_b32_e32 v127, v52
	v_mov_b32_e32 v60, v59
	v_mov_b32_e32 v52, v51
	v_pk_mul_f32 v[50:51], v[46:47], v[46:47]
	v_pk_mul_f32 v[54:55], v[126:127], v[54:55]
	v_pk_add_f32 v[58:59], v[60:61], 1.0 op_sel_hi:[1,0]
	v_pk_fma_f32 v[126:127], v[48:49], v[48:49], v[50:51]
	v_and_b32_e32 v51, 0xffff0000, v133
	v_and_b32_e32 v50, 0xffff0000, v132
	v_mov_b32_e32 v60, v62
	v_mov_b32_e32 v61, v64
	v_pk_mul_f32 v[58:59], v[52:53], v[58:59]
	v_lshlrev_b32_e32 v53, 16, v133
	v_lshlrev_b32_e32 v52, 16, v132
	v_pk_add_f32 v[60:61], v[60:61], 1.0 op_sel_hi:[1,0]
	v_mov_b32_e32 v128, v24
	v_mov_b32_e32 v129, v26
	v_mov_b32_e32 v26, v25
	v_pk_mul_f32 v[24:25], v[50:51], v[50:51]
	v_pk_mul_f32 v[60:61], v[128:129], v[60:61]
	v_pk_fma_f32 v[128:129], v[52:53], v[52:53], v[24:25]
	v_mov_b32_e32 v64, v63
	v_mov_b32_e32 v132, v16
	v_mov_b32_e32 v133, v18
	v_add_f32_e32 v16, v128, v129
	v_add_f32_e32 v18, v126, v127
	v_pk_add_f32 v[62:63], v[64:65], 1.0 op_sel_hi:[1,0]
	v_and_b32_e32 v25, 0xffff0000, v135
	v_and_b32_e32 v24, 0xffff0000, v134
	v_mov_b32_e32 v64, v66
	v_mov_b32_e32 v65, v68
	v_mov_b32_e32 v68, v67
	v_add_f32_e32 v16, v18, v16
	ds_bpermute_b32 v18, v120, v33
	v_pk_mul_f32 v[62:63], v[26:27], v[62:63]
	v_lshlrev_b32_e32 v27, 16, v135
	v_lshlrev_b32_e32 v26, 16, v134
	v_pk_add_f32 v[64:65], v[64:65], 1.0 op_sel_hi:[1,0]
	v_mov_b32_e32 v130, v20
	v_mov_b32_e32 v131, v22
	v_pk_add_f32 v[66:67], v[68:69], 1.0 op_sel_hi:[1,0]
	v_mov_b32_e32 v22, v21
	v_pk_mul_f32 v[20:21], v[24:25], v[24:25]
	v_mov_b32_e32 v68, v28
	v_mov_b32_e32 v69, v30
	v_pk_mul_f32 v[64:65], v[130:131], v[64:65]
	v_pk_fma_f32 v[130:131], v[26:27], v[26:27], v[20:21]
	v_and_b32_e32 v21, 0xffff0000, v137
	v_and_b32_e32 v20, 0xffff0000, v136
	v_pk_add_f32 v[68:69], v[68:69], 1.0 op_sel_hi:[1,0]
	v_pk_mul_f32 v[66:67], v[22:23], v[66:67]
	v_lshlrev_b32_e32 v23, 16, v137
	v_lshlrev_b32_e32 v22, 16, v136
	v_pk_mul_f32 v[68:69], v[132:133], v[68:69]
	v_pk_mul_f32 v[132:133], v[20:21], v[20:21]
	v_add_f32_e32 v41, v41, v43
	v_pk_fma_f32 v[132:133], v[22:23], v[22:23], v[132:133]
	v_add_f32_e32 v28, v130, v131
	v_add_f32_e32 v16, v16, v28
	v_add_f32_e32 v28, v132, v133
	s_waitcnt lgkmcnt(0)
	v_add_f32_e32 v18, v33, v18
	ds_bpermute_b32 v33, v120, v41
	v_add_f32_e32 v16, v16, v28
	ds_bpermute_b32 v43, v120, v16
	ds_bpermute_b32 v45, v121, v18
	v_mov_b32_e32 v30, v29
	v_pk_add_f32 v[28:29], v[30:31], 1.0 op_sel_hi:[1,0]
	s_waitcnt lgkmcnt(2)
	v_add_f32_e32 v30, v41, v33
	ds_bpermute_b32 v41, v121, v30
	s_waitcnt lgkmcnt(2)
	v_add_f32_e32 v31, v16, v43
	ds_bpermute_b32 v43, v121, v31
	s_waitcnt lgkmcnt(2)
	v_add_f32_e32 v33, v18, v45
	v_mov_b32_e32 v18, v17
	v_lshlrev_b32_e32 v126, 16, v112
	v_and_b32_e32 v112, 0xffff0000, v112
	v_pk_mul_f32 v[16:17], v[18:19], v[28:29]
	v_lshlrev_b32_e32 v127, 16, v113
	v_and_b32_e32 v113, 0xffff0000, v113
	v_mov_b32_e32 v18, v126
	v_mov_b32_e32 v19, v112
	v_mul_f32_e32 v28, v112, v112
	s_waitcnt lgkmcnt(1)
	v_add_f32_e32 v41, v30, v41
	v_pk_fma_f32 v[18:19], v[18:19], v[18:19], v[28:29] op_sel_hi:[1,1,0]
	v_mov_b32_e32 v28, v127
	v_mov_b32_e32 v29, v113
	v_mul_f32_e32 v30, v113, v113
	v_pk_fma_f32 v[28:29], v[28:29], v[28:29], v[30:31] op_sel_hi:[1,1,0]
	v_lshlrev_b32_e32 v129, 16, v109
	v_lshlrev_b32_e32 v128, 16, v108
	v_and_b32_e32 v109, 0xffff0000, v109
	v_and_b32_e32 v108, 0xffff0000, v108
	s_waitcnt lgkmcnt(0)
	v_add_f32_e32 v43, v31, v43
	v_pk_mul_f32 v[30:31], v[108:109], v[108:109]
	v_pk_mul_f32 v[130:131], v[128:129], v[128:129]
	v_pk_add_f32 v[18:19], v[18:19], v[28:29]
	v_mov_b32_e32 v117, v131
	v_mov_b32_e32 v119, v31
	v_mov_b32_e32 v19, v130
	v_mov_b32_e32 v115, v30
	v_pk_add_f32 v[116:117], v[116:117], v[118:119]
	v_pk_add_f32 v[18:19], v[18:19], v[114:115]
	ds_bpermute_b32 v45, v122, v33
	v_pk_add_f32 v[18:19], v[18:19], v[116:117]
	ds_bpermute_b32 v132, v122, v43
	v_add_f32_e32 v18, v18, v19
	ds_bpermute_b32 v19, v120, v18
	s_waitcnt lgkmcnt(2)
	v_add_f32_e32 v33, v33, v45
	ds_bpermute_b32 v45, v122, v41
	ds_bpermute_b32 v29, v123, v33
	s_waitcnt lgkmcnt(3)
	v_add_f32_e32 v30, v43, v132
	s_waitcnt lgkmcnt(2)
	v_add_f32_e32 v18, v18, v19
	ds_bpermute_b32 v19, v121, v18
	s_waitcnt lgkmcnt(2)
	v_add_f32_e32 v28, v41, v45
	ds_bpermute_b32 v31, v123, v28
	s_waitcnt lgkmcnt(2)
	v_add_f32_e32 v29, v33, v29
	ds_bpermute_b32 v33, v123, v30
	s_waitcnt lgkmcnt(2)
	v_add_f32_e32 v18, v18, v19
	ds_bpermute_b32 v19, v122, v18
	s_waitcnt lgkmcnt(2)
	v_add_f32_e32 v28, v28, v31
	v_mov_b32_e32 v116, v110
	s_waitcnt lgkmcnt(1)
	v_add_f32_e32 v41, v30, v33
	ds_bpermute_b32 v30, v124, v28
	s_waitcnt lgkmcnt(1)
	v_add_f32_e32 v18, v18, v19
	ds_bpermute_b32 v43, v124, v41
	ds_bpermute_b32 v19, v123, v18
	v_mov_b32_e32 v117, v102
	s_waitcnt lgkmcnt(2)
	v_add_f32_e32 v30, v28, v30
	v_mov_b32_e32 v102, v111
	s_waitcnt lgkmcnt(1)
	v_add_f32_e32 v28, v41, v43
	s_waitcnt lgkmcnt(0)
	v_add_f32_e32 v43, v18, v19
	ds_bpermute_b32 v45, v124, v43
	v_mov_b32_e32 v18, v12
	v_mov_b32_e32 v12, v8
	v_mov_b32_e32 v19, v14
	v_mov_b32_e32 v14, v13
	s_waitcnt lgkmcnt(0)
	v_add_f32_e32 v43, v43, v45
	ds_bpermute_b32 v45, v125, v43
	v_mov_b32_e32 v13, v10
	v_mov_b32_e32 v10, v9
	v_lshl_add_u64 v[114:115], s[2:3], 0, v[56:57]
	ds_bpermute_b32 v31, v124, v29
	s_waitcnt lgkmcnt(1)
	v_add_f32_e32 v8, v43, v45
	v_fmamk_f32 v8, v8, 0x3a800000, v206
	v_mul_f32_e32 v9, 0x4f800000, v8
	v_cmp_gt_f32_e32 vcc, s57, v8
	s_waitcnt lgkmcnt(0)
	v_add_f32_e32 v33, v29, v31
	ds_bpermute_b32 v41, v125, v33
	v_cndmask_b32_e32 v9, v8, v9, vcc
	v_sqrt_f32_e32 v43, v9
	v_mov_b32_e32 v8, v4
	ds_bpermute_b32 v31, v125, v30
	ds_bpermute_b32 v29, v125, v28
	v_add_u32_e32 v4, -1, v43
	v_fma_f32 v45, -v4, v43, v9
	v_cmp_ge_f32_e64 s[0:1], 0, v45
	v_add_u32_e32 v45, 1, v43
	s_nop 0
	v_cndmask_b32_e64 v4, v43, v4, s[0:1]
	v_fma_f32 v43, -v45, v43, v9
	v_cmp_lt_f32_e64 s[0:1], 0, v43
	s_nop 1
	v_cndmask_b32_e64 v4, v4, v45, s[0:1]
	v_mul_f32_e32 v43, 0x37800000, v4
	v_cndmask_b32_e32 v4, v4, v43, vcc
	v_cmp_class_f32_e32 vcc, v9, v207
	s_nop 1
	v_cndmask_b32_e32 v4, v4, v9, vcc
	v_div_scale_f32 v43, s[0:1], v4, v4, 1.0
	v_rcp_f32_e32 v45, v43
	v_mov_b32_e32 v9, v6
	v_mov_b32_e32 v6, v5
	s_mov_b32 s0, 0x3200000
	v_fma_f32 v5, -v43, v45, 1.0
	v_fmac_f32_e32 v45, v5, v45
	v_div_scale_f32 v5, vcc, 1.0, v4, 1.0
	v_mul_f32_e32 v110, v5, v45
	v_fma_f32 v111, -v43, v110, v5
	v_fmac_f32_e32 v110, v111, v45
	v_fma_f32 v5, -v43, v110, v5
	v_div_fmas_f32 v5, v5, v45, v110
	v_div_fixup_f32 v110, v5, v4, 1.0
	v_pk_mul_f32 v[4:5], v[110:111], v[126:127] op_sel_hi:[0,1]
	v_pk_fma_f32 v[4:5], v[54:55], v[4:5], v[18:19]
	v_pk_mul_f32 v[112:113], v[110:111], v[112:113] op_sel_hi:[0,1]
	v_pk_fma_f32 v[112:113], v[58:59], v[112:113], v[14:15]
	v_and_b32_sdwa v43, v5, v209 dst_sel:DWORD dst_unused:UNUSED_PAD src0_sel:WORD_1 src1_sel:DWORD
	v_and_b32_sdwa v45, v4, v209 dst_sel:DWORD dst_unused:UNUSED_PAD src0_sel:WORD_1 src1_sel:DWORD
	v_add3_u32 v4, v4, v45, s77
	v_add3_u32 v5, v5, v43, s77
	v_and_b32_sdwa v43, v113, v209 dst_sel:DWORD dst_unused:UNUSED_PAD src0_sel:WORD_1 src1_sel:DWORD
	v_and_b32_sdwa v45, v112, v209 dst_sel:DWORD dst_unused:UNUSED_PAD src0_sel:WORD_1 src1_sel:DWORD
	v_add3_u32 v43, v113, v43, s77
	v_add3_u32 v45, v112, v45, s77
	v_and_b32_e32 v43, 0xffff0000, v43
	v_and_b32_e32 v45, 0xffff0000, v45
	v_add_co_u32_e32 v112, vcc, s0, v114
	v_or_b32_sdwa v5, v43, v5 dst_sel:DWORD dst_unused:UNUSED_PAD src0_sel:DWORD src1_sel:WORD_1
	v_or_b32_sdwa v4, v45, v4 dst_sel:DWORD dst_unused:UNUSED_PAD src0_sel:DWORD src1_sel:WORD_1
	v_addc_co_u32_e32 v113, vcc, 0, v115, vcc
	global_store_dwordx2 v[112:113], v[4:5], off
	v_pk_mul_f32 v[4:5], v[110:111], v[106:107] op_sel_hi:[0,1]
	v_pk_fma_f32 v[4:5], v[60:61], v[4:5], v[12:13]
	v_pk_mul_f32 v[104:105], v[110:111], v[104:105] op_sel_hi:[0,1]
	v_pk_fma_f32 v[104:105], v[62:63], v[104:105], v[10:11]
	v_and_b32_sdwa v43, v5, v209 dst_sel:DWORD dst_unused:UNUSED_PAD src0_sel:WORD_1 src1_sel:DWORD
	v_and_b32_sdwa v45, v4, v209 dst_sel:DWORD dst_unused:UNUSED_PAD src0_sel:WORD_1 src1_sel:DWORD
	v_add3_u32 v4, v4, v45, s77
	v_add3_u32 v5, v5, v43, s77
	v_and_b32_sdwa v43, v105, v209 dst_sel:DWORD dst_unused:UNUSED_PAD src0_sel:WORD_1 src1_sel:DWORD
	v_and_b32_sdwa v45, v104, v209 dst_sel:DWORD dst_unused:UNUSED_PAD src0_sel:WORD_1 src1_sel:DWORD
	v_add3_u32 v43, v105, v43, s77
	v_add3_u32 v45, v104, v45, s77
	v_and_b32_e32 v43, 0xffff0000, v43
	v_and_b32_e32 v45, 0xffff0000, v45
	v_or_b32_sdwa v5, v43, v5 dst_sel:DWORD dst_unused:UNUSED_PAD src0_sel:DWORD src1_sel:WORD_1
	v_or_b32_sdwa v4, v45, v4 dst_sel:DWORD dst_unused:UNUSED_PAD src0_sel:DWORD src1_sel:WORD_1
	global_store_dwordx2 v[112:113], v[4:5], off offset:512
	v_pk_mul_f32 v[4:5], v[110:111], v[116:117] op_sel_hi:[0,1]
	v_pk_fma_f32 v[4:5], v[64:65], v[4:5], v[8:9]
	v_pk_mul_f32 v[102:103], v[110:111], v[102:103] op_sel_hi:[0,1]
	v_pk_fma_f32 v[102:103], v[66:67], v[102:103], v[6:7]
	v_and_b32_sdwa v43, v5, v209 dst_sel:DWORD dst_unused:UNUSED_PAD src0_sel:WORD_1 src1_sel:DWORD
	v_and_b32_sdwa v45, v4, v209 dst_sel:DWORD dst_unused:UNUSED_PAD src0_sel:WORD_1 src1_sel:DWORD
	v_add3_u32 v4, v4, v45, s77
	v_add3_u32 v5, v5, v43, s77
	v_and_b32_sdwa v43, v103, v209 dst_sel:DWORD dst_unused:UNUSED_PAD src0_sel:WORD_1 src1_sel:DWORD
	v_and_b32_sdwa v45, v102, v209 dst_sel:DWORD dst_unused:UNUSED_PAD src0_sel:WORD_1 src1_sel:DWORD
	v_add3_u32 v43, v103, v43, s77
	v_add3_u32 v45, v102, v45, s77
	v_and_b32_e32 v43, 0xffff0000, v43
	v_and_b32_e32 v45, 0xffff0000, v45
	v_or_b32_sdwa v5, v43, v5 dst_sel:DWORD dst_unused:UNUSED_PAD src0_sel:DWORD src1_sel:WORD_1
	v_or_b32_sdwa v4, v45, v4 dst_sel:DWORD dst_unused:UNUSED_PAD src0_sel:DWORD src1_sel:WORD_1
	global_store_dwordx2 v[112:113], v[4:5], off offset:1024
	v_pk_mul_f32 v[102:103], v[110:111], v[128:129] op_sel_hi:[0,1]
	v_mov_b32_e32 v4, v0
	v_mov_b32_e32 v5, v2
	v_pk_fma_f32 v[102:103], v[68:69], v[102:103], v[4:5]
	v_pk_mul_f32 v[104:105], v[110:111], v[108:109] op_sel_hi:[0,1]
	v_mov_b32_e32 v2, v1
	v_pk_fma_f32 v[0:1], v[16:17], v[104:105], v[2:3]
	v_and_b32_sdwa v43, v103, v209 dst_sel:DWORD dst_unused:UNUSED_PAD src0_sel:WORD_1 src1_sel:DWORD
	v_and_b32_sdwa v45, v102, v209 dst_sel:DWORD dst_unused:UNUSED_PAD src0_sel:WORD_1 src1_sel:DWORD
	v_add3_u32 v45, v102, v45, s77
	v_add3_u32 v43, v103, v43, s77
	v_and_b32_sdwa v102, v1, v209 dst_sel:DWORD dst_unused:UNUSED_PAD src0_sel:WORD_1 src1_sel:DWORD
	v_and_b32_sdwa v103, v0, v209 dst_sel:DWORD dst_unused:UNUSED_PAD src0_sel:WORD_1 src1_sel:DWORD
	v_add3_u32 v1, v1, v102, s77
	v_add3_u32 v0, v0, v103, s77
	v_and_b32_e32 v1, 0xffff0000, v1
	v_and_b32_e32 v0, 0xffff0000, v0
	v_or_b32_sdwa v1, v1, v43 dst_sel:DWORD dst_unused:UNUSED_PAD src0_sel:DWORD src1_sel:WORD_1
	v_or_b32_sdwa v0, v0, v45 dst_sel:DWORD dst_unused:UNUSED_PAD src0_sel:DWORD src1_sel:WORD_1
	global_store_dwordx2 v[112:113], v[0:1], off offset:1536
	s_cbranch_scc0 .LBB0_717
	s_andn2_b64 vcc, exec, s[24:25]
	s_cbranch_vccz .LBB0_718

.LBB0_717:
	s_waitcnt lgkmcnt(0)
	v_add_f32_e32 v0, v33, v41
	v_fmamk_f32 v0, v0, 0x3a800000, v206
	v_mul_f32_e32 v1, 0x4f800000, v0
	v_cmp_gt_f32_e32 vcc, s57, v0
	s_nop 1
	v_cndmask_b32_e32 v0, v0, v1, vcc
	v_sqrt_f32_e32 v1, v0
	s_nop 0
	v_add_u32_e32 v33, -1, v1
	v_fma_f32 v43, -v33, v1, v0
	v_add_u32_e32 v41, 1, v1
	v_cmp_ge_f32_e64 s[0:1], 0, v43
	s_nop 1
	v_cndmask_b32_e64 v33, v1, v33, s[0:1]
	v_fma_f32 v1, -v41, v1, v0
	v_cmp_lt_f32_e64 s[0:1], 0, v1
	s_nop 1
	v_cndmask_b32_e64 v1, v33, v41, s[0:1]
	v_mul_f32_e32 v33, 0x37800000, v1
	v_cndmask_b32_e32 v1, v1, v33, vcc
	v_cmp_class_f32_e32 vcc, v0, v207
	s_nop 1
	v_cndmask_b32_e32 v0, v1, v0, vcc
	v_div_scale_f32 v1, s[0:1], v0, v0, 1.0
	v_rcp_f32_e32 v33, v1
	s_nop 0
	v_fma_f32 v41, -v1, v33, 1.0
	v_fmac_f32_e32 v33, v41, v33
	v_div_scale_f32 v41, vcc, 1.0, v0, 1.0
	v_mul_f32_e32 v43, v41, v33
	v_fma_f32 v45, -v1, v43, v41
	v_fmac_f32_e32 v43, v45, v33
	v_fma_f32 v1, -v1, v43, v41
	v_div_fmas_f32 v1, v1, v33, v43
	v_div_fixup_f32 v0, v1, v0, 1.0
	v_pk_mul_f32 v[100:101], v[0:1], v[100:101] op_sel_hi:[0,1]
	v_pk_fma_f32 v[100:101], v[54:55], v[100:101], v[18:19]
	v_pk_mul_f32 v[98:99], v[0:1], v[98:99] op_sel_hi:[0,1]
	v_pk_fma_f32 v[98:99], v[58:59], v[98:99], v[14:15]
	v_and_b32_sdwa v1, v101, v209 dst_sel:DWORD dst_unused:UNUSED_PAD src0_sel:WORD_1 src1_sel:DWORD
	v_add3_u32 v1, v101, v1, s77
	v_and_b32_sdwa v41, v99, v209 dst_sel:DWORD dst_unused:UNUSED_PAD src0_sel:WORD_1 src1_sel:DWORD
	v_add3_u32 v41, v99, v41, s77
	v_pk_mul_f32 v[96:97], v[0:1], v[96:97] op_sel_hi:[0,1]
	v_and_b32_e32 v41, 0xffff0000, v41
	v_pk_fma_f32 v[96:97], v[60:61], v[96:97], v[12:13]
	v_pk_mul_f32 v[94:95], v[0:1], v[94:95] op_sel_hi:[0,1]
	v_and_b32_sdwa v43, v98, v209 dst_sel:DWORD dst_unused:UNUSED_PAD src0_sel:WORD_1 src1_sel:DWORD
	v_or_b32_sdwa v99, v41, v1 dst_sel:DWORD dst_unused:UNUSED_PAD src0_sel:DWORD src1_sel:WORD_1
	v_pk_fma_f32 v[94:95], v[62:63], v[94:95], v[10:11]
	v_and_b32_sdwa v1, v97, v209 dst_sel:DWORD dst_unused:UNUSED_PAD src0_sel:WORD_1 src1_sel:DWORD
	v_and_b32_sdwa v33, v100, v209 dst_sel:DWORD dst_unused:UNUSED_PAD src0_sel:WORD_1 src1_sel:DWORD
	v_add3_u32 v43, v98, v43, s77
	v_add3_u32 v1, v97, v1, s77
	v_and_b32_sdwa v41, v95, v209 dst_sel:DWORD dst_unused:UNUSED_PAD src0_sel:WORD_1 src1_sel:DWORD
	v_add3_u32 v33, v100, v33, s77
	v_and_b32_e32 v43, 0xffff0000, v43
	v_add3_u32 v41, v95, v41, s77
	v_pk_mul_f32 v[90:91], v[0:1], v[90:91] op_sel_hi:[0,1]
	v_or_b32_sdwa v98, v43, v33 dst_sel:DWORD dst_unused:UNUSED_PAD src0_sel:DWORD src1_sel:WORD_1
	v_and_b32_sdwa v43, v94, v209 dst_sel:DWORD dst_unused:UNUSED_PAD src0_sel:WORD_1 src1_sel:DWORD
	v_and_b32_e32 v41, 0xffff0000, v41
	v_pk_mul_f32 v[92:93], v[0:1], v[92:93] op_sel_hi:[0,1]
	v_pk_fma_f32 v[90:91], v[66:67], v[90:91], v[6:7]
	v_and_b32_sdwa v33, v96, v209 dst_sel:DWORD dst_unused:UNUSED_PAD src0_sel:WORD_1 src1_sel:DWORD
	v_add3_u32 v43, v94, v43, s77
	v_or_b32_sdwa v95, v41, v1 dst_sel:DWORD dst_unused:UNUSED_PAD src0_sel:DWORD src1_sel:WORD_1
	v_pk_fma_f32 v[92:93], v[64:65], v[92:93], v[8:9]
	v_and_b32_sdwa v41, v91, v209 dst_sel:DWORD dst_unused:UNUSED_PAD src0_sel:WORD_1 src1_sel:DWORD
	v_add3_u32 v33, v96, v33, s77
	v_and_b32_e32 v43, 0xffff0000, v43
	v_and_b32_sdwa v1, v93, v209 dst_sel:DWORD dst_unused:UNUSED_PAD src0_sel:WORD_1 src1_sel:DWORD
	v_add3_u32 v41, v91, v41, s77
	v_or_b32_sdwa v94, v43, v33 dst_sel:DWORD dst_unused:UNUSED_PAD src0_sel:DWORD src1_sel:WORD_1
	v_add3_u32 v1, v93, v1, s77
	v_and_b32_sdwa v43, v90, v209 dst_sel:DWORD dst_unused:UNUSED_PAD src0_sel:WORD_1 src1_sel:DWORD
	v_and_b32_e32 v41, 0xffff0000, v41
	v_and_b32_sdwa v33, v92, v209 dst_sel:DWORD dst_unused:UNUSED_PAD src0_sel:WORD_1 src1_sel:DWORD
	v_add3_u32 v43, v90, v43, s77
	v_or_b32_sdwa v91, v41, v1 dst_sel:DWORD dst_unused:UNUSED_PAD src0_sel:DWORD src1_sel:WORD_1
	v_pk_mul_f32 v[88:89], v[0:1], v[88:89] op_sel_hi:[0,1]
	v_pk_mul_f32 v[0:1], v[0:1], v[86:87] op_sel_hi:[0,1]
	v_add3_u32 v33, v92, v33, s77
	v_and_b32_e32 v43, 0xffff0000, v43
	v_pk_fma_f32 v[0:1], v[16:17], v[0:1], v[2:3]
	v_or_b32_sdwa v90, v43, v33 dst_sel:DWORD dst_unused:UNUSED_PAD src0_sel:DWORD src1_sel:WORD_1
	v_pk_fma_f32 v[88:89], v[68:69], v[88:89], v[4:5]
	v_and_b32_sdwa v43, v1, v209 dst_sel:DWORD dst_unused:UNUSED_PAD src0_sel:WORD_1 src1_sel:DWORD
	v_and_b32_sdwa v45, v0, v209 dst_sel:DWORD dst_unused:UNUSED_PAD src0_sel:WORD_1 src1_sel:DWORD
	v_and_b32_sdwa v33, v89, v209 dst_sel:DWORD dst_unused:UNUSED_PAD src0_sel:WORD_1 src1_sel:DWORD
	v_and_b32_sdwa v41, v88, v209 dst_sel:DWORD dst_unused:UNUSED_PAD src0_sel:WORD_1 src1_sel:DWORD
	v_add3_u32 v1, v1, v43, s77
	v_add3_u32 v0, v0, v45, s77
	v_add3_u32 v41, v88, v41, s77
	v_add3_u32 v33, v89, v33, s77
	v_and_b32_e32 v1, 0xffff0000, v1
	v_and_b32_e32 v0, 0xffff0000, v0
	v_lshl_add_u64 v[100:101], v[38:39], 0, s[22:23]
	v_or_b32_sdwa v1, v1, v33 dst_sel:DWORD dst_unused:UNUSED_PAD src0_sel:DWORD src1_sel:WORD_1
	v_or_b32_sdwa v0, v0, v41 dst_sel:DWORD dst_unused:UNUSED_PAD src0_sel:DWORD src1_sel:WORD_1
	global_store_dwordx2 v[100:101], v[98:99], off
	global_store_dwordx2 v[100:101], v[94:95], off offset:512
	global_store_dwordx2 v[100:101], v[90:91], off offset:1024
	global_store_dwordx2 v[100:101], v[0:1], off offset:1536
	s_andn2_b64 vcc, exec, s[24:25]
	s_cbranch_vccnz .LBB0_716
.LBB0_718:
	s_waitcnt lgkmcnt(0)
	v_add_f32_e32 v0, v30, v31
	v_fmamk_f32 v0, v0, 0x3a800000, v206
	v_mul_f32_e32 v1, 0x4f800000, v0
	v_cmp_gt_f32_e32 vcc, s57, v0
	s_nop 1
	v_cndmask_b32_e32 v0, v0, v1, vcc
	v_sqrt_f32_e32 v1, v0
	s_nop 0
	v_add_u32_e32 v30, -1, v1
	v_fma_f32 v33, -v30, v1, v0
	v_add_u32_e32 v31, 1, v1
	v_cmp_ge_f32_e64 s[0:1], 0, v33
	s_nop 1
	v_cndmask_b32_e64 v30, v1, v30, s[0:1]
	v_fma_f32 v1, -v31, v1, v0
	v_cmp_lt_f32_e64 s[0:1], 0, v1
	s_nop 1
	v_cndmask_b32_e64 v1, v30, v31, s[0:1]
	v_mul_f32_e32 v30, 0x37800000, v1
	v_cndmask_b32_e32 v1, v1, v30, vcc
	v_cmp_class_f32_e32 vcc, v0, v207
	s_nop 1
	v_cndmask_b32_e32 v0, v1, v0, vcc
	v_div_scale_f32 v1, s[0:1], v0, v0, 1.0
	v_rcp_f32_e32 v30, v1
	s_nop 0
	v_fma_f32 v31, -v1, v30, 1.0
	v_fmac_f32_e32 v30, v31, v30
	v_div_scale_f32 v31, vcc, 1.0, v0, 1.0
	v_mul_f32_e32 v33, v31, v30
	v_fma_f32 v41, -v1, v33, v31
	v_fmac_f32_e32 v33, v41, v30
	v_fma_f32 v1, -v1, v33, v31
	v_div_fmas_f32 v1, v1, v30, v33
	v_div_fixup_f32 v0, v1, v0, 1.0
	v_pk_mul_f32 v[30:31], v[0:1], v[84:85] op_sel_hi:[0,1]
	v_pk_fma_f32 v[30:31], v[54:55], v[30:31], v[18:19]
	v_pk_mul_f32 v[82:83], v[0:1], v[82:83] op_sel_hi:[0,1]
	v_pk_fma_f32 v[82:83], v[58:59], v[82:83], v[14:15]
	v_and_b32_sdwa v1, v31, v209 dst_sel:DWORD dst_unused:UNUSED_PAD src0_sel:WORD_1 src1_sel:DWORD
	v_and_b32_sdwa v33, v30, v209 dst_sel:DWORD dst_unused:UNUSED_PAD src0_sel:WORD_1 src1_sel:DWORD
	v_add3_u32 v30, v30, v33, s77
	v_add3_u32 v1, v31, v1, s77
	v_and_b32_sdwa v31, v83, v209 dst_sel:DWORD dst_unused:UNUSED_PAD src0_sel:WORD_1 src1_sel:DWORD
	v_and_b32_sdwa v33, v82, v209 dst_sel:DWORD dst_unused:UNUSED_PAD src0_sel:WORD_1 src1_sel:DWORD
	v_add3_u32 v31, v83, v31, s77
	v_add3_u32 v33, v82, v33, s77
	v_and_b32_e32 v31, 0xffff0000, v31
	v_and_b32_e32 v33, 0xffff0000, v33
	v_or_b32_sdwa v31, v31, v1 dst_sel:DWORD dst_unused:UNUSED_PAD src0_sel:DWORD src1_sel:WORD_1
	v_or_b32_sdwa v30, v33, v30 dst_sel:DWORD dst_unused:UNUSED_PAD src0_sel:DWORD src1_sel:WORD_1
	v_lshl_add_u64 v[82:83], v[38:39], 0, s[20:21]
	global_store_dwordx2 v[82:83], v[30:31], off
	v_pk_mul_f32 v[30:31], v[0:1], v[80:81] op_sel_hi:[0,1]
	v_pk_fma_f32 v[30:31], v[60:61], v[30:31], v[12:13]
	v_pk_mul_f32 v[78:79], v[0:1], v[78:79] op_sel_hi:[0,1]
	v_pk_fma_f32 v[78:79], v[62:63], v[78:79], v[10:11]
	v_and_b32_sdwa v1, v31, v209 dst_sel:DWORD dst_unused:UNUSED_PAD src0_sel:WORD_1 src1_sel:DWORD
	v_and_b32_sdwa v33, v30, v209 dst_sel:DWORD dst_unused:UNUSED_PAD src0_sel:WORD_1 src1_sel:DWORD
	v_add3_u32 v30, v30, v33, s77
	v_add3_u32 v1, v31, v1, s77
	v_and_b32_sdwa v31, v79, v209 dst_sel:DWORD dst_unused:UNUSED_PAD src0_sel:WORD_1 src1_sel:DWORD
	v_and_b32_sdwa v33, v78, v209 dst_sel:DWORD dst_unused:UNUSED_PAD src0_sel:WORD_1 src1_sel:DWORD
	v_add3_u32 v31, v79, v31, s77
	v_add3_u32 v33, v78, v33, s77
	v_and_b32_e32 v31, 0xffff0000, v31
	v_and_b32_e32 v33, 0xffff0000, v33
	v_or_b32_sdwa v31, v31, v1 dst_sel:DWORD dst_unused:UNUSED_PAD src0_sel:DWORD src1_sel:WORD_1
	v_or_b32_sdwa v30, v33, v30 dst_sel:DWORD dst_unused:UNUSED_PAD src0_sel:DWORD src1_sel:WORD_1
	global_store_dwordx2 v[82:83], v[30:31], off offset:512
	v_pk_mul_f32 v[30:31], v[0:1], v[76:77] op_sel_hi:[0,1]
	v_pk_fma_f32 v[30:31], v[64:65], v[30:31], v[8:9]
	v_pk_mul_f32 v[74:75], v[0:1], v[74:75] op_sel_hi:[0,1]
	v_pk_fma_f32 v[74:75], v[66:67], v[74:75], v[6:7]
	v_and_b32_sdwa v1, v31, v209 dst_sel:DWORD dst_unused:UNUSED_PAD src0_sel:WORD_1 src1_sel:DWORD
	v_and_b32_sdwa v33, v30, v209 dst_sel:DWORD dst_unused:UNUSED_PAD src0_sel:WORD_1 src1_sel:DWORD
	v_add3_u32 v30, v30, v33, s77
	v_add3_u32 v1, v31, v1, s77
	v_and_b32_sdwa v31, v75, v209 dst_sel:DWORD dst_unused:UNUSED_PAD src0_sel:WORD_1 src1_sel:DWORD
	v_and_b32_sdwa v33, v74, v209 dst_sel:DWORD dst_unused:UNUSED_PAD src0_sel:WORD_1 src1_sel:DWORD
	v_add3_u32 v31, v75, v31, s77
	v_add3_u32 v33, v74, v33, s77
	v_and_b32_e32 v31, 0xffff0000, v31
	v_and_b32_e32 v33, 0xffff0000, v33
	v_or_b32_sdwa v31, v31, v1 dst_sel:DWORD dst_unused:UNUSED_PAD src0_sel:DWORD src1_sel:WORD_1
	v_or_b32_sdwa v30, v33, v30 dst_sel:DWORD dst_unused:UNUSED_PAD src0_sel:DWORD src1_sel:WORD_1
	global_store_dwordx2 v[82:83], v[30:31], off offset:1024
	v_pk_mul_f32 v[30:31], v[0:1], v[72:73] op_sel_hi:[0,1]
	v_pk_fma_f32 v[30:31], v[68:69], v[30:31], v[4:5]
	v_pk_mul_f32 v[0:1], v[0:1], v[70:71] op_sel_hi:[0,1]
	v_pk_fma_f32 v[0:1], v[16:17], v[0:1], v[2:3]
	v_and_b32_sdwa v33, v31, v209 dst_sel:DWORD dst_unused:UNUSED_PAD src0_sel:WORD_1 src1_sel:DWORD
	v_and_b32_sdwa v41, v30, v209 dst_sel:DWORD dst_unused:UNUSED_PAD src0_sel:WORD_1 src1_sel:DWORD
	v_add3_u32 v30, v30, v41, s77
	v_add3_u32 v31, v31, v33, s77
	v_and_b32_sdwa v33, v1, v209 dst_sel:DWORD dst_unused:UNUSED_PAD src0_sel:WORD_1 src1_sel:DWORD
	v_and_b32_sdwa v41, v0, v209 dst_sel:DWORD dst_unused:UNUSED_PAD src0_sel:WORD_1 src1_sel:DWORD
	v_add3_u32 v1, v1, v33, s77
	v_add3_u32 v0, v0, v41, s77
	v_and_b32_e32 v1, 0xffff0000, v1
	v_and_b32_e32 v0, 0xffff0000, v0
	v_or_b32_sdwa v1, v1, v31 dst_sel:DWORD dst_unused:UNUSED_PAD src0_sel:DWORD src1_sel:WORD_1
	v_or_b32_sdwa v0, v0, v30 dst_sel:DWORD dst_unused:UNUSED_PAD src0_sel:DWORD src1_sel:WORD_1
	global_store_dwordx2 v[82:83], v[0:1], off offset:1536
	s_andn2_b64 vcc, exec, s[18:19]
	s_cbranch_vccnz .LBB0_713
.LBB0_719:
	s_waitcnt lgkmcnt(0)
	v_add_f32_e32 v0, v28, v29
	v_fmamk_f32 v0, v0, 0x3a800000, v206
	v_mul_f32_e32 v1, 0x4f800000, v0
	v_cmp_gt_f32_e32 vcc, s57, v0
	s_nop 1
	v_cndmask_b32_e32 v0, v0, v1, vcc
	v_sqrt_f32_e32 v1, v0
	s_nop 0
	v_add_u32_e32 v28, -1, v1
	v_fma_f32 v30, -v28, v1, v0
	v_add_u32_e32 v29, 1, v1
	v_cmp_ge_f32_e64 s[0:1], 0, v30
	s_nop 1
	v_cndmask_b32_e64 v28, v1, v28, s[0:1]
	v_fma_f32 v1, -v29, v1, v0
	v_cmp_lt_f32_e64 s[0:1], 0, v1
	s_nop 1
	v_cndmask_b32_e64 v1, v28, v29, s[0:1]
	v_mul_f32_e32 v28, 0x37800000, v1
	v_cndmask_b32_e32 v1, v1, v28, vcc
	v_cmp_class_f32_e32 vcc, v0, v207
	s_nop 1
	v_cndmask_b32_e32 v0, v1, v0, vcc
	v_div_scale_f32 v1, s[0:1], v0, v0, 1.0
	v_rcp_f32_e32 v28, v1
	s_nop 0
	v_fma_f32 v29, -v1, v28, 1.0
	v_fmac_f32_e32 v28, v29, v28
	v_div_scale_f32 v29, vcc, 1.0, v0, 1.0
	v_mul_f32_e32 v30, v29, v28
	v_fma_f32 v31, -v1, v30, v29
	v_fmac_f32_e32 v30, v31, v28
	v_fma_f32 v1, -v1, v30, v29
	v_div_fmas_f32 v1, v1, v28, v30
	v_div_fixup_f32 v0, v1, v0, 1.0
	v_pk_mul_f32 v[28:29], v[0:1], v[48:49] op_sel_hi:[0,1]
	v_pk_fma_f32 v[18:19], v[54:55], v[28:29], v[18:19]
	v_pk_mul_f32 v[28:29], v[0:1], v[46:47] op_sel_hi:[0,1]
	v_pk_fma_f32 v[14:15], v[58:59], v[28:29], v[14:15]
	v_and_b32_sdwa v1, v19, v209 dst_sel:DWORD dst_unused:UNUSED_PAD src0_sel:WORD_1 src1_sel:DWORD
	v_and_b32_sdwa v28, v18, v209 dst_sel:DWORD dst_unused:UNUSED_PAD src0_sel:WORD_1 src1_sel:DWORD
	v_add3_u32 v18, v18, v28, s77
	v_add3_u32 v1, v19, v1, s77
	v_and_b32_sdwa v19, v15, v209 dst_sel:DWORD dst_unused:UNUSED_PAD src0_sel:WORD_1 src1_sel:DWORD
	v_and_b32_sdwa v28, v14, v209 dst_sel:DWORD dst_unused:UNUSED_PAD src0_sel:WORD_1 src1_sel:DWORD
	v_add3_u32 v15, v15, v19, s77
	v_add3_u32 v14, v14, v28, s77
	v_and_b32_e32 v15, 0xffff0000, v15
	v_and_b32_e32 v14, 0xffff0000, v14
	v_or_b32_sdwa v15, v15, v1 dst_sel:DWORD dst_unused:UNUSED_PAD src0_sel:DWORD src1_sel:WORD_1
	v_or_b32_sdwa v14, v14, v18 dst_sel:DWORD dst_unused:UNUSED_PAD src0_sel:DWORD src1_sel:WORD_1
	v_lshl_add_u64 v[18:19], v[38:39], 0, s[16:17]
	global_store_dwordx2 v[18:19], v[14:15], off
	v_pk_mul_f32 v[14:15], v[0:1], v[52:53] op_sel_hi:[0,1]
	v_pk_fma_f32 v[12:13], v[60:61], v[14:15], v[12:13]
	v_pk_mul_f32 v[14:15], v[0:1], v[50:51] op_sel_hi:[0,1]
	v_pk_fma_f32 v[10:11], v[62:63], v[14:15], v[10:11]
	v_and_b32_sdwa v1, v13, v209 dst_sel:DWORD dst_unused:UNUSED_PAD src0_sel:WORD_1 src1_sel:DWORD
	v_and_b32_sdwa v14, v12, v209 dst_sel:DWORD dst_unused:UNUSED_PAD src0_sel:WORD_1 src1_sel:DWORD
	v_add3_u32 v12, v12, v14, s77
	v_add3_u32 v1, v13, v1, s77
	v_and_b32_sdwa v13, v11, v209 dst_sel:DWORD dst_unused:UNUSED_PAD src0_sel:WORD_1 src1_sel:DWORD
	v_and_b32_sdwa v14, v10, v209 dst_sel:DWORD dst_unused:UNUSED_PAD src0_sel:WORD_1 src1_sel:DWORD
	v_add3_u32 v11, v11, v13, s77
	v_add3_u32 v10, v10, v14, s77
	v_and_b32_e32 v11, 0xffff0000, v11
	v_and_b32_e32 v10, 0xffff0000, v10
	v_or_b32_sdwa v11, v11, v1 dst_sel:DWORD dst_unused:UNUSED_PAD src0_sel:DWORD src1_sel:WORD_1
	v_or_b32_sdwa v10, v10, v12 dst_sel:DWORD dst_unused:UNUSED_PAD src0_sel:DWORD src1_sel:WORD_1
	global_store_dwordx2 v[18:19], v[10:11], off offset:512
	v_pk_mul_f32 v[10:11], v[0:1], v[26:27] op_sel_hi:[0,1]
	v_pk_fma_f32 v[8:9], v[64:65], v[10:11], v[8:9]
	v_pk_mul_f32 v[10:11], v[0:1], v[24:25] op_sel_hi:[0,1]
	v_pk_fma_f32 v[6:7], v[66:67], v[10:11], v[6:7]
	v_and_b32_sdwa v1, v9, v209 dst_sel:DWORD dst_unused:UNUSED_PAD src0_sel:WORD_1 src1_sel:DWORD
	v_and_b32_sdwa v10, v8, v209 dst_sel:DWORD dst_unused:UNUSED_PAD src0_sel:WORD_1 src1_sel:DWORD
	v_add3_u32 v8, v8, v10, s77
	v_add3_u32 v1, v9, v1, s77
	v_and_b32_sdwa v9, v7, v209 dst_sel:DWORD dst_unused:UNUSED_PAD src0_sel:WORD_1 src1_sel:DWORD
	v_and_b32_sdwa v10, v6, v209 dst_sel:DWORD dst_unused:UNUSED_PAD src0_sel:WORD_1 src1_sel:DWORD
	v_add3_u32 v7, v7, v9, s77
	v_add3_u32 v6, v6, v10, s77
	v_and_b32_e32 v7, 0xffff0000, v7
	v_and_b32_e32 v6, 0xffff0000, v6
	v_or_b32_sdwa v7, v7, v1 dst_sel:DWORD dst_unused:UNUSED_PAD src0_sel:DWORD src1_sel:WORD_1
	v_or_b32_sdwa v6, v6, v8 dst_sel:DWORD dst_unused:UNUSED_PAD src0_sel:DWORD src1_sel:WORD_1
	global_store_dwordx2 v[18:19], v[6:7], off offset:1024
	v_pk_mul_f32 v[6:7], v[0:1], v[22:23] op_sel_hi:[0,1]
	v_pk_fma_f32 v[4:5], v[68:69], v[6:7], v[4:5]
	v_pk_mul_f32 v[0:1], v[0:1], v[20:21] op_sel_hi:[0,1]
	v_pk_fma_f32 v[0:1], v[16:17], v[0:1], v[2:3]
	v_and_b32_sdwa v2, v5, v209 dst_sel:DWORD dst_unused:UNUSED_PAD src0_sel:WORD_1 src1_sel:DWORD
	v_and_b32_sdwa v3, v4, v209 dst_sel:DWORD dst_unused:UNUSED_PAD src0_sel:WORD_1 src1_sel:DWORD
	v_add3_u32 v3, v4, v3, s77
	v_add3_u32 v2, v5, v2, s77
	v_and_b32_sdwa v4, v1, v209 dst_sel:DWORD dst_unused:UNUSED_PAD src0_sel:WORD_1 src1_sel:DWORD
	v_and_b32_sdwa v5, v0, v209 dst_sel:DWORD dst_unused:UNUSED_PAD src0_sel:WORD_1 src1_sel:DWORD
	v_add3_u32 v1, v1, v4, s77
	v_add3_u32 v0, v0, v5, s77
	v_and_b32_e32 v1, 0xffff0000, v1
	v_and_b32_e32 v0, 0xffff0000, v0
	v_or_b32_sdwa v1, v1, v2 dst_sel:DWORD dst_unused:UNUSED_PAD src0_sel:DWORD src1_sel:WORD_1
	v_or_b32_sdwa v0, v0, v3 dst_sel:DWORD dst_unused:UNUSED_PAD src0_sel:DWORD src1_sel:WORD_1
	global_store_dwordx2 v[18:19], v[0:1], off offset:1536
	s_branch .LBB0_713

.LBB0_722:
	s_waitcnt vmcnt(0) lgkmcnt(0)
	global_load_dwordx4 v[126:129], v[28:29], off
	global_load_dwordx4 v[130:133], v[30:31], off
	global_load_dwordx4 v[134:137], v[34:35], off
	global_load_dwordx4 v[138:141], v[28:29], off offset:1024
	global_load_dwordx4 v[142:145], v[36:37], off
	global_load_dwordx4 v[146:149], v[38:39], off
	global_load_dwordx4 v[150:153], v[28:29], off offset:2048
	global_load_dwordx4 v[154:157], v[40:41], off
	global_load_dwordx4 v[158:161], v[42:43], off
	global_load_dwordx4 v[170:173], v[28:29], off offset:3072
	global_load_dwordx4 v[174:177], v[44:45], off
	global_load_dwordx4 v[178:181], v[46:47], off
	v_pk_mul_f32 v[18:19], v[14:15], v[14:15]
	v_pk_mul_f32 v[20:21], v[12:13], v[12:13]
	v_mov_b32_e32 v58, v1
	v_mov_b32_e32 v1, v2
	v_mov_b32_e32 v59, v3
	v_pk_mul_f32 v[2:3], v[10:11], v[10:11]
	v_pk_mul_f32 v[16:17], v[8:9], v[8:9]
	v_pk_mov_b32 v[22:23], v[20:21], v[18:19] op_sel:[1,0]
	v_mov_b32_e32 v21, v19
	v_pk_add_f32 v[18:19], v[22:23], v[20:21]
	v_pk_mov_b32 v[20:21], v[16:17], v[2:3] op_sel:[1,0]
	v_mov_b32_e32 v17, v3
	v_pk_add_f32 v[2:3], v[20:21], v[16:17]
	v_pk_add_f32 v[18:19], v[18:19], v[18:19] op_sel_hi:[0,1]
	v_pk_add_f32 v[2:3], v[2:3], v[2:3] op_sel_hi:[0,1]
	v_mul_f32_e32 v2, v4, v4
	v_pk_fma_f32 v[16:17], v[4:5], v[4:5], v[2:3] op_sel_hi:[1,1,0]
	v_mul_f32_e32 v2, v6, v6
	v_pk_fma_f32 v[20:21], v[6:7], v[6:7], v[2:3] op_sel_hi:[1,1,0]
	v_mul_f32_e32 v16, v0, v0
	v_mul_f32_e32 v20, v58, v58
	v_mul_f32_e32 v18, v1, v1
	v_mul_f32_e32 v2, v59, v59
	v_pk_add_f32 v[16:17], v[16:17], v[20:21]
	v_pk_add_f32 v[2:3], v[18:19], v[2:3]
	v_mov_b32_e32 v60, v12
	v_pk_add_f32 v[2:3], v[16:17], v[2:3]
	v_mov_b32_e32 v61, v14
	v_add_f32_e32 v2, v2, v3
	ds_bpermute_b32 v3, v120, v2
	v_mov_b32_e32 v14, v13
	s_add_i32 s2, s2, s70
	s_waitcnt lgkmcnt(0)
	v_add_f32_e32 v2, v2, v3
	ds_bpermute_b32 v3, v121, v2
	s_waitcnt lgkmcnt(0)
	v_add_f32_e32 v2, v2, v3
	ds_bpermute_b32 v3, v122, v2
	s_waitcnt lgkmcnt(0)
	v_add_f32_e32 v2, v2, v3
	ds_bpermute_b32 v3, v123, v2
	s_waitcnt lgkmcnt(0)
	v_add_f32_e32 v2, v2, v3
	ds_bpermute_b32 v3, v124, v2
	s_waitcnt lgkmcnt(0)
	v_add_f32_e32 v2, v2, v3
	ds_bpermute_b32 v3, v125, v2
	s_waitcnt lgkmcnt(0)
	v_add_f32_e32 v2, v2, v3
	v_fmamk_f32 v2, v2, 0x3a800000, v206
	v_cmp_gt_f32_e32 vcc, s57, v2
	v_mul_f32_e32 v3, 0x4f800000, v2
	s_nop 0
	v_cndmask_b32_e32 v2, v2, v3, vcc
	v_sqrt_f32_e32 v3, v2
	s_nop 0
	v_add_u32_e32 v16, -1, v3
	v_fma_f32 v17, -v16, v3, v2
	v_cmp_ge_f32_e64 s[0:1], 0, v17
	v_add_u32_e32 v17, 1, v3
	s_nop 0
	v_cndmask_b32_e64 v16, v3, v16, s[0:1]
	v_fma_f32 v3, -v17, v3, v2
	v_cmp_lt_f32_e64 s[0:1], 0, v3
	s_nop 1
	v_cndmask_b32_e64 v3, v16, v17, s[0:1]
	v_mul_f32_e32 v16, 0x37800000, v3
	v_cndmask_b32_e32 v3, v3, v16, vcc
	v_cmp_class_f32_e32 vcc, v2, v207
	s_nop 1
	v_cndmask_b32_e32 v2, v3, v2, vcc
	v_div_scale_f32 v3, s[0:1], v2, v2, 1.0
	v_rcp_f32_e32 v16, v3
	v_readlane_b32 s0, v254, 14
	v_readlane_b32 s1, v254, 15
	s_add_u32 s4, s4, s0
	v_fma_f32 v17, -v3, v16, 1.0
	v_fmac_f32_e32 v16, v17, v16
	v_div_scale_f32 v17, vcc, 1.0, v2, 1.0
	v_mul_f32_e32 v18, v17, v16
	v_fma_f32 v19, -v3, v18, v17
	v_fmac_f32_e32 v18, v19, v16
	v_fma_f32 v3, -v3, v18, v17
	v_div_fmas_f32 v3, v3, v16, v18
	v_div_fixup_f32 v2, v3, v2, 1.0
	v_pk_mul_f32 v[60:61], v[60:61], v[2:3] op_sel_hi:[1,0]
	v_pk_mul_f32 v[12:13], v[14:15], v[2:3] op_sel_hi:[1,0]
	s_addc_u32 s5, s5, s1
	s_add_u32 s6, s6, s0
	s_addc_u32 s7, s7, s1
	s_cmp_lt_i32 s2, s14
	s_waitcnt vmcnt(0) lgkmcnt(0)
	v_mov_b32_e32 v16, v126
	v_mov_b32_e32 v17, v127
	v_mov_b32_e32 v18, v128
	v_mov_b32_e32 v19, v129
	v_mov_b32_e32 v20, v130
	v_mov_b32_e32 v21, v131
	v_mov_b32_e32 v22, v132
	v_mov_b32_e32 v23, v133
	v_mov_b32_e32 v24, v134
	v_mov_b32_e32 v25, v135
	v_mov_b32_e32 v26, v136
	v_mov_b32_e32 v27, v137
	v_mov_b32_e32 v62, v16
	v_mov_b32_e32 v63, v18
	v_pk_mul_f32 v[60:61], v[62:63], v[60:61]
	s_waitcnt lgkmcnt(0)
	v_mov_b32_e32 v63, v22
	v_mov_b32_e32 v18, v17
	v_mov_b32_e32 v22, v21
	v_mov_b32_e32 v62, v20
	v_mov_b32_e32 v65, v26
	v_pk_mul_f32 v[12:13], v[18:19], v[12:13]
	v_pk_add_f32 v[14:15], v[22:23], 1.0 op_sel_hi:[1,0]
	v_mov_b32_e32 v26, v25
	v_pk_add_f32 v[62:63], v[62:63], 1.0 op_sel_hi:[1,0]
	v_mov_b32_e32 v64, v24
	v_pk_fma_f32 v[12:13], v[14:15], v[12:13], v[26:27]
	v_pk_fma_f32 v[60:61], v[62:63], v[60:61], v[64:65]
	v_and_b32_sdwa v15, v13, v209 dst_sel:DWORD dst_unused:UNUSED_PAD src0_sel:WORD_1 src1_sel:DWORD
	v_and_b32_sdwa v16, v12, v209 dst_sel:DWORD dst_unused:UNUSED_PAD src0_sel:WORD_1 src1_sel:DWORD
	v_and_b32_sdwa v3, v61, v209 dst_sel:DWORD dst_unused:UNUSED_PAD src0_sel:WORD_1 src1_sel:DWORD
	v_and_b32_sdwa v14, v60, v209 dst_sel:DWORD dst_unused:UNUSED_PAD src0_sel:WORD_1 src1_sel:DWORD
	v_add3_u32 v13, v13, v15, s77
	v_add3_u32 v12, v12, v16, s77
	v_add3_u32 v14, v60, v14, s77
	v_add3_u32 v3, v61, v3, s77
	v_and_b32_e32 v13, 0xffff0000, v13
	v_and_b32_e32 v12, 0xffff0000, v12
	v_or_b32_sdwa v13, v13, v3 dst_sel:DWORD dst_unused:UNUSED_PAD src0_sel:DWORD src1_sel:WORD_1
	v_or_b32_sdwa v12, v12, v14 dst_sel:DWORD dst_unused:UNUSED_PAD src0_sel:DWORD src1_sel:WORD_1
	global_store_dwordx2 v[56:57], v[12:13], off
	s_nop 0
	v_mov_b32_e32 v24, v8
	v_mov_b32_e32 v25, v10
	v_pk_mul_f32 v[24:25], v[24:25], v[2:3] op_sel_hi:[1,0]
	v_mov_b32_e32 v10, v9
	v_pk_mul_f32 v[8:9], v[10:11], v[2:3] op_sel_hi:[1,0]
	v_mov_b32_e32 v12, v138
	v_mov_b32_e32 v13, v139
	v_mov_b32_e32 v14, v140
	v_mov_b32_e32 v15, v141
	v_mov_b32_e32 v16, v142
	v_mov_b32_e32 v17, v143
	v_mov_b32_e32 v18, v144
	v_mov_b32_e32 v19, v145
	v_mov_b32_e32 v20, v146
	v_mov_b32_e32 v21, v147
	v_mov_b32_e32 v22, v148
	v_mov_b32_e32 v23, v149
	v_mov_b32_e32 v26, v12
	v_mov_b32_e32 v27, v14
	v_pk_mul_f32 v[24:25], v[26:27], v[24:25]
	s_waitcnt lgkmcnt(0)
	v_mov_b32_e32 v27, v18
	v_mov_b32_e32 v14, v13
	v_mov_b32_e32 v18, v17
	v_mov_b32_e32 v26, v16
	v_mov_b32_e32 v61, v22
	v_pk_mul_f32 v[8:9], v[14:15], v[8:9]
	v_pk_add_f32 v[10:11], v[18:19], 1.0 op_sel_hi:[1,0]
	v_mov_b32_e32 v22, v21
	v_pk_add_f32 v[26:27], v[26:27], 1.0 op_sel_hi:[1,0]
	v_mov_b32_e32 v60, v20
	v_pk_fma_f32 v[8:9], v[10:11], v[8:9], v[22:23]
	v_pk_fma_f32 v[24:25], v[26:27], v[24:25], v[60:61]
	v_and_b32_sdwa v11, v9, v209 dst_sel:DWORD dst_unused:UNUSED_PAD src0_sel:WORD_1 src1_sel:DWORD
	v_and_b32_sdwa v12, v8, v209 dst_sel:DWORD dst_unused:UNUSED_PAD src0_sel:WORD_1 src1_sel:DWORD
	v_and_b32_sdwa v3, v25, v209 dst_sel:DWORD dst_unused:UNUSED_PAD src0_sel:WORD_1 src1_sel:DWORD
	v_and_b32_sdwa v10, v24, v209 dst_sel:DWORD dst_unused:UNUSED_PAD src0_sel:WORD_1 src1_sel:DWORD
	v_add3_u32 v9, v9, v11, s77
	v_add3_u32 v8, v8, v12, s77
	v_add3_u32 v10, v24, v10, s77
	v_add3_u32 v3, v25, v3, s77
	v_and_b32_e32 v9, 0xffff0000, v9
	v_and_b32_e32 v8, 0xffff0000, v8
	v_or_b32_sdwa v9, v9, v3 dst_sel:DWORD dst_unused:UNUSED_PAD src0_sel:DWORD src1_sel:WORD_1
	v_or_b32_sdwa v8, v8, v10 dst_sel:DWORD dst_unused:UNUSED_PAD src0_sel:DWORD src1_sel:WORD_1
	global_store_dwordx2 v[56:57], v[8:9], off offset:512
	s_nop 0
	v_mov_b32_e32 v20, v4
	v_mov_b32_e32 v21, v6
	v_pk_mul_f32 v[20:21], v[20:21], v[2:3] op_sel_hi:[1,0]
	v_mov_b32_e32 v6, v5
	v_pk_mul_f32 v[4:5], v[6:7], v[2:3] op_sel_hi:[1,0]
	v_mov_b32_e32 v8, v150
	v_mov_b32_e32 v9, v151
	v_mov_b32_e32 v10, v152
	v_mov_b32_e32 v11, v153
	v_mov_b32_e32 v12, v154
	v_mov_b32_e32 v13, v155
	v_mov_b32_e32 v14, v156
	v_mov_b32_e32 v15, v157
	v_mov_b32_e32 v16, v158
	v_mov_b32_e32 v17, v159
	v_mov_b32_e32 v18, v160
	v_mov_b32_e32 v19, v161
	v_mov_b32_e32 v22, v8
	v_mov_b32_e32 v23, v10
	v_pk_mul_f32 v[20:21], v[22:23], v[20:21]
	s_waitcnt lgkmcnt(0)
	v_mov_b32_e32 v23, v14
	v_mov_b32_e32 v10, v9
	v_mov_b32_e32 v14, v13
	v_mov_b32_e32 v22, v12
	v_mov_b32_e32 v25, v18
	v_pk_mul_f32 v[4:5], v[10:11], v[4:5]
	v_pk_add_f32 v[6:7], v[14:15], 1.0 op_sel_hi:[1,0]
	v_mov_b32_e32 v18, v17
	v_pk_add_f32 v[22:23], v[22:23], 1.0 op_sel_hi:[1,0]
	v_mov_b32_e32 v24, v16
	v_pk_fma_f32 v[4:5], v[6:7], v[4:5], v[18:19]
	v_pk_fma_f32 v[20:21], v[22:23], v[20:21], v[24:25]
	v_and_b32_sdwa v7, v5, v209 dst_sel:DWORD dst_unused:UNUSED_PAD src0_sel:WORD_1 src1_sel:DWORD
	v_and_b32_sdwa v8, v4, v209 dst_sel:DWORD dst_unused:UNUSED_PAD src0_sel:WORD_1 src1_sel:DWORD
	v_and_b32_sdwa v3, v21, v209 dst_sel:DWORD dst_unused:UNUSED_PAD src0_sel:WORD_1 src1_sel:DWORD
	v_and_b32_sdwa v6, v20, v209 dst_sel:DWORD dst_unused:UNUSED_PAD src0_sel:WORD_1 src1_sel:DWORD
	v_add3_u32 v5, v5, v7, s77
	v_add3_u32 v4, v4, v8, s77
	v_add3_u32 v6, v20, v6, s77
	v_add3_u32 v3, v21, v3, s77
	v_and_b32_e32 v5, 0xffff0000, v5
	v_and_b32_e32 v4, 0xffff0000, v4
	v_or_b32_sdwa v5, v5, v3 dst_sel:DWORD dst_unused:UNUSED_PAD src0_sel:DWORD src1_sel:WORD_1
	v_or_b32_sdwa v4, v4, v6 dst_sel:DWORD dst_unused:UNUSED_PAD src0_sel:DWORD src1_sel:WORD_1
	global_store_dwordx2 v[56:57], v[4:5], off offset:1024
	s_nop 0
	v_pk_mul_f32 v[0:1], v[0:1], v[2:3] op_sel_hi:[1,0]
	v_pk_mul_f32 v[2:3], v[58:59], v[2:3] op_sel_hi:[1,0]
	v_mov_b32_e32 v4, v170
	v_mov_b32_e32 v5, v171
	v_mov_b32_e32 v6, v172
	v_mov_b32_e32 v7, v173
	v_mov_b32_e32 v8, v174
	v_mov_b32_e32 v9, v175
	v_mov_b32_e32 v10, v176
	v_mov_b32_e32 v11, v177
	v_mov_b32_e32 v12, v178
	v_mov_b32_e32 v13, v179
	v_mov_b32_e32 v14, v180
	v_mov_b32_e32 v15, v181
	v_mov_b32_e32 v16, v4
	v_mov_b32_e32 v17, v6
	v_pk_mul_f32 v[0:1], v[0:1], v[16:17]
	s_waitcnt lgkmcnt(0)
	v_mov_b32_e32 v16, v8
	v_mov_b32_e32 v17, v10
	v_pk_add_f32 v[16:17], v[16:17], 1.0 op_sel_hi:[1,0]
	v_mov_b32_e32 v18, v12
	v_mov_b32_e32 v19, v14
	v_mov_b32_e32 v6, v5
	v_mov_b32_e32 v10, v9
	v_pk_fma_f32 v[0:1], v[0:1], v[16:17], v[18:19]
	v_pk_mul_f32 v[2:3], v[2:3], v[6:7]
	v_pk_add_f32 v[4:5], v[10:11], 1.0 op_sel_hi:[1,0]
	v_mov_b32_e32 v14, v13
	v_pk_fma_f32 v[2:3], v[2:3], v[4:5], v[14:15]
	v_and_b32_sdwa v4, v1, v209 dst_sel:DWORD dst_unused:UNUSED_PAD src0_sel:WORD_1 src1_sel:DWORD
	v_and_b32_sdwa v5, v0, v209 dst_sel:DWORD dst_unused:UNUSED_PAD src0_sel:WORD_1 src1_sel:DWORD
	v_add3_u32 v0, v0, v5, s77
	v_add3_u32 v1, v1, v4, s77
	v_and_b32_sdwa v4, v3, v209 dst_sel:DWORD dst_unused:UNUSED_PAD src0_sel:WORD_1 src1_sel:DWORD
	v_and_b32_sdwa v5, v2, v209 dst_sel:DWORD dst_unused:UNUSED_PAD src0_sel:WORD_1 src1_sel:DWORD
	v_add3_u32 v3, v3, v4, s77
	v_add3_u32 v2, v2, v5, s77
	v_and_b32_e32 v3, 0xffff0000, v3
	v_and_b32_e32 v2, 0xffff0000, v2
	v_or_b32_sdwa v1, v3, v1 dst_sel:DWORD dst_unused:UNUSED_PAD src0_sel:DWORD src1_sel:WORD_1
	v_or_b32_sdwa v0, v2, v0 dst_sel:DWORD dst_unused:UNUSED_PAD src0_sel:DWORD src1_sel:WORD_1
	global_store_dwordx2 v[56:57], v[0:1], off offset:1536
	v_lshl_add_u64 v[56:57], v[56:57], 0, s[58:59]
	s_cbranch_scc0 .LBB0_725
.LBB0_723:
	v_lshl_add_u64 v[16:17], s[4:5], 0, v[32:33]
	v_add_co_u32_e32 v0, vcc, 0xcf00000, v16
	s_nop 1
	v_addc_co_u32_e32 v1, vcc, 0, v17, vcc
	flat_load_dwordx4 v[12:15], v[0:1]
	flat_load_dwordx4 v[8:11], v[0:1] offset:1024
	flat_load_dwordx4 v[4:7], v[0:1] offset:2048
	s_nop 0
	flat_load_dwordx4 v[0:3], v[0:1] offset:3072
	s_andn2_b64 vcc, exec, s[52:53]
	s_cbranch_vccnz .LBB0_722
	v_lshl_add_u64 v[26:27], s[6:7], 0, v[32:33]
	v_add_co_u32_e32 v78, vcc, 0xe900000, v26
	s_mov_b64 s[0:1], 0xcf00000
	s_nop 0
	v_addc_co_u32_e32 v79, vcc, 0, v27, vcc
	v_add_co_u32_e32 v90, vcc, 0xeb00000, v26
	global_load_dwordx4 v[18:21], v[78:79], off
	s_nop 0
	v_addc_co_u32_e32 v91, vcc, 0, v27, vcc
	v_add_co_u32_e32 v102, vcc, 0xed00000, v26
	global_load_dwordx4 v[22:25], v[90:91], off
	s_nop 0
	v_addc_co_u32_e32 v103, vcc, 0, v27, vcc
	global_load_dwordx4 v[58:61], v[102:103], off
	v_add_co_u32_e32 v26, vcc, 0xef00000, v26
	v_lshl_add_u64 v[118:119], v[16:17], 0, s[0:1]
	s_nop 0
	v_addc_co_u32_e32 v27, vcc, 0, v27, vcc
	global_load_dwordx4 v[62:65], v[26:27], off
	flat_load_dwordx4 v[66:69], v[48:49]
	global_load_dwordx4 v[182:185], v[50:51], off
	global_load_dwordx4 v[186:189], v[52:53], off
	global_load_dwordx4 v[190:193], v[54:55], off
	global_load_dwordx4 v[70:73], v[78:79], off offset:1024
	global_load_dwordx4 v[74:77], v[78:79], off offset:2048
	s_nop 0
	global_load_dwordx4 v[78:81], v[78:79], off offset:3072
	s_nop 0
	global_load_dwordx4 v[82:85], v[90:91], off offset:1024
	global_load_dwordx4 v[86:89], v[90:91], off offset:2048
	s_nop 0
	global_load_dwordx4 v[90:93], v[90:91], off offset:3072
	s_nop 0
	global_load_dwordx4 v[94:97], v[102:103], off offset:1024
	global_load_dwordx4 v[98:101], v[102:103], off offset:2048
	s_nop 0
	global_load_dwordx4 v[102:105], v[102:103], off offset:3072
	s_nop 0
	global_load_dwordx4 v[106:109], v[26:27], off offset:1024
	global_load_dwordx4 v[110:113], v[26:27], off offset:2048
	global_load_dwordx4 v[114:117], v[26:27], off offset:3072
	s_mov_b64 s[0:1], 0xcf00400
	s_waitcnt vmcnt(0)
	v_pk_add_f32 v[18:19], v[18:19], 0 op_sel_hi:[1,0]
	v_pk_add_f32 v[20:21], v[20:21], 0 op_sel_hi:[1,0]
	v_pk_add_f32 v[26:27], v[72:73], 0 op_sel_hi:[1,0]
	v_pk_add_f32 v[18:19], v[18:19], v[22:23]
	v_pk_add_f32 v[20:21], v[20:21], v[24:25]
	v_pk_add_f32 v[24:25], v[70:71], 0 op_sel_hi:[1,0]
	v_pk_add_f32 v[18:19], v[18:19], v[58:59]
	v_pk_add_f32 v[20:21], v[20:21], v[60:61]
	v_pk_add_f32 v[24:25], v[24:25], v[82:83]
	v_pk_add_f32 v[26:27], v[26:27], v[84:85]
	v_pk_add_f32 v[24:25], v[24:25], v[94:95]
	v_pk_add_f32 v[18:19], v[18:19], v[62:63]
	v_pk_add_f32 v[20:21], v[20:21], v[64:65]
	s_waitcnt lgkmcnt(0)
	v_pk_fma_f32 v[12:13], v[18:19], v[66:67], v[12:13]
	v_pk_fma_f32 v[14:15], v[20:21], v[68:69], v[14:15]
	global_store_dwordx4 v[118:119], v[12:15], off
	v_pk_add_f32 v[26:27], v[26:27], v[96:97]
	v_pk_add_f32 v[24:25], v[24:25], v[106:107]
	v_pk_add_f32 v[26:27], v[26:27], v[108:109]
	v_lshl_add_u64 v[22:23], v[16:17], 0, s[0:1]
	s_mov_b64 s[0:1], 0xcf00800
	v_pk_fma_f32 v[8:9], v[24:25], v[182:183], v[8:9]
	v_pk_fma_f32 v[10:11], v[26:27], v[184:185], v[10:11]
	global_store_dwordx4 v[22:23], v[8:11], off
	v_pk_add_f32 v[24:25], v[74:75], 0 op_sel_hi:[1,0]
	v_pk_add_f32 v[26:27], v[76:77], 0 op_sel_hi:[1,0]
	v_pk_add_f32 v[24:25], v[24:25], v[86:87]
	v_pk_add_f32 v[26:27], v[26:27], v[88:89]
	v_pk_add_f32 v[24:25], v[24:25], v[98:99]
	v_pk_add_f32 v[26:27], v[26:27], v[100:101]
	v_pk_add_f32 v[24:25], v[24:25], v[110:111]
	v_pk_add_f32 v[26:27], v[26:27], v[112:113]
	v_lshl_add_u64 v[22:23], v[16:17], 0, s[0:1]
	s_mov_b64 s[0:1], 0xcf00c00
	v_lshl_add_u64 v[16:17], v[16:17], 0, s[0:1]
	v_pk_fma_f32 v[4:5], v[24:25], v[186:187], v[4:5]
	v_pk_fma_f32 v[6:7], v[26:27], v[188:189], v[6:7]
	global_store_dwordx4 v[22:23], v[4:7], off
	v_pk_add_f32 v[22:23], v[78:79], 0 op_sel_hi:[1,0]
	v_pk_add_f32 v[24:25], v[80:81], 0 op_sel_hi:[1,0]
	v_pk_add_f32 v[22:23], v[22:23], v[90:91]
	v_pk_add_f32 v[24:25], v[24:25], v[92:93]
	v_pk_add_f32 v[22:23], v[22:23], v[102:103]
	v_pk_add_f32 v[24:25], v[24:25], v[104:105]
	v_pk_add_f32 v[22:23], v[22:23], v[114:115]
	v_pk_add_f32 v[24:25], v[24:25], v[116:117]
	v_pk_fma_f32 v[0:1], v[22:23], v[190:191], v[0:1]
	v_pk_fma_f32 v[2:3], v[24:25], v[192:193], v[2:3]
	global_store_dwordx4 v[16:17], v[0:3], off
	s_branch .LBB0_722

.LBB0_838:
	v_cmp_eq_u32_e64 s[0:1], 0, v175
	v_cmp_eq_u32_e64 s[2:3], 15, v175
	s_cmp_gt_i32 s18, -2
	s_waitcnt lgkmcnt(0)
	v_cndmask_b32_e64 v171, v212, v171, s[0:1]
	s_waitcnt vmcnt(0)
	v_mul_f32_e32 v171, v158, v171
	v_cndmask_b32_e64 v172, v172, v170, s[2:3]
	v_fmac_f32_e32 v171, v102, v146
	v_fmac_f32_e32 v171, v154, v172
	v_add_f32_e32 v102, v150, v171
	v_mul_f32_e32 v171, 0xbfb8aa3b, v102
	v_exp_f32_e32 v171, v171
	v_cndmask_b32_e64 v172, v218, v212, s[0:1]
	v_mul_f32_e32 v172, v158, v172
	v_cndmask_b32_e64 v170, v170, v211, s[2:3]
	v_fmac_f32_e32 v172, v90, v146
	v_fmac_f32_e32 v172, v154, v170
	v_add_f32_e32 v171, 1.0, v171
	v_add_f32_e32 v90, v150, v172
	v_rcp_f32_e32 v171, v171
	v_mul_f32_e32 v170, 0xbfb8aa3b, v90
	v_exp_f32_e32 v170, v170
	v_cndmask_b32_e64 v172, v217, v214, s[2:3]
	v_mul_f32_e32 v102, v102, v171
	v_mul_f32_e32 v82, v82, v102
	v_add_f32_e32 v102, 1.0, v170
	v_cndmask_b32_e64 v170, v215, v218, s[0:1]
	v_mul_f32_e32 v170, v158, v170
	v_cndmask_b32_e64 v171, v211, v217, s[2:3]
	v_fmac_f32_e32 v170, v86, v146
	v_fmac_f32_e32 v170, v154, v171
	v_add_f32_e32 v86, v150, v170
	v_mul_f32_e32 v170, 0xbfb8aa3b, v86
	v_rcp_f32_e32 v102, v102
	v_exp_f32_e32 v170, v170
	v_cndmask_b32_e64 v171, v216, v215, s[0:1]
	v_mul_f32_e32 v158, v158, v171
	v_mul_f32_e32 v90, v90, v102
	v_add_f32_e32 v102, 1.0, v170
	v_rcp_f32_e32 v102, v102
	v_fmac_f32_e32 v158, v78, v146
	v_fmac_f32_e32 v158, v154, v172
	v_add_f32_e32 v78, v150, v158
	v_mul_f32_e32 v86, v86, v102
	v_mul_f32_e32 v70, v70, v86
	v_cndmask_b32_e64 v86, v250, v251, s[0:1]
	v_mul_f32_e32 v146, 0xbfb8aa3b, v78
	v_mul_f32_e32 v86, v157, v86
	v_exp_f32_e32 v146, v146
	v_fmac_f32_e32 v86, v101, v145
	v_cndmask_b32_e64 v101, v248, v250, s[0:1]
	v_mul_f32_e32 v101, v157, v101
	v_mul_f32_e32 v74, v74, v90
	v_cndmask_b32_e64 v90, v213, v252, s[2:3]
	v_cndmask_b32_e64 v102, v252, v249, s[2:3]
	v_fmac_f32_e32 v101, v89, v145
	v_fmac_f32_e32 v86, v153, v90
	v_fmac_f32_e32 v101, v153, v102
	v_add_f32_e32 v146, 1.0, v146
	v_add_f32_e32 v86, v149, v86
	v_add_f32_e32 v89, v149, v101
	v_rcp_f32_e32 v146, v146
	v_mul_f32_e32 v90, 0xbfb8aa3b, v86
	v_mul_f32_e32 v101, 0xbfb8aa3b, v89
	v_exp_f32_e32 v90, v90
	v_exp_f32_e32 v101, v101
	v_mul_f32_e32 v78, v78, v146
	v_mul_f32_e32 v66, v66, v78
	v_add_f32_e32 v78, 1.0, v90
	v_add_f32_e32 v90, 1.0, v101
	v_cndmask_b32_e64 v101, v245, v248, s[0:1]
	v_mul_f32_e32 v101, v157, v101
	v_cndmask_b32_e64 v102, v249, v247, s[2:3]
	v_fmac_f32_e32 v101, v85, v145
	v_fmac_f32_e32 v101, v153, v102
	v_add_f32_e32 v85, v149, v101
	v_rcp_f32_e32 v78, v78
	v_mul_f32_e32 v101, 0xbfb8aa3b, v85
	v_rcp_f32_e32 v90, v90
	v_exp_f32_e32 v101, v101
	v_mul_f32_e32 v78, v86, v78
	v_mul_f32_e32 v78, v81, v78
	v_mul_f32_e32 v81, v89, v90
	v_add_f32_e32 v86, 1.0, v101
	v_cndmask_b32_e64 v89, v246, v245, s[0:1]
	v_rcp_f32_e32 v86, v86
	v_mul_f32_e32 v89, v157, v89
	v_cndmask_b32_e64 v90, v247, v244, s[2:3]
	v_fmac_f32_e32 v89, v77, v145
	v_fmac_f32_e32 v89, v153, v90
	v_add_f32_e32 v77, v149, v89
	v_mul_f32_e32 v89, 0xbfb8aa3b, v77
	v_mul_f32_e32 v73, v73, v81
	v_mul_f32_e32 v81, v85, v86
	v_cndmask_b32_e64 v85, v238, v239, s[0:1]
	v_exp_f32_e32 v89, v89
	v_mul_f32_e32 v85, v156, v85
	v_cndmask_b32_e64 v86, v243, v240, s[2:3]
	v_fmac_f32_e32 v85, v100, v144
	v_fmac_f32_e32 v85, v152, v86
	v_add_f32_e32 v85, v148, v85
	v_mul_f32_e32 v69, v69, v81
	v_add_f32_e32 v81, 1.0, v89
	v_mul_f32_e32 v86, 0xbfb8aa3b, v85
	v_cndmask_b32_e64 v89, v236, v238, s[0:1]
	v_rcp_f32_e32 v81, v81
	v_exp_f32_e32 v86, v86
	v_mul_f32_e32 v89, v156, v89
	v_cndmask_b32_e64 v90, v240, v237, s[2:3]
	v_fmac_f32_e32 v89, v88, v144
	v_fmac_f32_e32 v89, v152, v90
	v_add_f32_e32 v88, v148, v89
	v_mul_f32_e32 v89, 0xbfb8aa3b, v88
	v_mul_f32_e32 v77, v77, v81
	v_add_f32_e32 v81, 1.0, v86
	v_exp_f32_e32 v89, v89
	v_rcp_f32_e32 v81, v81
	v_mul_f32_e32 v65, v65, v77
	v_cndmask_b32_e64 v100, v196, v193, s[2:3]
	v_add_f32_e32 v86, 1.0, v89
	v_mul_f32_e32 v77, v85, v81
	v_cndmask_b32_e64 v81, v233, v236, s[0:1]
	v_rcp_f32_e32 v86, v86
	v_mul_f32_e32 v81, v156, v81
	v_cndmask_b32_e64 v85, v237, v235, s[2:3]
	v_fmac_f32_e32 v81, v84, v144
	v_fmac_f32_e32 v81, v152, v85
	v_cndmask_b32_e64 v85, v234, v233, s[0:1]
	v_mul_f32_e32 v85, v156, v85
	v_mul_f32_e32 v77, v80, v77
	v_mul_f32_e32 v80, v88, v86
	v_cndmask_b32_e64 v86, v235, v232, s[2:3]
	v_fmac_f32_e32 v85, v76, v144
	v_fmac_f32_e32 v85, v152, v86
	v_add_f32_e32 v81, v148, v81
	v_add_f32_e32 v76, v148, v85
	v_mul_f32_e32 v84, 0xbfb8aa3b, v81
	v_mul_f32_e32 v85, 0xbfb8aa3b, v76
	v_exp_f32_e32 v84, v84
	v_exp_f32_e32 v85, v85
	v_mul_f32_e32 v72, v72, v80
	v_cndmask_b32_e64 v86, v231, v230, s[2:3]
	v_add_f32_e32 v80, 1.0, v84
	v_add_f32_e32 v84, 1.0, v85
	v_cndmask_b32_e64 v85, v229, v227, s[0:1]
	v_rcp_f32_e32 v80, v80
	v_mul_f32_e32 v85, v131, v85
	v_fmac_f32_e32 v85, v127, v135
	v_rcp_f32_e32 v84, v84
	v_fmac_f32_e32 v85, v139, v86
	v_add_f32_e32 v85, v143, v85
	v_mul_f32_e32 v86, 0xbfb8aa3b, v85
	v_mul_f32_e32 v80, v81, v80
	v_cndmask_b32_e64 v81, v226, v229, s[0:1]
	v_exp_f32_e32 v86, v86
	v_mul_f32_e32 v81, v131, v81
	v_mul_f32_e32 v76, v76, v84
	v_cndmask_b32_e64 v84, v230, v228, s[2:3]
	v_fmac_f32_e32 v81, v123, v135
	v_fmac_f32_e32 v81, v139, v84
	v_add_f32_e32 v81, v143, v81
	v_mul_f32_e32 v68, v68, v80
	v_add_f32_e32 v80, 1.0, v86
	v_mul_f32_e32 v84, 0xbfb8aa3b, v81
	v_rcp_f32_e32 v80, v80
	v_exp_f32_e32 v84, v84
	v_mul_f32_e32 v64, v64, v76
	v_cndmask_b32_e64 v86, v224, v223, s[0:1]
	v_mul_f32_e32 v76, v85, v80
	v_add_f32_e32 v80, 1.0, v84
	v_cndmask_b32_e64 v84, v223, v226, s[0:1]
	v_mul_f32_e32 v84, v131, v84
	v_cndmask_b32_e64 v85, v228, v225, s[2:3]
	v_fmac_f32_e32 v84, v119, v135
	v_mul_f32_e32 v86, v131, v86
	v_fmac_f32_e32 v84, v139, v85
	v_cndmask_b32_e64 v88, v225, v222, s[2:3]
	v_fmac_f32_e32 v86, v111, v135
	v_add_f32_e32 v84, v143, v84
	v_fmac_f32_e32 v86, v139, v88
	v_mul_f32_e32 v85, 0xbfb8aa3b, v84
	v_add_f32_e32 v86, v143, v86
	v_rcp_f32_e32 v80, v80
	v_exp_f32_e32 v85, v85
	v_mul_f32_e32 v88, 0xbfb8aa3b, v86
	v_exp_f32_e32 v88, v88
	v_mul_f32_e32 v80, v81, v80
	v_add_f32_e32 v81, 1.0, v85
	v_rcp_f32_e32 v81, v81
	v_add_f32_e32 v85, 1.0, v88
	v_rcp_f32_e32 v85, v85
	v_mul_f32_e32 v88, v107, v80
	v_mul_f32_e32 v80, v84, v81
	v_mul_f32_e32 v89, v99, v80
	v_mul_f32_e32 v80, v86, v85
	v_cndmask_b32_e64 v81, v205, v219, s[0:1]
	v_cndmask_b32_e64 v85, v203, v205, s[0:1]
	v_mul_f32_e32 v81, v130, v81
	v_mul_f32_e32 v85, v130, v85
	v_cndmask_b32_e64 v84, v221, v220, s[2:3]
	v_fmac_f32_e32 v81, v126, v134
	v_cndmask_b32_e64 v86, v220, v204, s[2:3]
	v_fmac_f32_e32 v85, v122, v134
	v_fmac_f32_e32 v81, v138, v84
	v_fmac_f32_e32 v85, v138, v86
	v_add_f32_e32 v81, v142, v81
	v_add_f32_e32 v85, v142, v85
	v_mul_f32_e32 v84, 0xbfb8aa3b, v81
	v_mul_f32_e32 v86, 0xbfb8aa3b, v85
	v_exp_f32_e32 v84, v84
	v_exp_f32_e32 v86, v86
	v_mul_f32_e32 v90, v95, v80
	v_cndmask_b32_e64 v95, v204, v202, s[2:3]
	v_add_f32_e32 v80, 1.0, v84
	v_add_f32_e32 v84, 1.0, v86
	v_cndmask_b32_e64 v86, v200, v203, s[0:1]
	v_mul_f32_e32 v86, v130, v86
	v_rcp_f32_e32 v80, v80
	v_fmac_f32_e32 v86, v118, v134
	v_rcp_f32_e32 v84, v84
	v_fmac_f32_e32 v86, v138, v95
	v_add_f32_e32 v86, v142, v86
	v_mul_f32_e32 v95, 0xbfb8aa3b, v86
	v_exp_f32_e32 v95, v95
	v_mul_f32_e32 v80, v81, v80
	v_mul_f32_e32 v99, v114, v80
	v_mul_f32_e32 v80, v85, v84
	v_cndmask_b32_e64 v84, v201, v200, s[0:1]
	v_mul_f32_e32 v84, v130, v84
	v_cndmask_b32_e64 v85, v202, v199, s[2:3]
	v_fmac_f32_e32 v84, v110, v134
	v_add_f32_e32 v81, 1.0, v95
	v_fmac_f32_e32 v84, v138, v85
	v_rcp_f32_e32 v81, v81
	v_add_f32_e32 v84, v142, v84
	v_mul_f32_e32 v85, 0xbfb8aa3b, v84
	v_exp_f32_e32 v85, v85
	v_mul_f32_e32 v95, v106, v80
	v_mul_f32_e32 v80, v86, v81
	v_cndmask_b32_e64 v81, v194, v195, s[0:1]
	v_mul_f32_e32 v81, v129, v81
	v_cndmask_b32_e64 v86, v192, v194, s[0:1]
	v_mul_f32_e32 v98, v98, v80
	v_add_f32_e32 v80, 1.0, v85
	v_cndmask_b32_e64 v85, v197, v196, s[2:3]
	v_fmac_f32_e32 v81, v125, v133
	v_mul_f32_e32 v86, v129, v86
	v_fmac_f32_e32 v81, v137, v85
	v_fmac_f32_e32 v86, v121, v133
	v_add_f32_e32 v81, v141, v81
	v_fmac_f32_e32 v86, v137, v100
	v_mul_f32_e32 v85, 0xbfb8aa3b, v81
	v_add_f32_e32 v86, v141, v86
	v_rcp_f32_e32 v80, v80
	v_exp_f32_e32 v85, v85
	v_mul_f32_e32 v100, 0xbfb8aa3b, v86
	v_exp_f32_e32 v100, v100
	v_mul_f32_e32 v80, v84, v80
	v_add_f32_e32 v84, 1.0, v85
	v_rcp_f32_e32 v84, v84
	v_add_f32_e32 v85, 1.0, v100
	v_rcp_f32_e32 v85, v85
	v_mul_f32_e32 v94, v94, v80
	v_mul_f32_e32 v80, v81, v84
	v_mul_f32_e32 v84, v113, v80
	v_mul_f32_e32 v80, v86, v85
	v_cndmask_b32_e64 v81, v188, v192, s[0:1]
	v_cndmask_b32_e64 v86, v190, v188, s[0:1]
	v_mul_f32_e32 v81, v129, v81
	v_mul_f32_e32 v86, v129, v86
	v_cndmask_b32_e64 v85, v193, v191, s[2:3]
	v_fmac_f32_e32 v81, v117, v133
	v_cndmask_b32_e64 v100, v191, v187, s[2:3]
	v_fmac_f32_e32 v86, v109, v133
	v_fmac_f32_e32 v81, v137, v85
	v_fmac_f32_e32 v86, v137, v100
	v_add_f32_e32 v81, v141, v81
	v_add_f32_e32 v86, v141, v86
	v_mul_f32_e32 v85, 0xbfb8aa3b, v81
	v_mul_f32_e32 v100, 0xbfb8aa3b, v86
	v_exp_f32_e32 v85, v85
	v_exp_f32_e32 v100, v100
	v_mul_f32_e32 v101, v105, v80
	v_cndmask_b32_e64 v102, v186, v185, s[2:3]
	v_add_f32_e32 v80, 1.0, v85
	v_add_f32_e32 v85, 1.0, v100
	v_cndmask_b32_e64 v100, v184, v183, s[0:1]
	v_mul_f32_e32 v100, v128, v100
	v_rcp_f32_e32 v80, v80
	v_fmac_f32_e32 v100, v124, v132
	v_rcp_f32_e32 v85, v85
	v_fmac_f32_e32 v100, v136, v102
	v_add_f32_e32 v100, v140, v100
	v_mul_f32_e32 v102, 0xbfb8aa3b, v100
	v_exp_f32_e32 v102, v102
	v_mul_f32_e32 v80, v81, v80
	v_mul_f32_e32 v97, v97, v80
	v_mul_f32_e32 v80, v86, v85
	v_cndmask_b32_e64 v85, v181, v184, s[0:1]
	v_mul_f32_e32 v85, v128, v85
	v_cndmask_b32_e64 v86, v185, v182, s[2:3]
	v_fmac_f32_e32 v85, v120, v132
	v_add_f32_e32 v81, 1.0, v102
	v_fmac_f32_e32 v85, v136, v86
	v_rcp_f32_e32 v81, v81
	v_add_f32_e32 v85, v140, v85
	v_mul_f32_e32 v86, 0xbfb8aa3b, v85
	v_exp_f32_e32 v86, v86
	v_mul_f32_e32 v93, v93, v80
	v_mul_f32_e32 v80, v100, v81
	v_cndmask_b32_e64 v81, v178, v181, s[0:1]
	v_mul_f32_e32 v81, v128, v81
	v_cndmask_b32_e64 v102, v179, v178, s[0:1]
	v_mul_f32_e32 v100, v112, v80
	v_add_f32_e32 v80, 1.0, v86
	v_cndmask_b32_e64 v86, v182, v180, s[2:3]
	v_fmac_f32_e32 v81, v116, v132
	v_mul_f32_e32 v102, v128, v102
	v_fmac_f32_e32 v81, v136, v86
	v_cndmask_b32_e64 v105, v180, v177, s[2:3]
	v_fmac_f32_e32 v102, v108, v132
	v_add_f32_e32 v81, v140, v81
	v_fmac_f32_e32 v102, v136, v105
	v_mul_f32_e32 v86, 0xbfb8aa3b, v81
	v_add_f32_e32 v102, v140, v102
	v_rcp_f32_e32 v80, v80
	v_exp_f32_e32 v86, v86
	v_mul_f32_e32 v105, 0xbfb8aa3b, v102
	v_exp_f32_e32 v105, v105
	v_mul_f32_e32 v80, v85, v80
	v_add_f32_e32 v85, 1.0, v86
	v_rcp_f32_e32 v85, v85
	v_add_f32_e32 v86, 1.0, v105
	v_rcp_f32_e32 v86, v86
	v_mul_f32_e32 v104, v104, v80
	v_mul_f32_e32 v80, v81, v85
	v_mul_f32_e32 v96, v96, v80
	v_mul_f32_e32 v80, v102, v86
	v_mul_f32_e32 v92, v92, v80
	v_mov_b32_e32 v85, v169
	v_mov_b32_e32 v80, v169
	v_mov_b32_e32 v102, v169
	v_mov_b32_dpp v85, v103 row_ror:1 row_mask:0xf bank_mask:0xf
	v_mov_b32_dpp v80, v103 row_ror:15 row_mask:0xf bank_mask:0xf
	v_mov_b32_dpp v102, v91 row_ror:15 row_mask:0xf bank_mask:0xf
	v_mov_b32_e32 v154, v159
	v_cndmask_b32_e64 v81, v80, v102, s[2:3]
	v_cndmask_b32_e64 v80, v85, v198, s[0:1]
	v_pk_mul_f32 v[80:81], v[154:155], v[80:81]
	v_mov_b32_e32 v86, v169
	v_fma_f32 v80, v103, v147, v80
	v_add_f32_e32 v80, v80, v81
	v_add_f32_e32 v103, v151, v80
	v_mul_f32_e32 v80, 0xbfb8aa3b, v103
	v_exp_f32_e32 v80, v80
	v_mov_b32_e32 v106, v169
	v_mov_b32_dpp v86, v91 row_ror:1 row_mask:0xf bank_mask:0xf
	v_mov_b32_e32 v105, v169
	v_mov_b32_dpp v106, v87 row_ror:15 row_mask:0xf bank_mask:0xf
	v_add_f32_e32 v80, 1.0, v80
	v_rcp_f32_e32 v109, v80
	v_cndmask_b32_e64 v81, v102, v106, s[2:3]
	v_cndmask_b32_e64 v80, v86, v85, s[0:1]
	v_pk_mul_f32 v[80:81], v[154:155], v[80:81]
	v_mov_b32_e32 v108, v169
	v_fma_f32 v80, v91, v147, v80
	v_add_f32_e32 v80, v80, v81
	v_add_f32_e32 v85, v151, v80
	v_mul_f32_e32 v80, 0xbfb8aa3b, v85
	v_exp_f32_e32 v80, v80
	v_mov_b32_dpp v105, v87 row_ror:1 row_mask:0xf bank_mask:0xf
	v_mov_b32_dpp v108, v79 row_ror:15 row_mask:0xf bank_mask:0xf
	v_mul_f32_e32 v81, v103, v109
	v_add_f32_e32 v80, 1.0, v80
	v_mul_f32_e32 v83, v83, v81
	v_rcp_f32_e32 v91, v80
	v_cndmask_b32_e64 v81, v106, v108, s[2:3]
	v_cndmask_b32_e64 v80, v105, v86, s[0:1]
	v_pk_mul_f32 v[80:81], v[154:155], v[80:81]
	v_mov_b32_e32 v107, v169
	v_fma_f32 v80, v87, v147, v80
	v_add_f32_e32 v80, v80, v81
	v_add_f32_e32 v86, v151, v80
	v_mov_b32_dpp v107, v79 row_ror:1 row_mask:0xf bank_mask:0xf
	v_mul_f32_e32 v80, 0xbfb8aa3b, v86
	v_exp_f32_e32 v87, v80
	v_cndmask_b32_e64 v80, v107, v105, s[0:1]
	v_cndmask_b32_e64 v81, v108, v189, s[2:3]
	v_pk_mul_f32 v[80:81], v[154:155], v[80:81]
	s_cselect_b64 s[10:11], -1, 0
	v_fma_f32 v79, v79, v147, v80
	v_add_f32_e32 v79, v79, v81
	v_add_f32_e32 v79, v151, v79
	v_mul_f32_e32 v80, 0xbfb8aa3b, v79
	v_exp_f32_e32 v80, v80
	v_mul_f32_e32 v81, v85, v91
	v_add_f32_e32 v85, 1.0, v87
	v_rcp_f32_e32 v85, v85
	v_add_f32_e32 v80, 1.0, v80
	v_rcp_f32_e32 v80, v80
	s_add_u32 s8, s6, 0x7400000
	s_addc_u32 s9, s7, 0
	v_mul_f32_e32 v75, v75, v81
	v_mul_f32_e32 v81, v86, v85
	v_readlane_b32 s4, v253, 60
	v_mul_f32_e32 v76, v115, v76
	v_mul_f32_e32 v71, v71, v81
	v_mul_f32_e32 v79, v79, v80
	v_add_u32_e32 v91, s4, v174
	v_mov_b64_e32 v[80:81], s[8:9]
	s_movk_i32 s6, 0x1600
	v_cvt_pk_bf16_f32 v84, v100, v84
	v_cvt_pk_bf16_f32 v85, v99, v76
	v_cvt_pk_bf16_f32 v86, v77, v78
	v_mad_i64_i32 v[76:77], s[4:5], v91, s6, v[80:81]
	v_lshlrev_b32_e32 v168, 1, v168
	v_cvt_pk_bf16_f32 v87, v82, v83
	v_lshl_add_u64 v[76:77], v[76:77], 0, v[168:169]
	v_add_u32_e32 v82, 16, v91
	global_store_dwordx4 v[76:77], v[84:87], off
	v_cvt_pk_bf16_f32 v76, v104, v101
	v_cvt_pk_bf16_f32 v77, v95, v88
	v_cvt_pk_bf16_f32 v78, v72, v73
	v_mad_i64_i32 v[72:73], s[4:5], v82, s6, v[80:81]
	v_lshl_add_u64 v[72:73], v[72:73], 0, v[168:169]
	v_mul_f32_e32 v67, v67, v79
	v_cvt_pk_bf16_f32 v79, v74, v75
	global_store_dwordx4 v[72:73], v[76:79], off
	v_cvt_pk_bf16_f32 v72, v96, v97
	v_cvt_pk_bf16_f32 v73, v98, v89
	v_cvt_pk_bf16_f32 v74, v68, v69
	v_cvt_pk_bf16_f32 v75, v70, v71
	v_mov_b32_e32 v103, 0
	s_nop 0
	v_add_u32_e32 v76, 32, v91
	v_mad_i64_i32 v[68:69], s[4:5], v76, s6, v[80:81]
	v_lshl_add_u64 v[68:69], v[68:69], 0, v[168:169]
	global_store_dwordx4 v[68:69], v[72:75], off
	v_cvt_pk_bf16_f32 v68, v92, v93
	v_cvt_pk_bf16_f32 v69, v94, v90
	v_cvt_pk_bf16_f32 v70, v64, v65
	v_cvt_pk_bf16_f32 v71, v66, v67
	v_mov_b32_e32 v98, 0
	s_nop 0
	v_add_u32_e32 v72, 48, v91
	v_mad_i64_i32 v[64:65], s[4:5], v72, s6, v[80:81]
	v_lshl_add_u64 v[64:65], v[64:65], 0, v[168:169]
	global_store_dwordx4 v[64:65], v[68:71], off
	global_load_dwordx4 v[64:67], v[162:163], off
	s_nop 0
	global_load_dwordx4 v[68:71], v[164:165], off
	global_load_dwordx4 v[76:79], v[166:167], off
	global_load_dwordx4 v[72:75], v[160:161], off
	s_add_i32 s4, s12, 0x20a00
	s_cmp_lt_i32 s18, -1
	v_lshl_add_u32 v96, v176, 2, s4
	s_cbranch_scc1 .LBB0_840
	ds_read_b32 v98, v96

.LBB0_870:
	v_mov_b32_e32 v172, v169
	v_mov_b32_e32 v171, v169
	v_mov_b32_e32 v126, v169
	v_mov_b32_e32 v173, v169
	v_mov_b32_e32 v129, v169
	v_mov_b32_dpp v172, v59 row_ror:1 row_mask:0xf bank_mask:0xf
	v_mov_b32_dpp v171, v59 row_ror:15 row_mask:0xf bank_mask:0xf
	v_mov_b32_dpp v126, v63 row_ror:1 row_mask:0xf bank_mask:0xf
	v_mov_b32_dpp v173, v63 row_ror:15 row_mask:0xf bank_mask:0xf
	v_mov_b32_dpp v129, v31 row_ror:15 row_mask:0xf bank_mask:0xf
	s_waitcnt vmcnt(0)
	v_mov_b32_e32 v96, v91
	v_mov_b32_e32 v97, v95
	v_cndmask_b32_e64 v171, v171, v173, s[2:3]
	s_waitcnt lgkmcnt(0)
	v_cndmask_b32_e64 v170, v172, v170, s[0:1]
	v_cndmask_b32_e64 v173, v173, v129, s[2:3]
	v_cndmask_b32_e64 v172, v126, v172, s[0:1]
	v_pk_mul_f32 v[172:173], v[96:97], v[172:173]
	v_pk_mul_f32 v[170:171], v[96:97], v[170:171]
	v_fma_f32 v63, v63, v83, v172
	v_add_f32_e32 v63, v63, v173
	v_fma_f32 v59, v59, v83, v170
	v_add_f32_e32 v63, v87, v63
	v_add_f32_e32 v59, v59, v171
	v_mul_f32_e32 v91, 0xbfb8aa3b, v63
	v_add_f32_e32 v59, v87, v59
	v_exp_f32_e32 v91, v91
	v_mul_f32_e32 v95, 0xbfb8aa3b, v59
	v_exp_f32_e32 v95, v95
	v_cndmask_b32_e64 v170, v179, v177, s[0:1]
	v_add_f32_e32 v91, 1.0, v91
	v_rcp_f32_e32 v91, v91
	v_add_f32_e32 v95, 1.0, v95
	v_rcp_f32_e32 v95, v95
	v_cndmask_b32_e64 v171, v178, v176, s[2:3]
	v_mul_f32_e32 v63, v63, v91
	v_mov_b32_e32 v91, v94
	v_mul_f32_e32 v59, v59, v95
	v_pk_mul_f32 v[94:95], v[90:91], v[170:171]
	v_mul_f32_e32 v55, v55, v63
	v_fma_f32 v14, v14, v82, v94
	v_add_f32_e32 v14, v14, v95
	v_cndmask_b32_e64 v94, v177, v167, s[0:1]
	v_cndmask_b32_e64 v95, v175, v178, s[2:3]
	v_pk_mul_f32 v[94:95], v[90:91], v[94:95]
	v_add_f32_e32 v14, v86, v14
	v_fma_f32 v30, v30, v82, v94
	v_add_f32_e32 v30, v30, v95
	v_add_f32_e32 v30, v86, v30
	v_mul_f32_e32 v94, 0xbfb8aa3b, v30
	v_exp_f32_e32 v94, v94
	v_mul_f32_e32 v63, 0xbfb8aa3b, v14
	v_exp_f32_e32 v63, v63
	v_mul_f32_e32 v170, v51, v59
	v_add_f32_e32 v59, 1.0, v94
	v_cndmask_b32_e64 v94, v167, v164, s[0:1]
	v_cndmask_b32_e64 v95, v166, v175, s[2:3]
	v_pk_mul_f32 v[94:95], v[90:91], v[94:95]
	v_add_f32_e32 v51, 1.0, v63
	v_fma_f32 v62, v62, v82, v94
	v_add_f32_e32 v62, v62, v95
	v_add_f32_e32 v94, v86, v62
	v_rcp_f32_e32 v51, v51
	v_mul_f32_e32 v62, 0xbfb8aa3b, v94
	v_rcp_f32_e32 v59, v59
	v_exp_f32_e32 v62, v62
	v_mul_f32_e32 v14, v14, v51
	v_mul_f32_e32 v2, v2, v14
	v_mul_f32_e32 v14, v30, v59
	v_add_f32_e32 v30, 1.0, v62
	v_cndmask_b32_e64 v62, v164, v163, s[0:1]
	v_cndmask_b32_e64 v63, v165, v166, s[2:3]
	v_pk_mul_f32 v[62:63], v[90:91], v[62:63]
	v_rcp_f32_e32 v30, v30
	v_fma_f32 v51, v58, v82, v62
	v_add_f32_e32 v51, v51, v63
	v_add_f32_e32 v51, v86, v51
	v_mul_f32_e32 v58, 0xbfb8aa3b, v51
	v_exp_f32_e32 v58, v58
	v_mul_f32_e32 v14, v6, v14
	v_mul_f32_e32 v6, v94, v30
	v_mul_f32_e32 v30, v54, v6
	v_add_f32_e32 v6, 1.0, v58
	v_cndmask_b32_e64 v58, v162, v160, s[0:1]
	v_cndmask_b32_e64 v59, v161, v159, s[2:3]
	v_mov_b32_e32 v62, v89
	v_mov_b32_e32 v63, v93
	v_pk_mul_f32 v[58:59], v[62:63], v[58:59]
	v_rcp_f32_e32 v6, v6
	v_fma_f32 v13, v13, v81, v58
	v_add_f32_e32 v13, v13, v59
	v_add_f32_e32 v13, v85, v13
	v_mul_f32_e32 v54, 0xbfb8aa3b, v13
	v_cndmask_b32_e64 v58, v160, v157, s[0:1]
	v_cndmask_b32_e64 v59, v158, v161, s[2:3]
	v_exp_f32_e32 v54, v54
	v_pk_mul_f32 v[58:59], v[62:63], v[58:59]
	v_mul_f32_e32 v6, v51, v6
	v_fma_f32 v29, v29, v81, v58
	v_add_f32_e32 v29, v29, v59
	v_add_f32_e32 v29, v85, v29
	v_mul_f32_e32 v58, 0xbfb8aa3b, v29
	v_add_f32_e32 v51, 1.0, v54
	v_exp_f32_e32 v58, v58
	v_rcp_f32_e32 v51, v51
	v_mov_b32_e32 v89, v92
	v_mov_b32_e32 v127, v169
	v_add_f32_e32 v54, 1.0, v58
	v_mul_f32_e32 v58, v50, v6
	v_mul_f32_e32 v6, v13, v51
	v_cndmask_b32_e64 v50, v157, v154, s[0:1]
	v_cndmask_b32_e64 v51, v156, v158, s[2:3]
	v_rcp_f32_e32 v54, v54
	v_pk_mul_f32 v[50:51], v[62:63], v[50:51]
	v_mul_f32_e32 v59, v1, v6
	v_fma_f32 v6, v61, v81, v50
	v_add_f32_e32 v6, v6, v51
	v_cndmask_b32_e64 v50, v154, v153, s[0:1]
	v_cndmask_b32_e64 v51, v155, v156, s[2:3]
	v_pk_mul_f32 v[50:51], v[62:63], v[50:51]
	v_mul_f32_e32 v1, v29, v54
	v_fma_f32 v29, v57, v81, v50
	v_add_f32_e32 v29, v29, v51
	v_add_f32_e32 v29, v85, v29
	v_mul_f32_e32 v50, 0xbfb8aa3b, v29
	v_exp_f32_e32 v50, v50
	v_add_f32_e32 v6, v85, v6
	v_mul_f32_e32 v13, 0xbfb8aa3b, v6
	v_exp_f32_e32 v13, v13
	v_mul_f32_e32 v54, v5, v1
	v_add_f32_e32 v5, 1.0, v50
	v_cndmask_b32_e64 v50, v152, v150, s[0:1]
	v_cndmask_b32_e64 v51, v151, v149, s[2:3]
	v_pk_mul_f32 v[50:51], v[88:89], v[50:51]
	v_add_f32_e32 v1, 1.0, v13
	v_fma_f32 v12, v12, v80, v50
	v_add_f32_e32 v12, v12, v51
	v_add_f32_e32 v50, v84, v12
	v_rcp_f32_e32 v1, v1
	v_mul_f32_e32 v12, 0xbfb8aa3b, v50
	v_rcp_f32_e32 v5, v5
	v_exp_f32_e32 v12, v12
	v_mul_f32_e32 v1, v6, v1
	v_mul_f32_e32 v51, v53, v1
	v_mul_f32_e32 v1, v29, v5
	v_add_f32_e32 v5, 1.0, v12
	v_cndmask_b32_e64 v12, v150, v147, s[0:1]
	v_cndmask_b32_e64 v13, v148, v151, s[2:3]
	v_pk_mul_f32 v[12:13], v[88:89], v[12:13]
	v_rcp_f32_e32 v5, v5
	v_fma_f32 v6, v28, v80, v12
	v_add_f32_e32 v6, v6, v13
	v_add_f32_e32 v6, v84, v6
	v_mul_f32_e32 v12, 0xbfb8aa3b, v6
	v_exp_f32_e32 v12, v12
	v_mul_f32_e32 v13, v49, v1
	v_mul_f32_e32 v1, v50, v5
	v_mul_f32_e32 v28, v0, v1
	v_add_f32_e32 v0, 1.0, v12
	v_rcp_f32_e32 v5, v0
	v_cndmask_b32_e64 v0, v147, v144, s[0:1]
	v_cndmask_b32_e64 v1, v146, v148, s[2:3]
	v_pk_mul_f32 v[0:1], v[88:89], v[0:1]
	v_mul_f32_e32 v5, v6, v5
	v_fma_f32 v0, v60, v80, v0
	v_add_f32_e32 v0, v0, v1
	v_add_f32_e32 v12, v84, v0
	v_mul_f32_e32 v0, 0xbfb8aa3b, v12
	v_exp_f32_e32 v29, v0
	v_cndmask_b32_e64 v0, v144, v143, s[0:1]
	v_cndmask_b32_e64 v1, v145, v146, s[2:3]
	v_pk_mul_f32 v[0:1], v[88:89], v[0:1]
	v_add_f32_e32 v6, 1.0, v29
	v_fma_f32 v0, v56, v80, v0
	v_add_f32_e32 v0, v0, v1
	v_add_f32_e32 v0, v84, v0
	v_mul_f32_e32 v1, 0xbfb8aa3b, v0
	v_exp_f32_e32 v1, v1
	v_rcp_f32_e32 v6, v6
	v_mul_f32_e32 v29, v4, v5
	v_mov_b32_e32 v5, v79
	v_add_f32_e32 v1, 1.0, v1
	v_rcp_f32_e32 v1, v1
	v_mul_f32_e32 v4, v12, v6
	v_mul_f32_e32 v12, v52, v4
	v_mov_b32_e32 v4, v67
	v_mul_f32_e32 v6, v0, v1
	v_cndmask_b32_e64 v0, v142, v140, s[0:1]
	v_cndmask_b32_e64 v1, v141, v137, s[2:3]
	v_pk_mul_f32 v[0:1], v[4:5], v[0:1]
	v_mul_f32_e32 v6, v48, v6
	v_fma_f32 v0, v47, v71, v0
	v_add_f32_e32 v0, v0, v1
	v_add_f32_e32 v47, v75, v0
	v_mul_f32_e32 v0, 0xbfb8aa3b, v47
	v_exp_f32_e32 v49, v0
	v_cndmask_b32_e64 v0, v140, v138, s[0:1]
	v_cndmask_b32_e64 v1, v139, v141, s[2:3]
	v_pk_mul_f32 v[0:1], v[4:5], v[0:1]
	v_mov_b32_e32 v67, v78
	v_fma_f32 v0, v43, v71, v0
	v_add_f32_e32 v0, v0, v1
	v_add_f32_e32 v43, v75, v0
	v_mul_f32_e32 v0, 0xbfb8aa3b, v43
	v_exp_f32_e32 v0, v0
	v_add_f32_e32 v1, 1.0, v49
	v_rcp_f32_e32 v48, v1
	v_cndmask_b32_e64 v1, v136, v139, s[2:3]
	v_add_f32_e32 v0, 1.0, v0
	v_rcp_f32_e32 v49, v0
	v_cndmask_b32_e64 v0, v138, v134, s[0:1]
	v_pk_mul_f32 v[0:1], v[4:5], v[0:1]
	v_mov_b32_e32 v131, v169
	v_fma_f32 v0, v39, v71, v0
	v_add_f32_e32 v0, v0, v1
	v_add_f32_e32 v39, v75, v0
	v_mul_f32_e32 v0, 0xbfb8aa3b, v39
	v_exp_f32_e32 v0, v0
	v_mul_f32_e32 v1, v47, v48
	v_mul_f32_e32 v27, v27, v1
	v_cndmask_b32_e64 v1, v135, v136, s[2:3]
	v_add_f32_e32 v0, 1.0, v0
	v_rcp_f32_e32 v47, v0
	v_cndmask_b32_e64 v0, v134, v133, s[0:1]
	v_pk_mul_f32 v[0:1], v[4:5], v[0:1]
	v_mov_b32_e32 v172, v169
	v_fma_f32 v0, v35, v71, v0
	v_add_f32_e32 v0, v0, v1
	v_add_f32_e32 v4, v75, v0
	v_mul_f32_e32 v0, 0xbfb8aa3b, v4
	v_exp_f32_e32 v0, v0
	v_mul_f32_e32 v1, v39, v47
	v_mul_f32_e32 v23, v23, v1
	v_cndmask_b32_e64 v1, v130, v125, s[2:3]
	v_add_f32_e32 v0, 1.0, v0
	v_rcp_f32_e32 v5, v0
	v_cndmask_b32_e64 v0, v132, v128, s[0:1]
	v_pk_mul_f32 v[0:1], v[66:67], v[0:1]
	v_mov_b32_dpp v127, v31 row_ror:1 row_mask:0xf bank_mask:0xf
	v_fma_f32 v0, v46, v70, v0
	v_add_f32_e32 v0, v0, v1
	v_add_f32_e32 v35, v74, v0
	v_mul_f32_e32 v0, 0xbfb8aa3b, v35
	v_exp_f32_e32 v39, v0
	v_cndmask_b32_e64 v0, v128, v122, s[0:1]
	v_cndmask_b32_e64 v1, v124, v130, s[2:3]
	v_pk_mul_f32 v[0:1], v[66:67], v[0:1]
	v_mul_f32_e32 v4, v4, v5
	v_fma_f32 v0, v42, v70, v0
	v_add_f32_e32 v0, v0, v1
	v_add_f32_e32 v0, v74, v0
	v_mul_f32_e32 v1, 0xbfb8aa3b, v0
	v_exp_f32_e32 v1, v1
	v_add_f32_e32 v5, 1.0, v39
	v_rcp_f32_e32 v5, v5
	v_mul_f32_e32 v11, v11, v4
	v_add_f32_e32 v1, 1.0, v1
	v_rcp_f32_e32 v1, v1
	v_mul_f32_e32 v4, v35, v5
	v_mul_f32_e32 v26, v26, v4
	v_mov_b32_dpp v131, v15 row_ror:1 row_mask:0xf bank_mask:0xf
	v_mul_f32_e32 v4, v0, v1
	v_cndmask_b32_e64 v0, v122, v119, s[0:1]
	v_cndmask_b32_e64 v1, v121, v124, s[2:3]
	v_pk_mul_f32 v[0:1], v[66:67], v[0:1]
	v_mul_f32_e32 v18, v18, v4
	v_fma_f32 v0, v38, v70, v0
	v_add_f32_e32 v0, v0, v1
	v_add_f32_e32 v35, v74, v0
	v_mul_f32_e32 v0, 0xbfb8aa3b, v35
	v_exp_f32_e32 v5, v0
	v_cndmask_b32_e64 v0, v119, v118, s[0:1]
	v_cndmask_b32_e64 v1, v120, v121, s[2:3]
	v_pk_mul_f32 v[0:1], v[66:67], v[0:1]
	v_mov_b32_e32 v4, v65
	v_fma_f32 v0, v34, v70, v0
	v_add_f32_e32 v0, v0, v1
	v_add_f32_e32 v34, v74, v0
	v_mul_f32_e32 v0, 0xbfb8aa3b, v34
	v_exp_f32_e32 v0, v0
	v_add_f32_e32 v1, 1.0, v5
	v_rcp_f32_e32 v38, v1
	v_cndmask_b32_e64 v1, v116, v114, s[2:3]
	v_add_f32_e32 v0, 1.0, v0
	v_rcp_f32_e32 v39, v0
	v_cndmask_b32_e64 v0, v117, v115, s[0:1]
	v_mov_b32_e32 v5, v77
	v_pk_mul_f32 v[0:1], v[4:5], v[0:1]
	v_mul_f32_e32 v34, v34, v39
	v_fma_f32 v0, v45, v69, v0
	v_add_f32_e32 v0, v0, v1
	v_add_f32_e32 v42, v73, v0
	v_mul_f32_e32 v0, 0xbfb8aa3b, v42
	v_exp_f32_e32 v0, v0
	v_mul_f32_e32 v1, v35, v38
	v_mul_f32_e32 v22, v22, v1
	v_cndmask_b32_e64 v1, v113, v116, s[2:3]
	v_add_f32_e32 v0, 1.0, v0
	v_rcp_f32_e32 v35, v0
	v_cndmask_b32_e64 v0, v115, v112, s[0:1]
	v_pk_mul_f32 v[0:1], v[4:5], v[0:1]
	v_mul_f32_e32 v10, v10, v34
	v_fma_f32 v0, v41, v69, v0
	v_add_f32_e32 v0, v0, v1
	v_add_f32_e32 v38, v73, v0
	v_mul_f32_e32 v0, 0xbfb8aa3b, v38
	v_exp_f32_e32 v0, v0
	v_mul_f32_e32 v1, v42, v35
	v_mul_f32_e32 v25, v25, v1
	v_cndmask_b32_e64 v1, v111, v113, s[2:3]
	v_add_f32_e32 v0, 1.0, v0
	v_rcp_f32_e32 v34, v0
	v_cndmask_b32_e64 v0, v112, v109, s[0:1]
	v_pk_mul_f32 v[0:1], v[4:5], v[0:1]
	v_mov_b32_e32 v65, v76
	v_fma_f32 v0, v37, v69, v0
	v_add_f32_e32 v0, v0, v1
	v_add_f32_e32 v35, v73, v0
	v_mul_f32_e32 v0, 0xbfb8aa3b, v35
	v_exp_f32_e32 v37, v0
	v_cndmask_b32_e64 v0, v109, v108, s[0:1]
	v_cndmask_b32_e64 v1, v110, v111, s[2:3]
	v_pk_mul_f32 v[0:1], v[4:5], v[0:1]
	v_add_f32_e32 v5, 1.0, v37
	v_fma_f32 v0, v33, v69, v0
	v_add_f32_e32 v0, v0, v1
	v_add_f32_e32 v0, v73, v0
	v_mul_f32_e32 v1, 0xbfb8aa3b, v0
	v_exp_f32_e32 v1, v1
	v_rcp_f32_e32 v5, v5
	v_mul_f32_e32 v4, v38, v34
	v_mul_f32_e32 v17, v17, v4
	v_add_f32_e32 v1, 1.0, v1
	v_rcp_f32_e32 v1, v1
	v_mul_f32_e32 v4, v35, v5
	v_mul_f32_e32 v21, v21, v4
	v_mov_b32_dpp v172, v15 row_ror:15 row_mask:0xf bank_mask:0xf
	v_mul_f32_e32 v4, v0, v1
	v_cndmask_b32_e64 v0, v107, v105, s[0:1]
	v_cndmask_b32_e64 v1, v106, v103, s[2:3]
	v_pk_mul_f32 v[0:1], v[64:65], v[0:1]
	v_mul_f32_e32 v9, v9, v4
	v_fma_f32 v0, v44, v68, v0
	v_add_f32_e32 v0, v0, v1
	v_add_f32_e32 v5, v72, v0
	v_mul_f32_e32 v0, 0xbfb8aa3b, v5
	v_exp_f32_e32 v33, v0
	v_cndmask_b32_e64 v0, v105, v102, s[0:1]
	v_cndmask_b32_e64 v1, v104, v106, s[2:3]
	v_pk_mul_f32 v[0:1], v[64:65], v[0:1]
	v_mul_f32_e32 v43, v43, v49
	v_fma_f32 v0, v40, v68, v0
	v_add_f32_e32 v0, v0, v1
	v_add_f32_e32 v34, v72, v0
	v_mul_f32_e32 v0, 0xbfb8aa3b, v34
	v_exp_f32_e32 v0, v0
	v_add_f32_e32 v1, 1.0, v33
	v_rcp_f32_e32 v4, v1
	v_cndmask_b32_e64 v1, v101, v104, s[2:3]
	v_add_f32_e32 v0, 1.0, v0
	v_rcp_f32_e32 v33, v0
	v_cndmask_b32_e64 v0, v102, v99, s[0:1]
	v_pk_mul_f32 v[0:1], v[64:65], v[0:1]
	v_mul_f32_e32 v19, v19, v43
	v_fma_f32 v0, v36, v68, v0
	v_add_f32_e32 v0, v0, v1
	v_add_f32_e32 v35, v72, v0
	v_mul_f32_e32 v0, 0xbfb8aa3b, v35
	v_exp_f32_e32 v0, v0
	v_mul_f32_e32 v1, v5, v4
	v_mul_f32_e32 v24, v24, v1
	v_cndmask_b32_e64 v1, v100, v101, s[2:3]
	v_add_f32_e32 v0, 1.0, v0
	v_rcp_f32_e32 v5, v0
	v_cndmask_b32_e64 v0, v99, v98, s[0:1]
	v_pk_mul_f32 v[0:1], v[64:65], v[0:1]
	v_mul_f32_e32 v4, v34, v33
	v_fma_f32 v0, v32, v68, v0
	v_add_f32_e32 v0, v0, v1
	v_add_f32_e32 v32, v72, v0
	v_mul_f32_e32 v0, 0xbfb8aa3b, v32
	v_exp_f32_e32 v0, v0
	v_mul_f32_e32 v1, v35, v5
	v_mul_f32_e32 v20, v20, v1
	v_cndmask_b32_e64 v1, v172, v123, s[2:3]
	v_add_f32_e32 v0, 1.0, v0
	v_rcp_f32_e32 v33, v0
	v_cndmask_b32_e64 v0, v131, v127, s[0:1]
	v_mul_f32_e32 v16, v16, v4
	v_cndmask_b32_e64 v5, v129, v172, s[2:3]
	v_cndmask_b32_e64 v4, v127, v126, s[0:1]
	v_pk_mul_f32 v[0:1], v[96:97], v[0:1]
	v_pk_mul_f32 v[4:5], v[96:97], v[4:5]
	v_fma_f32 v0, v15, v83, v0
	v_fma_f32 v4, v31, v83, v4
	v_add_f32_e32 v0, v0, v1
	v_add_f32_e32 v4, v4, v5
	v_add_f32_e32 v0, v87, v0
	v_add_f32_e32 v4, v87, v4
	v_mul_f32_e32 v1, 0xbfb8aa3b, v0
	v_mul_f32_e32 v5, 0xbfb8aa3b, v4
	v_exp_f32_e32 v1, v1
	v_exp_f32_e32 v5, v5
	v_mul_f32_e32 v15, v32, v33
	v_readlane_b32 s0, v253, 57
	v_add_f32_e32 v1, 1.0, v1
	v_add_f32_e32 v5, 1.0, v5
	v_rcp_f32_e32 v1, v1
	v_rcp_f32_e32 v5, v5
	v_mul_f32_e32 v8, v8, v15
	v_add_u32_e32 v31, s0, v174
	v_mul_f32_e32 v0, v0, v1
	v_mul_f32_e32 v4, v4, v5
	v_mul_f32_e32 v3, v3, v0
	v_mov_b64_e32 v[0:1], s[8:9]
	s_movk_i32 s2, 0x1600
	v_mul_f32_e32 v15, v7, v4
	v_cvt_pk_bf16_f32 v4, v8, v9
	v_mad_i64_i32 v[8:9], s[0:1], v31, s2, v[0:1]
	v_lshl_add_u64 v[8:9], v[8:9], 0, v[168:169]
	v_readlane_b32 s0, v253, 58
	v_cvt_pk_bf16_f32 v5, v10, v11
	v_cvt_pk_bf16_f32 v6, v6, v13
	v_cvt_pk_bf16_f32 v7, v58, v170
	global_store_dwordx4 v[8:9], v[4:7], off
	s_nop 0
	v_add_u32_e32 v8, s0, v174
	v_mad_i64_i32 v[8:9], s[0:1], v8, s2, v[0:1]
	v_lshl_add_u64 v[8:9], v[8:9], 0, v[168:169]
	v_readlane_b32 s0, v253, 59
	v_cvt_pk_bf16_f32 v4, v20, v21
	v_cvt_pk_bf16_f32 v5, v22, v23
	v_cvt_pk_bf16_f32 v6, v12, v51
	v_cvt_pk_bf16_f32 v7, v30, v55
	global_store_dwordx4 v[8:9], v[4:7], off
	s_nop 0
	v_add_u32_e32 v8, s0, v174
	v_mad_i64_i32 v[8:9], s[0:1], v8, s2, v[0:1]
	v_lshl_add_u64 v[8:9], v[8:9], 0, v[168:169]
	v_readlane_b32 s0, v253, 61
	v_cvt_pk_bf16_f32 v4, v16, v17
	v_cvt_pk_bf16_f32 v5, v18, v19
	v_cvt_pk_bf16_f32 v6, v29, v54
	v_cvt_pk_bf16_f32 v7, v14, v15
	global_store_dwordx4 v[8:9], v[4:7], off
	s_nop 0
	v_add_u32_e32 v8, s0, v174
	v_mad_i64_i32 v[0:1], s[0:1], v8, s2, v[0:1]
	v_lshl_add_u64 v[0:1], v[0:1], 0, v[168:169]
	v_cvt_pk_bf16_f32 v4, v24, v25
	v_cvt_pk_bf16_f32 v5, v26, v27
	v_cvt_pk_bf16_f32 v6, v28, v59
	v_cvt_pk_bf16_f32 v7, v2, v3
	global_store_dwordx4 v[0:1], v[4:7], off
	s_waitcnt vmcnt(0)
	s_barrier
